# attention: s_setprio 1 around MFMA clusters in dense attention; GEMM tile-head vmcnt(0) drain removed
# speedup vs baseline: 1.0012x; 1.0012x over previous
; DEVI int otid() { int t = threadIdx.x; asm volatile("" : "+v"(t)); return t; }
; #define RAW_BARRIER() do { asm volatile("s_waitcnt lgkmcnt(0)" ::: "memory"); __builtin_amdgcn_s_barrier(); } while (0)
; template <int EPI, int NB>
; DEVI void gemm_tile(const GemmJob& J, int m0, int n0, unsigned char* smem) {
;     ...
;   const int tid = otid(), lane = tid & 63, wid = tid >> 6, wm = wid >> 1, wn = wid & 1;
;   const int l16 = lane & 15, g = lane >> 4;
;   f32x4 acc[4][NB];
; #pragma unroll
;   for (int i = 0; i < 4; ++i)
; #pragma unroll
;     for (int j = 0; j < NB; ++j) acc[i][j] = (f32x4){0.f, 0.f, 0.f, 0.f};
;   const int srow = tid >> 2, sch = tid & 3;
;   const int gch = sch ^ ((0 - (tid >> 4)) & 3);
;   const bf16_t* Ag = J.A + (size_t)(m0 + srow) * (J.ablk ? 32 : J.lda) + gch * 8;
;   const bf16_t* Bg = J.Bt + (size_t)(n0 + srow) * 32 + gch * 8;
;   const size_t Astep = (size_t)64 * (J.ablk ? 32 : J.lda), Ak = J.ablk ? (size_t)MROWS * 32 : (size_t)32, Bstep = (size_t)64 * 32, Bk = (size_t)J.NR * 32;
;   const int nk = J.K >> 5;
;   unsigned char* lds_t = smem + tid * 16;
;   const unsigned lbase = (unsigned)(uintptr_t)(__attribute__((address_space(3))) unsigned char*)smem;
;     ...
;   asm volatile("s_waitcnt vmcnt(0)" ::: "memory");
;   RAW_BARRIER();
; #pragma unroll
;   for (int st = 0; st < S - 1; ++st) GEMM_ISSUE(st, st);
;   const int fsl = (g ^ ((0 - (l16 >> 2)) & 3)) << 4;
;   const int aofs = (wm * 64 + l16) * 64 + fsl;
;   const int bofs = A_BYTES + (wn * NB * 16 + l16) * 64 + fsl;
; template <int EPI, int NB>
; DEVI void gemm_run(const GemmJob& J, unsigned char* smem, int rot) {
;     ...
;     for (int t = b; t < ntiles; t += G) {
;       const int mt = t / J.ntn, nt = J.nt0 + (t - mt * J.ntn);
;       gemm_tile<EPI, NB>(J, mt * 128, nt * BN, smem);
.LBB0_152:
	s_mul_hi_i32 s0, s3, 0x2e8ba2e9
	s_lshr_b32 s1, s0, 31
	s_ashr_i32 s0, s0, 2
	s_add_i32 s0, s0, s1
	s_mul_i32 s1, s0, 0xffffffea
	s_add_i32 s1, s1, s3
	v_mov_b32_e32 v186, v177
	s_lshl_b32 s8, s0, 7
	s_lshl_b32 s9, s1, 8
	s_nop 0
	s_mov_b64 s[28:29], 0x1000
	v_ashrrev_i32_e32 v10, 2, v186
	v_lshrrev_b32_e32 v0, 4, v186
	v_sub_u32_e32 v11, 0, v0
	v_add_u32_e32 v2, s8, v10
	v_add_u32_e32 v6, s9, v10
	v_xor_b32_e32 v0, v186, v11
	v_ashrrev_i32_e32 v3, 31, v2
	v_ashrrev_i32_e32 v7, 31, v6
	v_lshlrev_b64 v[2:3], 6, v[2:3]
	v_lshlrev_b32_e32 v0, 4, v0
	v_lshlrev_b64 v[6:7], 6, v[6:7]
	v_lshl_add_u64 v[4:5], v[146:147], 0, v[2:3]
	v_and_b32_e32 v0, 48, v0
	v_lshl_add_u64 v[6:7], v[178:179], 0, v[6:7]
	v_lshlrev_b32_e32 v187, 4, v186
	v_lshl_add_u64 v[4:5], v[4:5], 0, v[0:1]
	v_lshl_add_u64 v[6:7], v[6:7], 0, v[0:1]
	v_readfirstlane_b32 s1, v187
	v_add_u32_e32 v0, 0x1000, v187
	s_mov_b32 m0, s1
	v_readfirstlane_b32 s1, v0
	v_add_u32_e32 v0, 0x2000, v187
	s_waitcnt lgkmcnt(0)
	s_barrier
	global_load_lds_dwordx4 v[4:5], off
	v_lshl_add_u64 v[8:9], v[4:5], 0, s[28:29]
	s_mov_b32 m0, s1
	v_readfirstlane_b32 s1, v0
	v_add_u32_e32 v0, 0x3000, v187
	global_load_lds_dwordx4 v[8:9], off
	s_mov_b32 m0, s1
	v_readfirstlane_b32 s1, v0
	v_add_u32_e32 v0, 0x4000, v187
	global_load_lds_dwordx4 v[6:7], off
	v_lshl_add_u64 v[8:9], v[6:7], 0, s[28:29]
	s_mov_b32 m0, s1
	s_mov_b64 s[28:29], 0x2000
	v_readfirstlane_b32 s1, v0
	v_add_u32_e32 v0, 0x5000, v187
	global_load_lds_dwordx4 v[8:9], off
	v_lshl_add_u64 v[8:9], v[6:7], 0, s[28:29]
	s_mov_b32 m0, s1
	s_mov_b64 s[28:29], 0x3000
	v_readfirstlane_b32 s1, v0
	v_add_u32_e32 v0, 0x6000, v187
	global_load_lds_dwordx4 v[8:9], off
	v_lshl_add_u64 v[8:9], v[6:7], 0, s[28:29]
	s_mov_b32 m0, s1
	v_readfirstlane_b32 s1, v0
	v_add_u32_e32 v0, 0x7000, v187
	global_load_lds_dwordx4 v[8:9], off
	v_lshl_add_u64 v[8:9], v[4:5], 0, s[94:95]
	s_mov_b32 m0, s1
	s_mov_b64 s[28:29], 0x30b000
	v_readfirstlane_b32 s1, v0
	v_add_u32_e32 v0, 0x8000, v187
	global_load_lds_dwordx4 v[8:9], off
	v_lshl_add_u64 v[4:5], v[4:5], 0, s[28:29]
	s_mov_b32 m0, s1
	v_readfirstlane_b32 s1, v0
	v_add_u32_e32 v0, 0x9000, v187
	global_load_lds_dwordx4 v[4:5], off
	v_lshl_add_u64 v[4:5], v[6:7], 0, s[50:51]
	s_mov_b32 m0, s1
	s_mov_b64 s[28:29], 0x59000
	v_readfirstlane_b32 s1, v0
	v_add_u32_e32 v0, 0xa000, v187
	global_load_lds_dwordx4 v[4:5], off
	v_lshl_add_u64 v[4:5], v[6:7], 0, s[28:29]
	s_mov_b32 m0, s1
	s_mov_b64 s[28:29], 0x5a000
	v_readfirstlane_b32 s1, v0
	v_add_u32_e32 v0, 0xb000, v187
	global_load_lds_dwordx4 v[4:5], off
	v_lshl_add_u64 v[4:5], v[6:7], 0, s[28:29]
	s_mov_b32 m0, s1
	s_mov_b64 s[28:29], 0x5b000
	v_readfirstlane_b32 s1, v0
	global_load_lds_dwordx4 v[4:5], off
	v_lshl_add_u64 v[4:5], v[6:7], 0, s[28:29]
	s_mov_b32 m0, s1
	v_lshlrev_b32_e32 v0, 2, v186
	global_load_lds_dwordx4 v[4:5], off
	v_and_b32_e32 v0, 48, v0
	v_ashrrev_i32_e32 v4, 1, v186
	v_and_b32_e32 v208, 15, v186
	v_sub_u32_e32 v0, 0, v0
	v_and_b32_e32 v209, 0xffffffc0, v4
	v_bitop3_b32 v0, v186, 48, v0 bitop3:0x48
	v_or_b32_e32 v4, v209, v208
	v_lshl_or_b32 v210, v4, 6, v0
	v_lshlrev_b32_e32 v4, 1, v186
	v_and_b32_e32 v211, 0x80, v4
	v_or_b32_e32 v4, v211, v208
	v_lshl_or_b32 v0, v4, 6, v0
	v_add_u32_e32 v4, s2, v10
	s_mulk_i32 s0, 0x1600
	v_subrev_u32_e32 v4, s0, v4
	v_ashrrev_i32_e32 v5, 31, v4
	v_add_u32_e32 v212, 0x2000, v0
	v_bitop3_b32 v0, v186, 3, v11 bitop3:0x48
	v_lshlrev_b64 v[4:5], 6, v[4:5]
	v_mov_b32_e32 v6, 0
	s_mov_b32 s42, 2
	s_mov_b32 s20, 0
	s_mov_b64 s[30:31], 0x1000
	v_lshlrev_b32_e32 v0, 4, v0
	v_lshl_add_u64 v[182:183], v[180:181], 0, v[4:5]
	v_lshl_add_u64 v[184:185], v[130:131], 0, v[2:3]
	s_mov_b32 s43, 0
	v_mov_b32_e32 v7, v6
	v_mov_b32_e32 v8, v6
	v_mov_b32_e32 v9, v6
	v_mov_b32_e32 v14, v6
	v_mov_b32_e32 v15, v6
	v_mov_b32_e32 v16, v6
	v_mov_b32_e32 v17, v6
	v_mov_b32_e32 v2, v6
	v_mov_b32_e32 v3, v6
	v_mov_b32_e32 v4, v6
	v_mov_b32_e32 v5, v6
	v_mov_b32_e32 v10, v6
	v_mov_b32_e32 v11, v6
	v_mov_b32_e32 v12, v6
	v_mov_b32_e32 v13, v6
	v_mov_b32_e32 v22, v6
	v_mov_b32_e32 v23, v6
	v_mov_b32_e32 v24, v6
	v_mov_b32_e32 v25, v6
	v_mov_b32_e32 v30, v6
; #define RAW_BARRIER() do { asm volatile("s_waitcnt lgkmcnt(0)" ::: "memory"); __builtin_amdgcn_s_barrier(); } while (0)
; template <int EPI, int NB>
; DEVI void gemm_tile(const GemmJob& J, int m0, int n0, unsigned char* smem) {
;     ...
;   f32x4 acc[4][NB];
; #pragma unroll
;   for (int i = 0; i < 4; ++i)
; #pragma unroll
;     for (int j = 0; j < NB; ++j) acc[i][j] = (f32x4){0.f, 0.f, 0.f, 0.f};
;     ...
;   int cs = 0, is = S - 1;
; #pragma clang loop unroll(disable)
;   for (int kt = 0; kt < nk; ++kt) {
;     if (nk - 1 - kt >= S - 2) {
;       if constexpr (NB == 8) asm volatile("s_waitcnt vmcnt(6)" ::: "memory");
;       else                   asm volatile("s_waitcnt vmcnt(8)" ::: "memory");
;     } else {
;       asm volatile("s_waitcnt vmcnt(0)" ::: "memory");
;     }
;     RAW_BARRIER();
;     if (kt + S - 1 < nk) GEMM_ISSUE(kt + S - 1, is);
;     is = (is + 1 == S) ? 0 : is + 1;
;     const unsigned cur = lbase + cs * STG;
	v_mov_b32_e32 v31, v6
	v_mov_b32_e32 v32, v6
	v_mov_b32_e32 v33, v6
	v_mov_b32_e32 v18, v6
	v_mov_b32_e32 v19, v6
	v_mov_b32_e32 v20, v6
	v_mov_b32_e32 v21, v6
	v_mov_b32_e32 v26, v6
	v_mov_b32_e32 v27, v6
	v_mov_b32_e32 v28, v6
	v_mov_b32_e32 v29, v6
	v_mov_b32_e32 v38, v6
	v_mov_b32_e32 v39, v6
	v_mov_b32_e32 v40, v6
	v_mov_b32_e32 v41, v6
	v_mov_b32_e32 v46, v6
	v_mov_b32_e32 v47, v6
	v_mov_b32_e32 v48, v6
	v_mov_b32_e32 v49, v6
	v_mov_b32_e32 v34, v6
	v_mov_b32_e32 v35, v6
	v_mov_b32_e32 v36, v6
	v_mov_b32_e32 v37, v6
	v_mov_b32_e32 v42, v6
	v_mov_b32_e32 v43, v6
	v_mov_b32_e32 v44, v6
	v_mov_b32_e32 v45, v6
	v_mov_b32_e32 v54, v6
	v_mov_b32_e32 v55, v6
	v_mov_b32_e32 v56, v6
	v_mov_b32_e32 v57, v6
	v_mov_b32_e32 v62, v6
	v_mov_b32_e32 v63, v6
	v_mov_b32_e32 v64, v6
	v_mov_b32_e32 v65, v6
	v_mov_b32_e32 v50, v6
	v_mov_b32_e32 v51, v6
	v_mov_b32_e32 v52, v6
	v_mov_b32_e32 v53, v6
	v_mov_b32_e32 v58, v6
	v_mov_b32_e32 v59, v6
	v_mov_b32_e32 v60, v6
	v_mov_b32_e32 v61, v6
	v_mov_b32_e32 v70, v6
	v_mov_b32_e32 v71, v6
	v_mov_b32_e32 v72, v6
	v_mov_b32_e32 v73, v6
	v_mov_b32_e32 v78, v6
	v_mov_b32_e32 v79, v6
	v_mov_b32_e32 v80, v6
	v_mov_b32_e32 v81, v6
	v_mov_b32_e32 v66, v6
	v_mov_b32_e32 v67, v6
	v_mov_b32_e32 v68, v6
	v_mov_b32_e32 v69, v6
	v_mov_b32_e32 v74, v6
	v_mov_b32_e32 v75, v6
	v_mov_b32_e32 v76, v6
	v_mov_b32_e32 v77, v6
	v_mov_b32_e32 v86, v6
	v_mov_b32_e32 v87, v6
	v_mov_b32_e32 v88, v6
	v_mov_b32_e32 v89, v6
	v_mov_b32_e32 v94, v6
	v_mov_b32_e32 v95, v6
	v_mov_b32_e32 v96, v6
	v_mov_b32_e32 v97, v6
	v_mov_b32_e32 v82, v6
	v_mov_b32_e32 v83, v6
	v_mov_b32_e32 v84, v6
	v_mov_b32_e32 v85, v6
	v_mov_b32_e32 v90, v6
	v_mov_b32_e32 v91, v6
	v_mov_b32_e32 v92, v6
	v_mov_b32_e32 v93, v6
	v_mov_b32_e32 v102, v6
	v_mov_b32_e32 v103, v6
	v_mov_b32_e32 v104, v6
	v_mov_b32_e32 v105, v6
	v_mov_b32_e32 v110, v6
	v_mov_b32_e32 v111, v6
	v_mov_b32_e32 v112, v6
	v_mov_b32_e32 v113, v6
	v_mov_b32_e32 v98, v6
	v_mov_b32_e32 v99, v6
	v_mov_b32_e32 v100, v6
	v_mov_b32_e32 v101, v6
	v_mov_b32_e32 v106, v6
	v_mov_b32_e32 v107, v6
	v_mov_b32_e32 v108, v6
	v_mov_b32_e32 v109, v6
	v_mov_b32_e32 v118, v6
	v_mov_b32_e32 v119, v6
	v_mov_b32_e32 v120, v6
	v_mov_b32_e32 v121, v6
	v_mov_b32_e32 v126, v6
	v_mov_b32_e32 v127, v6
	v_mov_b32_e32 v128, v6
	v_mov_b32_e32 v129, v6
	v_mov_b32_e32 v114, v6
	v_mov_b32_e32 v115, v6
	v_mov_b32_e32 v116, v6
	v_mov_b32_e32 v117, v6
	v_mov_b32_e32 v122, v6
	v_mov_b32_e32 v123, v6
	v_mov_b32_e32 v124, v6
	v_mov_b32_e32 v125, v6
	s_mul_i32 s0, s42, 0x6000
	v_add_u32_e32 v213, s0, v187
	v_lshl_add_u64 v[214:215], v[184:185], 0, v[0:1]
	v_readfirstlane_b32 s0, v213
	v_lshl_add_u64 v[216:217], v[214:215], 0, s[84:85]
	s_mov_b32 m0, s0
	v_lshl_add_u64 v[214:215], v[214:215], 0, s[12:13]
	s_nop 0
	v_readfirstlane_b32 s100, v216
	v_readfirstlane_b32 s101, v217
	s_nop 1
	v_subrev_u32_e32 v230, s100, v216
	v_add_u32_e32 v216, 0x1000, v213
	v_add_u32_e32 v218, 0x2000, v213
	v_readfirstlane_b32 s0, v216
	s_mov_b32 m0, s0
	s_mov_b64 s[0:1], 0x256000
	v_subrev_u32_e32 v231, s100, v214
	v_lshl_add_u64 v[214:215], v[182:183], 0, v[0:1]
	v_lshl_add_u64 v[216:217], v[214:215], 0, s[0:1]
	v_readfirstlane_b32 s0, v218
	s_mov_b32 m0, s0
	s_mov_b64 s[0:1], 0x257000
	v_add_u32_e32 v218, 0x3000, v213
	s_nop 0
	v_readfirstlane_b32 vcc_lo, v216
	v_readfirstlane_b32 vcc_hi, v217
	s_nop 1
	v_subrev_u32_e32 v232, vcc_lo, v216
	v_lshl_add_u64 v[216:217], v[214:215], 0, s[0:1]
	v_readfirstlane_b32 s0, v218
	s_mov_b32 m0, s0
	s_mov_b64 s[0:1], 0x258000
	v_add_u32_e32 v218, 0x4000, v213
	v_subrev_u32_e32 v233, vcc_lo, v216
	v_lshl_add_u64 v[216:217], v[214:215], 0, s[0:1]
	v_readfirstlane_b32 s0, v218
	s_mov_b32 m0, s0
	s_mov_b64 s[0:1], 0x259000
	v_add_u32_e32 v213, 0x5000, v213
	v_lshl_add_u64 v[214:215], v[214:215], 0, s[0:1]
	v_readfirstlane_b32 s0, v213
	v_subrev_u32_e32 v234, vcc_lo, v216
	s_mov_b32 m0, s0
	s_nop 0
	v_subrev_u32_e32 v235, vcc_lo, v214
	v_mov_b32_e32 v184, v230
	v_mov_b32_e32 v185, v231
	v_mov_b32_e32 v182, v232
	v_mov_b32_e32 v183, v233
	v_mov_b32_e32 v253, v234
	v_mov_b32_e32 v254, v235
	v_readfirstlane_b32 s0, v187
	s_branch .LBB0_154

; DEVI int otid() { int t = threadIdx.x; asm volatile("" : "+v"(t)); return t; }
; #define RAW_BARRIER() do { asm volatile("s_waitcnt lgkmcnt(0)" ::: "memory"); __builtin_amdgcn_s_barrier(); } while (0)
; template <int EPI, int NB>
; DEVI void gemm_tile(const GemmJob& J, int m0, int n0, unsigned char* smem) {
;     ...
;   const int tid = otid(), lane = tid & 63, wid = tid >> 6, wm = wid >> 1, wn = wid & 1;
;   const int l16 = lane & 15, g = lane >> 4;
;   f32x4 acc[4][NB];
; #pragma unroll
;   for (int i = 0; i < 4; ++i)
; #pragma unroll
;     for (int j = 0; j < NB; ++j) acc[i][j] = (f32x4){0.f, 0.f, 0.f, 0.f};
;   const int srow = tid >> 2, sch = tid & 3;
;   const int gch = sch ^ ((0 - (tid >> 4)) & 3);
;   const bf16_t* Ag = J.A + (size_t)(m0 + srow) * (J.ablk ? 32 : J.lda) + gch * 8;
;   const bf16_t* Bg = J.Bt + (size_t)(n0 + srow) * 32 + gch * 8;
;   const size_t Astep = (size_t)64 * (J.ablk ? 32 : J.lda), Ak = J.ablk ? (size_t)MROWS * 32 : (size_t)32, Bstep = (size_t)64 * 32, Bk = (size_t)J.NR * 32;
;   const int nk = J.K >> 5;
;   unsigned char* lds_t = smem + tid * 16;
;   const unsigned lbase = (unsigned)(uintptr_t)(__attribute__((address_space(3))) unsigned char*)smem;
;     ...
;   asm volatile("s_waitcnt vmcnt(0)" ::: "memory");
;   RAW_BARRIER();
; #pragma unroll
;   for (int st = 0; st < S - 1; ++st) GEMM_ISSUE(st, st);
;   const int fsl = (g ^ ((0 - (l16 >> 2)) & 3)) << 4;
;   const int aofs = (wm * 64 + l16) * 64 + fsl;
;   const int bofs = A_BYTES + (wn * NB * 16 + l16) * 64 + fsl;
; template <int EPI, int NB>
; DEVI void gemm_run(const GemmJob& J, unsigned char* smem, int rot) {
;     ...
;     for (int q0 = lb; q0 < ntot; q0 += nlb) {
;       const int q = J.rev ? ntot - 1 - q0 : q0;
;       int grp = q / gsz; const int qq = q - grp * gsz;
;       const int mg = min(8, mcnt - grp * 8);
;       const int nt = qq / mg, mi = qq - nt * mg;
;       gemm_tile<EPI, NB>(J, (mlo + grp * 8 + mi) * 128, (J.nt0 + nt) * BN, smem);
.LBB0_165:
	s_mul_hi_i32 s0, s3, 0x2e8ba2e9
	s_lshr_b32 s1, s0, 31
	s_ashr_i32 s0, s0, 5
	s_add_i32 s0, s0, s1
	s_lshl_b32 s1, s0, 3
	v_readlane_b32 s8, v251, 48
	s_sub_i32 s8, s8, s1
	s_min_i32 s9, s8, 8
	s_abs_i32 s20, s9
	v_cvt_f32_u32_e32 v0, s20
	s_sub_i32 s43, 0, s20
	s_mul_i32 s40, s0, 0xffffff50
	s_add_i32 s40, s40, s3
	v_rcp_iflag_f32_e32 v0, v0
	s_abs_i32 s41, s40
	s_xor_b32 s42, s40, s9
	s_ashr_i32 s42, s42, 31
	v_mul_f32_e32 v0, 0x4f7ffffe, v0
	v_cvt_u32_f32_e32 v0, v0
	v_mov_b32_e32 v186, v177
	s_nop 0
	v_readfirstlane_b32 s44, v0
	s_mul_i32 s43, s43, s44
	s_mul_hi_u32 s43, s44, s43
	s_add_i32 s44, s44, s43
	s_mul_hi_u32 s43, s41, s44
	s_mul_i32 s44, s43, s20
	s_sub_i32 s41, s41, s44
	s_add_i32 s45, s43, 1
	s_sub_i32 s44, s41, s20
	s_cmp_ge_u32 s41, s20
	s_cselect_b32 s43, s45, s43
	s_cselect_b32 s41, s44, s41
	s_add_i32 s44, s43, 1
	s_cmp_ge_u32 s41, s20
	s_cselect_b32 s20, s44, s43
	s_xor_b32 s20, s20, s42
	s_sub_i32 s20, s20, s42
	s_mul_i32 s41, s9, s20
	v_readlane_b32 s9, v250, 37
	s_add_i32 s1, s1, s9
	s_add_i32 s1, s1, s40
	s_sub_i32 s1, s1, s41
	s_lshl_b32 s9, s1, 7
	s_lshl_b32 s20, s20, 8
	v_ashrrev_i32_e32 v10, 2, v186
	v_lshrrev_b32_e32 v0, 4, v186
	v_sub_u32_e32 v11, 0, v0
	v_add_u32_e32 v2, s9, v10
	v_add_u32_e32 v4, s20, v10
	v_xor_b32_e32 v0, v186, v11
	v_ashrrev_i32_e32 v3, 31, v2
	v_ashrrev_i32_e32 v5, 31, v4
	v_lshlrev_b64 v[2:3], 6, v[2:3]
	v_lshlrev_b32_e32 v0, 4, v0
	v_lshlrev_b64 v[4:5], 6, v[4:5]
	v_lshl_add_u64 v[2:3], v[146:147], 0, v[2:3]
	v_and_b32_e32 v0, 48, v0
	v_lshl_add_u64 v[6:7], v[178:179], 0, v[4:5]
	v_lshlrev_b32_e32 v187, 4, v186
	v_lshl_add_u64 v[2:3], v[2:3], 0, v[0:1]
	v_lshl_add_u64 v[6:7], v[6:7], 0, v[0:1]
	v_readfirstlane_b32 s1, v187
	v_add_u32_e32 v0, 0x1000, v187
	s_mov_b32 m0, s1
	s_mov_b64 s[28:29], 0x1000
	v_readfirstlane_b32 s1, v0
	v_add_u32_e32 v0, 0x2000, v187
	s_waitcnt lgkmcnt(0)
	s_barrier
	global_load_lds_dwordx4 v[2:3], off
	v_lshl_add_u64 v[8:9], v[2:3], 0, s[28:29]
	s_mov_b32 m0, s1
	v_readfirstlane_b32 s1, v0
	v_add_u32_e32 v0, 0x3000, v187
	global_load_lds_dwordx4 v[8:9], off
	s_mov_b32 m0, s1
	v_readfirstlane_b32 s1, v0
	v_add_u32_e32 v0, 0x4000, v187
	global_load_lds_dwordx4 v[6:7], off
	v_lshl_add_u64 v[8:9], v[6:7], 0, s[28:29]
	s_mov_b32 m0, s1
	s_mov_b64 s[28:29], 0x2000
	v_readfirstlane_b32 s1, v0
	v_add_u32_e32 v0, 0x5000, v187
	global_load_lds_dwordx4 v[8:9], off
	v_lshl_add_u64 v[8:9], v[6:7], 0, s[28:29]
	s_mov_b32 m0, s1
	s_mov_b64 s[28:29], 0x3000
	v_readfirstlane_b32 s1, v0
	v_add_u32_e32 v0, 0x6000, v187
	global_load_lds_dwordx4 v[8:9], off
	v_lshl_add_u64 v[8:9], v[6:7], 0, s[28:29]
	s_mov_b32 m0, s1
	v_readfirstlane_b32 s1, v0
	v_add_u32_e32 v0, 0x7000, v187
	global_load_lds_dwordx4 v[8:9], off
	v_lshl_add_u64 v[8:9], v[2:3], 0, s[94:95]
	s_mov_b32 m0, s1
	s_mov_b64 s[28:29], 0x30b000
	v_readfirstlane_b32 s1, v0
	v_add_u32_e32 v0, 0x8000, v187
	global_load_lds_dwordx4 v[8:9], off
	v_lshl_add_u64 v[2:3], v[2:3], 0, s[28:29]
	s_mov_b32 m0, s1
	v_readfirstlane_b32 s1, v0
	v_add_u32_e32 v0, 0x9000, v187
	global_load_lds_dwordx4 v[2:3], off
	v_lshl_add_u64 v[2:3], v[6:7], 0, s[50:51]
	s_mov_b32 m0, s1
	s_mov_b64 s[28:29], 0x59000
	v_readfirstlane_b32 s1, v0
	v_add_u32_e32 v0, 0xa000, v187
	global_load_lds_dwordx4 v[2:3], off
	v_lshl_add_u64 v[2:3], v[6:7], 0, s[28:29]
	s_mov_b32 m0, s1
	s_mov_b64 s[28:29], 0x5a000
	v_readfirstlane_b32 s1, v0
	v_add_u32_e32 v0, 0xb000, v187
	global_load_lds_dwordx4 v[2:3], off
	v_lshl_add_u64 v[2:3], v[6:7], 0, s[28:29]
	s_mov_b32 m0, s1
	s_mov_b64 s[28:29], 0x5b000
	v_readfirstlane_b32 s1, v0
	global_load_lds_dwordx4 v[2:3], off
	v_lshl_add_u64 v[2:3], v[6:7], 0, s[28:29]
	s_mov_b32 m0, s1
	v_lshlrev_b32_e32 v0, 2, v186
	global_load_lds_dwordx4 v[2:3], off
	v_and_b32_e32 v0, 48, v0
	v_ashrrev_i32_e32 v2, 1, v186
	v_and_b32_e32 v208, 15, v186
	v_sub_u32_e32 v0, 0, v0
	v_and_b32_e32 v209, 0xffffffc0, v2
	v_bitop3_b32 v0, v186, 48, v0 bitop3:0x48
	v_or_b32_e32 v2, v209, v208
	v_lshl_or_b32 v210, v2, 6, v0
	v_lshlrev_b32_e32 v2, 1, v186
	v_and_b32_e32 v211, 0x80, v2
	s_sub_i32 s1, s2, s41
	s_mulk_i32 s0, 0xa8
	v_or_b32_e32 v2, v211, v208
	s_sub_i32 s0, s1, s0
	v_lshl_or_b32 v0, v2, 6, v0
	v_lshl_add_u32 v2, s0, 7, v10
	v_ashrrev_i32_e32 v3, 31, v2
	v_add_u32_e32 v212, 0x2000, v0
	v_bitop3_b32 v0, v186, 3, v11 bitop3:0x48
	v_lshlrev_b64 v[2:3], 6, v[2:3]
	v_mov_b32_e32 v6, 0
	s_mov_b32 s8, 0
	s_mov_b32 s42, 2
	s_mov_b64 s[30:31], 0x1000
	v_lshlrev_b32_e32 v0, 4, v0
	v_lshl_add_u64 v[182:183], v[180:181], 0, v[4:5]
	v_lshl_add_u64 v[184:185], v[130:131], 0, v[2:3]
	s_mov_b32 s43, 0
; #define RAW_BARRIER() do { asm volatile("s_waitcnt lgkmcnt(0)" ::: "memory"); __builtin_amdgcn_s_barrier(); } while (0)
; template <int EPI, int NB>
; DEVI void gemm_tile(const GemmJob& J, int m0, int n0, unsigned char* smem) {
;     ...
;   f32x4 acc[4][NB];
; #pragma unroll
;   for (int i = 0; i < 4; ++i)
; #pragma unroll
;     for (int j = 0; j < NB; ++j) acc[i][j] = (f32x4){0.f, 0.f, 0.f, 0.f};
;     ...
;   int cs = 0, is = S - 1;
; #pragma clang loop unroll(disable)
;   for (int kt = 0; kt < nk; ++kt) {
;     if (nk - 1 - kt >= S - 2) {
;       if constexpr (NB == 8) asm volatile("s_waitcnt vmcnt(6)" ::: "memory");
;       else                   asm volatile("s_waitcnt vmcnt(8)" ::: "memory");
;     } else {
;       asm volatile("s_waitcnt vmcnt(0)" ::: "memory");
;     }
;     RAW_BARRIER();
;     if (kt + S - 1 < nk) GEMM_ISSUE(kt + S - 1, is);
;     is = (is + 1 == S) ? 0 : is + 1;
;     const unsigned cur = lbase + cs * STG;
	v_mov_b32_e32 v7, v6
	v_mov_b32_e32 v8, v6
	v_mov_b32_e32 v9, v6
	v_mov_b32_e32 v14, v6
	v_mov_b32_e32 v15, v6
	v_mov_b32_e32 v16, v6
	v_mov_b32_e32 v17, v6
	v_mov_b32_e32 v2, v6
	v_mov_b32_e32 v3, v6
	v_mov_b32_e32 v4, v6
	v_mov_b32_e32 v5, v6
	v_mov_b32_e32 v10, v6
	v_mov_b32_e32 v11, v6
	v_mov_b32_e32 v12, v6
	v_mov_b32_e32 v13, v6
	v_mov_b32_e32 v22, v6
	v_mov_b32_e32 v23, v6
	v_mov_b32_e32 v24, v6
	v_mov_b32_e32 v25, v6
	v_mov_b32_e32 v30, v6
	v_mov_b32_e32 v31, v6
	v_mov_b32_e32 v32, v6
	v_mov_b32_e32 v33, v6
	v_mov_b32_e32 v18, v6
	v_mov_b32_e32 v19, v6
	v_mov_b32_e32 v20, v6
	v_mov_b32_e32 v21, v6
	v_mov_b32_e32 v26, v6
	v_mov_b32_e32 v27, v6
	v_mov_b32_e32 v28, v6
	v_mov_b32_e32 v29, v6
	v_mov_b32_e32 v38, v6
	v_mov_b32_e32 v39, v6
	v_mov_b32_e32 v40, v6
	v_mov_b32_e32 v41, v6
	v_mov_b32_e32 v46, v6
	v_mov_b32_e32 v47, v6
	v_mov_b32_e32 v48, v6
	v_mov_b32_e32 v49, v6
	v_mov_b32_e32 v34, v6
	v_mov_b32_e32 v35, v6
	v_mov_b32_e32 v36, v6
	v_mov_b32_e32 v37, v6
	v_mov_b32_e32 v42, v6
	v_mov_b32_e32 v43, v6
	v_mov_b32_e32 v44, v6
	v_mov_b32_e32 v45, v6
	v_mov_b32_e32 v54, v6
	v_mov_b32_e32 v55, v6
	v_mov_b32_e32 v56, v6
	v_mov_b32_e32 v57, v6
	v_mov_b32_e32 v62, v6
	v_mov_b32_e32 v63, v6
	v_mov_b32_e32 v64, v6
	v_mov_b32_e32 v65, v6
	v_mov_b32_e32 v50, v6
	v_mov_b32_e32 v51, v6
	v_mov_b32_e32 v52, v6
	v_mov_b32_e32 v53, v6
	v_mov_b32_e32 v58, v6
	v_mov_b32_e32 v59, v6
	v_mov_b32_e32 v60, v6
	v_mov_b32_e32 v61, v6
	v_mov_b32_e32 v70, v6
	v_mov_b32_e32 v71, v6
	v_mov_b32_e32 v72, v6
	v_mov_b32_e32 v73, v6
	v_mov_b32_e32 v78, v6
	v_mov_b32_e32 v79, v6
	v_mov_b32_e32 v80, v6
	v_mov_b32_e32 v81, v6
	v_mov_b32_e32 v66, v6
	v_mov_b32_e32 v67, v6
	v_mov_b32_e32 v68, v6
	v_mov_b32_e32 v69, v6
	v_mov_b32_e32 v74, v6
	v_mov_b32_e32 v75, v6
	v_mov_b32_e32 v76, v6
	v_mov_b32_e32 v77, v6
	v_mov_b32_e32 v86, v6
	v_mov_b32_e32 v87, v6
	v_mov_b32_e32 v88, v6
	v_mov_b32_e32 v89, v6
	v_mov_b32_e32 v94, v6
	v_mov_b32_e32 v95, v6
	v_mov_b32_e32 v96, v6
	v_mov_b32_e32 v97, v6
	v_mov_b32_e32 v82, v6
	v_mov_b32_e32 v83, v6
	v_mov_b32_e32 v84, v6
	v_mov_b32_e32 v85, v6
	v_mov_b32_e32 v90, v6
	v_mov_b32_e32 v91, v6
	v_mov_b32_e32 v92, v6
	v_mov_b32_e32 v93, v6
	v_mov_b32_e32 v102, v6
	v_mov_b32_e32 v103, v6
	v_mov_b32_e32 v104, v6
	v_mov_b32_e32 v105, v6
	v_mov_b32_e32 v110, v6
	v_mov_b32_e32 v111, v6
	v_mov_b32_e32 v112, v6
	v_mov_b32_e32 v113, v6
	v_mov_b32_e32 v98, v6
	v_mov_b32_e32 v99, v6
	v_mov_b32_e32 v100, v6
	v_mov_b32_e32 v101, v6
	v_mov_b32_e32 v106, v6
	v_mov_b32_e32 v107, v6
	v_mov_b32_e32 v108, v6
	v_mov_b32_e32 v109, v6
	v_mov_b32_e32 v118, v6
	v_mov_b32_e32 v119, v6
	v_mov_b32_e32 v120, v6
	v_mov_b32_e32 v121, v6
	v_mov_b32_e32 v126, v6
	v_mov_b32_e32 v127, v6
	v_mov_b32_e32 v128, v6
	v_mov_b32_e32 v129, v6
	v_mov_b32_e32 v114, v6
	v_mov_b32_e32 v115, v6
	v_mov_b32_e32 v116, v6
	v_mov_b32_e32 v117, v6
	v_mov_b32_e32 v122, v6
	v_mov_b32_e32 v123, v6
	v_mov_b32_e32 v124, v6
	v_mov_b32_e32 v125, v6
	s_mul_i32 s0, s42, 0x6000
	v_add_u32_e32 v213, s0, v187
	v_lshl_add_u64 v[214:215], v[184:185], 0, v[0:1]
	v_readfirstlane_b32 s0, v213
	v_lshl_add_u64 v[216:217], v[214:215], 0, s[84:85]
	s_mov_b32 m0, s0
	v_lshl_add_u64 v[214:215], v[214:215], 0, s[12:13]
	s_nop 0
	v_readfirstlane_b32 s100, v216
	v_readfirstlane_b32 s101, v217
	s_nop 1
	v_subrev_u32_e32 v230, s100, v216
	v_add_u32_e32 v216, 0x1000, v213
	v_add_u32_e32 v218, 0x2000, v213
	v_readfirstlane_b32 s0, v216
	s_mov_b32 m0, s0
	s_mov_b64 s[0:1], 0x256000
	v_subrev_u32_e32 v231, s100, v214
	v_lshl_add_u64 v[214:215], v[182:183], 0, v[0:1]
	v_lshl_add_u64 v[216:217], v[214:215], 0, s[0:1]
	v_readfirstlane_b32 s0, v218
	s_mov_b32 m0, s0
	s_mov_b64 s[0:1], 0x257000
	v_add_u32_e32 v218, 0x3000, v213
	s_nop 0
	v_readfirstlane_b32 vcc_lo, v216
	v_readfirstlane_b32 vcc_hi, v217
	s_nop 1
	v_subrev_u32_e32 v232, vcc_lo, v216
	v_lshl_add_u64 v[216:217], v[214:215], 0, s[0:1]
	v_readfirstlane_b32 s0, v218
	s_mov_b32 m0, s0
	s_mov_b64 s[0:1], 0x258000
	v_add_u32_e32 v218, 0x4000, v213
	v_subrev_u32_e32 v233, vcc_lo, v216
	v_lshl_add_u64 v[216:217], v[214:215], 0, s[0:1]
	v_readfirstlane_b32 s0, v218
	s_mov_b32 m0, s0
	s_mov_b64 s[0:1], 0x259000
	v_add_u32_e32 v213, 0x5000, v213
	v_lshl_add_u64 v[214:215], v[214:215], 0, s[0:1]
	v_readfirstlane_b32 s0, v213
	v_subrev_u32_e32 v234, vcc_lo, v216
	s_mov_b32 m0, s0
	s_nop 0
	v_subrev_u32_e32 v235, vcc_lo, v214
	v_mov_b32_e32 v184, v230
	v_mov_b32_e32 v185, v231
	v_mov_b32_e32 v182, v232
	v_mov_b32_e32 v183, v233
	v_mov_b32_e32 v253, v234
	v_mov_b32_e32 v254, v235
	v_readfirstlane_b32 s0, v187
	s_branch .LBB0_167

; DEVI int otid() { int t = threadIdx.x; asm volatile("" : "+v"(t)); return t; }
; #define RAW_BARRIER() do { asm volatile("s_waitcnt lgkmcnt(0)" ::: "memory"); __builtin_amdgcn_s_barrier(); } while (0)
; template <int EPI, int NB>
; DEVI void gemm_tile(const GemmJob& J, int m0, int n0, unsigned char* smem) {
;     ...
;   const int tid = otid(), lane = tid & 63, wid = tid >> 6, wm = wid >> 1, wn = wid & 1;
;   const int l16 = lane & 15, g = lane >> 4;
;   f32x4 acc[4][NB];
; #pragma unroll
;   for (int i = 0; i < 4; ++i)
; #pragma unroll
;     for (int j = 0; j < NB; ++j) acc[i][j] = (f32x4){0.f, 0.f, 0.f, 0.f};
;   const int srow = tid >> 2, sch = tid & 3;
;   const int gch = sch ^ ((0 - (tid >> 4)) & 3);
;   const bf16_t* Ag = J.A + (size_t)(m0 + srow) * (J.ablk ? 32 : J.lda) + gch * 8;
;   const bf16_t* Bg = J.Bt + (size_t)(n0 + srow) * 32 + gch * 8;
;   const size_t Astep = (size_t)64 * (J.ablk ? 32 : J.lda), Ak = J.ablk ? (size_t)MROWS * 32 : (size_t)32, Bstep = (size_t)64 * 32, Bk = (size_t)J.NR * 32;
;   const int nk = J.K >> 5;
;   unsigned char* lds_t = smem + tid * 16;
;   const unsigned lbase = (unsigned)(uintptr_t)(__attribute__((address_space(3))) unsigned char*)smem;
;     ...
;   asm volatile("s_waitcnt vmcnt(0)" ::: "memory");
;   RAW_BARRIER();
; #pragma unroll
;   for (int st = 0; st < S - 1; ++st) GEMM_ISSUE(st, st);
;   const int fsl = (g ^ ((0 - (l16 >> 2)) & 3)) << 4;
;   const int aofs = (wm * 64 + l16) * 64 + fsl;
;   const int bofs = A_BYTES + (wn * NB * 16 + l16) * 64 + fsl;
; template <int EPI, int NB>
; DEVI void gemm_run(const GemmJob& J, unsigned char* smem, int rot) {
;     ...
;     for (int t = b; t < ntiles; t += G) {
;       const int mt = t / J.ntn, nt = J.nt0 + (t - mt * J.ntn);
;       gemm_tile<EPI, NB>(J, mt * 128, nt * BN, smem);
.LBB0_229:
	s_ashr_i32 s0, s9, 31
	s_lshr_b32 s0, s0, 30
	s_add_i32 s0, s9, s0
	s_ashr_i32 s0, s0, 2
	s_lshl_b32 s3, s0, 7
	s_lshl_b32 s0, s0, 10
	s_lshl_b32 s1, s9, 8
	v_mov_b32_e32 v208, v177
	s_sub_i32 s2, s1, s0
	s_nop 0
	s_mov_b64 s[28:29], 0x1000
	v_ashrrev_i32_e32 v10, 2, v208
	v_lshrrev_b32_e32 v0, 4, v208
	v_sub_u32_e32 v11, 0, v0
	v_add_u32_e32 v2, s3, v10
	v_add_u32_e32 v6, s2, v10
	v_xor_b32_e32 v0, v208, v11
	v_ashrrev_i32_e32 v3, 31, v2
	v_ashrrev_i32_e32 v7, 31, v6
	v_lshlrev_b64 v[2:3], 6, v[2:3]
	v_lshlrev_b32_e32 v0, 4, v0
	v_lshlrev_b64 v[6:7], 6, v[6:7]
	v_lshl_add_u64 v[4:5], v[152:153], 0, v[2:3]
	v_and_b32_e32 v0, 48, v0
	v_lshl_add_u64 v[6:7], v[180:181], 0, v[6:7]
	v_lshlrev_b32_e32 v209, 4, v208
	v_lshl_add_u64 v[4:5], v[4:5], 0, v[0:1]
	v_lshl_add_u64 v[6:7], v[6:7], 0, v[0:1]
	v_readfirstlane_b32 s1, v209
	v_add_u32_e32 v0, 0x1000, v209
	s_mov_b32 m0, s1
	v_readfirstlane_b32 s1, v0
	v_add_u32_e32 v0, 0x2000, v209
	s_waitcnt lgkmcnt(0)
	s_barrier
	global_load_lds_dwordx4 v[4:5], off
	v_lshl_add_u64 v[8:9], v[4:5], 0, s[28:29]
	s_mov_b32 m0, s1
	v_readfirstlane_b32 s1, v0
	v_add_u32_e32 v0, 0x3000, v209
	global_load_lds_dwordx4 v[8:9], off
	s_mov_b32 m0, s1
	v_readfirstlane_b32 s1, v0
	v_add_u32_e32 v0, 0x4000, v209
	global_load_lds_dwordx4 v[6:7], off
	v_lshl_add_u64 v[8:9], v[6:7], 0, s[28:29]
	s_mov_b32 m0, s1
	s_mov_b64 s[28:29], 0x2000
	v_readfirstlane_b32 s1, v0
	v_add_u32_e32 v0, 0x5000, v209
	global_load_lds_dwordx4 v[8:9], off
	v_lshl_add_u64 v[8:9], v[6:7], 0, s[28:29]
	s_mov_b32 m0, s1
	s_mov_b64 s[28:29], 0x3000
	v_readfirstlane_b32 s1, v0
	v_add_u32_e32 v0, 0x6000, v209
	global_load_lds_dwordx4 v[8:9], off
	v_lshl_add_u64 v[8:9], v[6:7], 0, s[28:29]
	s_mov_b32 m0, s1
	v_readfirstlane_b32 s1, v0
	v_add_u32_e32 v0, 0x7000, v209
	global_load_lds_dwordx4 v[8:9], off
	v_lshl_add_u64 v[8:9], v[4:5], 0, s[94:95]
	s_mov_b32 m0, s1
	s_mov_b64 s[28:29], 0x30b000
	v_readfirstlane_b32 s1, v0
	v_add_u32_e32 v0, 0x8000, v209
	global_load_lds_dwordx4 v[8:9], off
	v_lshl_add_u64 v[4:5], v[4:5], 0, s[28:29]
	s_mov_b32 m0, s1
	v_readfirstlane_b32 s1, v0
	v_add_u32_e32 v0, 0x9000, v209
	global_load_lds_dwordx4 v[4:5], off
	v_lshl_add_u64 v[4:5], v[6:7], 0, s[22:23]
	s_mov_b32 m0, s1
	s_mov_b64 s[28:29], 0x11000
	v_readfirstlane_b32 s1, v0
	v_add_u32_e32 v0, 0xa000, v209
	global_load_lds_dwordx4 v[4:5], off
	v_lshl_add_u64 v[4:5], v[6:7], 0, s[28:29]
	s_mov_b32 m0, s1
	s_mov_b64 s[28:29], 0x12000
	v_readfirstlane_b32 s1, v0
	v_add_u32_e32 v0, 0xb000, v209
	global_load_lds_dwordx4 v[4:5], off
	v_lshl_add_u64 v[4:5], v[6:7], 0, s[28:29]
	s_mov_b32 m0, s1
	s_mov_b64 s[28:29], 0x13000
	v_readfirstlane_b32 s1, v0
	global_load_lds_dwordx4 v[4:5], off
	v_lshl_add_u64 v[4:5], v[6:7], 0, s[28:29]
	s_mov_b32 m0, s1
	v_lshlrev_b32_e32 v0, 2, v208
	global_load_lds_dwordx4 v[4:5], off
	v_and_b32_e32 v0, 48, v0
	v_ashrrev_i32_e32 v4, 1, v208
	v_and_b32_e32 v210, 15, v208
	v_sub_u32_e32 v0, 0, v0
	v_and_b32_e32 v211, 0xffffffc0, v4
	v_bitop3_b32 v0, v208, 48, v0 bitop3:0x48
	v_or_b32_e32 v4, v211, v210
	v_lshl_or_b32 v213, v4, 6, v0
	v_lshlrev_b32_e32 v4, 1, v208
	v_and_b32_e32 v212, 0x80, v4
	v_or_b32_e32 v4, v212, v210
	v_lshl_or_b32 v0, v4, 6, v0
	v_add_u32_e32 v4, s8, v10
	v_subrev_u32_e32 v4, s0, v4
	v_ashrrev_i32_e32 v5, 31, v4
	v_add_u32_e32 v214, 0x2000, v0
	v_bitop3_b32 v0, v208, 3, v11 bitop3:0x48
	v_lshlrev_b64 v[4:5], 6, v[4:5]
	v_lshl_add_u64 v[186:187], v[130:131], 0, v[2:3]
	v_mov_b32_e32 v2, 0
	s_mov_b32 s42, 2
	s_mov_b32 s20, 0
	s_mov_b64 s[30:31], 0x1000
	v_lshlrev_b32_e32 v0, 4, v0
	v_lshl_add_u64 v[184:185], v[182:183], 0, v[4:5]
	s_mov_b32 s43, 0
	v_mov_b32_e32 v3, v2
	v_mov_b32_e32 v4, v2
	v_mov_b32_e32 v5, v2
	v_mov_b32_e32 v6, v2
	v_mov_b32_e32 v7, v2
	v_mov_b32_e32 v8, v2
	v_mov_b32_e32 v9, v2
	v_mov_b32_e32 v10, v2
	v_mov_b32_e32 v11, v2
	v_mov_b32_e32 v12, v2
	v_mov_b32_e32 v13, v2
	v_mov_b32_e32 v14, v2
	v_mov_b32_e32 v15, v2
	v_mov_b32_e32 v16, v2
	v_mov_b32_e32 v17, v2
	v_mov_b32_e32 v18, v2
	v_mov_b32_e32 v19, v2
	v_mov_b32_e32 v20, v2
	v_mov_b32_e32 v21, v2
	v_mov_b32_e32 v22, v2
	v_mov_b32_e32 v23, v2
; #define RAW_BARRIER() do { asm volatile("s_waitcnt lgkmcnt(0)" ::: "memory"); __builtin_amdgcn_s_barrier(); } while (0)
; template <int EPI, int NB>
; DEVI void gemm_tile(const GemmJob& J, int m0, int n0, unsigned char* smem) {
;     ...
;   f32x4 acc[4][NB];
; #pragma unroll
;   for (int i = 0; i < 4; ++i)
; #pragma unroll
;     for (int j = 0; j < NB; ++j) acc[i][j] = (f32x4){0.f, 0.f, 0.f, 0.f};
;     ...
;   int cs = 0, is = S - 1;
; #pragma clang loop unroll(disable)
;   for (int kt = 0; kt < nk; ++kt) {
;     if (nk - 1 - kt >= S - 2) {
;       if constexpr (NB == 8) asm volatile("s_waitcnt vmcnt(6)" ::: "memory");
;       else                   asm volatile("s_waitcnt vmcnt(8)" ::: "memory");
;     } else {
;       asm volatile("s_waitcnt vmcnt(0)" ::: "memory");
;     }
;     RAW_BARRIER();
;     if (kt + S - 1 < nk) GEMM_ISSUE(kt + S - 1, is);
;     is = (is + 1 == S) ? 0 : is + 1;
;     const unsigned cur = lbase + cs * STG;
	v_mov_b32_e32 v24, v2
	v_mov_b32_e32 v25, v2
	v_mov_b32_e32 v26, v2
	v_mov_b32_e32 v27, v2
	v_mov_b32_e32 v28, v2
	v_mov_b32_e32 v29, v2
	v_mov_b32_e32 v30, v2
	v_mov_b32_e32 v31, v2
	v_mov_b32_e32 v32, v2
	v_mov_b32_e32 v33, v2
	v_mov_b32_e32 v34, v2
	v_mov_b32_e32 v35, v2
	v_mov_b32_e32 v36, v2
	v_mov_b32_e32 v37, v2
	v_mov_b32_e32 v38, v2
	v_mov_b32_e32 v39, v2
	v_mov_b32_e32 v40, v2
	v_mov_b32_e32 v41, v2
	v_mov_b32_e32 v42, v2
	v_mov_b32_e32 v43, v2
	v_mov_b32_e32 v44, v2
	v_mov_b32_e32 v45, v2
	v_mov_b32_e32 v46, v2
	v_mov_b32_e32 v47, v2
	v_mov_b32_e32 v48, v2
	v_mov_b32_e32 v49, v2
	v_mov_b32_e32 v50, v2
	v_mov_b32_e32 v51, v2
	v_mov_b32_e32 v52, v2
	v_mov_b32_e32 v53, v2
	v_mov_b32_e32 v54, v2
	v_mov_b32_e32 v55, v2
	v_mov_b32_e32 v56, v2
	v_mov_b32_e32 v57, v2
	v_mov_b32_e32 v58, v2
	v_mov_b32_e32 v59, v2
	v_mov_b32_e32 v60, v2
	v_mov_b32_e32 v61, v2
	v_mov_b32_e32 v62, v2
	v_mov_b32_e32 v63, v2
	v_mov_b32_e32 v64, v2
	v_mov_b32_e32 v65, v2
	v_mov_b32_e32 v66, v2
	v_mov_b32_e32 v67, v2
	v_mov_b32_e32 v68, v2
	v_mov_b32_e32 v69, v2
	v_mov_b32_e32 v70, v2
	v_mov_b32_e32 v71, v2
	v_mov_b32_e32 v72, v2
	v_mov_b32_e32 v73, v2
	v_mov_b32_e32 v74, v2
	v_mov_b32_e32 v75, v2
	v_mov_b32_e32 v76, v2
	v_mov_b32_e32 v77, v2
	v_mov_b32_e32 v78, v2
	v_mov_b32_e32 v79, v2
	v_mov_b32_e32 v80, v2
	v_mov_b32_e32 v81, v2
	v_mov_b32_e32 v82, v2
	v_mov_b32_e32 v83, v2
	v_mov_b32_e32 v84, v2
	v_mov_b32_e32 v85, v2
	v_mov_b32_e32 v86, v2
	v_mov_b32_e32 v87, v2
	v_mov_b32_e32 v88, v2
	v_mov_b32_e32 v89, v2
	v_mov_b32_e32 v90, v2
	v_mov_b32_e32 v91, v2
	v_mov_b32_e32 v92, v2
	v_mov_b32_e32 v93, v2
	v_mov_b32_e32 v94, v2
	v_mov_b32_e32 v95, v2
	v_mov_b32_e32 v96, v2
	v_mov_b32_e32 v97, v2
	v_mov_b32_e32 v98, v2
	v_mov_b32_e32 v99, v2
	v_mov_b32_e32 v100, v2
	v_mov_b32_e32 v101, v2
	v_mov_b32_e32 v102, v2
	v_mov_b32_e32 v103, v2
	v_mov_b32_e32 v104, v2
	v_mov_b32_e32 v105, v2
	v_mov_b32_e32 v106, v2
	v_mov_b32_e32 v107, v2
	v_mov_b32_e32 v108, v2
	v_mov_b32_e32 v109, v2
	v_mov_b32_e32 v110, v2
	v_mov_b32_e32 v111, v2
	v_mov_b32_e32 v112, v2
	v_mov_b32_e32 v113, v2
	v_mov_b32_e32 v114, v2
	v_mov_b32_e32 v115, v2
	v_mov_b32_e32 v116, v2
	v_mov_b32_e32 v117, v2
	v_mov_b32_e32 v118, v2
	v_mov_b32_e32 v119, v2
	v_mov_b32_e32 v120, v2
	v_mov_b32_e32 v121, v2
	v_mov_b32_e32 v122, v2
	v_mov_b32_e32 v123, v2
	v_mov_b32_e32 v124, v2
	v_mov_b32_e32 v125, v2
	v_mov_b32_e32 v126, v2
	v_mov_b32_e32 v127, v2
	v_mov_b32_e32 v128, v2
	v_mov_b32_e32 v129, v2
	s_mul_i32 s0, s42, 0x6000
	v_add_u32_e32 v215, s0, v209
	v_lshl_add_u64 v[216:217], v[186:187], 0, v[0:1]
	v_readfirstlane_b32 s0, v215
	v_lshl_add_u64 v[218:219], v[216:217], 0, s[24:25]
	s_mov_b32 m0, s0
	v_lshl_add_u64 v[216:217], v[216:217], 0, s[26:27]
	s_nop 0
	v_readfirstlane_b32 s100, v218
	v_readfirstlane_b32 s101, v219
	s_nop 1
	v_subrev_u32_e32 v232, s100, v218
	v_add_u32_e32 v218, 0x1000, v215
	v_add_u32_e32 v220, 0x2000, v215
	v_readfirstlane_b32 s0, v218
	s_mov_b32 m0, s0
	s_mov_b64 s[0:1], 0xcc6000
	v_subrev_u32_e32 v233, s100, v216
	v_lshl_add_u64 v[216:217], v[184:185], 0, v[0:1]
	v_lshl_add_u64 v[218:219], v[216:217], 0, s[0:1]
	v_readfirstlane_b32 s0, v220
	s_mov_b32 m0, s0
	s_mov_b64 s[0:1], 0xcc7000
	v_add_u32_e32 v220, 0x3000, v215
	s_nop 0
	v_readfirstlane_b32 vcc_lo, v218
	v_readfirstlane_b32 vcc_hi, v219
	s_nop 1
	v_subrev_u32_e32 v234, vcc_lo, v218
	v_lshl_add_u64 v[218:219], v[216:217], 0, s[0:1]
	v_readfirstlane_b32 s0, v220
	s_mov_b32 m0, s0
	s_mov_b64 s[0:1], 0xcc8000
	v_add_u32_e32 v220, 0x4000, v215
	v_subrev_u32_e32 v235, vcc_lo, v218
	v_lshl_add_u64 v[218:219], v[216:217], 0, s[0:1]
	v_readfirstlane_b32 s0, v220
	s_mov_b32 m0, s0
	s_mov_b64 s[0:1], 0xcc9000
	v_add_u32_e32 v215, 0x5000, v215
	v_lshl_add_u64 v[216:217], v[216:217], 0, s[0:1]
	v_readfirstlane_b32 s0, v215
	v_subrev_u32_e32 v236, vcc_lo, v218
	s_mov_b32 m0, s0
	s_nop 0
	v_subrev_u32_e32 v237, vcc_lo, v216
	v_mov_b32_e32 v186, v232
	v_mov_b32_e32 v187, v233
	v_mov_b32_e32 v184, v234
	v_mov_b32_e32 v185, v235
	v_mov_b32_e32 v253, v236
	v_mov_b32_e32 v254, v237
	v_readfirstlane_b32 s0, v209
	s_branch .LBB0_231

; DEVI int otid() { int t = threadIdx.x; asm volatile("" : "+v"(t)); return t; }
; #define RAW_BARRIER() do { asm volatile("s_waitcnt lgkmcnt(0)" ::: "memory"); __builtin_amdgcn_s_barrier(); } while (0)
; template <int EPI, int NB>
; DEVI void gemm_tile(const GemmJob& J, int m0, int n0, unsigned char* smem) {
;     ...
;   const int tid = otid(), lane = tid & 63, wid = tid >> 6, wm = wid >> 1, wn = wid & 1;
;   const int l16 = lane & 15, g = lane >> 4;
;   f32x4 acc[4][NB];
; #pragma unroll
;   for (int i = 0; i < 4; ++i)
; #pragma unroll
;     for (int j = 0; j < NB; ++j) acc[i][j] = (f32x4){0.f, 0.f, 0.f, 0.f};
;   const int srow = tid >> 2, sch = tid & 3;
;   const int gch = sch ^ ((0 - (tid >> 4)) & 3);
;   const bf16_t* Ag = J.A + (size_t)(m0 + srow) * (J.ablk ? 32 : J.lda) + gch * 8;
;   const bf16_t* Bg = J.Bt + (size_t)(n0 + srow) * 32 + gch * 8;
;   const size_t Astep = (size_t)64 * (J.ablk ? 32 : J.lda), Ak = J.ablk ? (size_t)MROWS * 32 : (size_t)32, Bstep = (size_t)64 * 32, Bk = (size_t)J.NR * 32;
;   const int nk = J.K >> 5;
;   unsigned char* lds_t = smem + tid * 16;
;   const unsigned lbase = (unsigned)(uintptr_t)(__attribute__((address_space(3))) unsigned char*)smem;
;     ...
;   asm volatile("s_waitcnt vmcnt(0)" ::: "memory");
;   RAW_BARRIER();
; #pragma unroll
;   for (int st = 0; st < S - 1; ++st) GEMM_ISSUE(st, st);
;   const int fsl = (g ^ ((0 - (l16 >> 2)) & 3)) << 4;
;   const int aofs = (wm * 64 + l16) * 64 + fsl;
;   const int bofs = A_BYTES + (wn * NB * 16 + l16) * 64 + fsl;
; template <int EPI, int NB>
; DEVI void gemm_run(const GemmJob& J, unsigned char* smem, int rot) {
;     ...
;     for (int q0 = lb; q0 < ntot; q0 += nlb) {
;       const int q = J.rev ? ntot - 1 - q0 : q0;
;       int grp = q / gsz; const int qq = q - grp * gsz;
;       const int mg = min(8, mcnt - grp * 8);
;       const int nt = qq / mg, mi = qq - nt * mg;
;       gemm_tile<EPI, NB>(J, (mlo + grp * 8 + mi) * 128, (J.nt0 + nt) * BN, smem);
.LBB0_307:
	s_not_b32 s0, s9
	s_add_i32 s0, s1, s0
	s_ashr_i32 s1, s0, 31
	s_lshr_b32 s1, s1, 27
	s_add_i32 s1, s0, s1
	s_ashr_i32 s40, s1, 5
	s_lshl_b32 s3, s40, 3
	v_readlane_b32 s2, v251, 48
	s_sub_i32 s2, s2, s3
	s_min_i32 s20, s2, 8
	s_abs_i32 s41, s20
	v_cvt_f32_u32_e32 v0, s41
	s_sub_i32 s43, 0, s41
	s_andn2_b32 s1, s1, 31
	s_sub_i32 s0, s0, s1
	v_rcp_iflag_f32_e32 v0, v0
	s_abs_i32 s1, s0
	s_xor_b32 s42, s0, s20
	s_ashr_i32 s42, s42, 31
	v_mul_f32_e32 v0, 0x4f7ffffe, v0
	v_cvt_u32_f32_e32 v0, v0
	v_mov_b32_e32 v208, v177
	s_nop 0
	v_readfirstlane_b32 s44, v0
	s_mul_i32 s43, s43, s44
	s_mul_hi_u32 s43, s44, s43
	s_add_i32 s44, s44, s43
	s_mul_hi_u32 s43, s1, s44
	s_mul_i32 s44, s43, s41
	s_sub_i32 s1, s1, s44
	s_add_i32 s45, s43, 1
	s_sub_i32 s44, s1, s41
	s_cmp_ge_u32 s1, s41
	s_cselect_b32 s43, s45, s43
	s_cselect_b32 s1, s44, s1
	s_add_i32 s44, s43, 1
	s_cmp_ge_u32 s1, s41
	s_cselect_b32 s1, s44, s43
	s_xor_b32 s1, s1, s42
	s_sub_i32 s1, s1, s42
	s_mul_i32 s41, s20, s1
	v_readlane_b32 s20, v250, 37
	s_add_i32 s3, s3, s20
	s_add_i32 s3, s3, s0
	s_sub_i32 s0, s3, s41
	s_lshl_b32 s20, s0, 7
	s_lshl_b32 s3, s1, 8
	v_ashrrev_i32_e32 v10, 2, v208
	v_lshrrev_b32_e32 v0, 4, v208
	v_sub_u32_e32 v11, 0, v0
	v_add_u32_e32 v2, s20, v10
	v_add_u32_e32 v4, s3, v10
	v_xor_b32_e32 v0, v208, v11
	v_ashrrev_i32_e32 v3, 31, v2
	v_ashrrev_i32_e32 v5, 31, v4
	v_lshlrev_b64 v[2:3], 6, v[2:3]
	v_lshlrev_b32_e32 v0, 4, v0
	v_lshlrev_b64 v[4:5], 6, v[4:5]
	v_lshl_add_u64 v[2:3], v[152:153], 0, v[2:3]
	v_and_b32_e32 v0, 48, v0
	v_lshl_add_u64 v[6:7], v[180:181], 0, v[4:5]
	v_lshlrev_b32_e32 v209, 4, v208
	v_lshl_add_u64 v[2:3], v[2:3], 0, v[0:1]
	v_lshl_add_u64 v[6:7], v[6:7], 0, v[0:1]
	v_readfirstlane_b32 s0, v209
	v_add_u32_e32 v0, 0x1000, v209
	s_mov_b32 m0, s0
	s_mov_b64 s[28:29], 0x1000
	v_readfirstlane_b32 s0, v0
	v_add_u32_e32 v0, 0x2000, v209
	s_waitcnt lgkmcnt(0)
	s_barrier
	global_load_lds_dwordx4 v[2:3], off
	v_lshl_add_u64 v[8:9], v[2:3], 0, s[28:29]
	s_mov_b32 m0, s0
	v_readfirstlane_b32 s0, v0
	v_add_u32_e32 v0, 0x3000, v209
	global_load_lds_dwordx4 v[8:9], off
	s_mov_b32 m0, s0
	v_readfirstlane_b32 s0, v0
	global_load_lds_dwordx4 v[6:7], off
	v_lshl_add_u64 v[8:9], v[6:7], 0, s[28:29]
	s_mov_b32 m0, s0
	s_mov_b64 s[0:1], 0x2000
	v_add_u32_e32 v0, 0x4000, v209
	global_load_lds_dwordx4 v[8:9], off
	v_lshl_add_u64 v[8:9], v[6:7], 0, s[0:1]
	v_readfirstlane_b32 s0, v0
	s_mov_b32 m0, s0
	s_mov_b64 s[0:1], 0x3000
	v_add_u32_e32 v0, 0x5000, v209
	global_load_lds_dwordx4 v[8:9], off
	v_lshl_add_u64 v[8:9], v[6:7], 0, s[0:1]
	v_readfirstlane_b32 s0, v0
	v_add_u32_e32 v0, 0x6000, v209
	s_mov_b32 m0, s0
	v_readfirstlane_b32 s0, v0
	global_load_lds_dwordx4 v[8:9], off
	s_mov_b32 m0, s0
	s_mov_b64 s[0:1], 0x30b000
	v_add_u32_e32 v0, 0x7000, v209
	v_lshl_add_u64 v[8:9], v[2:3], 0, s[94:95]
	v_lshl_add_u64 v[2:3], v[2:3], 0, s[0:1]
	v_readfirstlane_b32 s0, v0
	v_add_u32_e32 v0, 0x8000, v209
	global_load_lds_dwordx4 v[8:9], off
	s_mov_b32 m0, s0
	v_readfirstlane_b32 s0, v0
	global_load_lds_dwordx4 v[2:3], off
	v_lshl_add_u64 v[2:3], v[6:7], 0, s[22:23]
	s_mov_b32 m0, s0
	s_mov_b64 s[0:1], 0x11000
	v_add_u32_e32 v0, 0x9000, v209
	global_load_lds_dwordx4 v[2:3], off
	v_lshl_add_u64 v[2:3], v[6:7], 0, s[0:1]
	v_readfirstlane_b32 s0, v0
	s_mov_b32 m0, s0
	s_mov_b64 s[0:1], 0x12000
	v_add_u32_e32 v0, 0xa000, v209
	global_load_lds_dwordx4 v[2:3], off
	v_lshl_add_u64 v[2:3], v[6:7], 0, s[0:1]
	v_readfirstlane_b32 s0, v0
	s_mov_b32 m0, s0
	s_mov_b64 s[0:1], 0x13000
	v_add_u32_e32 v0, 0xb000, v209
	global_load_lds_dwordx4 v[2:3], off
	v_lshl_add_u64 v[2:3], v[6:7], 0, s[0:1]
	v_readfirstlane_b32 s0, v0
	s_mov_b32 m0, s0
	v_lshlrev_b32_e32 v0, 2, v208
	global_load_lds_dwordx4 v[2:3], off
	v_and_b32_e32 v0, 48, v0
	v_ashrrev_i32_e32 v2, 1, v208
	v_and_b32_e32 v210, 15, v208
	v_sub_u32_e32 v0, 0, v0
	v_and_b32_e32 v211, 0xffffffc0, v2
	v_bitop3_b32 v0, v208, 48, v0 bitop3:0x48
	v_or_b32_e32 v2, v211, v210
	v_lshl_or_b32 v213, v2, 6, v0
	v_lshlrev_b32_e32 v2, 1, v208
	v_and_b32_e32 v212, 0x80, v2
	s_sub_i32 s0, s8, s41
	s_mul_i32 s40, s40, 24
	v_or_b32_e32 v2, v212, v210
	s_sub_i32 s0, s0, s40
	v_lshl_or_b32 v0, v2, 6, v0
	v_lshl_add_u32 v2, s0, 7, v10
	v_ashrrev_i32_e32 v3, 31, v2
	v_lshlrev_b64 v[2:3], 6, v[2:3]
	v_add_u32_e32 v214, 0x2000, v0
	v_bitop3_b32 v0, v208, 3, v11 bitop3:0x48
	v_lshl_add_u64 v[186:187], v[130:131], 0, v[2:3]
	v_mov_b32_e32 v2, 0
	s_mov_b32 s2, 0
	s_mov_b32 s42, 2
	s_mov_b64 s[30:31], 0x1000
	v_lshlrev_b32_e32 v0, 4, v0
	v_lshl_add_u64 v[184:185], v[182:183], 0, v[4:5]
	s_mov_b32 s43, 0
; #define RAW_BARRIER() do { asm volatile("s_waitcnt lgkmcnt(0)" ::: "memory"); __builtin_amdgcn_s_barrier(); } while (0)
; template <int EPI, int NB>
; DEVI void gemm_tile(const GemmJob& J, int m0, int n0, unsigned char* smem) {
;     ...
;   f32x4 acc[4][NB];
; #pragma unroll
;   for (int i = 0; i < 4; ++i)
; #pragma unroll
;     for (int j = 0; j < NB; ++j) acc[i][j] = (f32x4){0.f, 0.f, 0.f, 0.f};
;     ...
;   int cs = 0, is = S - 1;
; #pragma clang loop unroll(disable)
;   for (int kt = 0; kt < nk; ++kt) {
;     if (nk - 1 - kt >= S - 2) {
;       if constexpr (NB == 8) asm volatile("s_waitcnt vmcnt(6)" ::: "memory");
;       else                   asm volatile("s_waitcnt vmcnt(8)" ::: "memory");
;     } else {
;       asm volatile("s_waitcnt vmcnt(0)" ::: "memory");
;     }
;     RAW_BARRIER();
;     if (kt + S - 1 < nk) GEMM_ISSUE(kt + S - 1, is);
;     is = (is + 1 == S) ? 0 : is + 1;
;     const unsigned cur = lbase + cs * STG;
	v_mov_b32_e32 v3, v2
	v_mov_b32_e32 v4, v2
	v_mov_b32_e32 v5, v2
	v_mov_b32_e32 v6, v2
	v_mov_b32_e32 v7, v2
	v_mov_b32_e32 v8, v2
	v_mov_b32_e32 v9, v2
	v_mov_b32_e32 v10, v2
	v_mov_b32_e32 v11, v2
	v_mov_b32_e32 v12, v2
	v_mov_b32_e32 v13, v2
	v_mov_b32_e32 v14, v2
	v_mov_b32_e32 v15, v2
	v_mov_b32_e32 v16, v2
	v_mov_b32_e32 v17, v2
	v_mov_b32_e32 v18, v2
	v_mov_b32_e32 v19, v2
	v_mov_b32_e32 v20, v2
	v_mov_b32_e32 v21, v2
	v_mov_b32_e32 v22, v2
	v_mov_b32_e32 v23, v2
	v_mov_b32_e32 v24, v2
	v_mov_b32_e32 v25, v2
	v_mov_b32_e32 v26, v2
	v_mov_b32_e32 v27, v2
	v_mov_b32_e32 v28, v2
	v_mov_b32_e32 v29, v2
	v_mov_b32_e32 v30, v2
	v_mov_b32_e32 v31, v2
	v_mov_b32_e32 v32, v2
	v_mov_b32_e32 v33, v2
	v_mov_b32_e32 v34, v2
	v_mov_b32_e32 v35, v2
	v_mov_b32_e32 v36, v2
	v_mov_b32_e32 v37, v2
	v_mov_b32_e32 v38, v2
	v_mov_b32_e32 v39, v2
	v_mov_b32_e32 v40, v2
	v_mov_b32_e32 v41, v2
	v_mov_b32_e32 v42, v2
	v_mov_b32_e32 v43, v2
	v_mov_b32_e32 v44, v2
	v_mov_b32_e32 v45, v2
	v_mov_b32_e32 v46, v2
	v_mov_b32_e32 v47, v2
	v_mov_b32_e32 v48, v2
	v_mov_b32_e32 v49, v2
	v_mov_b32_e32 v50, v2
	v_mov_b32_e32 v51, v2
	v_mov_b32_e32 v52, v2
	v_mov_b32_e32 v53, v2
	v_mov_b32_e32 v54, v2
	v_mov_b32_e32 v55, v2
	v_mov_b32_e32 v56, v2
	v_mov_b32_e32 v57, v2
	v_mov_b32_e32 v58, v2
	v_mov_b32_e32 v59, v2
	v_mov_b32_e32 v60, v2
	v_mov_b32_e32 v61, v2
	v_mov_b32_e32 v62, v2
	v_mov_b32_e32 v63, v2
	v_mov_b32_e32 v64, v2
	v_mov_b32_e32 v65, v2
	v_mov_b32_e32 v66, v2
	v_mov_b32_e32 v67, v2
	v_mov_b32_e32 v68, v2
	v_mov_b32_e32 v69, v2
	v_mov_b32_e32 v70, v2
	v_mov_b32_e32 v71, v2
	v_mov_b32_e32 v72, v2
	v_mov_b32_e32 v73, v2
	v_mov_b32_e32 v74, v2
	v_mov_b32_e32 v75, v2
	v_mov_b32_e32 v76, v2
	v_mov_b32_e32 v77, v2
	v_mov_b32_e32 v78, v2
	v_mov_b32_e32 v79, v2
	v_mov_b32_e32 v80, v2
	v_mov_b32_e32 v81, v2
	v_mov_b32_e32 v82, v2
	v_mov_b32_e32 v83, v2
	v_mov_b32_e32 v84, v2
	v_mov_b32_e32 v85, v2
	v_mov_b32_e32 v86, v2
	v_mov_b32_e32 v87, v2
	v_mov_b32_e32 v88, v2
	v_mov_b32_e32 v89, v2
	v_mov_b32_e32 v90, v2
	v_mov_b32_e32 v91, v2
	v_mov_b32_e32 v92, v2
	v_mov_b32_e32 v93, v2
	v_mov_b32_e32 v94, v2
	v_mov_b32_e32 v95, v2
	v_mov_b32_e32 v96, v2
	v_mov_b32_e32 v97, v2
	v_mov_b32_e32 v98, v2
	v_mov_b32_e32 v99, v2
	v_mov_b32_e32 v100, v2
	v_mov_b32_e32 v101, v2
	v_mov_b32_e32 v102, v2
	v_mov_b32_e32 v103, v2
	v_mov_b32_e32 v104, v2
	v_mov_b32_e32 v105, v2
	v_mov_b32_e32 v106, v2
	v_mov_b32_e32 v107, v2
	v_mov_b32_e32 v108, v2
	v_mov_b32_e32 v109, v2
	v_mov_b32_e32 v110, v2
	v_mov_b32_e32 v111, v2
	v_mov_b32_e32 v112, v2
	v_mov_b32_e32 v113, v2
	v_mov_b32_e32 v114, v2
	v_mov_b32_e32 v115, v2
	v_mov_b32_e32 v116, v2
	v_mov_b32_e32 v117, v2
	v_mov_b32_e32 v118, v2
	v_mov_b32_e32 v119, v2
	v_mov_b32_e32 v120, v2
	v_mov_b32_e32 v121, v2
	v_mov_b32_e32 v122, v2
	v_mov_b32_e32 v123, v2
	v_mov_b32_e32 v124, v2
	v_mov_b32_e32 v125, v2
	v_mov_b32_e32 v126, v2
	v_mov_b32_e32 v127, v2
	v_mov_b32_e32 v128, v2
	v_mov_b32_e32 v129, v2
	s_mul_i32 s0, s42, 0x6000
	v_add_u32_e32 v215, s0, v209
	v_lshl_add_u64 v[216:217], v[186:187], 0, v[0:1]
	v_readfirstlane_b32 s0, v215
	v_lshl_add_u64 v[218:219], v[216:217], 0, s[24:25]
	s_mov_b32 m0, s0
	v_lshl_add_u64 v[216:217], v[216:217], 0, s[26:27]
	s_nop 0
	v_readfirstlane_b32 s100, v218
	v_readfirstlane_b32 s101, v219
	s_nop 1
	v_subrev_u32_e32 v232, s100, v218
	v_add_u32_e32 v218, 0x1000, v215
	v_add_u32_e32 v220, 0x2000, v215
	v_readfirstlane_b32 s0, v218
	s_mov_b32 m0, s0
	s_mov_b64 s[0:1], 0xcc6000
	v_subrev_u32_e32 v233, s100, v216
	v_lshl_add_u64 v[216:217], v[184:185], 0, v[0:1]
	v_lshl_add_u64 v[218:219], v[216:217], 0, s[0:1]
	v_readfirstlane_b32 s0, v220
	s_mov_b32 m0, s0
	s_mov_b64 s[0:1], 0xcc7000
	v_add_u32_e32 v220, 0x3000, v215
	s_nop 0
	v_readfirstlane_b32 vcc_lo, v218
	v_readfirstlane_b32 vcc_hi, v219
	s_nop 1
	v_subrev_u32_e32 v234, vcc_lo, v218
	v_lshl_add_u64 v[218:219], v[216:217], 0, s[0:1]
	v_readfirstlane_b32 s0, v220
	s_mov_b32 m0, s0
	s_mov_b64 s[0:1], 0xcc8000
	v_add_u32_e32 v220, 0x4000, v215
	v_subrev_u32_e32 v235, vcc_lo, v218
	v_lshl_add_u64 v[218:219], v[216:217], 0, s[0:1]
	v_readfirstlane_b32 s0, v220
	s_mov_b32 m0, s0
	s_mov_b64 s[0:1], 0xcc9000
	v_add_u32_e32 v215, 0x5000, v215
	v_lshl_add_u64 v[216:217], v[216:217], 0, s[0:1]
	v_readfirstlane_b32 s0, v215
	v_subrev_u32_e32 v236, vcc_lo, v218
	s_mov_b32 m0, s0
	s_nop 0
	v_subrev_u32_e32 v237, vcc_lo, v216
	v_mov_b32_e32 v186, v232
	v_mov_b32_e32 v187, v233
	v_mov_b32_e32 v184, v234
	v_mov_b32_e32 v185, v235
	v_mov_b32_e32 v253, v236
	v_mov_b32_e32 v254, v237
	v_readfirstlane_b32 s0, v209
	s_branch .LBB0_309

; DEVI int otid() { int t = threadIdx.x; asm volatile("" : "+v"(t)); return t; }
; #define RAW_BARRIER() do { asm volatile("s_waitcnt lgkmcnt(0)" ::: "memory"); __builtin_amdgcn_s_barrier(); } while (0)
; template <int EPI, int NB>
; DEVI void gemm_tile(const GemmJob& J, int m0, int n0, unsigned char* smem) {
;     ...
;   const int tid = otid(), lane = tid & 63, wid = tid >> 6, wm = wid >> 1, wn = wid & 1;
;   const int l16 = lane & 15, g = lane >> 4;
;   f32x4 acc[4][NB];
; #pragma unroll
;   for (int i = 0; i < 4; ++i)
; #pragma unroll
;     for (int j = 0; j < NB; ++j) acc[i][j] = (f32x4){0.f, 0.f, 0.f, 0.f};
;   const int srow = tid >> 2, sch = tid & 3;
;   const int gch = sch ^ ((0 - (tid >> 4)) & 3);
;   const bf16_t* Ag = J.A + (size_t)(m0 + srow) * (J.ablk ? 32 : J.lda) + gch * 8;
;   const bf16_t* Bg = J.Bt + (size_t)(n0 + srow) * 32 + gch * 8;
;   const size_t Astep = (size_t)64 * (J.ablk ? 32 : J.lda), Ak = J.ablk ? (size_t)MROWS * 32 : (size_t)32, Bstep = (size_t)64 * 32, Bk = (size_t)J.NR * 32;
;   const int nk = J.K >> 5;
;   unsigned char* lds_t = smem + tid * 16;
;   const unsigned lbase = (unsigned)(uintptr_t)(__attribute__((address_space(3))) unsigned char*)smem;
;     ...
;   asm volatile("s_waitcnt vmcnt(0)" ::: "memory");
;   RAW_BARRIER();
; #pragma unroll
;   for (int st = 0; st < S - 1; ++st) GEMM_ISSUE(st, st);
;   const int fsl = (g ^ ((0 - (l16 >> 2)) & 3)) << 4;
;   const int aofs = (wm * 64 + l16) * 64 + fsl;
;   const int bofs = A_BYTES + (wn * NB * 16 + l16) * 64 + fsl;
; template <int EPI, int NB>
; DEVI void gemm_run(const GemmJob& J, unsigned char* smem, int rot) {
;     ...
;     for (int t = b; t < ntiles; t += G) {
;       const int mt = t / J.ntn, nt = J.nt0 + (t - mt * J.ntn);
;       gemm_tile<EPI, NB>(J, mt * 128, nt * BN, smem);
.LBB0_527:
	s_ashr_i32 s0, s9, 31
	s_lshr_b32 s0, s0, 29
	s_add_i32 s0, s9, s0
	s_ashr_i32 s0, s0, 3
	s_lshl_b32 s3, s0, 7
	s_lshl_b32 s0, s0, 11
	s_lshl_b32 s1, s9, 8
	v_mov_b32_e32 v184, v177
	s_sub_i32 s2, s1, s0
	s_nop 0
	s_mov_b64 s[28:29], 0x1000
	v_ashrrev_i32_e32 v10, 2, v184
	v_lshrrev_b32_e32 v0, 4, v184
	v_sub_u32_e32 v11, 0, v0
	v_add_u32_e32 v2, s3, v10
	v_add_u32_e32 v6, s2, v10
	v_xor_b32_e32 v0, v184, v11
	v_ashrrev_i32_e32 v3, 31, v2
	v_ashrrev_i32_e32 v7, 31, v6
	v_lshlrev_b64 v[2:3], 6, v[2:3]
	v_lshlrev_b32_e32 v0, 4, v0
	v_lshlrev_b64 v[6:7], 6, v[6:7]
	v_lshl_add_u64 v[4:5], v[146:147], 0, v[2:3]
	v_and_b32_e32 v0, 48, v0
	v_lshl_add_u64 v[6:7], v[142:143], 0, v[6:7]
	v_lshlrev_b32_e32 v185, 4, v184
	v_lshl_add_u64 v[4:5], v[4:5], 0, v[0:1]
	v_lshl_add_u64 v[6:7], v[6:7], 0, v[0:1]
	v_readfirstlane_b32 s1, v185
	v_add_u32_e32 v0, 0x1000, v185
	s_mov_b32 m0, s1
	v_readfirstlane_b32 s1, v0
	v_add_u32_e32 v0, 0x2000, v185
	s_waitcnt lgkmcnt(0)
	s_barrier
	global_load_lds_dwordx4 v[4:5], off
	v_lshl_add_u64 v[8:9], v[4:5], 0, s[28:29]
	s_mov_b32 m0, s1
	v_readfirstlane_b32 s1, v0
	v_add_u32_e32 v0, 0x3000, v185
	global_load_lds_dwordx4 v[8:9], off
	s_mov_b32 m0, s1
	v_readfirstlane_b32 s1, v0
	v_add_u32_e32 v0, 0x4000, v185
	global_load_lds_dwordx4 v[6:7], off
	v_lshl_add_u64 v[8:9], v[6:7], 0, s[28:29]
	s_mov_b32 m0, s1
	s_mov_b64 s[28:29], 0x2000
	v_readfirstlane_b32 s1, v0
	v_add_u32_e32 v0, 0x5000, v185
	global_load_lds_dwordx4 v[8:9], off
	v_lshl_add_u64 v[8:9], v[6:7], 0, s[28:29]
	s_mov_b32 m0, s1
	s_mov_b64 s[28:29], 0x3000
	v_readfirstlane_b32 s1, v0
	v_add_u32_e32 v0, 0x6000, v185
	global_load_lds_dwordx4 v[8:9], off
	v_lshl_add_u64 v[8:9], v[6:7], 0, s[28:29]
	s_mov_b32 m0, s1
	v_readfirstlane_b32 s1, v0
	v_add_u32_e32 v0, 0x7000, v185
	global_load_lds_dwordx4 v[8:9], off
	v_lshl_add_u64 v[8:9], v[4:5], 0, s[94:95]
	s_mov_b32 m0, s1
	s_mov_b64 s[28:29], 0x30b000
	v_readfirstlane_b32 s1, v0
	v_add_u32_e32 v0, 0x8000, v185
	global_load_lds_dwordx4 v[8:9], off
	v_lshl_add_u64 v[4:5], v[4:5], 0, s[28:29]
	s_mov_b32 m0, s1
	v_readfirstlane_b32 s1, v0
	v_add_u32_e32 v0, 0x9000, v185
	global_load_lds_dwordx4 v[4:5], off
	v_lshl_add_u64 v[4:5], v[6:7], 0, s[4:5]
	s_mov_b32 m0, s1
	s_mov_b64 s[28:29], 0x31000
	v_readfirstlane_b32 s1, v0
	v_add_u32_e32 v0, 0xa000, v185
	global_load_lds_dwordx4 v[4:5], off
	v_lshl_add_u64 v[4:5], v[6:7], 0, s[28:29]
	s_mov_b32 m0, s1
	s_mov_b64 s[28:29], 0x32000
	v_readfirstlane_b32 s1, v0
	v_add_u32_e32 v0, 0xb000, v185
	global_load_lds_dwordx4 v[4:5], off
	v_lshl_add_u64 v[4:5], v[6:7], 0, s[28:29]
	s_mov_b32 m0, s1
	s_mov_b64 s[28:29], 0x33000
	v_readfirstlane_b32 s1, v0
	global_load_lds_dwordx4 v[4:5], off
	v_lshl_add_u64 v[4:5], v[6:7], 0, s[28:29]
	s_mov_b32 m0, s1
	v_lshlrev_b32_e32 v0, 2, v184
	global_load_lds_dwordx4 v[4:5], off
	v_and_b32_e32 v0, 48, v0
	v_ashrrev_i32_e32 v4, 1, v184
	v_and_b32_e32 v186, 15, v184
	v_sub_u32_e32 v0, 0, v0
	v_and_b32_e32 v187, 0xffffffc0, v4
	v_bitop3_b32 v0, v184, 48, v0 bitop3:0x48
	v_or_b32_e32 v4, v187, v186
	v_lshl_or_b32 v209, v4, 6, v0
	v_lshlrev_b32_e32 v4, 1, v184
	v_and_b32_e32 v208, 0x80, v4
	v_or_b32_e32 v4, v208, v186
	v_lshl_or_b32 v0, v4, 6, v0
	v_add_u32_e32 v4, s8, v10
	v_subrev_u32_e32 v4, s0, v4
	v_ashrrev_i32_e32 v5, 31, v4
	v_add_u32_e32 v210, 0x2000, v0
	v_bitop3_b32 v0, v184, 3, v11 bitop3:0x48
	v_lshlrev_b64 v[4:5], 6, v[4:5]
	v_lshl_add_u64 v[182:183], v[130:131], 0, v[2:3]
	v_mov_b32_e32 v2, 0
	s_mov_b32 s42, 2
	s_mov_b32 s20, 0
	s_mov_b64 s[30:31], 0x1000
	v_lshlrev_b32_e32 v0, 4, v0
	v_lshl_add_u64 v[180:181], v[130:131], 0, v[4:5]
	s_mov_b32 s43, 0
	v_mov_b32_e32 v3, v2
	v_mov_b32_e32 v4, v2
	v_mov_b32_e32 v5, v2
	v_mov_b32_e32 v6, v2
	v_mov_b32_e32 v7, v2
	v_mov_b32_e32 v8, v2
	v_mov_b32_e32 v9, v2
	v_mov_b32_e32 v10, v2
	v_mov_b32_e32 v11, v2
	v_mov_b32_e32 v12, v2
	v_mov_b32_e32 v13, v2
	v_mov_b32_e32 v14, v2
	v_mov_b32_e32 v15, v2
	v_mov_b32_e32 v16, v2
	v_mov_b32_e32 v17, v2
	v_mov_b32_e32 v18, v2
	v_mov_b32_e32 v19, v2
	v_mov_b32_e32 v20, v2
	v_mov_b32_e32 v21, v2
	v_mov_b32_e32 v22, v2
	v_mov_b32_e32 v23, v2
; #define RAW_BARRIER() do { asm volatile("s_waitcnt lgkmcnt(0)" ::: "memory"); __builtin_amdgcn_s_barrier(); } while (0)
; template <int EPI, int NB>
; DEVI void gemm_tile(const GemmJob& J, int m0, int n0, unsigned char* smem) {
;     ...
;   f32x4 acc[4][NB];
; #pragma unroll
;   for (int i = 0; i < 4; ++i)
; #pragma unroll
;     for (int j = 0; j < NB; ++j) acc[i][j] = (f32x4){0.f, 0.f, 0.f, 0.f};
;     ...
;   int cs = 0, is = S - 1;
; #pragma clang loop unroll(disable)
;   for (int kt = 0; kt < nk; ++kt) {
;     if (nk - 1 - kt >= S - 2) {
;       if constexpr (NB == 8) asm volatile("s_waitcnt vmcnt(6)" ::: "memory");
;       else                   asm volatile("s_waitcnt vmcnt(8)" ::: "memory");
;     } else {
;       asm volatile("s_waitcnt vmcnt(0)" ::: "memory");
;     }
;     RAW_BARRIER();
;     if (kt + S - 1 < nk) GEMM_ISSUE(kt + S - 1, is);
;     is = (is + 1 == S) ? 0 : is + 1;
;     const unsigned cur = lbase + cs * STG;
	v_mov_b32_e32 v24, v2
	v_mov_b32_e32 v25, v2
	v_mov_b32_e32 v26, v2
	v_mov_b32_e32 v27, v2
	v_mov_b32_e32 v28, v2
	v_mov_b32_e32 v29, v2
	v_mov_b32_e32 v30, v2
	v_mov_b32_e32 v31, v2
	v_mov_b32_e32 v32, v2
	v_mov_b32_e32 v33, v2
	v_mov_b32_e32 v34, v2
	v_mov_b32_e32 v35, v2
	v_mov_b32_e32 v36, v2
	v_mov_b32_e32 v37, v2
	v_mov_b32_e32 v38, v2
	v_mov_b32_e32 v39, v2
	v_mov_b32_e32 v40, v2
	v_mov_b32_e32 v41, v2
	v_mov_b32_e32 v42, v2
	v_mov_b32_e32 v43, v2
	v_mov_b32_e32 v44, v2
	v_mov_b32_e32 v45, v2
	v_mov_b32_e32 v46, v2
	v_mov_b32_e32 v47, v2
	v_mov_b32_e32 v48, v2
	v_mov_b32_e32 v49, v2
	v_mov_b32_e32 v50, v2
	v_mov_b32_e32 v51, v2
	v_mov_b32_e32 v52, v2
	v_mov_b32_e32 v53, v2
	v_mov_b32_e32 v54, v2
	v_mov_b32_e32 v55, v2
	v_mov_b32_e32 v56, v2
	v_mov_b32_e32 v57, v2
	v_mov_b32_e32 v58, v2
	v_mov_b32_e32 v59, v2
	v_mov_b32_e32 v60, v2
	v_mov_b32_e32 v61, v2
	v_mov_b32_e32 v62, v2
	v_mov_b32_e32 v63, v2
	v_mov_b32_e32 v64, v2
	v_mov_b32_e32 v65, v2
	v_mov_b32_e32 v66, v2
	v_mov_b32_e32 v67, v2
	v_mov_b32_e32 v68, v2
	v_mov_b32_e32 v69, v2
	v_mov_b32_e32 v70, v2
	v_mov_b32_e32 v71, v2
	v_mov_b32_e32 v72, v2
	v_mov_b32_e32 v73, v2
	v_mov_b32_e32 v74, v2
	v_mov_b32_e32 v75, v2
	v_mov_b32_e32 v76, v2
	v_mov_b32_e32 v77, v2
	v_mov_b32_e32 v78, v2
	v_mov_b32_e32 v79, v2
	v_mov_b32_e32 v80, v2
	v_mov_b32_e32 v81, v2
	v_mov_b32_e32 v82, v2
	v_mov_b32_e32 v83, v2
	v_mov_b32_e32 v84, v2
	v_mov_b32_e32 v85, v2
	v_mov_b32_e32 v86, v2
	v_mov_b32_e32 v87, v2
	v_mov_b32_e32 v88, v2
	v_mov_b32_e32 v89, v2
	v_mov_b32_e32 v90, v2
	v_mov_b32_e32 v91, v2
	v_mov_b32_e32 v92, v2
	v_mov_b32_e32 v93, v2
	v_mov_b32_e32 v94, v2
	v_mov_b32_e32 v95, v2
	v_mov_b32_e32 v96, v2
	v_mov_b32_e32 v97, v2
	v_mov_b32_e32 v98, v2
	v_mov_b32_e32 v99, v2
	v_mov_b32_e32 v100, v2
	v_mov_b32_e32 v101, v2
	v_mov_b32_e32 v102, v2
	v_mov_b32_e32 v103, v2
	v_mov_b32_e32 v104, v2
	v_mov_b32_e32 v105, v2
	v_mov_b32_e32 v106, v2
	v_mov_b32_e32 v107, v2
	v_mov_b32_e32 v108, v2
	v_mov_b32_e32 v109, v2
	v_mov_b32_e32 v110, v2
	v_mov_b32_e32 v111, v2
	v_mov_b32_e32 v112, v2
	v_mov_b32_e32 v113, v2
	v_mov_b32_e32 v114, v2
	v_mov_b32_e32 v115, v2
	v_mov_b32_e32 v116, v2
	v_mov_b32_e32 v117, v2
	v_mov_b32_e32 v118, v2
	v_mov_b32_e32 v119, v2
	v_mov_b32_e32 v120, v2
	v_mov_b32_e32 v121, v2
	v_mov_b32_e32 v122, v2
	v_mov_b32_e32 v123, v2
	v_mov_b32_e32 v124, v2
	v_mov_b32_e32 v125, v2
	v_mov_b32_e32 v126, v2
	v_mov_b32_e32 v127, v2
	v_mov_b32_e32 v128, v2
	v_mov_b32_e32 v129, v2
	s_mul_i32 s0, s42, 0x6000
	v_add_u32_e32 v211, s0, v185
	v_lshl_add_u64 v[212:213], v[182:183], 0, v[0:1]
	v_readfirstlane_b32 s0, v211
	v_lshl_add_u64 v[214:215], v[212:213], 0, s[84:85]
	s_mov_b32 m0, s0
	v_lshl_add_u64 v[212:213], v[212:213], 0, s[12:13]
	s_nop 0
	v_readfirstlane_b32 s100, v214
	v_readfirstlane_b32 s101, v215
	s_nop 1
	v_subrev_u32_e32 v228, s100, v214
	v_add_u32_e32 v214, 0x1000, v211
	v_add_u32_e32 v216, 0x2000, v211
	v_readfirstlane_b32 s0, v214
	s_mov_b32 m0, s0
	s_mov_b64 s[0:1], 0x49a6000
	v_subrev_u32_e32 v229, s100, v212
	v_lshl_add_u64 v[212:213], v[180:181], 0, v[0:1]
	v_lshl_add_u64 v[214:215], v[212:213], 0, s[0:1]
	v_readfirstlane_b32 s0, v216
	s_mov_b32 m0, s0
	s_mov_b64 s[0:1], 0x49a7000
	v_add_u32_e32 v216, 0x3000, v211
	s_nop 0
	v_readfirstlane_b32 vcc_lo, v214
	v_readfirstlane_b32 vcc_hi, v215
	s_nop 1
	v_subrev_u32_e32 v230, vcc_lo, v214
	v_lshl_add_u64 v[214:215], v[212:213], 0, s[0:1]
	v_readfirstlane_b32 s0, v216
	s_mov_b32 m0, s0
	s_mov_b64 s[0:1], 0x49a8000
	v_add_u32_e32 v216, 0x4000, v211
	v_subrev_u32_e32 v231, vcc_lo, v214
	v_lshl_add_u64 v[214:215], v[212:213], 0, s[0:1]
	v_readfirstlane_b32 s0, v216
	s_mov_b32 m0, s0
	s_mov_b64 s[0:1], 0x49a9000
	v_add_u32_e32 v211, 0x5000, v211
	v_lshl_add_u64 v[212:213], v[212:213], 0, s[0:1]
	v_readfirstlane_b32 s0, v211
	v_subrev_u32_e32 v232, vcc_lo, v214
	s_mov_b32 m0, s0
	s_nop 0
	v_subrev_u32_e32 v233, vcc_lo, v212
	v_mov_b32_e32 v182, v228
	v_mov_b32_e32 v183, v229
	v_mov_b32_e32 v180, v230
	v_mov_b32_e32 v181, v231
	v_mov_b32_e32 v253, v232
	v_mov_b32_e32 v254, v233
	v_readfirstlane_b32 s0, v185
	s_branch .LBB0_529

; DEVI int otid() { int t = threadIdx.x; asm volatile("" : "+v"(t)); return t; }
; #define RAW_BARRIER() do { asm volatile("s_waitcnt lgkmcnt(0)" ::: "memory"); __builtin_amdgcn_s_barrier(); } while (0)
; template <int EPI, int NB>
; DEVI void gemm_tile(const GemmJob& J, int m0, int n0, unsigned char* smem) {
;     ...
;   const int tid = otid(), lane = tid & 63, wid = tid >> 6, wm = wid >> 1, wn = wid & 1;
;   const int l16 = lane & 15, g = lane >> 4;
;   f32x4 acc[4][NB];
; #pragma unroll
;   for (int i = 0; i < 4; ++i)
; #pragma unroll
;     for (int j = 0; j < NB; ++j) acc[i][j] = (f32x4){0.f, 0.f, 0.f, 0.f};
;   const int srow = tid >> 2, sch = tid & 3;
;   const int gch = sch ^ ((0 - (tid >> 4)) & 3);
;   const bf16_t* Ag = J.A + (size_t)(m0 + srow) * (J.ablk ? 32 : J.lda) + gch * 8;
;   const bf16_t* Bg = J.Bt + (size_t)(n0 + srow) * 32 + gch * 8;
;   const size_t Astep = (size_t)64 * (J.ablk ? 32 : J.lda), Ak = J.ablk ? (size_t)MROWS * 32 : (size_t)32, Bstep = (size_t)64 * 32, Bk = (size_t)J.NR * 32;
;   const int nk = J.K >> 5;
;   unsigned char* lds_t = smem + tid * 16;
;   const unsigned lbase = (unsigned)(uintptr_t)(__attribute__((address_space(3))) unsigned char*)smem;
;     ...
;   asm volatile("s_waitcnt vmcnt(0)" ::: "memory");
;   RAW_BARRIER();
; #pragma unroll
;   for (int st = 0; st < S - 1; ++st) GEMM_ISSUE(st, st);
;   const int fsl = (g ^ ((0 - (l16 >> 2)) & 3)) << 4;
;   const int aofs = (wm * 64 + l16) * 64 + fsl;
;   const int bofs = A_BYTES + (wn * NB * 16 + l16) * 64 + fsl;
; template <int EPI, int NB>
; DEVI void gemm_run(const GemmJob& J, unsigned char* smem, int rot) {
;     ...
;     for (int t = b; t < ntiles; t += G) {
;       const int mt = t / J.ntn, nt = J.nt0 + (t - mt * J.ntn);
;       gemm_tile<EPI, NB>(J, mt * 128, nt * BN, smem);
.LBB0_605:
	s_ashr_i32 s0, s9, 31
	s_lshr_b32 s0, s0, 30
	s_add_i32 s0, s9, s0
	s_ashr_i32 s0, s0, 2
	s_lshl_b32 s3, s0, 7
	s_lshl_b32 s1, s9, 8
	s_lshl_b32 s0, s0, 10
	s_sub_i32 s2, s1, s0
	v_mov_b32_e32 v184, v177
	s_addk_i32 s2, 0x800
	s_nop 0
	s_mov_b64 s[28:29], 0x1000
	v_ashrrev_i32_e32 v10, 2, v184
	v_lshrrev_b32_e32 v0, 4, v184
	v_sub_u32_e32 v11, 0, v0
	v_add_u32_e32 v2, s3, v10
	v_add_u32_e32 v6, s2, v10
	v_xor_b32_e32 v0, v184, v11
	v_ashrrev_i32_e32 v3, 31, v2
	v_ashrrev_i32_e32 v7, 31, v6
	v_lshlrev_b64 v[2:3], 6, v[2:3]
	v_lshlrev_b32_e32 v0, 4, v0
	v_lshlrev_b64 v[6:7], 6, v[6:7]
	v_lshl_add_u64 v[4:5], v[146:147], 0, v[2:3]
	v_and_b32_e32 v0, 48, v0
	v_lshl_add_u64 v[6:7], v[142:143], 0, v[6:7]
	v_lshlrev_b32_e32 v185, 4, v184
	v_lshl_add_u64 v[4:5], v[4:5], 0, v[0:1]
	v_lshl_add_u64 v[6:7], v[6:7], 0, v[0:1]
	v_readfirstlane_b32 s1, v185
	v_add_u32_e32 v0, 0x1000, v185
	s_mov_b32 m0, s1
	v_readfirstlane_b32 s1, v0
	v_add_u32_e32 v0, 0x2000, v185
	s_waitcnt lgkmcnt(0)
	s_barrier
	global_load_lds_dwordx4 v[4:5], off
	v_lshl_add_u64 v[8:9], v[4:5], 0, s[28:29]
	s_mov_b32 m0, s1
	v_readfirstlane_b32 s1, v0
	v_add_u32_e32 v0, 0x3000, v185
	global_load_lds_dwordx4 v[8:9], off
	s_mov_b32 m0, s1
	v_readfirstlane_b32 s1, v0
	v_add_u32_e32 v0, 0x4000, v185
	global_load_lds_dwordx4 v[6:7], off
	v_lshl_add_u64 v[8:9], v[6:7], 0, s[28:29]
	s_mov_b32 m0, s1
	s_mov_b64 s[28:29], 0x2000
	v_readfirstlane_b32 s1, v0
	v_add_u32_e32 v0, 0x5000, v185
	global_load_lds_dwordx4 v[8:9], off
	v_lshl_add_u64 v[8:9], v[6:7], 0, s[28:29]
	s_mov_b32 m0, s1
	s_mov_b64 s[28:29], 0x3000
	v_readfirstlane_b32 s1, v0
	v_add_u32_e32 v0, 0x6000, v185
	global_load_lds_dwordx4 v[8:9], off
	v_lshl_add_u64 v[8:9], v[6:7], 0, s[28:29]
	s_mov_b32 m0, s1
	v_readfirstlane_b32 s1, v0
	v_add_u32_e32 v0, 0x7000, v185
	global_load_lds_dwordx4 v[8:9], off
	v_lshl_add_u64 v[8:9], v[4:5], 0, s[94:95]
	s_mov_b32 m0, s1
	s_mov_b64 s[28:29], 0x30b000
	v_readfirstlane_b32 s1, v0
	v_add_u32_e32 v0, 0x8000, v185
	global_load_lds_dwordx4 v[8:9], off
	v_lshl_add_u64 v[4:5], v[4:5], 0, s[28:29]
	s_mov_b32 m0, s1
	v_readfirstlane_b32 s1, v0
	v_add_u32_e32 v0, 0x9000, v185
	global_load_lds_dwordx4 v[4:5], off
	v_lshl_add_u64 v[4:5], v[6:7], 0, s[4:5]
	s_mov_b32 m0, s1
	s_mov_b64 s[28:29], 0x31000
	v_readfirstlane_b32 s1, v0
	v_add_u32_e32 v0, 0xa000, v185
	global_load_lds_dwordx4 v[4:5], off
	v_lshl_add_u64 v[4:5], v[6:7], 0, s[28:29]
	s_mov_b32 m0, s1
	s_mov_b64 s[28:29], 0x32000
	v_readfirstlane_b32 s1, v0
	v_add_u32_e32 v0, 0xb000, v185
	global_load_lds_dwordx4 v[4:5], off
	v_lshl_add_u64 v[4:5], v[6:7], 0, s[28:29]
	s_mov_b32 m0, s1
	s_mov_b64 s[28:29], 0x33000
	v_readfirstlane_b32 s1, v0
	global_load_lds_dwordx4 v[4:5], off
	v_lshl_add_u64 v[4:5], v[6:7], 0, s[28:29]
	s_mov_b32 m0, s1
	v_and_b32_e32 v0, 15, v184
	global_load_lds_dwordx4 v[4:5], off
	v_lshlrev_b32_e32 v4, 2, v184
	v_and_b32_e32 v4, 48, v4
	v_ashrrev_i32_e32 v5, 1, v184
	v_sub_u32_e32 v4, 0, v4
	v_and_b32_e32 v187, 0xffffffc0, v5
	v_bitop3_b32 v4, v184, 48, v4 bitop3:0x48
	v_or_b32_e32 v5, v187, v0
	v_lshl_or_b32 v208, v5, 6, v4
	v_lshlrev_b32_e32 v5, 1, v184
	s_movk_i32 s1, 0x80
	v_and_or_b32 v186, v5, s1, v0
	v_lshl_or_b32 v0, v186, 6, v4
	v_add_u32_e32 v4, s8, v10
	v_subrev_u32_e32 v4, s0, v4
	v_ashrrev_i32_e32 v5, 31, v4
	v_add_u32_e32 v209, 0x2000, v0
	v_bitop3_b32 v0, v184, 3, v11 bitop3:0x48
	v_lshlrev_b64 v[4:5], 6, v[4:5]
	v_lshl_add_u64 v[182:183], v[130:131], 0, v[2:3]
	v_mov_b32_e32 v2, 0
	s_mov_b32 s42, 2
	s_mov_b32 s20, 0
	s_mov_b64 s[30:31], 0x1000
	v_lshlrev_b32_e32 v0, 4, v0
	v_lshl_add_u64 v[180:181], v[130:131], 0, v[4:5]
	s_mov_b32 s43, 0
	v_mov_b32_e32 v3, v2
	v_mov_b32_e32 v4, v2
	v_mov_b32_e32 v5, v2
	v_mov_b32_e32 v6, v2
	v_mov_b32_e32 v7, v2
	v_mov_b32_e32 v8, v2
	v_mov_b32_e32 v9, v2
	v_mov_b32_e32 v10, v2
	v_mov_b32_e32 v11, v2
	v_mov_b32_e32 v12, v2
	v_mov_b32_e32 v13, v2
	v_mov_b32_e32 v14, v2
	v_mov_b32_e32 v15, v2
	v_mov_b32_e32 v16, v2
	v_mov_b32_e32 v17, v2
	v_mov_b32_e32 v18, v2
	v_mov_b32_e32 v19, v2
	v_mov_b32_e32 v20, v2
	v_mov_b32_e32 v21, v2
	v_mov_b32_e32 v22, v2
	v_mov_b32_e32 v23, v2
; #define RAW_BARRIER() do { asm volatile("s_waitcnt lgkmcnt(0)" ::: "memory"); __builtin_amdgcn_s_barrier(); } while (0)
; template <int EPI, int NB>
; DEVI void gemm_tile(const GemmJob& J, int m0, int n0, unsigned char* smem) {
;     ...
;   f32x4 acc[4][NB];
; #pragma unroll
;   for (int i = 0; i < 4; ++i)
; #pragma unroll
;     for (int j = 0; j < NB; ++j) acc[i][j] = (f32x4){0.f, 0.f, 0.f, 0.f};
;     ...
;   int cs = 0, is = S - 1;
; #pragma clang loop unroll(disable)
;   for (int kt = 0; kt < nk; ++kt) {
;     if (nk - 1 - kt >= S - 2) {
;       if constexpr (NB == 8) asm volatile("s_waitcnt vmcnt(6)" ::: "memory");
;       else                   asm volatile("s_waitcnt vmcnt(8)" ::: "memory");
;     } else {
;       asm volatile("s_waitcnt vmcnt(0)" ::: "memory");
;     }
;     RAW_BARRIER();
;     if (kt + S - 1 < nk) GEMM_ISSUE(kt + S - 1, is);
;     is = (is + 1 == S) ? 0 : is + 1;
;     const unsigned cur = lbase + cs * STG;
	v_mov_b32_e32 v24, v2
	v_mov_b32_e32 v25, v2
	v_mov_b32_e32 v26, v2
	v_mov_b32_e32 v27, v2
	v_mov_b32_e32 v28, v2
	v_mov_b32_e32 v29, v2
	v_mov_b32_e32 v30, v2
	v_mov_b32_e32 v31, v2
	v_mov_b32_e32 v32, v2
	v_mov_b32_e32 v33, v2
	v_mov_b32_e32 v34, v2
	v_mov_b32_e32 v35, v2
	v_mov_b32_e32 v36, v2
	v_mov_b32_e32 v37, v2
	v_mov_b32_e32 v38, v2
	v_mov_b32_e32 v39, v2
	v_mov_b32_e32 v40, v2
	v_mov_b32_e32 v41, v2
	v_mov_b32_e32 v42, v2
	v_mov_b32_e32 v43, v2
	v_mov_b32_e32 v44, v2
	v_mov_b32_e32 v45, v2
	v_mov_b32_e32 v46, v2
	v_mov_b32_e32 v47, v2
	v_mov_b32_e32 v48, v2
	v_mov_b32_e32 v49, v2
	v_mov_b32_e32 v50, v2
	v_mov_b32_e32 v51, v2
	v_mov_b32_e32 v52, v2
	v_mov_b32_e32 v53, v2
	v_mov_b32_e32 v54, v2
	v_mov_b32_e32 v55, v2
	v_mov_b32_e32 v56, v2
	v_mov_b32_e32 v57, v2
	v_mov_b32_e32 v58, v2
	v_mov_b32_e32 v59, v2
	v_mov_b32_e32 v60, v2
	v_mov_b32_e32 v61, v2
	v_mov_b32_e32 v62, v2
	v_mov_b32_e32 v63, v2
	v_mov_b32_e32 v64, v2
	v_mov_b32_e32 v65, v2
	v_mov_b32_e32 v66, v2
	v_mov_b32_e32 v67, v2
	v_mov_b32_e32 v68, v2
	v_mov_b32_e32 v69, v2
	v_mov_b32_e32 v70, v2
	v_mov_b32_e32 v71, v2
	v_mov_b32_e32 v72, v2
	v_mov_b32_e32 v73, v2
	v_mov_b32_e32 v74, v2
	v_mov_b32_e32 v75, v2
	v_mov_b32_e32 v76, v2
	v_mov_b32_e32 v77, v2
	v_mov_b32_e32 v78, v2
	v_mov_b32_e32 v79, v2
	v_mov_b32_e32 v80, v2
	v_mov_b32_e32 v81, v2
	v_mov_b32_e32 v82, v2
	v_mov_b32_e32 v83, v2
	v_mov_b32_e32 v84, v2
	v_mov_b32_e32 v85, v2
	v_mov_b32_e32 v86, v2
	v_mov_b32_e32 v87, v2
	v_mov_b32_e32 v88, v2
	v_mov_b32_e32 v89, v2
	v_mov_b32_e32 v90, v2
	v_mov_b32_e32 v91, v2
	v_mov_b32_e32 v92, v2
	v_mov_b32_e32 v93, v2
	v_mov_b32_e32 v94, v2
	v_mov_b32_e32 v95, v2
	v_mov_b32_e32 v96, v2
	v_mov_b32_e32 v97, v2
	v_mov_b32_e32 v98, v2
	v_mov_b32_e32 v99, v2
	v_mov_b32_e32 v100, v2
	v_mov_b32_e32 v101, v2
	v_mov_b32_e32 v102, v2
	v_mov_b32_e32 v103, v2
	v_mov_b32_e32 v104, v2
	v_mov_b32_e32 v105, v2
	v_mov_b32_e32 v106, v2
	v_mov_b32_e32 v107, v2
	v_mov_b32_e32 v108, v2
	v_mov_b32_e32 v109, v2
	v_mov_b32_e32 v110, v2
	v_mov_b32_e32 v111, v2
	v_mov_b32_e32 v112, v2
	v_mov_b32_e32 v113, v2
	v_mov_b32_e32 v114, v2
	v_mov_b32_e32 v115, v2
	v_mov_b32_e32 v116, v2
	v_mov_b32_e32 v117, v2
	v_mov_b32_e32 v118, v2
	v_mov_b32_e32 v119, v2
	v_mov_b32_e32 v120, v2
	v_mov_b32_e32 v121, v2
	v_mov_b32_e32 v122, v2
	v_mov_b32_e32 v123, v2
	v_mov_b32_e32 v124, v2
	v_mov_b32_e32 v125, v2
	v_mov_b32_e32 v126, v2
	v_mov_b32_e32 v127, v2
	v_mov_b32_e32 v128, v2
	v_mov_b32_e32 v129, v2
	s_mul_i32 s0, s42, 0x6000
	v_add_u32_e32 v214, s0, v185
	v_lshl_add_u64 v[210:211], v[182:183], 0, v[0:1]
	v_readfirstlane_b32 s0, v214
	v_lshl_add_u64 v[212:213], v[210:211], 0, s[84:85]
	s_mov_b32 m0, s0
	v_lshl_add_u64 v[210:211], v[210:211], 0, s[12:13]
	s_nop 0
	v_readfirstlane_b32 s100, v212
	v_readfirstlane_b32 s101, v213
	s_nop 1
	v_subrev_u32_e32 v226, s100, v212
	v_add_u32_e32 v212, 0x1000, v214
	v_add_u32_e32 v215, 0x2000, v214
	v_readfirstlane_b32 s0, v212
	s_mov_b32 m0, s0
	s_mov_b64 s[0:1], 0x49a6000
	v_subrev_u32_e32 v227, s100, v210
	v_lshl_add_u64 v[210:211], v[180:181], 0, v[0:1]
	v_lshl_add_u64 v[212:213], v[210:211], 0, s[0:1]
	v_readfirstlane_b32 s0, v215
	s_mov_b32 m0, s0
	s_mov_b64 s[0:1], 0x49a7000
	v_add_u32_e32 v215, 0x3000, v214
	s_nop 0
	v_readfirstlane_b32 vcc_lo, v212
	v_readfirstlane_b32 vcc_hi, v213
	s_nop 1
	v_subrev_u32_e32 v228, vcc_lo, v212
	v_lshl_add_u64 v[212:213], v[210:211], 0, s[0:1]
	v_readfirstlane_b32 s0, v215
	s_mov_b32 m0, s0
	s_mov_b64 s[0:1], 0x49a8000
	v_add_u32_e32 v215, 0x4000, v214
	v_subrev_u32_e32 v229, vcc_lo, v212
	v_lshl_add_u64 v[212:213], v[210:211], 0, s[0:1]
	v_readfirstlane_b32 s0, v215
	s_mov_b32 m0, s0
	s_mov_b64 s[0:1], 0x49a9000
	v_subrev_u32_e32 v230, vcc_lo, v212
	v_add_u32_e32 v212, 0x5000, v214
	v_lshl_add_u64 v[210:211], v[210:211], 0, s[0:1]
	v_readfirstlane_b32 s0, v212
	s_mov_b32 m0, s0
	s_nop 0
	v_subrev_u32_e32 v231, vcc_lo, v210
	v_mov_b32_e32 v182, v226
	v_mov_b32_e32 v183, v227
	v_mov_b32_e32 v180, v228
	v_mov_b32_e32 v181, v229
	v_mov_b32_e32 v253, v230
	v_mov_b32_e32 v254, v231
	v_readfirstlane_b32 s0, v185
	s_branch .LBB0_607

; DEVI int otid() { int t = threadIdx.x; asm volatile("" : "+v"(t)); return t; }
; #define RAW_BARRIER() do { asm volatile("s_waitcnt lgkmcnt(0)" ::: "memory"); __builtin_amdgcn_s_barrier(); } while (0)
; template <int EPI, int NB>
; DEVI void gemm_tile(const GemmJob& J, int m0, int n0, unsigned char* smem) {
;     ...
;   const int tid = otid(), lane = tid & 63, wid = tid >> 6, wm = wid >> 1, wn = wid & 1;
;   const int l16 = lane & 15, g = lane >> 4;
;   f32x4 acc[4][NB];
; #pragma unroll
;   for (int i = 0; i < 4; ++i)
; #pragma unroll
;     for (int j = 0; j < NB; ++j) acc[i][j] = (f32x4){0.f, 0.f, 0.f, 0.f};
;   const int srow = tid >> 2, sch = tid & 3;
;   const int gch = sch ^ ((0 - (tid >> 4)) & 3);
;   const bf16_t* Ag = J.A + (size_t)(m0 + srow) * (J.ablk ? 32 : J.lda) + gch * 8;
;   const bf16_t* Bg = J.Bt + (size_t)(n0 + srow) * 32 + gch * 8;
;   const size_t Astep = (size_t)64 * (J.ablk ? 32 : J.lda), Ak = J.ablk ? (size_t)MROWS * 32 : (size_t)32, Bstep = (size_t)64 * 32, Bk = (size_t)J.NR * 32;
;   const int nk = J.K >> 5;
;   unsigned char* lds_t = smem + tid * 16;
;   const unsigned lbase = (unsigned)(uintptr_t)(__attribute__((address_space(3))) unsigned char*)smem;
;     ...
;   asm volatile("s_waitcnt vmcnt(0)" ::: "memory");
;   RAW_BARRIER();
; #pragma unroll
;   for (int st = 0; st < S - 1; ++st) GEMM_ISSUE(st, st);
;   const int fsl = (g ^ ((0 - (l16 >> 2)) & 3)) << 4;
;   const int aofs = (wm * 64 + l16) * 64 + fsl;
;   const int bofs = A_BYTES + (wn * NB * 16 + l16) * 64 + fsl;
; template <int EPI, int NB>
; DEVI void gemm_run(const GemmJob& J, unsigned char* smem, int rot) {
;     ...
;     for (int q0 = lb; q0 < ntot; q0 += nlb) {
;       const int q = J.rev ? ntot - 1 - q0 : q0;
;       int grp = q / gsz; const int qq = q - grp * gsz;
;       const int mg = min(8, mcnt - grp * 8);
;       const int nt = qq / mg, mi = qq - nt * mg;
;       gemm_tile<EPI, NB>(J, (mlo + grp * 8 + mi) * 128, (J.nt0 + nt) * BN, smem);
.LBB0_694:
	s_ashr_i32 s0, s9, 31
	s_lshr_b32 s0, s0, 26
	s_add_i32 s0, s9, s0
	s_ashr_i32 s1, s0, 6
	s_lshl_b32 s3, s1, 3
	v_readlane_b32 s2, v251, 48
	s_sub_i32 s2, s2, s3
	s_min_i32 s20, s2, 8
	s_abs_i32 s40, s20
	v_cvt_f32_u32_e32 v0, s40
	s_sub_i32 s43, 0, s40
	s_andn2_b32 s0, s0, 63
	s_sub_i32 s0, s9, s0
	v_rcp_iflag_f32_e32 v0, v0
	s_abs_i32 s41, s0
	s_xor_b32 s42, s0, s20
	s_ashr_i32 s42, s42, 31
	v_mul_f32_e32 v0, 0x4f7ffffe, v0
	v_cvt_u32_f32_e32 v0, v0
	v_mov_b32_e32 v184, v177
	s_nop 0
	v_readfirstlane_b32 s44, v0
	s_mul_i32 s43, s43, s44
	s_mul_hi_u32 s43, s44, s43
	s_add_i32 s44, s44, s43
	s_mul_hi_u32 s43, s41, s44
	s_mul_i32 s44, s43, s40
	s_sub_i32 s41, s41, s44
	s_add_i32 s45, s43, 1
	s_sub_i32 s44, s41, s40
	s_cmp_ge_u32 s41, s40
	s_cselect_b32 s43, s45, s43
	s_cselect_b32 s41, s44, s41
	s_add_i32 s44, s43, 1
	s_cmp_ge_u32 s41, s40
	s_cselect_b32 s40, s44, s43
	s_xor_b32 s40, s40, s42
	s_sub_i32 s40, s40, s42
	s_mul_i32 s41, s20, s40
	v_readlane_b32 s20, v250, 37
	s_add_i32 s3, s3, s20
	s_add_i32 s3, s3, s0
	s_sub_i32 s0, s3, s41
	s_lshl_b32 s20, s0, 7
	s_lshl_b32 s3, s40, 8
	v_ashrrev_i32_e32 v10, 2, v184
	v_lshrrev_b32_e32 v0, 4, v184
	v_sub_u32_e32 v11, 0, v0
	v_add_u32_e32 v2, s20, v10
	v_add_u32_e32 v4, s3, v10
	v_xor_b32_e32 v0, v184, v11
	v_ashrrev_i32_e32 v3, 31, v2
	v_ashrrev_i32_e32 v5, 31, v4
	v_lshlrev_b64 v[2:3], 6, v[2:3]
	v_lshlrev_b32_e32 v0, 4, v0
	v_lshlrev_b64 v[4:5], 6, v[4:5]
	v_lshl_add_u64 v[2:3], v[146:147], 0, v[2:3]
	v_and_b32_e32 v0, 48, v0
	v_lshl_add_u64 v[6:7], v[142:143], 0, v[4:5]
	v_lshlrev_b32_e32 v185, 4, v184
	v_lshl_add_u64 v[2:3], v[2:3], 0, v[0:1]
	v_lshl_add_u64 v[6:7], v[6:7], 0, v[0:1]
	v_readfirstlane_b32 s0, v185
	v_add_u32_e32 v0, 0x1000, v185
	s_mov_b32 m0, s0
	s_mov_b64 s[28:29], 0x1000
	v_readfirstlane_b32 s0, v0
	v_add_u32_e32 v0, 0x2000, v185
	s_waitcnt lgkmcnt(0)
	s_barrier
	global_load_lds_dwordx4 v[2:3], off
	v_lshl_add_u64 v[8:9], v[2:3], 0, s[28:29]
	s_mov_b32 m0, s0
	v_readfirstlane_b32 s0, v0
	v_add_u32_e32 v0, 0x3000, v185
	global_load_lds_dwordx4 v[8:9], off
	s_mov_b32 m0, s0
	v_readfirstlane_b32 s0, v0
	v_add_u32_e32 v0, 0x4000, v185
	global_load_lds_dwordx4 v[6:7], off
	v_lshl_add_u64 v[8:9], v[6:7], 0, s[28:29]
	s_mov_b32 m0, s0
	s_mov_b64 s[28:29], 0x2000
	v_readfirstlane_b32 s0, v0
	v_add_u32_e32 v0, 0x5000, v185
	global_load_lds_dwordx4 v[8:9], off
	v_lshl_add_u64 v[8:9], v[6:7], 0, s[28:29]
	s_mov_b32 m0, s0
	s_mov_b64 s[28:29], 0x3000
	v_readfirstlane_b32 s0, v0
	v_add_u32_e32 v0, 0x6000, v185
	global_load_lds_dwordx4 v[8:9], off
	v_lshl_add_u64 v[8:9], v[6:7], 0, s[28:29]
	s_mov_b32 m0, s0
	v_readfirstlane_b32 s0, v0
	v_add_u32_e32 v0, 0x7000, v185
	global_load_lds_dwordx4 v[8:9], off
	v_lshl_add_u64 v[8:9], v[2:3], 0, s[94:95]
	s_mov_b32 m0, s0
	s_mov_b64 s[28:29], 0x30b000
	v_readfirstlane_b32 s0, v0
	v_add_u32_e32 v0, 0x8000, v185
	global_load_lds_dwordx4 v[8:9], off
	v_lshl_add_u64 v[2:3], v[2:3], 0, s[28:29]
	s_mov_b32 m0, s0
	v_readfirstlane_b32 s0, v0
	v_add_u32_e32 v0, 0x9000, v185
	global_load_lds_dwordx4 v[2:3], off
	v_lshl_add_u64 v[2:3], v[6:7], 0, s[4:5]
	s_mov_b32 m0, s0
	s_mov_b64 s[28:29], 0x31000
	v_readfirstlane_b32 s0, v0
	v_add_u32_e32 v0, 0xa000, v185
	global_load_lds_dwordx4 v[2:3], off
	v_lshl_add_u64 v[2:3], v[6:7], 0, s[28:29]
	s_mov_b32 m0, s0
	s_mov_b64 s[28:29], 0x32000
	v_readfirstlane_b32 s0, v0
	v_add_u32_e32 v0, 0xb000, v185
	global_load_lds_dwordx4 v[2:3], off
	v_lshl_add_u64 v[2:3], v[6:7], 0, s[28:29]
	s_mov_b32 m0, s0
	s_mov_b64 s[28:29], 0x33000
	v_readfirstlane_b32 s0, v0
	global_load_lds_dwordx4 v[2:3], off
	v_lshl_add_u64 v[2:3], v[6:7], 0, s[28:29]
	s_mov_b32 m0, s0
	v_lshlrev_b32_e32 v0, 2, v184
	global_load_lds_dwordx4 v[2:3], off
	v_and_b32_e32 v0, 48, v0
	v_ashrrev_i32_e32 v2, 1, v184
	v_and_b32_e32 v186, 15, v184
	v_sub_u32_e32 v0, 0, v0
	v_and_b32_e32 v187, 0xffffffc0, v2
	v_bitop3_b32 v0, v184, 48, v0 bitop3:0x48
	v_or_b32_e32 v2, v187, v186
	v_lshl_or_b32 v209, v2, 6, v0
	v_lshlrev_b32_e32 v2, 1, v184
	v_and_b32_e32 v208, 0x80, v2
	s_sub_i32 s0, s8, s41
	s_mul_i32 s1, s1, 56
	v_or_b32_e32 v2, v208, v186
	s_sub_i32 s0, s0, s1
	v_lshl_or_b32 v0, v2, 6, v0
	v_lshl_add_u32 v2, s0, 7, v10
	v_ashrrev_i32_e32 v3, 31, v2
	v_lshlrev_b64 v[2:3], 6, v[2:3]
	v_add_u32_e32 v210, 0x2000, v0
	v_bitop3_b32 v0, v184, 3, v11 bitop3:0x48
	v_lshl_add_u64 v[182:183], v[130:131], 0, v[2:3]
	v_mov_b32_e32 v2, 0
	s_mov_b32 s2, 0
	s_mov_b32 s42, 2
	s_mov_b64 s[30:31], 0x1000
	v_lshlrev_b32_e32 v0, 4, v0
	v_lshl_add_u64 v[180:181], v[130:131], 0, v[4:5]
	s_mov_b32 s43, 0
; #define RAW_BARRIER() do { asm volatile("s_waitcnt lgkmcnt(0)" ::: "memory"); __builtin_amdgcn_s_barrier(); } while (0)
; template <int EPI, int NB>
; DEVI void gemm_tile(const GemmJob& J, int m0, int n0, unsigned char* smem) {
;     ...
;   f32x4 acc[4][NB];
; #pragma unroll
;   for (int i = 0; i < 4; ++i)
; #pragma unroll
;     for (int j = 0; j < NB; ++j) acc[i][j] = (f32x4){0.f, 0.f, 0.f, 0.f};
;     ...
;   int cs = 0, is = S - 1;
; #pragma clang loop unroll(disable)
;   for (int kt = 0; kt < nk; ++kt) {
;     if (nk - 1 - kt >= S - 2) {
;       if constexpr (NB == 8) asm volatile("s_waitcnt vmcnt(6)" ::: "memory");
;       else                   asm volatile("s_waitcnt vmcnt(8)" ::: "memory");
;     } else {
;       asm volatile("s_waitcnt vmcnt(0)" ::: "memory");
;     }
;     RAW_BARRIER();
;     if (kt + S - 1 < nk) GEMM_ISSUE(kt + S - 1, is);
;     is = (is + 1 == S) ? 0 : is + 1;
;     const unsigned cur = lbase + cs * STG;
	v_mov_b32_e32 v3, v2
	v_mov_b32_e32 v4, v2
	v_mov_b32_e32 v5, v2
	v_mov_b32_e32 v6, v2
	v_mov_b32_e32 v7, v2
	v_mov_b32_e32 v8, v2
	v_mov_b32_e32 v9, v2
	v_mov_b32_e32 v10, v2
	v_mov_b32_e32 v11, v2
	v_mov_b32_e32 v12, v2
	v_mov_b32_e32 v13, v2
	v_mov_b32_e32 v14, v2
	v_mov_b32_e32 v15, v2
	v_mov_b32_e32 v16, v2
	v_mov_b32_e32 v17, v2
	v_mov_b32_e32 v18, v2
	v_mov_b32_e32 v19, v2
	v_mov_b32_e32 v20, v2
	v_mov_b32_e32 v21, v2
	v_mov_b32_e32 v22, v2
	v_mov_b32_e32 v23, v2
	v_mov_b32_e32 v24, v2
	v_mov_b32_e32 v25, v2
	v_mov_b32_e32 v26, v2
	v_mov_b32_e32 v27, v2
	v_mov_b32_e32 v28, v2
	v_mov_b32_e32 v29, v2
	v_mov_b32_e32 v30, v2
	v_mov_b32_e32 v31, v2
	v_mov_b32_e32 v32, v2
	v_mov_b32_e32 v33, v2
	v_mov_b32_e32 v34, v2
	v_mov_b32_e32 v35, v2
	v_mov_b32_e32 v36, v2
	v_mov_b32_e32 v37, v2
	v_mov_b32_e32 v38, v2
	v_mov_b32_e32 v39, v2
	v_mov_b32_e32 v40, v2
	v_mov_b32_e32 v41, v2
	v_mov_b32_e32 v42, v2
	v_mov_b32_e32 v43, v2
	v_mov_b32_e32 v44, v2
	v_mov_b32_e32 v45, v2
	v_mov_b32_e32 v46, v2
	v_mov_b32_e32 v47, v2
	v_mov_b32_e32 v48, v2
	v_mov_b32_e32 v49, v2
	v_mov_b32_e32 v50, v2
	v_mov_b32_e32 v51, v2
	v_mov_b32_e32 v52, v2
	v_mov_b32_e32 v53, v2
	v_mov_b32_e32 v54, v2
	v_mov_b32_e32 v55, v2
	v_mov_b32_e32 v56, v2
	v_mov_b32_e32 v57, v2
	v_mov_b32_e32 v58, v2
	v_mov_b32_e32 v59, v2
	v_mov_b32_e32 v60, v2
	v_mov_b32_e32 v61, v2
	v_mov_b32_e32 v62, v2
	v_mov_b32_e32 v63, v2
	v_mov_b32_e32 v64, v2
	v_mov_b32_e32 v65, v2
	v_mov_b32_e32 v66, v2
	v_mov_b32_e32 v67, v2
	v_mov_b32_e32 v68, v2
	v_mov_b32_e32 v69, v2
	v_mov_b32_e32 v70, v2
	v_mov_b32_e32 v71, v2
	v_mov_b32_e32 v72, v2
	v_mov_b32_e32 v73, v2
	v_mov_b32_e32 v74, v2
	v_mov_b32_e32 v75, v2
	v_mov_b32_e32 v76, v2
	v_mov_b32_e32 v77, v2
	v_mov_b32_e32 v78, v2
	v_mov_b32_e32 v79, v2
	v_mov_b32_e32 v80, v2
	v_mov_b32_e32 v81, v2
	v_mov_b32_e32 v82, v2
	v_mov_b32_e32 v83, v2
	v_mov_b32_e32 v84, v2
	v_mov_b32_e32 v85, v2
	v_mov_b32_e32 v86, v2
	v_mov_b32_e32 v87, v2
	v_mov_b32_e32 v88, v2
	v_mov_b32_e32 v89, v2
	v_mov_b32_e32 v90, v2
	v_mov_b32_e32 v91, v2
	v_mov_b32_e32 v92, v2
	v_mov_b32_e32 v93, v2
	v_mov_b32_e32 v94, v2
	v_mov_b32_e32 v95, v2
	v_mov_b32_e32 v96, v2
	v_mov_b32_e32 v97, v2
	v_mov_b32_e32 v98, v2
	v_mov_b32_e32 v99, v2
	v_mov_b32_e32 v100, v2
	v_mov_b32_e32 v101, v2
	v_mov_b32_e32 v102, v2
	v_mov_b32_e32 v103, v2
	v_mov_b32_e32 v104, v2
	v_mov_b32_e32 v105, v2
	v_mov_b32_e32 v106, v2
	v_mov_b32_e32 v107, v2
	v_mov_b32_e32 v108, v2
	v_mov_b32_e32 v109, v2
	v_mov_b32_e32 v110, v2
	v_mov_b32_e32 v111, v2
	v_mov_b32_e32 v112, v2
	v_mov_b32_e32 v113, v2
	v_mov_b32_e32 v114, v2
	v_mov_b32_e32 v115, v2
	v_mov_b32_e32 v116, v2
	v_mov_b32_e32 v117, v2
	v_mov_b32_e32 v118, v2
	v_mov_b32_e32 v119, v2
	v_mov_b32_e32 v120, v2
	v_mov_b32_e32 v121, v2
	v_mov_b32_e32 v122, v2
	v_mov_b32_e32 v123, v2
	v_mov_b32_e32 v124, v2
	v_mov_b32_e32 v125, v2
	v_mov_b32_e32 v126, v2
	v_mov_b32_e32 v127, v2
	v_mov_b32_e32 v128, v2
	v_mov_b32_e32 v129, v2
	s_mul_i32 s0, s42, 0x6000
	v_add_u32_e32 v211, s0, v185
	v_lshl_add_u64 v[212:213], v[182:183], 0, v[0:1]
	v_readfirstlane_b32 s0, v211
	v_lshl_add_u64 v[214:215], v[212:213], 0, s[84:85]
	s_mov_b32 m0, s0
	v_lshl_add_u64 v[212:213], v[212:213], 0, s[12:13]
	s_nop 0
	v_readfirstlane_b32 s100, v214
	v_readfirstlane_b32 s101, v215
	s_nop 1
	v_subrev_u32_e32 v228, s100, v214
	v_add_u32_e32 v214, 0x1000, v211
	v_add_u32_e32 v216, 0x2000, v211
	v_readfirstlane_b32 s0, v214
	s_mov_b32 m0, s0
	s_mov_b64 s[0:1], 0x49a6000
	v_subrev_u32_e32 v229, s100, v212
	v_lshl_add_u64 v[212:213], v[180:181], 0, v[0:1]
	v_lshl_add_u64 v[214:215], v[212:213], 0, s[0:1]
	v_readfirstlane_b32 s0, v216
	s_mov_b32 m0, s0
	s_mov_b64 s[0:1], 0x49a7000
	v_add_u32_e32 v216, 0x3000, v211
	s_nop 0
	v_readfirstlane_b32 vcc_lo, v214
	v_readfirstlane_b32 vcc_hi, v215
	s_nop 1
	v_subrev_u32_e32 v230, vcc_lo, v214
	v_lshl_add_u64 v[214:215], v[212:213], 0, s[0:1]
	v_readfirstlane_b32 s0, v216
	s_mov_b32 m0, s0
	s_mov_b64 s[0:1], 0x49a8000
	v_add_u32_e32 v216, 0x4000, v211
	v_subrev_u32_e32 v231, vcc_lo, v214
	v_lshl_add_u64 v[214:215], v[212:213], 0, s[0:1]
	v_readfirstlane_b32 s0, v216
	s_mov_b32 m0, s0
	s_mov_b64 s[0:1], 0x49a9000
	v_add_u32_e32 v211, 0x5000, v211
	v_lshl_add_u64 v[212:213], v[212:213], 0, s[0:1]
	v_readfirstlane_b32 s0, v211
	v_subrev_u32_e32 v232, vcc_lo, v214
	s_mov_b32 m0, s0
	s_nop 0
	v_subrev_u32_e32 v233, vcc_lo, v212
	v_mov_b32_e32 v182, v228
	v_mov_b32_e32 v183, v229
	v_mov_b32_e32 v180, v230
	v_mov_b32_e32 v181, v231
	v_mov_b32_e32 v253, v232
	v_mov_b32_e32 v254, v233
	v_readfirstlane_b32 s0, v185
	s_branch .LBB0_696

; DEVI int otid() { int t = threadIdx.x; asm volatile("" : "+v"(t)); return t; }
; #define RAW_BARRIER() do { asm volatile("s_waitcnt lgkmcnt(0)" ::: "memory"); __builtin_amdgcn_s_barrier(); } while (0)
; template <int EPI, int NB>
; DEVI void gemm_tile(const GemmJob& J, int m0, int n0, unsigned char* smem) {
;     ...
;   const int tid = otid(), lane = tid & 63, wid = tid >> 6, wm = wid >> 1, wn = wid & 1;
;   const int l16 = lane & 15, g = lane >> 4;
;   f32x4 acc[4][NB];
; #pragma unroll
;   for (int i = 0; i < 4; ++i)
; #pragma unroll
;     for (int j = 0; j < NB; ++j) acc[i][j] = (f32x4){0.f, 0.f, 0.f, 0.f};
;   const int srow = tid >> 2, sch = tid & 3;
;   const int gch = sch ^ ((0 - (tid >> 4)) & 3);
;   const bf16_t* Ag = J.A + (size_t)(m0 + srow) * (J.ablk ? 32 : J.lda) + gch * 8;
;   const bf16_t* Bg = J.Bt + (size_t)(n0 + srow) * 32 + gch * 8;
;   const size_t Astep = (size_t)64 * (J.ablk ? 32 : J.lda), Ak = J.ablk ? (size_t)MROWS * 32 : (size_t)32, Bstep = (size_t)64 * 32, Bk = (size_t)J.NR * 32;
;   const int nk = J.K >> 5;
;   unsigned char* lds_t = smem + tid * 16;
;   const unsigned lbase = (unsigned)(uintptr_t)(__attribute__((address_space(3))) unsigned char*)smem;
;     ...
;   asm volatile("s_waitcnt vmcnt(0)" ::: "memory");
;   RAW_BARRIER();
; #pragma unroll
;   for (int st = 0; st < S - 1; ++st) GEMM_ISSUE(st, st);
;   const int fsl = (g ^ ((0 - (l16 >> 2)) & 3)) << 4;
;   const int aofs = (wm * 64 + l16) * 64 + fsl;
;   const int bofs = A_BYTES + (wn * NB * 16 + l16) * 64 + fsl;
; template <int EPI, int NB>
; DEVI void gemm_run(const GemmJob& J, unsigned char* smem, int rot) {
;     ...
;     for (int q0 = lb; q0 < ntot; q0 += nlb) {
;       const int q = J.rev ? ntot - 1 - q0 : q0;
;       int grp = q / gsz; const int qq = q - grp * gsz;
;       const int mg = min(8, mcnt - grp * 8);
;       const int nt = qq / mg, mi = qq - nt * mg;
;       gemm_tile<EPI, NB>(J, (mlo + grp * 8 + mi) * 128, (J.nt0 + nt) * BN, smem);
.LBB0_772:
	s_ashr_i32 s0, s9, 31
	s_lshr_b32 s0, s0, 27
	s_add_i32 s0, s9, s0
	s_ashr_i32 s1, s0, 5
	s_lshl_b32 s2, s1, 3
	v_readlane_b32 s3, v251, 48
	s_sub_i32 s3, s3, s2
	s_min_i32 s20, s3, 8
	s_abs_i32 s40, s20
	v_cvt_f32_u32_e32 v0, s40
	s_sub_i32 s43, 0, s40
	s_andn2_b32 s0, s0, 31
	s_sub_i32 s0, s9, s0
	v_rcp_iflag_f32_e32 v0, v0
	s_abs_i32 s41, s0
	s_xor_b32 s42, s0, s20
	s_ashr_i32 s42, s42, 31
	v_mul_f32_e32 v0, 0x4f7ffffe, v0
	v_cvt_u32_f32_e32 v0, v0
	v_mov_b32_e32 v184, v177
	s_nop 0
	v_readfirstlane_b32 s44, v0
	s_mul_i32 s43, s43, s44
	s_mul_hi_u32 s43, s44, s43
	s_add_i32 s44, s44, s43
	s_mul_hi_u32 s43, s41, s44
	s_mul_i32 s44, s43, s40
	s_sub_i32 s41, s41, s44
	s_add_i32 s45, s43, 1
	s_sub_i32 s44, s41, s40
	s_cmp_ge_u32 s41, s40
	s_cselect_b32 s43, s45, s43
	s_cselect_b32 s41, s44, s41
	s_add_i32 s44, s43, 1
	s_cmp_ge_u32 s41, s40
	s_cselect_b32 s40, s44, s43
	s_xor_b32 s40, s40, s42
	s_sub_i32 s40, s40, s42
	s_mul_i32 s41, s20, s40
	v_readlane_b32 s20, v250, 37
	s_add_i32 s2, s2, s20
	s_add_i32 s2, s2, s0
	s_sub_i32 s0, s2, s41
	s_lshl_b32 s2, s40, 8
	s_lshl_b32 s20, s0, 7
	s_addk_i32 s2, 0x800
	v_ashrrev_i32_e32 v10, 2, v184
	v_lshrrev_b32_e32 v0, 4, v184
	v_sub_u32_e32 v11, 0, v0
	v_add_u32_e32 v2, s20, v10
	v_add_u32_e32 v4, s2, v10
	v_xor_b32_e32 v0, v184, v11
	v_ashrrev_i32_e32 v3, 31, v2
	v_ashrrev_i32_e32 v5, 31, v4
	v_lshlrev_b64 v[2:3], 6, v[2:3]
	v_lshlrev_b32_e32 v0, 4, v0
	v_lshlrev_b64 v[4:5], 6, v[4:5]
	v_lshl_add_u64 v[2:3], v[146:147], 0, v[2:3]
	v_and_b32_e32 v0, 48, v0
	v_lshl_add_u64 v[6:7], v[142:143], 0, v[4:5]
	v_lshlrev_b32_e32 v185, 4, v184
	v_lshl_add_u64 v[2:3], v[2:3], 0, v[0:1]
	v_lshl_add_u64 v[6:7], v[6:7], 0, v[0:1]
	v_readfirstlane_b32 s0, v185
	v_add_u32_e32 v0, 0x1000, v185
	s_mov_b32 m0, s0
	s_mov_b64 s[28:29], 0x1000
	v_readfirstlane_b32 s0, v0
	v_add_u32_e32 v0, 0x2000, v185
	s_waitcnt lgkmcnt(0)
	s_barrier
	global_load_lds_dwordx4 v[2:3], off
	v_lshl_add_u64 v[8:9], v[2:3], 0, s[28:29]
	s_mov_b32 m0, s0
	v_readfirstlane_b32 s0, v0
	v_add_u32_e32 v0, 0x3000, v185
	global_load_lds_dwordx4 v[8:9], off
	s_mov_b32 m0, s0
	v_readfirstlane_b32 s0, v0
	v_add_u32_e32 v0, 0x4000, v185
	global_load_lds_dwordx4 v[6:7], off
	v_lshl_add_u64 v[8:9], v[6:7], 0, s[28:29]
	s_mov_b32 m0, s0
	s_mov_b64 s[28:29], 0x2000
	v_readfirstlane_b32 s0, v0
	v_add_u32_e32 v0, 0x5000, v185
	global_load_lds_dwordx4 v[8:9], off
	v_lshl_add_u64 v[8:9], v[6:7], 0, s[28:29]
	s_mov_b32 m0, s0
	s_mov_b64 s[28:29], 0x3000
	v_readfirstlane_b32 s0, v0
	v_add_u32_e32 v0, 0x6000, v185
	global_load_lds_dwordx4 v[8:9], off
	v_lshl_add_u64 v[8:9], v[6:7], 0, s[28:29]
	s_mov_b32 m0, s0
	v_readfirstlane_b32 s0, v0
	v_add_u32_e32 v0, 0x7000, v185
	global_load_lds_dwordx4 v[8:9], off
	v_lshl_add_u64 v[8:9], v[2:3], 0, s[94:95]
	s_mov_b32 m0, s0
	s_mov_b64 s[28:29], 0x30b000
	v_readfirstlane_b32 s0, v0
	v_add_u32_e32 v0, 0x8000, v185
	global_load_lds_dwordx4 v[8:9], off
	v_lshl_add_u64 v[2:3], v[2:3], 0, s[28:29]
	s_mov_b32 m0, s0
	v_readfirstlane_b32 s0, v0
	v_add_u32_e32 v0, 0x9000, v185
	global_load_lds_dwordx4 v[2:3], off
	v_lshl_add_u64 v[2:3], v[6:7], 0, s[4:5]
	s_mov_b32 m0, s0
	s_mov_b64 s[28:29], 0x31000
	v_readfirstlane_b32 s0, v0
	v_add_u32_e32 v0, 0xa000, v185
	global_load_lds_dwordx4 v[2:3], off
	v_lshl_add_u64 v[2:3], v[6:7], 0, s[28:29]
	s_mov_b32 m0, s0
	s_mov_b64 s[28:29], 0x32000
	v_readfirstlane_b32 s0, v0
	v_add_u32_e32 v0, 0xb000, v185
	global_load_lds_dwordx4 v[2:3], off
	v_lshl_add_u64 v[2:3], v[6:7], 0, s[28:29]
	s_mov_b32 m0, s0
	s_mov_b64 s[28:29], 0x33000
	v_readfirstlane_b32 s0, v0
	global_load_lds_dwordx4 v[2:3], off
	v_lshl_add_u64 v[2:3], v[6:7], 0, s[28:29]
	s_mov_b32 m0, s0
	v_and_b32_e32 v0, 15, v184
	global_load_lds_dwordx4 v[2:3], off
	v_lshlrev_b32_e32 v2, 2, v184
	v_and_b32_e32 v2, 48, v2
	v_ashrrev_i32_e32 v3, 1, v184
	v_sub_u32_e32 v2, 0, v2
	v_and_b32_e32 v187, 0xffffffc0, v3
	v_bitop3_b32 v2, v184, 48, v2 bitop3:0x48
	v_or_b32_e32 v3, v187, v0
	v_lshl_or_b32 v208, v3, 6, v2
	v_lshlrev_b32_e32 v3, 1, v184
	s_movk_i32 s0, 0x80
	v_and_or_b32 v186, v3, s0, v0
	s_sub_i32 s0, s8, s41
	s_mul_i32 s1, s1, 24
	s_sub_i32 s0, s0, s1
	v_lshl_or_b32 v0, v186, 6, v2
	v_lshl_add_u32 v2, s0, 7, v10
	v_ashrrev_i32_e32 v3, 31, v2
	v_lshlrev_b64 v[2:3], 6, v[2:3]
	v_add_u32_e32 v209, 0x2000, v0
	v_bitop3_b32 v0, v184, 3, v11 bitop3:0x48
	v_lshl_add_u64 v[182:183], v[130:131], 0, v[2:3]
	v_mov_b32_e32 v2, 0
	s_mov_b32 s3, 0
	s_mov_b32 s42, 2
	s_mov_b64 s[30:31], 0x1000
	v_lshlrev_b32_e32 v0, 4, v0
	v_lshl_add_u64 v[180:181], v[130:131], 0, v[4:5]
	s_mov_b32 s43, 0
; #define RAW_BARRIER() do { asm volatile("s_waitcnt lgkmcnt(0)" ::: "memory"); __builtin_amdgcn_s_barrier(); } while (0)
; template <int EPI, int NB>
; DEVI void gemm_tile(const GemmJob& J, int m0, int n0, unsigned char* smem) {
;     ...
;   f32x4 acc[4][NB];
; #pragma unroll
;   for (int i = 0; i < 4; ++i)
; #pragma unroll
;     for (int j = 0; j < NB; ++j) acc[i][j] = (f32x4){0.f, 0.f, 0.f, 0.f};
;     ...
;   int cs = 0, is = S - 1;
; #pragma clang loop unroll(disable)
;   for (int kt = 0; kt < nk; ++kt) {
;     if (nk - 1 - kt >= S - 2) {
;       if constexpr (NB == 8) asm volatile("s_waitcnt vmcnt(6)" ::: "memory");
;       else                   asm volatile("s_waitcnt vmcnt(8)" ::: "memory");
;     } else {
;       asm volatile("s_waitcnt vmcnt(0)" ::: "memory");
;     }
;     RAW_BARRIER();
;     if (kt + S - 1 < nk) GEMM_ISSUE(kt + S - 1, is);
;     is = (is + 1 == S) ? 0 : is + 1;
;     const unsigned cur = lbase + cs * STG;
	v_mov_b32_e32 v3, v2
	v_mov_b32_e32 v4, v2
	v_mov_b32_e32 v5, v2
	v_mov_b32_e32 v6, v2
	v_mov_b32_e32 v7, v2
	v_mov_b32_e32 v8, v2
	v_mov_b32_e32 v9, v2
	v_mov_b32_e32 v10, v2
	v_mov_b32_e32 v11, v2
	v_mov_b32_e32 v12, v2
	v_mov_b32_e32 v13, v2
	v_mov_b32_e32 v14, v2
	v_mov_b32_e32 v15, v2
	v_mov_b32_e32 v16, v2
	v_mov_b32_e32 v17, v2
	v_mov_b32_e32 v18, v2
	v_mov_b32_e32 v19, v2
	v_mov_b32_e32 v20, v2
	v_mov_b32_e32 v21, v2
	v_mov_b32_e32 v22, v2
	v_mov_b32_e32 v23, v2
	v_mov_b32_e32 v24, v2
	v_mov_b32_e32 v25, v2
	v_mov_b32_e32 v26, v2
	v_mov_b32_e32 v27, v2
	v_mov_b32_e32 v28, v2
	v_mov_b32_e32 v29, v2
	v_mov_b32_e32 v30, v2
	v_mov_b32_e32 v31, v2
	v_mov_b32_e32 v32, v2
	v_mov_b32_e32 v33, v2
	v_mov_b32_e32 v34, v2
	v_mov_b32_e32 v35, v2
	v_mov_b32_e32 v36, v2
	v_mov_b32_e32 v37, v2
	v_mov_b32_e32 v38, v2
	v_mov_b32_e32 v39, v2
	v_mov_b32_e32 v40, v2
	v_mov_b32_e32 v41, v2
	v_mov_b32_e32 v42, v2
	v_mov_b32_e32 v43, v2
	v_mov_b32_e32 v44, v2
	v_mov_b32_e32 v45, v2
	v_mov_b32_e32 v46, v2
	v_mov_b32_e32 v47, v2
	v_mov_b32_e32 v48, v2
	v_mov_b32_e32 v49, v2
	v_mov_b32_e32 v50, v2
	v_mov_b32_e32 v51, v2
	v_mov_b32_e32 v52, v2
	v_mov_b32_e32 v53, v2
	v_mov_b32_e32 v54, v2
	v_mov_b32_e32 v55, v2
	v_mov_b32_e32 v56, v2
	v_mov_b32_e32 v57, v2
	v_mov_b32_e32 v58, v2
	v_mov_b32_e32 v59, v2
	v_mov_b32_e32 v60, v2
	v_mov_b32_e32 v61, v2
	v_mov_b32_e32 v62, v2
	v_mov_b32_e32 v63, v2
	v_mov_b32_e32 v64, v2
	v_mov_b32_e32 v65, v2
	v_mov_b32_e32 v66, v2
	v_mov_b32_e32 v67, v2
	v_mov_b32_e32 v68, v2
	v_mov_b32_e32 v69, v2
	v_mov_b32_e32 v70, v2
	v_mov_b32_e32 v71, v2
	v_mov_b32_e32 v72, v2
	v_mov_b32_e32 v73, v2
	v_mov_b32_e32 v74, v2
	v_mov_b32_e32 v75, v2
	v_mov_b32_e32 v76, v2
	v_mov_b32_e32 v77, v2
	v_mov_b32_e32 v78, v2
	v_mov_b32_e32 v79, v2
	v_mov_b32_e32 v80, v2
	v_mov_b32_e32 v81, v2
	v_mov_b32_e32 v82, v2
	v_mov_b32_e32 v83, v2
	v_mov_b32_e32 v84, v2
	v_mov_b32_e32 v85, v2
	v_mov_b32_e32 v86, v2
	v_mov_b32_e32 v87, v2
	v_mov_b32_e32 v88, v2
	v_mov_b32_e32 v89, v2
	v_mov_b32_e32 v90, v2
	v_mov_b32_e32 v91, v2
	v_mov_b32_e32 v92, v2
	v_mov_b32_e32 v93, v2
	v_mov_b32_e32 v94, v2
	v_mov_b32_e32 v95, v2
	v_mov_b32_e32 v96, v2
	v_mov_b32_e32 v97, v2
	v_mov_b32_e32 v98, v2
	v_mov_b32_e32 v99, v2
	v_mov_b32_e32 v100, v2
	v_mov_b32_e32 v101, v2
	v_mov_b32_e32 v102, v2
	v_mov_b32_e32 v103, v2
	v_mov_b32_e32 v104, v2
	v_mov_b32_e32 v105, v2
	v_mov_b32_e32 v106, v2
	v_mov_b32_e32 v107, v2
	v_mov_b32_e32 v108, v2
	v_mov_b32_e32 v109, v2
	v_mov_b32_e32 v110, v2
	v_mov_b32_e32 v111, v2
	v_mov_b32_e32 v112, v2
	v_mov_b32_e32 v113, v2
	v_mov_b32_e32 v114, v2
	v_mov_b32_e32 v115, v2
	v_mov_b32_e32 v116, v2
	v_mov_b32_e32 v117, v2
	v_mov_b32_e32 v118, v2
	v_mov_b32_e32 v119, v2
	v_mov_b32_e32 v120, v2
	v_mov_b32_e32 v121, v2
	v_mov_b32_e32 v122, v2
	v_mov_b32_e32 v123, v2
	v_mov_b32_e32 v124, v2
	v_mov_b32_e32 v125, v2
	v_mov_b32_e32 v126, v2
	v_mov_b32_e32 v127, v2
	v_mov_b32_e32 v128, v2
	v_mov_b32_e32 v129, v2
	s_mul_i32 s0, s42, 0x6000
	v_add_u32_e32 v214, s0, v185
	v_lshl_add_u64 v[210:211], v[182:183], 0, v[0:1]
	v_readfirstlane_b32 s0, v214
	v_lshl_add_u64 v[212:213], v[210:211], 0, s[84:85]
	s_mov_b32 m0, s0
	v_lshl_add_u64 v[210:211], v[210:211], 0, s[12:13]
	s_nop 0
	v_readfirstlane_b32 s100, v212
	v_readfirstlane_b32 s101, v213
	s_nop 1
	v_subrev_u32_e32 v226, s100, v212
	v_add_u32_e32 v212, 0x1000, v214
	v_add_u32_e32 v215, 0x2000, v214
	v_readfirstlane_b32 s0, v212
	s_mov_b32 m0, s0
	s_mov_b64 s[0:1], 0x49a6000
	v_subrev_u32_e32 v227, s100, v210
	v_lshl_add_u64 v[210:211], v[180:181], 0, v[0:1]
	v_lshl_add_u64 v[212:213], v[210:211], 0, s[0:1]
	v_readfirstlane_b32 s0, v215
	s_mov_b32 m0, s0
	s_mov_b64 s[0:1], 0x49a7000
	v_add_u32_e32 v215, 0x3000, v214
	s_nop 0
	v_readfirstlane_b32 vcc_lo, v212
	v_readfirstlane_b32 vcc_hi, v213
	s_nop 1
	v_subrev_u32_e32 v228, vcc_lo, v212
	v_lshl_add_u64 v[212:213], v[210:211], 0, s[0:1]
	v_readfirstlane_b32 s0, v215
	s_mov_b32 m0, s0
	s_mov_b64 s[0:1], 0x49a8000
	v_add_u32_e32 v215, 0x4000, v214
	v_subrev_u32_e32 v229, vcc_lo, v212
	v_lshl_add_u64 v[212:213], v[210:211], 0, s[0:1]
	v_readfirstlane_b32 s0, v215
	s_mov_b32 m0, s0
	s_mov_b64 s[0:1], 0x49a9000
	v_subrev_u32_e32 v230, vcc_lo, v212
	v_add_u32_e32 v212, 0x5000, v214
	v_lshl_add_u64 v[210:211], v[210:211], 0, s[0:1]
	v_readfirstlane_b32 s0, v212
	s_mov_b32 m0, s0
	s_nop 0
	v_subrev_u32_e32 v231, vcc_lo, v210
	v_mov_b32_e32 v182, v226
	v_mov_b32_e32 v183, v227
	v_mov_b32_e32 v180, v228
	v_mov_b32_e32 v181, v229
	v_mov_b32_e32 v253, v230
	v_mov_b32_e32 v254, v231
	v_readfirstlane_b32 s0, v185
	s_branch .LBB0_774

; DEVI int otid() { int t = threadIdx.x; asm volatile("" : "+v"(t)); return t; }
; #define RAW_BARRIER() do { asm volatile("s_waitcnt lgkmcnt(0)" ::: "memory"); __builtin_amdgcn_s_barrier(); } while (0)
; template <int EPI, int NB>
; DEVI void gemm_tile(const GemmJob& J, int m0, int n0, unsigned char* smem) {
;     ...
;   const int tid = otid(), lane = tid & 63, wid = tid >> 6, wm = wid >> 1, wn = wid & 1;
;   const int l16 = lane & 15, g = lane >> 4;
;   f32x4 acc[4][NB];
; #pragma unroll
;   for (int i = 0; i < 4; ++i)
; #pragma unroll
;     for (int j = 0; j < NB; ++j) acc[i][j] = (f32x4){0.f, 0.f, 0.f, 0.f};
;   const int srow = tid >> 2, sch = tid & 3;
;   const int gch = sch ^ ((0 - (tid >> 4)) & 3);
;   const bf16_t* Ag = J.A + (size_t)(m0 + srow) * (J.ablk ? 32 : J.lda) + gch * 8;
;   const bf16_t* Bg = J.Bt + (size_t)(n0 + srow) * 32 + gch * 8;
;   const size_t Astep = (size_t)64 * (J.ablk ? 32 : J.lda), Ak = J.ablk ? (size_t)MROWS * 32 : (size_t)32, Bstep = (size_t)64 * 32, Bk = (size_t)J.NR * 32;
;   const int nk = J.K >> 5;
;   unsigned char* lds_t = smem + tid * 16;
;   const unsigned lbase = (unsigned)(uintptr_t)(__attribute__((address_space(3))) unsigned char*)smem;
;     ...
;   asm volatile("s_waitcnt vmcnt(0)" ::: "memory");
;   RAW_BARRIER();
; #pragma unroll
;   for (int st = 0; st < S - 1; ++st) GEMM_ISSUE(st, st);
;   const int fsl = (g ^ ((0 - (l16 >> 2)) & 3)) << 4;
;   const int aofs = (wm * 64 + l16) * 64 + fsl;
;   const int bofs = A_BYTES + (wn * NB * 16 + l16) * 64 + fsl;
; template <int EPI, int NB>
; DEVI void gemm_run(const GemmJob& J, unsigned char* smem, int rot) {
;     ...
;     for (int t = b; t < ntiles; t += G) {
;       const int mt = t / J.ntn, nt = J.nt0 + (t - mt * J.ntn);
;       gemm_tile<EPI, NB>(J, mt * 128, nt * BN, smem);
.LBB0_1010:
	s_ashr_i32 s0, s9, 31
	s_lshr_b32 s0, s0, 30
	s_add_i32 s0, s9, s0
	s_ashr_i32 s0, s0, 2
	s_lshl_b32 s3, s0, 7
	s_lshl_b32 s0, s0, 10
	s_lshl_b32 s1, s9, 8
	v_mov_b32_e32 v184, v177
	s_sub_i32 s2, s1, s0
	s_nop 0
	s_mov_b64 s[28:29], 0x1000
	v_ashrrev_i32_e32 v10, 2, v184
	v_lshrrev_b32_e32 v0, 4, v184
	v_sub_u32_e32 v11, 0, v0
	v_add_u32_e32 v2, s3, v10
	v_add_u32_e32 v6, s2, v10
	v_xor_b32_e32 v0, v184, v11
	v_ashrrev_i32_e32 v3, 31, v2
	v_ashrrev_i32_e32 v7, 31, v6
	v_lshlrev_b64 v[2:3], 6, v[2:3]
	v_lshlrev_b32_e32 v0, 4, v0
	v_lshlrev_b64 v[6:7], 6, v[6:7]
	v_lshl_add_u64 v[4:5], v[146:147], 0, v[2:3]
	v_and_b32_e32 v0, 48, v0
	v_lshl_add_u64 v[6:7], v[144:145], 0, v[6:7]
	v_lshlrev_b32_e32 v185, 4, v184
	v_lshl_add_u64 v[4:5], v[4:5], 0, v[0:1]
	v_lshl_add_u64 v[6:7], v[6:7], 0, v[0:1]
	v_readfirstlane_b32 s1, v185
	v_add_u32_e32 v0, 0x1000, v185
	s_mov_b32 m0, s1
	v_readfirstlane_b32 s1, v0
	v_add_u32_e32 v0, 0x2000, v185
	s_waitcnt lgkmcnt(0)
	s_barrier
	global_load_lds_dwordx4 v[4:5], off
	v_lshl_add_u64 v[8:9], v[4:5], 0, s[28:29]
	s_mov_b32 m0, s1
	v_readfirstlane_b32 s1, v0
	v_add_u32_e32 v0, 0x3000, v185
	global_load_lds_dwordx4 v[8:9], off
	s_mov_b32 m0, s1
	v_readfirstlane_b32 s1, v0
	v_add_u32_e32 v0, 0x4000, v185
	global_load_lds_dwordx4 v[6:7], off
	v_lshl_add_u64 v[8:9], v[6:7], 0, s[28:29]
	s_mov_b32 m0, s1
	s_mov_b64 s[28:29], 0x2000
	v_readfirstlane_b32 s1, v0
	v_add_u32_e32 v0, 0x5000, v185
	global_load_lds_dwordx4 v[8:9], off
	v_lshl_add_u64 v[8:9], v[6:7], 0, s[28:29]
	s_mov_b32 m0, s1
	s_mov_b64 s[28:29], 0x3000
	v_readfirstlane_b32 s1, v0
	v_add_u32_e32 v0, 0x6000, v185
	global_load_lds_dwordx4 v[8:9], off
	v_lshl_add_u64 v[8:9], v[6:7], 0, s[28:29]
	s_mov_b32 m0, s1
	v_readfirstlane_b32 s1, v0
	v_add_u32_e32 v0, 0x7000, v185
	global_load_lds_dwordx4 v[8:9], off
	v_lshl_add_u64 v[8:9], v[4:5], 0, s[94:95]
	s_mov_b32 m0, s1
	s_mov_b64 s[28:29], 0x30b000
	v_readfirstlane_b32 s1, v0
	v_add_u32_e32 v0, 0x8000, v185
	global_load_lds_dwordx4 v[8:9], off
	v_lshl_add_u64 v[4:5], v[4:5], 0, s[28:29]
	s_mov_b32 m0, s1
	v_readfirstlane_b32 s1, v0
	v_add_u32_e32 v0, 0x9000, v185
	global_load_lds_dwordx4 v[4:5], off
	v_lshl_add_u64 v[4:5], v[6:7], 0, s[22:23]
	s_mov_b32 m0, s1
	s_mov_b64 s[28:29], 0x11000
	v_readfirstlane_b32 s1, v0
	v_add_u32_e32 v0, 0xa000, v185
	global_load_lds_dwordx4 v[4:5], off
	v_lshl_add_u64 v[4:5], v[6:7], 0, s[28:29]
	s_mov_b32 m0, s1
	s_mov_b64 s[28:29], 0x12000
	v_readfirstlane_b32 s1, v0
	v_add_u32_e32 v0, 0xb000, v185
	global_load_lds_dwordx4 v[4:5], off
	v_lshl_add_u64 v[4:5], v[6:7], 0, s[28:29]
	s_mov_b32 m0, s1
	s_mov_b64 s[28:29], 0x13000
	v_readfirstlane_b32 s1, v0
	global_load_lds_dwordx4 v[4:5], off
	v_lshl_add_u64 v[4:5], v[6:7], 0, s[28:29]
	s_mov_b32 m0, s1
	v_lshlrev_b32_e32 v0, 2, v184
	global_load_lds_dwordx4 v[4:5], off
	v_and_b32_e32 v0, 48, v0
	v_ashrrev_i32_e32 v4, 1, v184
	v_and_b32_e32 v186, 15, v184
	v_sub_u32_e32 v0, 0, v0
	v_and_b32_e32 v187, 0xffffffc0, v4
	v_bitop3_b32 v0, v184, 48, v0 bitop3:0x48
	v_or_b32_e32 v4, v187, v186
	v_lshl_or_b32 v209, v4, 6, v0
	v_lshlrev_b32_e32 v4, 1, v184
	v_and_b32_e32 v208, 0x80, v4
	v_or_b32_e32 v4, v208, v186
	v_lshl_or_b32 v0, v4, 6, v0
	v_add_u32_e32 v4, s8, v10
	v_subrev_u32_e32 v4, s0, v4
	v_ashrrev_i32_e32 v5, 31, v4
	v_add_u32_e32 v210, 0x2000, v0
	v_bitop3_b32 v0, v184, 3, v11 bitop3:0x48
	v_lshlrev_b64 v[4:5], 6, v[4:5]
	v_lshl_add_u64 v[182:183], v[130:131], 0, v[2:3]
	v_mov_b32_e32 v2, 0
	s_mov_b32 s42, 2
	s_mov_b32 s20, 0
	s_mov_b64 s[30:31], 0x1000
	v_lshlrev_b32_e32 v0, 4, v0
	v_lshl_add_u64 v[180:181], v[130:131], 0, v[4:5]
	s_mov_b32 s43, 0
	v_mov_b32_e32 v3, v2
	v_mov_b32_e32 v4, v2
	v_mov_b32_e32 v5, v2
	v_mov_b32_e32 v6, v2
	v_mov_b32_e32 v7, v2
	v_mov_b32_e32 v8, v2
	v_mov_b32_e32 v9, v2
	v_mov_b32_e32 v10, v2
	v_mov_b32_e32 v11, v2
	v_mov_b32_e32 v12, v2
	v_mov_b32_e32 v13, v2
	v_mov_b32_e32 v14, v2
	v_mov_b32_e32 v15, v2
	v_mov_b32_e32 v16, v2
	v_mov_b32_e32 v17, v2
	v_mov_b32_e32 v18, v2
	v_mov_b32_e32 v19, v2
	v_mov_b32_e32 v20, v2
	v_mov_b32_e32 v21, v2
	v_mov_b32_e32 v22, v2
	v_mov_b32_e32 v23, v2
; #define RAW_BARRIER() do { asm volatile("s_waitcnt lgkmcnt(0)" ::: "memory"); __builtin_amdgcn_s_barrier(); } while (0)
; template <int EPI, int NB>
; DEVI void gemm_tile(const GemmJob& J, int m0, int n0, unsigned char* smem) {
;     ...
;   f32x4 acc[4][NB];
; #pragma unroll
;   for (int i = 0; i < 4; ++i)
; #pragma unroll
;     for (int j = 0; j < NB; ++j) acc[i][j] = (f32x4){0.f, 0.f, 0.f, 0.f};
;     ...
;   int cs = 0, is = S - 1;
; #pragma clang loop unroll(disable)
;   for (int kt = 0; kt < nk; ++kt) {
;     if (nk - 1 - kt >= S - 2) {
;       if constexpr (NB == 8) asm volatile("s_waitcnt vmcnt(6)" ::: "memory");
;       else                   asm volatile("s_waitcnt vmcnt(8)" ::: "memory");
;     } else {
;       asm volatile("s_waitcnt vmcnt(0)" ::: "memory");
;     }
;     RAW_BARRIER();
;     if (kt + S - 1 < nk) GEMM_ISSUE(kt + S - 1, is);
;     is = (is + 1 == S) ? 0 : is + 1;
;     const unsigned cur = lbase + cs * STG;
	v_mov_b32_e32 v24, v2
	v_mov_b32_e32 v25, v2
	v_mov_b32_e32 v26, v2
	v_mov_b32_e32 v27, v2
	v_mov_b32_e32 v28, v2
	v_mov_b32_e32 v29, v2
	v_mov_b32_e32 v30, v2
	v_mov_b32_e32 v31, v2
	v_mov_b32_e32 v32, v2
	v_mov_b32_e32 v33, v2
	v_mov_b32_e32 v34, v2
	v_mov_b32_e32 v35, v2
	v_mov_b32_e32 v36, v2
	v_mov_b32_e32 v37, v2
	v_mov_b32_e32 v38, v2
	v_mov_b32_e32 v39, v2
	v_mov_b32_e32 v40, v2
	v_mov_b32_e32 v41, v2
	v_mov_b32_e32 v42, v2
	v_mov_b32_e32 v43, v2
	v_mov_b32_e32 v44, v2
	v_mov_b32_e32 v45, v2
	v_mov_b32_e32 v46, v2
	v_mov_b32_e32 v47, v2
	v_mov_b32_e32 v48, v2
	v_mov_b32_e32 v49, v2
	v_mov_b32_e32 v50, v2
	v_mov_b32_e32 v51, v2
	v_mov_b32_e32 v52, v2
	v_mov_b32_e32 v53, v2
	v_mov_b32_e32 v54, v2
	v_mov_b32_e32 v55, v2
	v_mov_b32_e32 v56, v2
	v_mov_b32_e32 v57, v2
	v_mov_b32_e32 v58, v2
	v_mov_b32_e32 v59, v2
	v_mov_b32_e32 v60, v2
	v_mov_b32_e32 v61, v2
	v_mov_b32_e32 v62, v2
	v_mov_b32_e32 v63, v2
	v_mov_b32_e32 v64, v2
	v_mov_b32_e32 v65, v2
	v_mov_b32_e32 v66, v2
	v_mov_b32_e32 v67, v2
	v_mov_b32_e32 v68, v2
	v_mov_b32_e32 v69, v2
	v_mov_b32_e32 v70, v2
	v_mov_b32_e32 v71, v2
	v_mov_b32_e32 v72, v2
	v_mov_b32_e32 v73, v2
	v_mov_b32_e32 v74, v2
	v_mov_b32_e32 v75, v2
	v_mov_b32_e32 v76, v2
	v_mov_b32_e32 v77, v2
	v_mov_b32_e32 v78, v2
	v_mov_b32_e32 v79, v2
	v_mov_b32_e32 v80, v2
	v_mov_b32_e32 v81, v2
	v_mov_b32_e32 v82, v2
	v_mov_b32_e32 v83, v2
	v_mov_b32_e32 v84, v2
	v_mov_b32_e32 v85, v2
	v_mov_b32_e32 v86, v2
	v_mov_b32_e32 v87, v2
	v_mov_b32_e32 v88, v2
	v_mov_b32_e32 v89, v2
	v_mov_b32_e32 v90, v2
	v_mov_b32_e32 v91, v2
	v_mov_b32_e32 v92, v2
	v_mov_b32_e32 v93, v2
	v_mov_b32_e32 v94, v2
	v_mov_b32_e32 v95, v2
	v_mov_b32_e32 v96, v2
	v_mov_b32_e32 v97, v2
	v_mov_b32_e32 v98, v2
	v_mov_b32_e32 v99, v2
	v_mov_b32_e32 v100, v2
	v_mov_b32_e32 v101, v2
	v_mov_b32_e32 v102, v2
	v_mov_b32_e32 v103, v2
	v_mov_b32_e32 v104, v2
	v_mov_b32_e32 v105, v2
	v_mov_b32_e32 v106, v2
	v_mov_b32_e32 v107, v2
	v_mov_b32_e32 v108, v2
	v_mov_b32_e32 v109, v2
	v_mov_b32_e32 v110, v2
	v_mov_b32_e32 v111, v2
	v_mov_b32_e32 v112, v2
	v_mov_b32_e32 v113, v2
	v_mov_b32_e32 v114, v2
	v_mov_b32_e32 v115, v2
	v_mov_b32_e32 v116, v2
	v_mov_b32_e32 v117, v2
	v_mov_b32_e32 v118, v2
	v_mov_b32_e32 v119, v2
	v_mov_b32_e32 v120, v2
	v_mov_b32_e32 v121, v2
	v_mov_b32_e32 v122, v2
	v_mov_b32_e32 v123, v2
	v_mov_b32_e32 v124, v2
	v_mov_b32_e32 v125, v2
	v_mov_b32_e32 v126, v2
	v_mov_b32_e32 v127, v2
	v_mov_b32_e32 v128, v2
	v_mov_b32_e32 v129, v2
	s_mul_i32 s0, s42, 0x6000
	v_add_u32_e32 v211, s0, v185
	v_lshl_add_u64 v[212:213], v[182:183], 0, v[0:1]
	v_readfirstlane_b32 s0, v211
	v_lshl_add_u64 v[214:215], v[212:213], 0, s[84:85]
	s_mov_b32 m0, s0
	v_lshl_add_u64 v[212:213], v[212:213], 0, s[12:13]
	s_nop 0
	v_readfirstlane_b32 s100, v214
	v_readfirstlane_b32 s101, v215
	s_nop 1
	v_subrev_u32_e32 v228, s100, v214
	v_add_u32_e32 v214, 0x1000, v211
	v_add_u32_e32 v216, 0x2000, v211
	v_readfirstlane_b32 s0, v214
	s_mov_b32 m0, s0
	s_mov_b64 s[0:1], 0x4f66000
	v_subrev_u32_e32 v229, s100, v212
	v_lshl_add_u64 v[212:213], v[180:181], 0, v[0:1]
	v_lshl_add_u64 v[214:215], v[212:213], 0, s[0:1]
	v_readfirstlane_b32 s0, v216
	s_mov_b32 m0, s0
	s_mov_b64 s[0:1], 0x4f67000
	v_add_u32_e32 v216, 0x3000, v211
	s_nop 0
	v_readfirstlane_b32 vcc_lo, v214
	v_readfirstlane_b32 vcc_hi, v215
	s_nop 1
	v_subrev_u32_e32 v230, vcc_lo, v214
	v_lshl_add_u64 v[214:215], v[212:213], 0, s[0:1]
	v_readfirstlane_b32 s0, v216
	s_mov_b32 m0, s0
	s_mov_b64 s[0:1], 0x4f68000
	v_add_u32_e32 v216, 0x4000, v211
	v_subrev_u32_e32 v231, vcc_lo, v214
	v_lshl_add_u64 v[214:215], v[212:213], 0, s[0:1]
	v_readfirstlane_b32 s0, v216
	s_mov_b32 m0, s0
	s_mov_b64 s[0:1], 0x4f69000
	v_add_u32_e32 v211, 0x5000, v211
	v_lshl_add_u64 v[212:213], v[212:213], 0, s[0:1]
	v_readfirstlane_b32 s0, v211
	v_subrev_u32_e32 v232, vcc_lo, v214
	s_mov_b32 m0, s0
	s_nop 0
	v_subrev_u32_e32 v233, vcc_lo, v212
	v_mov_b32_e32 v182, v228
	v_mov_b32_e32 v183, v229
	v_mov_b32_e32 v180, v230
	v_mov_b32_e32 v181, v231
	v_mov_b32_e32 v253, v232
	v_mov_b32_e32 v254, v233
	v_readfirstlane_b32 s0, v185
	s_branch .LBB0_1012

; DEVI int otid() { int t = threadIdx.x; asm volatile("" : "+v"(t)); return t; }
; #define RAW_BARRIER() do { asm volatile("s_waitcnt lgkmcnt(0)" ::: "memory"); __builtin_amdgcn_s_barrier(); } while (0)
; template <int EPI, int NB>
; DEVI void gemm_tile(const GemmJob& J, int m0, int n0, unsigned char* smem) {
;     ...
;   const int tid = otid(), lane = tid & 63, wid = tid >> 6, wm = wid >> 1, wn = wid & 1;
;   const int l16 = lane & 15, g = lane >> 4;
;   f32x4 acc[4][NB];
; #pragma unroll
;   for (int i = 0; i < 4; ++i)
; #pragma unroll
;     for (int j = 0; j < NB; ++j) acc[i][j] = (f32x4){0.f, 0.f, 0.f, 0.f};
;   const int srow = tid >> 2, sch = tid & 3;
;   const int gch = sch ^ ((0 - (tid >> 4)) & 3);
;   const bf16_t* Ag = J.A + (size_t)(m0 + srow) * (J.ablk ? 32 : J.lda) + gch * 8;
;   const bf16_t* Bg = J.Bt + (size_t)(n0 + srow) * 32 + gch * 8;
;   const size_t Astep = (size_t)64 * (J.ablk ? 32 : J.lda), Ak = J.ablk ? (size_t)MROWS * 32 : (size_t)32, Bstep = (size_t)64 * 32, Bk = (size_t)J.NR * 32;
;   const int nk = J.K >> 5;
;   unsigned char* lds_t = smem + tid * 16;
;   const unsigned lbase = (unsigned)(uintptr_t)(__attribute__((address_space(3))) unsigned char*)smem;
;     ...
;   asm volatile("s_waitcnt vmcnt(0)" ::: "memory");
;   RAW_BARRIER();
; #pragma unroll
;   for (int st = 0; st < S - 1; ++st) GEMM_ISSUE(st, st);
;   const int fsl = (g ^ ((0 - (l16 >> 2)) & 3)) << 4;
;   const int aofs = (wm * 64 + l16) * 64 + fsl;
;   const int bofs = A_BYTES + (wn * NB * 16 + l16) * 64 + fsl;
; template <int EPI, int NB>
; DEVI void gemm_run(const GemmJob& J, unsigned char* smem, int rot) {
;     ...
;     for (int q0 = lb; q0 < ntot; q0 += nlb) {
;       const int q = J.rev ? ntot - 1 - q0 : q0;
;       int grp = q / gsz; const int qq = q - grp * gsz;
;       const int mg = min(8, mcnt - grp * 8);
;       const int nt = qq / mg, mi = qq - nt * mg;
;       gemm_tile<EPI, NB>(J, (mlo + grp * 8 + mi) * 128, (J.nt0 + nt) * BN, smem);
.LBB0_1088:
	s_ashr_i32 s0, s9, 31
	s_lshr_b32 s0, s0, 27
	s_add_i32 s0, s9, s0
	s_ashr_i32 s1, s0, 5
	s_lshl_b32 s3, s1, 3
	v_readlane_b32 s2, v251, 48
	s_sub_i32 s2, s2, s3
	s_min_i32 s20, s2, 8
	s_abs_i32 s40, s20
	v_cvt_f32_u32_e32 v0, s40
	s_sub_i32 s43, 0, s40
	s_andn2_b32 s0, s0, 31
	s_sub_i32 s0, s9, s0
	v_rcp_iflag_f32_e32 v0, v0
	s_abs_i32 s41, s0
	s_xor_b32 s42, s0, s20
	s_ashr_i32 s42, s42, 31
	v_mul_f32_e32 v0, 0x4f7ffffe, v0
	v_cvt_u32_f32_e32 v0, v0
	v_mov_b32_e32 v184, v177
	s_nop 0
	v_readfirstlane_b32 s44, v0
	s_mul_i32 s43, s43, s44
	s_mul_hi_u32 s43, s44, s43
	s_add_i32 s44, s44, s43
	s_mul_hi_u32 s43, s41, s44
	s_mul_i32 s44, s43, s40
	s_sub_i32 s41, s41, s44
	s_add_i32 s45, s43, 1
	s_sub_i32 s44, s41, s40
	s_cmp_ge_u32 s41, s40
	s_cselect_b32 s43, s45, s43
	s_cselect_b32 s41, s44, s41
	s_add_i32 s44, s43, 1
	s_cmp_ge_u32 s41, s40
	s_cselect_b32 s40, s44, s43
	s_xor_b32 s40, s40, s42
	s_sub_i32 s40, s40, s42
	s_mul_i32 s41, s20, s40
	v_readlane_b32 s20, v250, 37
	s_add_i32 s3, s3, s20
	s_add_i32 s3, s3, s0
	s_sub_i32 s0, s3, s41
	s_lshl_b32 s20, s0, 7
	s_lshl_b32 s3, s40, 8
	v_ashrrev_i32_e32 v10, 2, v184
	v_lshrrev_b32_e32 v0, 4, v184
	v_sub_u32_e32 v11, 0, v0
	v_add_u32_e32 v2, s20, v10
	v_add_u32_e32 v4, s3, v10
	v_xor_b32_e32 v0, v184, v11
	v_ashrrev_i32_e32 v3, 31, v2
	v_ashrrev_i32_e32 v5, 31, v4
	v_lshlrev_b64 v[2:3], 6, v[2:3]
	v_lshlrev_b32_e32 v0, 4, v0
	v_lshlrev_b64 v[4:5], 6, v[4:5]
	v_lshl_add_u64 v[2:3], v[146:147], 0, v[2:3]
	v_and_b32_e32 v0, 48, v0
	v_lshl_add_u64 v[6:7], v[144:145], 0, v[4:5]
	v_lshlrev_b32_e32 v185, 4, v184
	v_lshl_add_u64 v[2:3], v[2:3], 0, v[0:1]
	v_lshl_add_u64 v[6:7], v[6:7], 0, v[0:1]
	v_readfirstlane_b32 s0, v185
	v_add_u32_e32 v0, 0x1000, v185
	s_mov_b32 m0, s0
	s_mov_b64 s[28:29], 0x1000
	v_readfirstlane_b32 s0, v0
	v_add_u32_e32 v0, 0x2000, v185
	s_waitcnt lgkmcnt(0)
	s_barrier
	global_load_lds_dwordx4 v[2:3], off
	v_lshl_add_u64 v[8:9], v[2:3], 0, s[28:29]
	s_mov_b32 m0, s0
	v_readfirstlane_b32 s0, v0
	v_add_u32_e32 v0, 0x3000, v185
	global_load_lds_dwordx4 v[8:9], off
	s_mov_b32 m0, s0
	v_readfirstlane_b32 s0, v0
	v_add_u32_e32 v0, 0x4000, v185
	global_load_lds_dwordx4 v[6:7], off
	v_lshl_add_u64 v[8:9], v[6:7], 0, s[28:29]
	s_mov_b32 m0, s0
	s_mov_b64 s[28:29], 0x2000
	v_readfirstlane_b32 s0, v0
	v_add_u32_e32 v0, 0x5000, v185
	global_load_lds_dwordx4 v[8:9], off
	v_lshl_add_u64 v[8:9], v[6:7], 0, s[28:29]
	s_mov_b32 m0, s0
	s_mov_b64 s[28:29], 0x3000
	v_readfirstlane_b32 s0, v0
	v_add_u32_e32 v0, 0x6000, v185
	global_load_lds_dwordx4 v[8:9], off
	v_lshl_add_u64 v[8:9], v[6:7], 0, s[28:29]
	s_mov_b32 m0, s0
	v_readfirstlane_b32 s0, v0
	v_add_u32_e32 v0, 0x7000, v185
	global_load_lds_dwordx4 v[8:9], off
	v_lshl_add_u64 v[8:9], v[2:3], 0, s[94:95]
	s_mov_b32 m0, s0
	s_mov_b64 s[28:29], 0x30b000
	v_readfirstlane_b32 s0, v0
	v_add_u32_e32 v0, 0x8000, v185
	global_load_lds_dwordx4 v[8:9], off
	v_lshl_add_u64 v[2:3], v[2:3], 0, s[28:29]
	s_mov_b32 m0, s0
	v_readfirstlane_b32 s0, v0
	v_add_u32_e32 v0, 0x9000, v185
	global_load_lds_dwordx4 v[2:3], off
	v_lshl_add_u64 v[2:3], v[6:7], 0, s[22:23]
	s_mov_b32 m0, s0
	s_mov_b64 s[28:29], 0x11000
	v_readfirstlane_b32 s0, v0
	v_add_u32_e32 v0, 0xa000, v185
	global_load_lds_dwordx4 v[2:3], off
	v_lshl_add_u64 v[2:3], v[6:7], 0, s[28:29]
	s_mov_b32 m0, s0
	s_mov_b64 s[28:29], 0x12000
	v_readfirstlane_b32 s0, v0
	v_add_u32_e32 v0, 0xb000, v185
	global_load_lds_dwordx4 v[2:3], off
	v_lshl_add_u64 v[2:3], v[6:7], 0, s[28:29]
	s_mov_b32 m0, s0
	s_mov_b64 s[28:29], 0x13000
	v_readfirstlane_b32 s0, v0
	global_load_lds_dwordx4 v[2:3], off
	v_lshl_add_u64 v[2:3], v[6:7], 0, s[28:29]
	s_mov_b32 m0, s0
	v_lshlrev_b32_e32 v0, 2, v184
	global_load_lds_dwordx4 v[2:3], off
	v_and_b32_e32 v0, 48, v0
	v_ashrrev_i32_e32 v2, 1, v184
	v_and_b32_e32 v186, 15, v184
	v_sub_u32_e32 v0, 0, v0
	v_and_b32_e32 v187, 0xffffffc0, v2
	v_bitop3_b32 v0, v184, 48, v0 bitop3:0x48
	v_or_b32_e32 v2, v187, v186
	v_lshl_or_b32 v209, v2, 6, v0
	v_lshlrev_b32_e32 v2, 1, v184
	v_and_b32_e32 v208, 0x80, v2
	s_sub_i32 s0, s8, s41
	s_mul_i32 s1, s1, 24
	v_or_b32_e32 v2, v208, v186
	s_sub_i32 s0, s0, s1
	v_lshl_or_b32 v0, v2, 6, v0
	v_lshl_add_u32 v2, s0, 7, v10
	v_ashrrev_i32_e32 v3, 31, v2
	v_lshlrev_b64 v[2:3], 6, v[2:3]
	v_add_u32_e32 v210, 0x2000, v0
	v_bitop3_b32 v0, v184, 3, v11 bitop3:0x48
	v_lshl_add_u64 v[182:183], v[130:131], 0, v[2:3]
	v_mov_b32_e32 v2, 0
	s_mov_b32 s2, 0
	s_mov_b32 s42, 2
	s_mov_b64 s[30:31], 0x1000
	v_lshlrev_b32_e32 v0, 4, v0
	v_lshl_add_u64 v[180:181], v[130:131], 0, v[4:5]
	s_mov_b32 s43, 0
; #define RAW_BARRIER() do { asm volatile("s_waitcnt lgkmcnt(0)" ::: "memory"); __builtin_amdgcn_s_barrier(); } while (0)
; template <int EPI, int NB>
; DEVI void gemm_tile(const GemmJob& J, int m0, int n0, unsigned char* smem) {
;     ...
;   f32x4 acc[4][NB];
; #pragma unroll
;   for (int i = 0; i < 4; ++i)
; #pragma unroll
;     for (int j = 0; j < NB; ++j) acc[i][j] = (f32x4){0.f, 0.f, 0.f, 0.f};
;     ...
;   int cs = 0, is = S - 1;
; #pragma clang loop unroll(disable)
;   for (int kt = 0; kt < nk; ++kt) {
;     if (nk - 1 - kt >= S - 2) {
;       if constexpr (NB == 8) asm volatile("s_waitcnt vmcnt(6)" ::: "memory");
;       else                   asm volatile("s_waitcnt vmcnt(8)" ::: "memory");
;     } else {
;       asm volatile("s_waitcnt vmcnt(0)" ::: "memory");
;     }
;     RAW_BARRIER();
;     if (kt + S - 1 < nk) GEMM_ISSUE(kt + S - 1, is);
;     is = (is + 1 == S) ? 0 : is + 1;
;     const unsigned cur = lbase + cs * STG;
	v_mov_b32_e32 v3, v2
	v_mov_b32_e32 v4, v2
	v_mov_b32_e32 v5, v2
	v_mov_b32_e32 v6, v2
	v_mov_b32_e32 v7, v2
	v_mov_b32_e32 v8, v2
	v_mov_b32_e32 v9, v2
	v_mov_b32_e32 v10, v2
	v_mov_b32_e32 v11, v2
	v_mov_b32_e32 v12, v2
	v_mov_b32_e32 v13, v2
	v_mov_b32_e32 v14, v2
	v_mov_b32_e32 v15, v2
	v_mov_b32_e32 v16, v2
	v_mov_b32_e32 v17, v2
	v_mov_b32_e32 v18, v2
	v_mov_b32_e32 v19, v2
	v_mov_b32_e32 v20, v2
	v_mov_b32_e32 v21, v2
	v_mov_b32_e32 v22, v2
	v_mov_b32_e32 v23, v2
	v_mov_b32_e32 v24, v2
	v_mov_b32_e32 v25, v2
	v_mov_b32_e32 v26, v2
	v_mov_b32_e32 v27, v2
	v_mov_b32_e32 v28, v2
	v_mov_b32_e32 v29, v2
	v_mov_b32_e32 v30, v2
	v_mov_b32_e32 v31, v2
	v_mov_b32_e32 v32, v2
	v_mov_b32_e32 v33, v2
	v_mov_b32_e32 v34, v2
	v_mov_b32_e32 v35, v2
	v_mov_b32_e32 v36, v2
	v_mov_b32_e32 v37, v2
	v_mov_b32_e32 v38, v2
	v_mov_b32_e32 v39, v2
	v_mov_b32_e32 v40, v2
	v_mov_b32_e32 v41, v2
	v_mov_b32_e32 v42, v2
	v_mov_b32_e32 v43, v2
	v_mov_b32_e32 v44, v2
	v_mov_b32_e32 v45, v2
	v_mov_b32_e32 v46, v2
	v_mov_b32_e32 v47, v2
	v_mov_b32_e32 v48, v2
	v_mov_b32_e32 v49, v2
	v_mov_b32_e32 v50, v2
	v_mov_b32_e32 v51, v2
	v_mov_b32_e32 v52, v2
	v_mov_b32_e32 v53, v2
	v_mov_b32_e32 v54, v2
	v_mov_b32_e32 v55, v2
	v_mov_b32_e32 v56, v2
	v_mov_b32_e32 v57, v2
	v_mov_b32_e32 v58, v2
	v_mov_b32_e32 v59, v2
	v_mov_b32_e32 v60, v2
	v_mov_b32_e32 v61, v2
	v_mov_b32_e32 v62, v2
	v_mov_b32_e32 v63, v2
	v_mov_b32_e32 v64, v2
	v_mov_b32_e32 v65, v2
	v_mov_b32_e32 v66, v2
	v_mov_b32_e32 v67, v2
	v_mov_b32_e32 v68, v2
	v_mov_b32_e32 v69, v2
	v_mov_b32_e32 v70, v2
	v_mov_b32_e32 v71, v2
	v_mov_b32_e32 v72, v2
	v_mov_b32_e32 v73, v2
	v_mov_b32_e32 v74, v2
	v_mov_b32_e32 v75, v2
	v_mov_b32_e32 v76, v2
	v_mov_b32_e32 v77, v2
	v_mov_b32_e32 v78, v2
	v_mov_b32_e32 v79, v2
	v_mov_b32_e32 v80, v2
	v_mov_b32_e32 v81, v2
	v_mov_b32_e32 v82, v2
	v_mov_b32_e32 v83, v2
	v_mov_b32_e32 v84, v2
	v_mov_b32_e32 v85, v2
	v_mov_b32_e32 v86, v2
	v_mov_b32_e32 v87, v2
	v_mov_b32_e32 v88, v2
	v_mov_b32_e32 v89, v2
	v_mov_b32_e32 v90, v2
	v_mov_b32_e32 v91, v2
	v_mov_b32_e32 v92, v2
	v_mov_b32_e32 v93, v2
	v_mov_b32_e32 v94, v2
	v_mov_b32_e32 v95, v2
	v_mov_b32_e32 v96, v2
	v_mov_b32_e32 v97, v2
	v_mov_b32_e32 v98, v2
	v_mov_b32_e32 v99, v2
	v_mov_b32_e32 v100, v2
	v_mov_b32_e32 v101, v2
	v_mov_b32_e32 v102, v2
	v_mov_b32_e32 v103, v2
	v_mov_b32_e32 v104, v2
	v_mov_b32_e32 v105, v2
	v_mov_b32_e32 v106, v2
	v_mov_b32_e32 v107, v2
	v_mov_b32_e32 v108, v2
	v_mov_b32_e32 v109, v2
	v_mov_b32_e32 v110, v2
	v_mov_b32_e32 v111, v2
	v_mov_b32_e32 v112, v2
	v_mov_b32_e32 v113, v2
	v_mov_b32_e32 v114, v2
	v_mov_b32_e32 v115, v2
	v_mov_b32_e32 v116, v2
	v_mov_b32_e32 v117, v2
	v_mov_b32_e32 v118, v2
	v_mov_b32_e32 v119, v2
	v_mov_b32_e32 v120, v2
	v_mov_b32_e32 v121, v2
	v_mov_b32_e32 v122, v2
	v_mov_b32_e32 v123, v2
	v_mov_b32_e32 v124, v2
	v_mov_b32_e32 v125, v2
	v_mov_b32_e32 v126, v2
	v_mov_b32_e32 v127, v2
	v_mov_b32_e32 v128, v2
	v_mov_b32_e32 v129, v2
	s_mul_i32 s0, s42, 0x6000
	v_add_u32_e32 v211, s0, v185
	v_lshl_add_u64 v[212:213], v[182:183], 0, v[0:1]
	v_readfirstlane_b32 s0, v211
	v_lshl_add_u64 v[214:215], v[212:213], 0, s[84:85]
	s_mov_b32 m0, s0
	v_lshl_add_u64 v[212:213], v[212:213], 0, s[12:13]
	s_nop 0
	v_readfirstlane_b32 s100, v214
	v_readfirstlane_b32 s101, v215
	s_nop 1
	v_subrev_u32_e32 v228, s100, v214
	v_add_u32_e32 v214, 0x1000, v211
	v_add_u32_e32 v216, 0x2000, v211
	v_readfirstlane_b32 s0, v214
	s_mov_b32 m0, s0
	s_mov_b64 s[0:1], 0x4f66000
	v_subrev_u32_e32 v229, s100, v212
	v_lshl_add_u64 v[212:213], v[180:181], 0, v[0:1]
	v_lshl_add_u64 v[214:215], v[212:213], 0, s[0:1]
	v_readfirstlane_b32 s0, v216
	s_mov_b32 m0, s0
	s_mov_b64 s[0:1], 0x4f67000
	v_add_u32_e32 v216, 0x3000, v211
	s_nop 0
	v_readfirstlane_b32 vcc_lo, v214
	v_readfirstlane_b32 vcc_hi, v215
	s_nop 1
	v_subrev_u32_e32 v230, vcc_lo, v214
	v_lshl_add_u64 v[214:215], v[212:213], 0, s[0:1]
	v_readfirstlane_b32 s0, v216
	s_mov_b32 m0, s0
	s_mov_b64 s[0:1], 0x4f68000
	v_add_u32_e32 v216, 0x4000, v211
	v_subrev_u32_e32 v231, vcc_lo, v214
	v_lshl_add_u64 v[214:215], v[212:213], 0, s[0:1]
	v_readfirstlane_b32 s0, v216
	s_mov_b32 m0, s0
	s_mov_b64 s[0:1], 0x4f69000
	v_add_u32_e32 v211, 0x5000, v211
	v_lshl_add_u64 v[212:213], v[212:213], 0, s[0:1]
	v_readfirstlane_b32 s0, v211
	v_subrev_u32_e32 v232, vcc_lo, v214
	s_mov_b32 m0, s0
	s_nop 0
	v_subrev_u32_e32 v233, vcc_lo, v212
	v_mov_b32_e32 v182, v228
	v_mov_b32_e32 v183, v229
	v_mov_b32_e32 v180, v230
	v_mov_b32_e32 v181, v231
	v_mov_b32_e32 v253, v232
	v_mov_b32_e32 v254, v233
	v_readfirstlane_b32 s0, v185
	s_branch .LBB0_1090

; DEVI int otid() { int t = threadIdx.x; asm volatile("" : "+v"(t)); return t; }
; #define RAW_BARRIER() do { asm volatile("s_waitcnt lgkmcnt(0)" ::: "memory"); __builtin_amdgcn_s_barrier(); } while (0)
; template <int EPI, int NB>
; DEVI void gemm_tile(const GemmJob& J, int m0, int n0, unsigned char* smem) {
;     ...
;   const int tid = otid(), lane = tid & 63, wid = tid >> 6, wm = wid >> 1, wn = wid & 1;
;   const int l16 = lane & 15, g = lane >> 4;
;   f32x4 acc[4][NB];
; #pragma unroll
;   for (int i = 0; i < 4; ++i)
; #pragma unroll
;     for (int j = 0; j < NB; ++j) acc[i][j] = (f32x4){0.f, 0.f, 0.f, 0.f};
;   const int srow = tid >> 2, sch = tid & 3;
;   const int gch = sch ^ ((0 - (tid >> 4)) & 3);
;   const bf16_t* Ag = J.A + (size_t)(m0 + srow) * (J.ablk ? 32 : J.lda) + gch * 8;
;   const bf16_t* Bg = J.Bt + (size_t)(n0 + srow) * 32 + gch * 8;
;   const size_t Astep = (size_t)64 * (J.ablk ? 32 : J.lda), Ak = J.ablk ? (size_t)MROWS * 32 : (size_t)32, Bstep = (size_t)64 * 32, Bk = (size_t)J.NR * 32;
;   const int nk = J.K >> 5;
;   unsigned char* lds_t = smem + tid * 16;
;   const unsigned lbase = (unsigned)(uintptr_t)(__attribute__((address_space(3))) unsigned char*)smem;
;     ...
;   asm volatile("s_waitcnt vmcnt(0)" ::: "memory");
;   RAW_BARRIER();
; #pragma unroll
;   for (int st = 0; st < S - 1; ++st) GEMM_ISSUE(st, st);
;   const int fsl = (g ^ ((0 - (l16 >> 2)) & 3)) << 4;
;   const int aofs = (wm * 64 + l16) * 64 + fsl;
;   const int bofs = A_BYTES + (wn * NB * 16 + l16) * 64 + fsl;
; template <int EPI, int NB>
; DEVI void gemm_run(const GemmJob& J, unsigned char* smem, int rot) {
;     ...
;     for (int t = b; t < ntiles; t += G) {
;       const int mt = t / J.ntn, nt = J.nt0 + (t - mt * J.ntn);
;       gemm_tile<EPI, NB>(J, mt * 128, nt * BN, smem);
.LBB0_1215:
	s_mul_hi_i32 s0, s9, 0x66666667
	s_lshr_b32 s1, s0, 31
	s_ashr_i32 s0, s0, 1
	s_add_i32 s0, s0, s1
	s_mul_i32 s1, s0, -5
	s_add_i32 s1, s1, s9
	v_mov_b32_e32 v184, v177
	s_lshl_b32 s3, s0, 7
	s_lshl_b32 s2, s1, 8
	s_nop 0
	s_mov_b64 s[28:29], 0x1000
	v_ashrrev_i32_e32 v10, 2, v184
	v_lshrrev_b32_e32 v0, 4, v184
	v_sub_u32_e32 v11, 0, v0
	v_add_u32_e32 v2, s3, v10
	v_add_u32_e32 v6, s2, v10
	v_xor_b32_e32 v0, v184, v11
	v_ashrrev_i32_e32 v3, 31, v2
	v_ashrrev_i32_e32 v7, 31, v6
	v_lshlrev_b64 v[2:3], 6, v[2:3]
	v_lshlrev_b32_e32 v0, 4, v0
	v_lshlrev_b64 v[6:7], 6, v[6:7]
	v_lshl_add_u64 v[4:5], v[146:147], 0, v[2:3]
	v_and_b32_e32 v0, 48, v0
	v_lshl_add_u64 v[6:7], v[134:135], 0, v[6:7]
	v_lshlrev_b32_e32 v185, 4, v184
	v_lshl_add_u64 v[4:5], v[4:5], 0, v[0:1]
	v_lshl_add_u64 v[6:7], v[6:7], 0, v[0:1]
	v_readfirstlane_b32 s1, v185
	v_add_u32_e32 v0, 0x1000, v185
	s_mov_b32 m0, s1
	v_readfirstlane_b32 s1, v0
	v_add_u32_e32 v0, 0x2000, v185
	s_waitcnt lgkmcnt(0)
	s_barrier
	global_load_lds_dwordx4 v[4:5], off
	v_lshl_add_u64 v[8:9], v[4:5], 0, s[28:29]
	s_mov_b32 m0, s1
	v_readfirstlane_b32 s1, v0
	v_add_u32_e32 v0, 0x3000, v185
	global_load_lds_dwordx4 v[8:9], off
	s_mov_b32 m0, s1
	v_readfirstlane_b32 s1, v0
	v_add_u32_e32 v0, 0x4000, v185
	global_load_lds_dwordx4 v[6:7], off
	v_lshl_add_u64 v[8:9], v[6:7], 0, s[28:29]
	s_mov_b32 m0, s1
	s_mov_b64 s[28:29], 0x2000
	v_readfirstlane_b32 s1, v0
	v_add_u32_e32 v0, 0x5000, v185
	global_load_lds_dwordx4 v[8:9], off
	v_lshl_add_u64 v[8:9], v[6:7], 0, s[28:29]
	s_mov_b32 m0, s1
	s_mov_b64 s[28:29], 0x3000
	v_readfirstlane_b32 s1, v0
	v_add_u32_e32 v0, 0x6000, v185
	global_load_lds_dwordx4 v[8:9], off
	v_lshl_add_u64 v[8:9], v[6:7], 0, s[28:29]
	s_mov_b32 m0, s1
	v_readfirstlane_b32 s1, v0
	v_add_u32_e32 v0, 0x7000, v185
	global_load_lds_dwordx4 v[8:9], off
	v_lshl_add_u64 v[8:9], v[4:5], 0, s[94:95]
	s_mov_b32 m0, s1
	s_mov_b64 s[28:29], 0x30b000
	v_readfirstlane_b32 s1, v0
	v_add_u32_e32 v0, 0x8000, v185
	global_load_lds_dwordx4 v[8:9], off
	v_lshl_add_u64 v[4:5], v[4:5], 0, s[28:29]
	s_mov_b32 m0, s1
	v_readfirstlane_b32 s1, v0
	v_add_u32_e32 v0, 0x9000, v185
	global_load_lds_dwordx4 v[4:5], off
	v_lshl_add_u64 v[4:5], v[6:7], 0, s[38:39]
	s_mov_b32 m0, s1
	s_mov_b64 s[28:29], 0x19000
	v_readfirstlane_b32 s1, v0
	v_add_u32_e32 v0, 0xa000, v185
	global_load_lds_dwordx4 v[4:5], off
	v_lshl_add_u64 v[4:5], v[6:7], 0, s[28:29]
	s_mov_b32 m0, s1
	s_mov_b64 s[28:29], 0x1a000
	v_readfirstlane_b32 s1, v0
	v_add_u32_e32 v0, 0xb000, v185
	global_load_lds_dwordx4 v[4:5], off
	v_lshl_add_u64 v[4:5], v[6:7], 0, s[28:29]
	s_mov_b32 m0, s1
	s_mov_b64 s[28:29], 0x1b000
	v_readfirstlane_b32 s1, v0
	global_load_lds_dwordx4 v[4:5], off
	v_lshl_add_u64 v[4:5], v[6:7], 0, s[28:29]
	s_mov_b32 m0, s1
	v_lshlrev_b32_e32 v0, 2, v184
	global_load_lds_dwordx4 v[4:5], off
	v_and_b32_e32 v0, 48, v0
	v_ashrrev_i32_e32 v4, 1, v184
	v_and_b32_e32 v186, 15, v184
	v_sub_u32_e32 v0, 0, v0
	v_and_b32_e32 v187, 0xffffffc0, v4
	v_bitop3_b32 v0, v184, 48, v0 bitop3:0x48
	v_or_b32_e32 v4, v187, v186
	v_lshl_or_b32 v209, v4, 6, v0
	v_lshlrev_b32_e32 v4, 1, v184
	v_and_b32_e32 v208, 0x80, v4
	v_or_b32_e32 v4, v208, v186
	v_lshl_or_b32 v0, v4, 6, v0
	v_add_u32_e32 v4, s8, v10
	s_mulk_i32 s0, 0x500
	v_subrev_u32_e32 v4, s0, v4
	v_ashrrev_i32_e32 v5, 31, v4
	v_add_u32_e32 v210, 0x2000, v0
	v_bitop3_b32 v0, v184, 3, v11 bitop3:0x48
	v_lshlrev_b64 v[4:5], 6, v[4:5]
	v_lshl_add_u64 v[182:183], v[130:131], 0, v[2:3]
	v_mov_b32_e32 v2, 0
	s_mov_b32 s42, 2
	s_mov_b32 s20, 0
	s_mov_b64 s[30:31], 0x1000
	v_lshlrev_b32_e32 v0, 4, v0
	v_lshl_add_u64 v[180:181], v[130:131], 0, v[4:5]
	s_mov_b32 s43, 0
	v_mov_b32_e32 v3, v2
	v_mov_b32_e32 v4, v2
	v_mov_b32_e32 v5, v2
	v_mov_b32_e32 v6, v2
	v_mov_b32_e32 v7, v2
	v_mov_b32_e32 v8, v2
	v_mov_b32_e32 v9, v2
	v_mov_b32_e32 v10, v2
	v_mov_b32_e32 v11, v2
	v_mov_b32_e32 v12, v2
	v_mov_b32_e32 v13, v2
	v_mov_b32_e32 v14, v2
	v_mov_b32_e32 v15, v2
	v_mov_b32_e32 v16, v2
	v_mov_b32_e32 v17, v2
	v_mov_b32_e32 v18, v2
	v_mov_b32_e32 v19, v2
	v_mov_b32_e32 v20, v2
	v_mov_b32_e32 v21, v2
	v_mov_b32_e32 v22, v2
; #define RAW_BARRIER() do { asm volatile("s_waitcnt lgkmcnt(0)" ::: "memory"); __builtin_amdgcn_s_barrier(); } while (0)
; template <int EPI, int NB>
; DEVI void gemm_tile(const GemmJob& J, int m0, int n0, unsigned char* smem) {
;     ...
;   f32x4 acc[4][NB];
; #pragma unroll
;   for (int i = 0; i < 4; ++i)
; #pragma unroll
;     for (int j = 0; j < NB; ++j) acc[i][j] = (f32x4){0.f, 0.f, 0.f, 0.f};
;     ...
;   int cs = 0, is = S - 1;
; #pragma clang loop unroll(disable)
;   for (int kt = 0; kt < nk; ++kt) {
;     if (nk - 1 - kt >= S - 2) {
;       if constexpr (NB == 8) asm volatile("s_waitcnt vmcnt(6)" ::: "memory");
;       else                   asm volatile("s_waitcnt vmcnt(8)" ::: "memory");
;     } else {
;       asm volatile("s_waitcnt vmcnt(0)" ::: "memory");
;     }
;     RAW_BARRIER();
;     if (kt + S - 1 < nk) GEMM_ISSUE(kt + S - 1, is);
;     is = (is + 1 == S) ? 0 : is + 1;
;     const unsigned cur = lbase + cs * STG;
	v_mov_b32_e32 v23, v2
	v_mov_b32_e32 v24, v2
	v_mov_b32_e32 v25, v2
	v_mov_b32_e32 v26, v2
	v_mov_b32_e32 v27, v2
	v_mov_b32_e32 v28, v2
	v_mov_b32_e32 v29, v2
	v_mov_b32_e32 v30, v2
	v_mov_b32_e32 v31, v2
	v_mov_b32_e32 v32, v2
	v_mov_b32_e32 v33, v2
	v_mov_b32_e32 v34, v2
	v_mov_b32_e32 v35, v2
	v_mov_b32_e32 v36, v2
	v_mov_b32_e32 v37, v2
	v_mov_b32_e32 v38, v2
	v_mov_b32_e32 v39, v2
	v_mov_b32_e32 v40, v2
	v_mov_b32_e32 v41, v2
	v_mov_b32_e32 v42, v2
	v_mov_b32_e32 v43, v2
	v_mov_b32_e32 v44, v2
	v_mov_b32_e32 v45, v2
	v_mov_b32_e32 v46, v2
	v_mov_b32_e32 v47, v2
	v_mov_b32_e32 v48, v2
	v_mov_b32_e32 v49, v2
	v_mov_b32_e32 v50, v2
	v_mov_b32_e32 v51, v2
	v_mov_b32_e32 v52, v2
	v_mov_b32_e32 v53, v2
	v_mov_b32_e32 v54, v2
	v_mov_b32_e32 v55, v2
	v_mov_b32_e32 v56, v2
	v_mov_b32_e32 v57, v2
	v_mov_b32_e32 v58, v2
	v_mov_b32_e32 v59, v2
	v_mov_b32_e32 v60, v2
	v_mov_b32_e32 v61, v2
	v_mov_b32_e32 v62, v2
	v_mov_b32_e32 v63, v2
	v_mov_b32_e32 v64, v2
	v_mov_b32_e32 v65, v2
	v_mov_b32_e32 v66, v2
	v_mov_b32_e32 v67, v2
	v_mov_b32_e32 v68, v2
	v_mov_b32_e32 v69, v2
	v_mov_b32_e32 v70, v2
	v_mov_b32_e32 v71, v2
	v_mov_b32_e32 v72, v2
	v_mov_b32_e32 v73, v2
	v_mov_b32_e32 v74, v2
	v_mov_b32_e32 v75, v2
	v_mov_b32_e32 v76, v2
	v_mov_b32_e32 v77, v2
	v_mov_b32_e32 v78, v2
	v_mov_b32_e32 v79, v2
	v_mov_b32_e32 v80, v2
	v_mov_b32_e32 v81, v2
	v_mov_b32_e32 v82, v2
	v_mov_b32_e32 v83, v2
	v_mov_b32_e32 v84, v2
	v_mov_b32_e32 v85, v2
	v_mov_b32_e32 v86, v2
	v_mov_b32_e32 v87, v2
	v_mov_b32_e32 v88, v2
	v_mov_b32_e32 v89, v2
	v_mov_b32_e32 v90, v2
	v_mov_b32_e32 v91, v2
	v_mov_b32_e32 v92, v2
	v_mov_b32_e32 v93, v2
	v_mov_b32_e32 v94, v2
	v_mov_b32_e32 v95, v2
	v_mov_b32_e32 v96, v2
	v_mov_b32_e32 v97, v2
	v_mov_b32_e32 v98, v2
	v_mov_b32_e32 v99, v2
	v_mov_b32_e32 v100, v2
	v_mov_b32_e32 v101, v2
	v_mov_b32_e32 v102, v2
	v_mov_b32_e32 v103, v2
	v_mov_b32_e32 v104, v2
	v_mov_b32_e32 v105, v2
	v_mov_b32_e32 v106, v2
	v_mov_b32_e32 v107, v2
	v_mov_b32_e32 v108, v2
	v_mov_b32_e32 v109, v2
	v_mov_b32_e32 v110, v2
	v_mov_b32_e32 v111, v2
	v_mov_b32_e32 v112, v2
	v_mov_b32_e32 v113, v2
	v_mov_b32_e32 v114, v2
	v_mov_b32_e32 v115, v2
	v_mov_b32_e32 v116, v2
	v_mov_b32_e32 v117, v2
	v_mov_b32_e32 v118, v2
	v_mov_b32_e32 v119, v2
	v_mov_b32_e32 v120, v2
	v_mov_b32_e32 v121, v2
	v_mov_b32_e32 v122, v2
	v_mov_b32_e32 v123, v2
	v_mov_b32_e32 v124, v2
	v_mov_b32_e32 v125, v2
	v_mov_b32_e32 v126, v2
	v_mov_b32_e32 v127, v2
	v_mov_b32_e32 v128, v2
	v_mov_b32_e32 v129, v2
	s_mul_i32 s0, s42, 0x6000
	v_add_u32_e32 v211, s0, v185
	v_lshl_add_u64 v[212:213], v[182:183], 0, v[0:1]
	v_readfirstlane_b32 s0, v211
	v_lshl_add_u64 v[214:215], v[212:213], 0, s[84:85]
	s_mov_b32 m0, s0
	v_lshl_add_u64 v[212:213], v[212:213], 0, s[12:13]
	s_nop 0
	v_readfirstlane_b32 s100, v214
	v_readfirstlane_b32 s101, v215
	s_nop 1
	v_subrev_u32_e32 v228, s100, v214
	v_add_u32_e32 v214, 0x1000, v211
	v_add_u32_e32 v216, 0x2000, v211
	v_readfirstlane_b32 s0, v214
	s_mov_b32 m0, s0
	s_mov_b64 s[0:1], 0x43d6000
	v_subrev_u32_e32 v229, s100, v212
	v_lshl_add_u64 v[212:213], v[180:181], 0, v[0:1]
	v_lshl_add_u64 v[214:215], v[212:213], 0, s[0:1]
	v_readfirstlane_b32 s0, v216
	s_mov_b32 m0, s0
	s_mov_b64 s[0:1], 0x43d7000
	v_add_u32_e32 v216, 0x3000, v211
	s_nop 0
	v_readfirstlane_b32 vcc_lo, v214
	v_readfirstlane_b32 vcc_hi, v215
	s_nop 1
	v_subrev_u32_e32 v230, vcc_lo, v214
	v_lshl_add_u64 v[214:215], v[212:213], 0, s[0:1]
	v_readfirstlane_b32 s0, v216
	s_mov_b32 m0, s0
	s_mov_b64 s[0:1], 0x43d8000
	v_add_u32_e32 v216, 0x4000, v211
	v_subrev_u32_e32 v231, vcc_lo, v214
	v_lshl_add_u64 v[214:215], v[212:213], 0, s[0:1]
	v_readfirstlane_b32 s0, v216
	s_mov_b32 m0, s0
	s_mov_b64 s[0:1], 0x43d9000
	v_add_u32_e32 v211, 0x5000, v211
	v_lshl_add_u64 v[212:213], v[212:213], 0, s[0:1]
	v_readfirstlane_b32 s0, v211
	v_subrev_u32_e32 v232, vcc_lo, v214
	s_mov_b32 m0, s0
	s_nop 0
	v_subrev_u32_e32 v233, vcc_lo, v212
	v_mov_b32_e32 v182, v228
	v_mov_b32_e32 v183, v229
	v_mov_b32_e32 v180, v230
	v_mov_b32_e32 v181, v231
	v_mov_b32_e32 v253, v232
	v_mov_b32_e32 v254, v233
	v_readfirstlane_b32 s0, v185
	s_branch .LBB0_1217

; DEVI int otid() { int t = threadIdx.x; asm volatile("" : "+v"(t)); return t; }
; #define RAW_BARRIER() do { asm volatile("s_waitcnt lgkmcnt(0)" ::: "memory"); __builtin_amdgcn_s_barrier(); } while (0)
; template <int EPI, int NB>
; DEVI void gemm_tile(const GemmJob& J, int m0, int n0, unsigned char* smem) {
;     ...
;   const int tid = otid(), lane = tid & 63, wid = tid >> 6, wm = wid >> 1, wn = wid & 1;
;   const int l16 = lane & 15, g = lane >> 4;
;   f32x4 acc[4][NB];
; #pragma unroll
;   for (int i = 0; i < 4; ++i)
; #pragma unroll
;     for (int j = 0; j < NB; ++j) acc[i][j] = (f32x4){0.f, 0.f, 0.f, 0.f};
;   const int srow = tid >> 2, sch = tid & 3;
;   const int gch = sch ^ ((0 - (tid >> 4)) & 3);
;   const bf16_t* Ag = J.A + (size_t)(m0 + srow) * (J.ablk ? 32 : J.lda) + gch * 8;
;   const bf16_t* Bg = J.Bt + (size_t)(n0 + srow) * 32 + gch * 8;
;   const size_t Astep = (size_t)64 * (J.ablk ? 32 : J.lda), Ak = J.ablk ? (size_t)MROWS * 32 : (size_t)32, Bstep = (size_t)64 * 32, Bk = (size_t)J.NR * 32;
;   const int nk = J.K >> 5;
;   unsigned char* lds_t = smem + tid * 16;
;   const unsigned lbase = (unsigned)(uintptr_t)(__attribute__((address_space(3))) unsigned char*)smem;
;     ...
;   asm volatile("s_waitcnt vmcnt(0)" ::: "memory");
;   RAW_BARRIER();
; #pragma unroll
;   for (int st = 0; st < S - 1; ++st) GEMM_ISSUE(st, st);
;   const int fsl = (g ^ ((0 - (l16 >> 2)) & 3)) << 4;
;   const int aofs = (wm * 64 + l16) * 64 + fsl;
;   const int bofs = A_BYTES + (wn * NB * 16 + l16) * 64 + fsl;
; template <int EPI, int NB>
; DEVI void gemm_run(const GemmJob& J, unsigned char* smem, int rot) {
;     ...
;     for (int t = b; t < ntiles; t += G) {
;       const int mt = t / J.ntn, nt = J.nt0 + (t - mt * J.ntn);
;       gemm_tile<EPI, NB>(J, mt * 128, nt * BN, smem);
.LBB0_1293:
	v_mov_b32_e32 v185, v177
	s_lshl_b32 s8, s3, 7
	v_lshrrev_b32_e32 v0, 4, v185
	v_ashrrev_i32_e32 v2, 2, v185
	v_sub_u32_e32 v14, 0, v0
	v_xor_b32_e32 v0, v185, v14
	v_add_u32_e32 v4, s8, v2
	v_ashrrev_i32_e32 v3, 31, v2
	v_ashrrev_i32_e32 v5, 31, v4
	v_lshlrev_b32_e32 v0, 4, v0
	v_lshlrev_b64 v[6:7], 6, v[2:3]
	v_lshlrev_b64 v[4:5], 6, v[4:5]
	v_and_b32_e32 v0, 48, v0
	v_lshl_add_u64 v[8:9], v[134:135], 0, v[6:7]
	v_lshl_add_u64 v[4:5], v[146:147], 0, v[4:5]
	v_lshl_add_u64 v[8:9], v[8:9], 0, v[0:1]
	s_mov_b64 s[0:1], 0x14000
	v_lshlrev_b32_e32 v186, 4, v185
	v_lshl_add_u64 v[4:5], v[4:5], 0, v[0:1]
	v_lshl_add_u64 v[10:11], v[8:9], 0, s[0:1]
	v_readfirstlane_b32 s0, v186
	v_add_u32_e32 v0, 0x1000, v186
	s_nop 0
	s_mov_b32 m0, s0
	v_readfirstlane_b32 s0, v0
	v_add_u32_e32 v0, 0x2000, v186
	s_waitcnt lgkmcnt(0)
	s_barrier
	global_load_lds_dwordx4 v[4:5], off
	v_lshl_add_u64 v[12:13], v[4:5], 0, s[30:31]
	s_mov_b32 m0, s0
	v_readfirstlane_b32 s0, v0
	global_load_lds_dwordx4 v[12:13], off
	s_mov_b32 m0, s0
	s_mov_b64 s[0:1], 0x15000
	v_add_u32_e32 v0, 0x3000, v186
	global_load_lds_dwordx4 v[10:11], off
	v_lshl_add_u64 v[10:11], v[8:9], 0, s[0:1]
	v_readfirstlane_b32 s0, v0
	s_mov_b32 m0, s0
	s_mov_b64 s[0:1], 0x16000
	v_add_u32_e32 v0, 0x4000, v186
	global_load_lds_dwordx4 v[10:11], off
	v_lshl_add_u64 v[10:11], v[8:9], 0, s[0:1]
	v_readfirstlane_b32 s0, v0
	s_mov_b32 m0, s0
	s_mov_b64 s[0:1], 0x17000
	v_add_u32_e32 v0, 0x5000, v186
	global_load_lds_dwordx4 v[10:11], off
	v_lshl_add_u64 v[10:11], v[8:9], 0, s[0:1]
	v_readfirstlane_b32 s0, v0
	v_add_u32_e32 v0, 0x6000, v186
	s_mov_b32 m0, s0
	v_readfirstlane_b32 s0, v0
	global_load_lds_dwordx4 v[10:11], off
	s_mov_b32 m0, s0
	s_mov_b64 s[0:1], 0x30b000
	v_add_u32_e32 v0, 0x7000, v186
	v_lshl_add_u64 v[10:11], v[4:5], 0, s[94:95]
	v_lshl_add_u64 v[4:5], v[4:5], 0, s[0:1]
	v_readfirstlane_b32 s0, v0
	global_load_lds_dwordx4 v[10:11], off
	s_mov_b32 m0, s0
	s_mov_b64 s[0:1], 0x2c000
	v_add_u32_e32 v0, 0x8000, v186
	global_load_lds_dwordx4 v[4:5], off
	v_lshl_add_u64 v[4:5], v[8:9], 0, s[0:1]
	v_readfirstlane_b32 s0, v0
	s_mov_b32 m0, s0
	s_mov_b64 s[0:1], 0x2d000
	v_add_u32_e32 v0, 0x9000, v186
	global_load_lds_dwordx4 v[4:5], off
	v_lshl_add_u64 v[4:5], v[8:9], 0, s[0:1]
	v_readfirstlane_b32 s0, v0
	s_mov_b32 m0, s0
	s_mov_b64 s[0:1], 0x2e000
	v_add_u32_e32 v0, 0xa000, v186
	global_load_lds_dwordx4 v[4:5], off
	v_lshl_add_u64 v[4:5], v[8:9], 0, s[0:1]
	v_readfirstlane_b32 s0, v0
	s_mov_b32 m0, s0
	s_mov_b64 s[0:1], 0x2f000
	v_add_u32_e32 v0, 0xb000, v186
	global_load_lds_dwordx4 v[4:5], off
	v_lshl_add_u64 v[4:5], v[8:9], 0, s[0:1]
	v_readfirstlane_b32 s0, v0
	s_mov_b32 m0, s0
	v_lshlrev_b32_e32 v3, 2, v185
	global_load_lds_dwordx4 v[4:5], off
	v_and_b32_e32 v3, 48, v3
	v_ashrrev_i32_e32 v4, 1, v185
	v_and_b32_e32 v0, 15, v185
	v_sub_u32_e32 v3, 0, v3
	v_and_b32_e32 v208, 0xffffffc0, v4
	v_bitop3_b32 v3, v185, 48, v3 bitop3:0x48
	v_or_b32_e32 v4, v208, v0
	v_lshl_or_b32 v209, v4, 6, v3
	v_lshlrev_b32_e32 v4, 1, v185
	v_and_b32_e32 v187, 0x80, v4
	v_or_b32_e32 v184, v187, v0
	v_add_u32_e32 v2, s2, v2
	v_lshl_or_b32 v0, v184, 6, v3
	v_ashrrev_i32_e32 v3, 31, v2
	v_lshlrev_b64 v[2:3], 6, v[2:3]
	v_add_u32_e32 v210, 0x2000, v0
	v_bitop3_b32 v0, v185, 3, v14 bitop3:0x48
	v_lshl_add_u64 v[182:183], v[130:131], 0, v[2:3]
	v_mov_b32_e32 v2, 0
	s_mov_b32 s20, 2
	s_mov_b32 s9, 0
	v_lshlrev_b32_e32 v0, 4, v0
	v_lshl_add_u64 v[180:181], v[130:131], 0, v[6:7]
	s_mov_b32 s42, 0
	v_mov_b32_e32 v3, v2
	v_mov_b32_e32 v4, v2
	v_mov_b32_e32 v5, v2
	v_mov_b32_e32 v6, v2
	v_mov_b32_e32 v7, v2
	v_mov_b32_e32 v8, v2
	v_mov_b32_e32 v9, v2
	v_mov_b32_e32 v10, v2
	v_mov_b32_e32 v11, v2
	v_mov_b32_e32 v12, v2
	v_mov_b32_e32 v13, v2
	v_mov_b32_e32 v14, v2
	v_mov_b32_e32 v15, v2
	v_mov_b32_e32 v16, v2
	v_mov_b32_e32 v17, v2
	v_mov_b32_e32 v18, v2
	v_mov_b32_e32 v19, v2
	v_mov_b32_e32 v20, v2
	v_mov_b32_e32 v21, v2
	v_mov_b32_e32 v22, v2
	v_mov_b32_e32 v23, v2
	v_mov_b32_e32 v24, v2
	v_mov_b32_e32 v25, v2
	v_mov_b32_e32 v26, v2
; #define RAW_BARRIER() do { asm volatile("s_waitcnt lgkmcnt(0)" ::: "memory"); __builtin_amdgcn_s_barrier(); } while (0)
; template <int EPI, int NB>
; DEVI void gemm_tile(const GemmJob& J, int m0, int n0, unsigned char* smem) {
;     ...
;   f32x4 acc[4][NB];
; #pragma unroll
;   for (int i = 0; i < 4; ++i)
; #pragma unroll
;     for (int j = 0; j < NB; ++j) acc[i][j] = (f32x4){0.f, 0.f, 0.f, 0.f};
;     ...
;   int cs = 0, is = S - 1;
; #pragma clang loop unroll(disable)
;   for (int kt = 0; kt < nk; ++kt) {
;     if (nk - 1 - kt >= S - 2) {
;       if constexpr (NB == 8) asm volatile("s_waitcnt vmcnt(6)" ::: "memory");
;       else                   asm volatile("s_waitcnt vmcnt(8)" ::: "memory");
;     } else {
;       asm volatile("s_waitcnt vmcnt(0)" ::: "memory");
;     }
;     RAW_BARRIER();
;     if (kt + S - 1 < nk) GEMM_ISSUE(kt + S - 1, is);
;     is = (is + 1 == S) ? 0 : is + 1;
;     const unsigned cur = lbase + cs * STG;
	v_mov_b32_e32 v27, v2
	v_mov_b32_e32 v28, v2
	v_mov_b32_e32 v29, v2
	v_mov_b32_e32 v30, v2
	v_mov_b32_e32 v31, v2
	v_mov_b32_e32 v32, v2
	v_mov_b32_e32 v33, v2
	v_mov_b32_e32 v34, v2
	v_mov_b32_e32 v35, v2
	v_mov_b32_e32 v36, v2
	v_mov_b32_e32 v37, v2
	v_mov_b32_e32 v38, v2
	v_mov_b32_e32 v39, v2
	v_mov_b32_e32 v40, v2
	v_mov_b32_e32 v41, v2
	v_mov_b32_e32 v42, v2
	v_mov_b32_e32 v43, v2
	v_mov_b32_e32 v44, v2
	v_mov_b32_e32 v45, v2
	v_mov_b32_e32 v46, v2
	v_mov_b32_e32 v47, v2
	v_mov_b32_e32 v48, v2
	v_mov_b32_e32 v49, v2
	v_mov_b32_e32 v50, v2
	v_mov_b32_e32 v51, v2
	v_mov_b32_e32 v52, v2
	v_mov_b32_e32 v53, v2
	v_mov_b32_e32 v54, v2
	v_mov_b32_e32 v55, v2
	v_mov_b32_e32 v56, v2
	v_mov_b32_e32 v57, v2
	v_mov_b32_e32 v58, v2
	v_mov_b32_e32 v59, v2
	v_mov_b32_e32 v60, v2
	v_mov_b32_e32 v61, v2
	v_mov_b32_e32 v62, v2
	v_mov_b32_e32 v63, v2
	v_mov_b32_e32 v64, v2
	v_mov_b32_e32 v65, v2
	v_mov_b32_e32 v66, v2
	v_mov_b32_e32 v67, v2
	v_mov_b32_e32 v68, v2
	v_mov_b32_e32 v69, v2
	v_mov_b32_e32 v70, v2
	v_mov_b32_e32 v71, v2
	v_mov_b32_e32 v72, v2
	v_mov_b32_e32 v73, v2
	v_mov_b32_e32 v74, v2
	v_mov_b32_e32 v75, v2
	v_mov_b32_e32 v76, v2
	v_mov_b32_e32 v77, v2
	v_mov_b32_e32 v78, v2
	v_mov_b32_e32 v79, v2
	v_mov_b32_e32 v80, v2
	v_mov_b32_e32 v81, v2
	v_mov_b32_e32 v82, v2
	v_mov_b32_e32 v83, v2
	v_mov_b32_e32 v84, v2
	v_mov_b32_e32 v85, v2
	v_mov_b32_e32 v86, v2
	v_mov_b32_e32 v87, v2
	v_mov_b32_e32 v88, v2
	v_mov_b32_e32 v89, v2
	v_mov_b32_e32 v90, v2
	v_mov_b32_e32 v91, v2
	v_mov_b32_e32 v92, v2
	v_mov_b32_e32 v93, v2
	v_mov_b32_e32 v94, v2
	v_mov_b32_e32 v95, v2
	v_mov_b32_e32 v96, v2
	v_mov_b32_e32 v97, v2
	v_mov_b32_e32 v98, v2
	v_mov_b32_e32 v99, v2
	v_mov_b32_e32 v100, v2
	v_mov_b32_e32 v101, v2
	v_mov_b32_e32 v102, v2
	v_mov_b32_e32 v103, v2
	v_mov_b32_e32 v104, v2
	v_mov_b32_e32 v105, v2
	v_mov_b32_e32 v106, v2
	v_mov_b32_e32 v107, v2
	v_mov_b32_e32 v108, v2
	v_mov_b32_e32 v109, v2
	v_mov_b32_e32 v110, v2
	v_mov_b32_e32 v111, v2
	v_mov_b32_e32 v112, v2
	v_mov_b32_e32 v113, v2
	v_mov_b32_e32 v114, v2
	v_mov_b32_e32 v115, v2
	v_mov_b32_e32 v116, v2
	v_mov_b32_e32 v117, v2
	v_mov_b32_e32 v118, v2
	v_mov_b32_e32 v119, v2
	v_mov_b32_e32 v120, v2
	v_mov_b32_e32 v121, v2
	v_mov_b32_e32 v122, v2
	v_mov_b32_e32 v123, v2
	v_mov_b32_e32 v124, v2
	v_mov_b32_e32 v125, v2
	v_mov_b32_e32 v126, v2
	v_mov_b32_e32 v127, v2
	v_mov_b32_e32 v128, v2
	v_mov_b32_e32 v129, v2
	s_mul_i32 s0, s20, 0x6000
	v_add_u32_e32 v211, s0, v186
	v_lshl_add_u64 v[212:213], v[182:183], 0, v[0:1]
	v_readfirstlane_b32 s0, v211
	v_lshl_add_u64 v[214:215], v[212:213], 0, s[84:85]
	s_mov_b32 m0, s0
	v_lshl_add_u64 v[212:213], v[212:213], 0, s[12:13]
	s_nop 0
	v_readfirstlane_b32 s100, v214
	v_readfirstlane_b32 s101, v215
	s_nop 1
	v_subrev_u32_e32 v228, s100, v214
	v_add_u32_e32 v214, 0x1000, v211
	v_add_u32_e32 v216, 0x2000, v211
	v_readfirstlane_b32 s0, v214
	s_mov_b32 m0, s0
	s_mov_b64 s[0:1], 0x43ea000
	v_subrev_u32_e32 v229, s100, v212
	v_lshl_add_u64 v[212:213], v[180:181], 0, v[0:1]
	v_lshl_add_u64 v[214:215], v[212:213], 0, s[0:1]
	v_readfirstlane_b32 s0, v216
	s_mov_b32 m0, s0
	s_mov_b64 s[0:1], 0x43eb000
	v_add_u32_e32 v216, 0x3000, v211
	s_nop 0
	v_readfirstlane_b32 vcc_lo, v214
	v_readfirstlane_b32 vcc_hi, v215
	s_nop 1
	v_subrev_u32_e32 v230, vcc_lo, v214
	v_lshl_add_u64 v[214:215], v[212:213], 0, s[0:1]
	v_readfirstlane_b32 s0, v216
	s_mov_b32 m0, s0
	s_mov_b64 s[0:1], 0x43ec000
	v_add_u32_e32 v216, 0x4000, v211
	v_subrev_u32_e32 v231, vcc_lo, v214
	v_lshl_add_u64 v[214:215], v[212:213], 0, s[0:1]
	v_readfirstlane_b32 s0, v216
	s_mov_b32 m0, s0
	s_mov_b64 s[0:1], 0x43ed000
	v_add_u32_e32 v211, 0x5000, v211
	v_lshl_add_u64 v[212:213], v[212:213], 0, s[0:1]
	v_readfirstlane_b32 s0, v211
	v_subrev_u32_e32 v232, vcc_lo, v214
	s_mov_b32 m0, s0
	s_nop 0
	v_subrev_u32_e32 v233, vcc_lo, v212
	v_mov_b32_e32 v182, v228
	v_mov_b32_e32 v183, v229
	v_mov_b32_e32 v180, v230
	v_mov_b32_e32 v181, v231
	v_mov_b32_e32 v253, v232
	v_mov_b32_e32 v254, v233
	v_readfirstlane_b32 s0, v186
	s_branch .LBB0_1295

; DEVI int otid() { int t = threadIdx.x; asm volatile("" : "+v"(t)); return t; }
; #define RAW_BARRIER() do { asm volatile("s_waitcnt lgkmcnt(0)" ::: "memory"); __builtin_amdgcn_s_barrier(); } while (0)
; template <int EPI, int NB>
; DEVI void gemm_tile(const GemmJob& J, int m0, int n0, unsigned char* smem) {
;     ...
;   const int tid = otid(), lane = tid & 63, wid = tid >> 6, wm = wid >> 1, wn = wid & 1;
;   const int l16 = lane & 15, g = lane >> 4;
;   f32x4 acc[4][NB];
; #pragma unroll
;   for (int i = 0; i < 4; ++i)
; #pragma unroll
;     for (int j = 0; j < NB; ++j) acc[i][j] = (f32x4){0.f, 0.f, 0.f, 0.f};
;   const int srow = tid >> 2, sch = tid & 3;
;   const int gch = sch ^ ((0 - (tid >> 4)) & 3);
;   const bf16_t* Ag = J.A + (size_t)(m0 + srow) * (J.ablk ? 32 : J.lda) + gch * 8;
;   const bf16_t* Bg = J.Bt + (size_t)(n0 + srow) * 32 + gch * 8;
;   const size_t Astep = (size_t)64 * (J.ablk ? 32 : J.lda), Ak = J.ablk ? (size_t)MROWS * 32 : (size_t)32, Bstep = (size_t)64 * 32, Bk = (size_t)J.NR * 32;
;   const int nk = J.K >> 5;
;   unsigned char* lds_t = smem + tid * 16;
;   const unsigned lbase = (unsigned)(uintptr_t)(__attribute__((address_space(3))) unsigned char*)smem;
;     ...
;   asm volatile("s_waitcnt vmcnt(0)" ::: "memory");
;   RAW_BARRIER();
; #pragma unroll
;   for (int st = 0; st < S - 1; ++st) GEMM_ISSUE(st, st);
;   const int fsl = (g ^ ((0 - (l16 >> 2)) & 3)) << 4;
;   const int aofs = (wm * 64 + l16) * 64 + fsl;
;   const int bofs = A_BYTES + (wn * NB * 16 + l16) * 64 + fsl;
; template <int EPI, int NB>
; DEVI void gemm_run(const GemmJob& J, unsigned char* smem, int rot) {
;     ...
;     for (int q0 = lb; q0 < ntot; q0 += nlb) {
;       const int q = J.rev ? ntot - 1 - q0 : q0;
;       int grp = q / gsz; const int qq = q - grp * gsz;
;       const int mg = min(8, mcnt - grp * 8);
;       const int nt = qq / mg, mi = qq - nt * mg;
;       gemm_tile<EPI, NB>(J, (mlo + grp * 8 + mi) * 128, (J.nt0 + nt) * BN, smem);
.LBB0_1340:
	s_mul_hi_i32 s0, s9, 0x66666667
	s_lshr_b32 s1, s0, 31
	s_ashr_i32 s0, s0, 4
	s_add_i32 s0, s0, s1
	s_lshl_b32 s1, s0, 3
	v_readlane_b32 s2, v251, 48
	s_sub_i32 s2, s2, s1
	s_min_i32 s3, s2, 8
	s_abs_i32 s20, s3
	v_cvt_f32_u32_e32 v0, s20
	s_sub_i32 s43, 0, s20
	s_mul_i32 s40, s0, 0xffffffd8
	s_add_i32 s40, s40, s9
	v_rcp_iflag_f32_e32 v0, v0
	s_abs_i32 s41, s40
	s_xor_b32 s42, s40, s3
	s_ashr_i32 s42, s42, 31
	v_mul_f32_e32 v0, 0x4f7ffffe, v0
	v_cvt_u32_f32_e32 v0, v0
	v_mov_b32_e32 v184, v177
	s_nop 0
	v_readfirstlane_b32 s44, v0
	s_mul_i32 s43, s43, s44
	s_mul_hi_u32 s43, s44, s43
	s_add_i32 s44, s44, s43
	s_mul_hi_u32 s43, s41, s44
	s_mul_i32 s44, s43, s20
	s_sub_i32 s41, s41, s44
	s_add_i32 s45, s43, 1
	s_sub_i32 s44, s41, s20
	s_cmp_ge_u32 s41, s20
	s_cselect_b32 s43, s45, s43
	s_cselect_b32 s41, s44, s41
	s_add_i32 s44, s43, 1
	s_cmp_ge_u32 s41, s20
	s_cselect_b32 s20, s44, s43
	s_xor_b32 s20, s20, s42
	s_sub_i32 s41, s20, s42
	s_mul_i32 s43, s3, s41
	v_readlane_b32 s3, v250, 37
	s_add_i32 s1, s1, s3
	s_add_i32 s1, s1, s40
	s_sub_i32 s1, s1, s43
	s_lshl_b32 s20, s1, 7
	s_lshl_b32 s3, s41, 8
	v_ashrrev_i32_e32 v10, 2, v184
	v_lshrrev_b32_e32 v0, 4, v184
	v_sub_u32_e32 v11, 0, v0
	v_add_u32_e32 v2, s20, v10
	v_add_u32_e32 v4, s3, v10
	v_xor_b32_e32 v0, v184, v11
	v_ashrrev_i32_e32 v3, 31, v2
	v_ashrrev_i32_e32 v5, 31, v4
	v_lshlrev_b64 v[2:3], 6, v[2:3]
	v_lshlrev_b32_e32 v0, 4, v0
	v_lshlrev_b64 v[4:5], 6, v[4:5]
	v_lshl_add_u64 v[2:3], v[146:147], 0, v[2:3]
	v_and_b32_e32 v0, 48, v0
	v_lshl_add_u64 v[6:7], v[134:135], 0, v[4:5]
	v_lshlrev_b32_e32 v185, 4, v184
	v_lshl_add_u64 v[2:3], v[2:3], 0, v[0:1]
	v_lshl_add_u64 v[6:7], v[6:7], 0, v[0:1]
	v_readfirstlane_b32 s1, v185
	v_add_u32_e32 v0, 0x1000, v185
	s_mov_b32 m0, s1
	s_mov_b64 s[28:29], 0x1000
	v_readfirstlane_b32 s1, v0
	v_add_u32_e32 v0, 0x2000, v185
	s_waitcnt lgkmcnt(0)
	s_barrier
	global_load_lds_dwordx4 v[2:3], off
	v_lshl_add_u64 v[8:9], v[2:3], 0, s[28:29]
	s_mov_b32 m0, s1
	v_readfirstlane_b32 s1, v0
	v_add_u32_e32 v0, 0x3000, v185
	global_load_lds_dwordx4 v[8:9], off
	s_mov_b32 m0, s1
	v_readfirstlane_b32 s1, v0
	v_add_u32_e32 v0, 0x4000, v185
	global_load_lds_dwordx4 v[6:7], off
	v_lshl_add_u64 v[8:9], v[6:7], 0, s[28:29]
	s_mov_b32 m0, s1
	s_mov_b64 s[28:29], 0x2000
	v_readfirstlane_b32 s1, v0
	v_add_u32_e32 v0, 0x5000, v185
	global_load_lds_dwordx4 v[8:9], off
	v_lshl_add_u64 v[8:9], v[6:7], 0, s[28:29]
	s_mov_b32 m0, s1
	s_mov_b64 s[28:29], 0x3000
	v_readfirstlane_b32 s1, v0
	v_add_u32_e32 v0, 0x6000, v185
	global_load_lds_dwordx4 v[8:9], off
	v_lshl_add_u64 v[8:9], v[6:7], 0, s[28:29]
	s_mov_b32 m0, s1
	v_readfirstlane_b32 s1, v0
	v_add_u32_e32 v0, 0x7000, v185
	global_load_lds_dwordx4 v[8:9], off
	v_lshl_add_u64 v[8:9], v[2:3], 0, s[94:95]
	s_mov_b32 m0, s1
	s_mov_b64 s[28:29], 0x30b000
	v_readfirstlane_b32 s1, v0
	v_add_u32_e32 v0, 0x8000, v185
	global_load_lds_dwordx4 v[8:9], off
	v_lshl_add_u64 v[2:3], v[2:3], 0, s[28:29]
	s_mov_b32 m0, s1
	v_readfirstlane_b32 s1, v0
	v_add_u32_e32 v0, 0x9000, v185
	global_load_lds_dwordx4 v[2:3], off
	v_lshl_add_u64 v[2:3], v[6:7], 0, s[38:39]
	s_mov_b32 m0, s1
	s_mov_b64 s[28:29], 0x19000
	v_readfirstlane_b32 s1, v0
	v_add_u32_e32 v0, 0xa000, v185
	global_load_lds_dwordx4 v[2:3], off
	v_lshl_add_u64 v[2:3], v[6:7], 0, s[28:29]
	s_mov_b32 m0, s1
	s_mov_b64 s[28:29], 0x1a000
	v_readfirstlane_b32 s1, v0
	v_add_u32_e32 v0, 0xb000, v185
	global_load_lds_dwordx4 v[2:3], off
	v_lshl_add_u64 v[2:3], v[6:7], 0, s[28:29]
	s_mov_b32 m0, s1
	s_mov_b64 s[28:29], 0x1b000
	v_readfirstlane_b32 s1, v0
	global_load_lds_dwordx4 v[2:3], off
	v_lshl_add_u64 v[2:3], v[6:7], 0, s[28:29]
	s_mov_b32 m0, s1
	v_lshlrev_b32_e32 v0, 2, v184
	global_load_lds_dwordx4 v[2:3], off
	v_and_b32_e32 v0, 48, v0
	v_ashrrev_i32_e32 v2, 1, v184
	v_and_b32_e32 v186, 15, v184
	v_sub_u32_e32 v0, 0, v0
	v_and_b32_e32 v187, 0xffffffc0, v2
	v_bitop3_b32 v0, v184, 48, v0 bitop3:0x48
	v_or_b32_e32 v2, v187, v186
	v_lshl_or_b32 v209, v2, 6, v0
	v_lshlrev_b32_e32 v2, 1, v184
	v_and_b32_e32 v208, 0x80, v2
	s_sub_i32 s1, s8, s43
	s_lshl_b32 s0, s0, 5
	v_or_b32_e32 v2, v208, v186
	s_sub_i32 s0, s1, s0
	v_lshl_or_b32 v0, v2, 6, v0
	v_lshl_add_u32 v2, s0, 7, v10
	v_ashrrev_i32_e32 v3, 31, v2
	v_lshlrev_b64 v[2:3], 6, v[2:3]
	v_add_u32_e32 v210, 0x2000, v0
	v_bitop3_b32 v0, v184, 3, v11 bitop3:0x48
	v_lshl_add_u64 v[182:183], v[130:131], 0, v[2:3]
	v_mov_b32_e32 v2, 0
	s_mov_b32 s2, 0
	s_mov_b32 s42, 2
	s_mov_b64 s[30:31], 0x1000
	v_lshlrev_b32_e32 v0, 4, v0
	v_lshl_add_u64 v[180:181], v[130:131], 0, v[4:5]
	s_mov_b32 s43, 0
; #define RAW_BARRIER() do { asm volatile("s_waitcnt lgkmcnt(0)" ::: "memory"); __builtin_amdgcn_s_barrier(); } while (0)
; template <int EPI, int NB>
; DEVI void gemm_tile(const GemmJob& J, int m0, int n0, unsigned char* smem) {
;     ...
;   f32x4 acc[4][NB];
; #pragma unroll
;   for (int i = 0; i < 4; ++i)
; #pragma unroll
;     for (int j = 0; j < NB; ++j) acc[i][j] = (f32x4){0.f, 0.f, 0.f, 0.f};
;     ...
;   int cs = 0, is = S - 1;
; #pragma clang loop unroll(disable)
;   for (int kt = 0; kt < nk; ++kt) {
;     if (nk - 1 - kt >= S - 2) {
;       if constexpr (NB == 8) asm volatile("s_waitcnt vmcnt(6)" ::: "memory");
;       else                   asm volatile("s_waitcnt vmcnt(8)" ::: "memory");
;     } else {
;       asm volatile("s_waitcnt vmcnt(0)" ::: "memory");
;     }
;     RAW_BARRIER();
;     if (kt + S - 1 < nk) GEMM_ISSUE(kt + S - 1, is);
;     is = (is + 1 == S) ? 0 : is + 1;
;     const unsigned cur = lbase + cs * STG;
	v_mov_b32_e32 v3, v2
	v_mov_b32_e32 v4, v2
	v_mov_b32_e32 v5, v2
	v_mov_b32_e32 v6, v2
	v_mov_b32_e32 v7, v2
	v_mov_b32_e32 v8, v2
	v_mov_b32_e32 v9, v2
	v_mov_b32_e32 v10, v2
	v_mov_b32_e32 v11, v2
	v_mov_b32_e32 v12, v2
	v_mov_b32_e32 v13, v2
	v_mov_b32_e32 v14, v2
	v_mov_b32_e32 v15, v2
	v_mov_b32_e32 v16, v2
	v_mov_b32_e32 v17, v2
	v_mov_b32_e32 v18, v2
	v_mov_b32_e32 v19, v2
	v_mov_b32_e32 v20, v2
	v_mov_b32_e32 v21, v2
	v_mov_b32_e32 v22, v2
	v_mov_b32_e32 v23, v2
	v_mov_b32_e32 v24, v2
	v_mov_b32_e32 v25, v2
	v_mov_b32_e32 v26, v2
	v_mov_b32_e32 v27, v2
	v_mov_b32_e32 v28, v2
	v_mov_b32_e32 v29, v2
	v_mov_b32_e32 v30, v2
	v_mov_b32_e32 v31, v2
	v_mov_b32_e32 v32, v2
	v_mov_b32_e32 v33, v2
	v_mov_b32_e32 v34, v2
	v_mov_b32_e32 v35, v2
	v_mov_b32_e32 v36, v2
	v_mov_b32_e32 v37, v2
	v_mov_b32_e32 v38, v2
	v_mov_b32_e32 v39, v2
	v_mov_b32_e32 v40, v2
	v_mov_b32_e32 v41, v2
	v_mov_b32_e32 v42, v2
	v_mov_b32_e32 v43, v2
	v_mov_b32_e32 v44, v2
	v_mov_b32_e32 v45, v2
	v_mov_b32_e32 v46, v2
	v_mov_b32_e32 v47, v2
	v_mov_b32_e32 v48, v2
	v_mov_b32_e32 v49, v2
	v_mov_b32_e32 v50, v2
	v_mov_b32_e32 v51, v2
	v_mov_b32_e32 v52, v2
	v_mov_b32_e32 v53, v2
	v_mov_b32_e32 v54, v2
	v_mov_b32_e32 v55, v2
	v_mov_b32_e32 v56, v2
	v_mov_b32_e32 v57, v2
	v_mov_b32_e32 v58, v2
	v_mov_b32_e32 v59, v2
	v_mov_b32_e32 v60, v2
	v_mov_b32_e32 v61, v2
	v_mov_b32_e32 v62, v2
	v_mov_b32_e32 v63, v2
	v_mov_b32_e32 v64, v2
	v_mov_b32_e32 v65, v2
	v_mov_b32_e32 v66, v2
	v_mov_b32_e32 v67, v2
	v_mov_b32_e32 v68, v2
	v_mov_b32_e32 v69, v2
	v_mov_b32_e32 v70, v2
	v_mov_b32_e32 v71, v2
	v_mov_b32_e32 v72, v2
	v_mov_b32_e32 v73, v2
	v_mov_b32_e32 v74, v2
	v_mov_b32_e32 v75, v2
	v_mov_b32_e32 v76, v2
	v_mov_b32_e32 v77, v2
	v_mov_b32_e32 v78, v2
	v_mov_b32_e32 v79, v2
	v_mov_b32_e32 v80, v2
	v_mov_b32_e32 v81, v2
	v_mov_b32_e32 v82, v2
	v_mov_b32_e32 v83, v2
	v_mov_b32_e32 v84, v2
	v_mov_b32_e32 v85, v2
	v_mov_b32_e32 v86, v2
	v_mov_b32_e32 v87, v2
	v_mov_b32_e32 v88, v2
	v_mov_b32_e32 v89, v2
	v_mov_b32_e32 v90, v2
	v_mov_b32_e32 v91, v2
	v_mov_b32_e32 v92, v2
	v_mov_b32_e32 v93, v2
	v_mov_b32_e32 v94, v2
	v_mov_b32_e32 v95, v2
	v_mov_b32_e32 v96, v2
	v_mov_b32_e32 v97, v2
	v_mov_b32_e32 v98, v2
	v_mov_b32_e32 v99, v2
	v_mov_b32_e32 v100, v2
	v_mov_b32_e32 v101, v2
	v_mov_b32_e32 v102, v2
	v_mov_b32_e32 v103, v2
	v_mov_b32_e32 v104, v2
	v_mov_b32_e32 v105, v2
	v_mov_b32_e32 v106, v2
	v_mov_b32_e32 v107, v2
	v_mov_b32_e32 v108, v2
	v_mov_b32_e32 v109, v2
	v_mov_b32_e32 v110, v2
	v_mov_b32_e32 v111, v2
	v_mov_b32_e32 v112, v2
	v_mov_b32_e32 v113, v2
	v_mov_b32_e32 v114, v2
	v_mov_b32_e32 v115, v2
	v_mov_b32_e32 v116, v2
	v_mov_b32_e32 v117, v2
	v_mov_b32_e32 v118, v2
	v_mov_b32_e32 v119, v2
	v_mov_b32_e32 v120, v2
	v_mov_b32_e32 v121, v2
	v_mov_b32_e32 v122, v2
	v_mov_b32_e32 v123, v2
	v_mov_b32_e32 v124, v2
	v_mov_b32_e32 v125, v2
	v_mov_b32_e32 v126, v2
	v_mov_b32_e32 v127, v2
	v_mov_b32_e32 v128, v2
	v_mov_b32_e32 v129, v2
	s_mul_i32 s0, s42, 0x6000
	v_add_u32_e32 v211, s0, v185
	v_lshl_add_u64 v[212:213], v[182:183], 0, v[0:1]
	v_readfirstlane_b32 s0, v211
	v_lshl_add_u64 v[214:215], v[212:213], 0, s[84:85]
	s_mov_b32 m0, s0
	v_lshl_add_u64 v[212:213], v[212:213], 0, s[12:13]
	s_nop 0
	v_readfirstlane_b32 s100, v214
	v_readfirstlane_b32 s101, v215
	s_nop 1
	v_subrev_u32_e32 v228, s100, v214
	v_add_u32_e32 v214, 0x1000, v211
	v_add_u32_e32 v216, 0x2000, v211
	v_readfirstlane_b32 s0, v214
	s_mov_b32 m0, s0
	s_mov_b64 s[0:1], 0x43d6000
	v_subrev_u32_e32 v229, s100, v212
	v_lshl_add_u64 v[212:213], v[180:181], 0, v[0:1]
	v_lshl_add_u64 v[214:215], v[212:213], 0, s[0:1]
	v_readfirstlane_b32 s0, v216
	s_mov_b32 m0, s0
	s_mov_b64 s[0:1], 0x43d7000
	v_add_u32_e32 v216, 0x3000, v211
	s_nop 0
	v_readfirstlane_b32 vcc_lo, v214
	v_readfirstlane_b32 vcc_hi, v215
	s_nop 1
	v_subrev_u32_e32 v230, vcc_lo, v214
	v_lshl_add_u64 v[214:215], v[212:213], 0, s[0:1]
	v_readfirstlane_b32 s0, v216
	s_mov_b32 m0, s0
	s_mov_b64 s[0:1], 0x43d8000
	v_add_u32_e32 v216, 0x4000, v211
	v_subrev_u32_e32 v231, vcc_lo, v214
	v_lshl_add_u64 v[214:215], v[212:213], 0, s[0:1]
	v_readfirstlane_b32 s0, v216
	s_mov_b32 m0, s0
	s_mov_b64 s[0:1], 0x43d9000
	v_add_u32_e32 v211, 0x5000, v211
	v_lshl_add_u64 v[212:213], v[212:213], 0, s[0:1]
	v_readfirstlane_b32 s0, v211
	v_subrev_u32_e32 v232, vcc_lo, v214
	s_mov_b32 m0, s0
	s_nop 0
	v_subrev_u32_e32 v233, vcc_lo, v212
	v_mov_b32_e32 v182, v228
	v_mov_b32_e32 v183, v229
	v_mov_b32_e32 v180, v230
	v_mov_b32_e32 v181, v231
	v_mov_b32_e32 v253, v232
	v_mov_b32_e32 v254, v233
	v_readfirstlane_b32 s0, v185
	s_branch .LBB0_1342

; DEVI int otid() { int t = threadIdx.x; asm volatile("" : "+v"(t)); return t; }
; #define RAW_BARRIER() do { asm volatile("s_waitcnt lgkmcnt(0)" ::: "memory"); __builtin_amdgcn_s_barrier(); } while (0)
; template <int EPI, int NB>
; DEVI void gemm_tile(const GemmJob& J, int m0, int n0, unsigned char* smem) {
;     ...
;   const int tid = otid(), lane = tid & 63, wid = tid >> 6, wm = wid >> 1, wn = wid & 1;
;   const int l16 = lane & 15, g = lane >> 4;
;   f32x4 acc[4][NB];
; #pragma unroll
;   for (int i = 0; i < 4; ++i)
; #pragma unroll
;     for (int j = 0; j < NB; ++j) acc[i][j] = (f32x4){0.f, 0.f, 0.f, 0.f};
;   const int srow = tid >> 2, sch = tid & 3;
;   const int gch = sch ^ ((0 - (tid >> 4)) & 3);
;   const bf16_t* Ag = J.A + (size_t)(m0 + srow) * (J.ablk ? 32 : J.lda) + gch * 8;
;   const bf16_t* Bg = J.Bt + (size_t)(n0 + srow) * 32 + gch * 8;
;   const size_t Astep = (size_t)64 * (J.ablk ? 32 : J.lda), Ak = J.ablk ? (size_t)MROWS * 32 : (size_t)32, Bstep = (size_t)64 * 32, Bk = (size_t)J.NR * 32;
;   const int nk = J.K >> 5;
;   unsigned char* lds_t = smem + tid * 16;
;   const unsigned lbase = (unsigned)(uintptr_t)(__attribute__((address_space(3))) unsigned char*)smem;
;     ...
;   asm volatile("s_waitcnt vmcnt(0)" ::: "memory");
;   RAW_BARRIER();
; #pragma unroll
;   for (int st = 0; st < S - 1; ++st) GEMM_ISSUE(st, st);
;   const int fsl = (g ^ ((0 - (l16 >> 2)) & 3)) << 4;
;   const int aofs = (wm * 64 + l16) * 64 + fsl;
;   const int bofs = A_BYTES + (wn * NB * 16 + l16) * 64 + fsl;
; template <int EPI, int NB>
; DEVI void gemm_run(const GemmJob& J, unsigned char* smem, int rot) {
;     ...
;     for (int q0 = lb; q0 < ntot; q0 += nlb) {
;       const int q = J.rev ? ntot - 1 - q0 : q0;
;       int grp = q / gsz; const int qq = q - grp * gsz;
;       const int mg = min(8, mcnt - grp * 8);
;       const int nt = qq / mg, mi = qq - nt * mg;
;       gemm_tile<EPI, NB>(J, (mlo + grp * 8 + mi) * 128, (J.nt0 + nt) * BN, smem);
.LBB0_1419:
	s_ashr_i32 s0, s9, 31
	s_lshr_b32 s0, s0, 29
	s_add_i32 s0, s9, s0
	s_and_b32 s0, s0, -8
	s_sub_i32 s1, s1, s0
	s_min_i32 s1, s1, 8
	s_abs_i32 s2, s1
	v_cvt_f32_u32_e32 v0, s2
	s_sub_i32 s40, 0, s2
	s_sub_i32 s0, s9, s0
	s_abs_i32 s20, s0
	v_rcp_iflag_f32_e32 v0, v0
	s_xor_b32 s0, s0, s1
	s_ashr_i32 s0, s0, 31
	v_mov_b32_e32 v184, v177
	v_mul_f32_e32 v0, 0x4f7ffffe, v0
	v_cvt_u32_f32_e32 v0, v0
	s_nop 0
	s_mov_b64 s[28:29], 0x1000
	v_readfirstlane_b32 s41, v0
	s_mul_i32 s40, s40, s41
	s_mul_hi_u32 s40, s41, s40
	s_add_i32 s41, s41, s40
	s_mul_hi_u32 s40, s20, s41
	s_mul_i32 s41, s40, s2
	s_sub_i32 s20, s20, s41
	s_add_i32 s42, s40, 1
	s_sub_i32 s41, s20, s2
	s_cmp_ge_u32 s20, s2
	s_cselect_b32 s40, s42, s40
	s_cselect_b32 s20, s41, s20
	s_add_i32 s41, s40, 1
	s_cmp_ge_u32 s20, s2
	s_cselect_b32 s2, s41, s40
	s_xor_b32 s2, s2, s0
	v_readlane_b32 s20, v250, 53
	s_sub_i32 s0, s2, s0
	s_add_i32 s20, s9, s20
	s_mul_i32 s1, s1, s0
	s_sub_i32 s2, s20, s1
	s_lshl_b32 s20, s2, 7
	s_lshl_b32 s2, s0, 8
	s_addk_i32 s2, 0x500
	v_ashrrev_i32_e32 v10, 2, v184
	v_lshrrev_b32_e32 v0, 4, v184
	v_sub_u32_e32 v11, 0, v0
	v_add_u32_e32 v2, s20, v10
	v_add_u32_e32 v4, s2, v10
	v_xor_b32_e32 v0, v184, v11
	v_ashrrev_i32_e32 v3, 31, v2
	v_ashrrev_i32_e32 v5, 31, v4
	v_lshlrev_b64 v[2:3], 6, v[2:3]
	v_lshlrev_b32_e32 v0, 4, v0
	v_lshlrev_b64 v[4:5], 6, v[4:5]
	v_lshl_add_u64 v[2:3], v[146:147], 0, v[2:3]
	v_and_b32_e32 v0, 48, v0
	v_lshl_add_u64 v[6:7], v[134:135], 0, v[4:5]
	v_lshlrev_b32_e32 v185, 4, v184
	v_lshl_add_u64 v[2:3], v[2:3], 0, v[0:1]
	v_lshl_add_u64 v[6:7], v[6:7], 0, v[0:1]
	v_readfirstlane_b32 s0, v185
	v_add_u32_e32 v0, 0x1000, v185
	s_mov_b32 m0, s0
	v_readfirstlane_b32 s0, v0
	v_add_u32_e32 v0, 0x2000, v185
	s_waitcnt lgkmcnt(0)
	s_barrier
	global_load_lds_dwordx4 v[2:3], off
	v_lshl_add_u64 v[8:9], v[2:3], 0, s[28:29]
	s_mov_b32 m0, s0
	v_readfirstlane_b32 s0, v0
	v_add_u32_e32 v0, 0x3000, v185
	global_load_lds_dwordx4 v[8:9], off
	s_mov_b32 m0, s0
	v_readfirstlane_b32 s0, v0
	v_add_u32_e32 v0, 0x4000, v185
	global_load_lds_dwordx4 v[6:7], off
	v_lshl_add_u64 v[8:9], v[6:7], 0, s[28:29]
	s_mov_b32 m0, s0
	s_mov_b64 s[28:29], 0x2000
	v_readfirstlane_b32 s0, v0
	v_add_u32_e32 v0, 0x5000, v185
	global_load_lds_dwordx4 v[8:9], off
	v_lshl_add_u64 v[8:9], v[6:7], 0, s[28:29]
	s_mov_b32 m0, s0
	s_mov_b64 s[28:29], 0x3000
	v_readfirstlane_b32 s0, v0
	v_add_u32_e32 v0, 0x6000, v185
	global_load_lds_dwordx4 v[8:9], off
	v_lshl_add_u64 v[8:9], v[6:7], 0, s[28:29]
	s_mov_b32 m0, s0
	v_readfirstlane_b32 s0, v0
	v_add_u32_e32 v0, 0x7000, v185
	global_load_lds_dwordx4 v[8:9], off
	v_lshl_add_u64 v[8:9], v[2:3], 0, s[94:95]
	s_mov_b32 m0, s0
	s_mov_b64 s[28:29], 0x30b000
	v_readfirstlane_b32 s0, v0
	v_add_u32_e32 v0, 0x8000, v185
	global_load_lds_dwordx4 v[8:9], off
	v_lshl_add_u64 v[2:3], v[2:3], 0, s[28:29]
	s_mov_b32 m0, s0
	v_readfirstlane_b32 s0, v0
	v_add_u32_e32 v0, 0x9000, v185
	global_load_lds_dwordx4 v[2:3], off
	v_lshl_add_u64 v[2:3], v[6:7], 0, s[38:39]
	s_mov_b32 m0, s0
	s_mov_b64 s[28:29], 0x19000
	v_readfirstlane_b32 s0, v0
	v_add_u32_e32 v0, 0xa000, v185
	global_load_lds_dwordx4 v[2:3], off
	v_lshl_add_u64 v[2:3], v[6:7], 0, s[28:29]
	s_mov_b32 m0, s0
	s_mov_b64 s[28:29], 0x1a000
	v_readfirstlane_b32 s0, v0
	v_add_u32_e32 v0, 0xb000, v185
	global_load_lds_dwordx4 v[2:3], off
	v_lshl_add_u64 v[2:3], v[6:7], 0, s[28:29]
	s_mov_b32 m0, s0
	s_mov_b64 s[28:29], 0x1b000
	v_readfirstlane_b32 s0, v0
	global_load_lds_dwordx4 v[2:3], off
	v_lshl_add_u64 v[2:3], v[6:7], 0, s[28:29]
	s_mov_b32 m0, s0
	v_and_b32_e32 v0, 15, v184
	global_load_lds_dwordx4 v[2:3], off
	v_lshlrev_b32_e32 v2, 2, v184
	v_and_b32_e32 v2, 48, v2
	v_ashrrev_i32_e32 v3, 1, v184
	v_sub_u32_e32 v2, 0, v2
	v_and_b32_e32 v187, 0xffffffc0, v3
	v_bitop3_b32 v2, v184, 48, v2 bitop3:0x48
	v_or_b32_e32 v3, v187, v0
	v_lshl_or_b32 v208, v3, 6, v2
	v_lshlrev_b32_e32 v3, 1, v184
	s_movk_i32 s0, 0x80
	v_and_or_b32 v186, v3, s0, v0
	v_lshl_or_b32 v0, v186, 6, v2
	v_add_u32_e32 v2, s8, v10
	s_lshl_b32 s0, s1, 7
	v_subrev_u32_e32 v2, s0, v2
	v_ashrrev_i32_e32 v3, 31, v2
	v_lshlrev_b64 v[2:3], 6, v[2:3]
	v_add_u32_e32 v209, 0x2000, v0
	v_bitop3_b32 v0, v184, 3, v11 bitop3:0x48
	v_lshl_add_u64 v[182:183], v[130:131], 0, v[2:3]
	v_mov_b32_e32 v2, 0
	s_mov_b32 s3, 0
	s_mov_b32 s42, 2
	s_mov_b64 s[30:31], 0x1000
	v_lshlrev_b32_e32 v0, 4, v0
	v_lshl_add_u64 v[180:181], v[130:131], 0, v[4:5]
	s_mov_b32 s43, 0
	v_mov_b32_e32 v3, v2
	v_mov_b32_e32 v4, v2
	v_mov_b32_e32 v5, v2
; #define RAW_BARRIER() do { asm volatile("s_waitcnt lgkmcnt(0)" ::: "memory"); __builtin_amdgcn_s_barrier(); } while (0)
; template <int EPI, int NB>
; DEVI void gemm_tile(const GemmJob& J, int m0, int n0, unsigned char* smem) {
;     ...
;   f32x4 acc[4][NB];
; #pragma unroll
;   for (int i = 0; i < 4; ++i)
; #pragma unroll
;     for (int j = 0; j < NB; ++j) acc[i][j] = (f32x4){0.f, 0.f, 0.f, 0.f};
;     ...
;   int cs = 0, is = S - 1;
; #pragma clang loop unroll(disable)
;   for (int kt = 0; kt < nk; ++kt) {
;     if (nk - 1 - kt >= S - 2) {
;       if constexpr (NB == 8) asm volatile("s_waitcnt vmcnt(6)" ::: "memory");
;       else                   asm volatile("s_waitcnt vmcnt(8)" ::: "memory");
;     } else {
;       asm volatile("s_waitcnt vmcnt(0)" ::: "memory");
;     }
;     RAW_BARRIER();
;     if (kt + S - 1 < nk) GEMM_ISSUE(kt + S - 1, is);
;     is = (is + 1 == S) ? 0 : is + 1;
;     const unsigned cur = lbase + cs * STG;
	v_mov_b32_e32 v6, v2
	v_mov_b32_e32 v7, v2
	v_mov_b32_e32 v8, v2
	v_mov_b32_e32 v9, v2
	v_mov_b32_e32 v10, v2
	v_mov_b32_e32 v11, v2
	v_mov_b32_e32 v12, v2
	v_mov_b32_e32 v13, v2
	v_mov_b32_e32 v14, v2
	v_mov_b32_e32 v15, v2
	v_mov_b32_e32 v16, v2
	v_mov_b32_e32 v17, v2
	v_mov_b32_e32 v18, v2
	v_mov_b32_e32 v19, v2
	v_mov_b32_e32 v20, v2
	v_mov_b32_e32 v21, v2
	v_mov_b32_e32 v22, v2
	v_mov_b32_e32 v23, v2
	v_mov_b32_e32 v24, v2
	v_mov_b32_e32 v25, v2
	v_mov_b32_e32 v26, v2
	v_mov_b32_e32 v27, v2
	v_mov_b32_e32 v28, v2
	v_mov_b32_e32 v29, v2
	v_mov_b32_e32 v30, v2
	v_mov_b32_e32 v31, v2
	v_mov_b32_e32 v32, v2
	v_mov_b32_e32 v33, v2
	v_mov_b32_e32 v34, v2
	v_mov_b32_e32 v35, v2
	v_mov_b32_e32 v36, v2
	v_mov_b32_e32 v37, v2
	v_mov_b32_e32 v38, v2
	v_mov_b32_e32 v39, v2
	v_mov_b32_e32 v40, v2
	v_mov_b32_e32 v41, v2
	v_mov_b32_e32 v42, v2
	v_mov_b32_e32 v43, v2
	v_mov_b32_e32 v44, v2
	v_mov_b32_e32 v45, v2
	v_mov_b32_e32 v46, v2
	v_mov_b32_e32 v47, v2
	v_mov_b32_e32 v48, v2
	v_mov_b32_e32 v49, v2
	v_mov_b32_e32 v50, v2
	v_mov_b32_e32 v51, v2
	v_mov_b32_e32 v52, v2
	v_mov_b32_e32 v53, v2
	v_mov_b32_e32 v54, v2
	v_mov_b32_e32 v55, v2
	v_mov_b32_e32 v56, v2
	v_mov_b32_e32 v57, v2
	v_mov_b32_e32 v58, v2
	v_mov_b32_e32 v59, v2
	v_mov_b32_e32 v60, v2
	v_mov_b32_e32 v61, v2
	v_mov_b32_e32 v62, v2
	v_mov_b32_e32 v63, v2
	v_mov_b32_e32 v64, v2
	v_mov_b32_e32 v65, v2
	v_mov_b32_e32 v66, v2
	v_mov_b32_e32 v67, v2
	v_mov_b32_e32 v68, v2
	v_mov_b32_e32 v69, v2
	v_mov_b32_e32 v70, v2
	v_mov_b32_e32 v71, v2
	v_mov_b32_e32 v72, v2
	v_mov_b32_e32 v73, v2
	v_mov_b32_e32 v74, v2
	v_mov_b32_e32 v75, v2
	v_mov_b32_e32 v76, v2
	v_mov_b32_e32 v77, v2
	v_mov_b32_e32 v78, v2
	v_mov_b32_e32 v79, v2
	v_mov_b32_e32 v80, v2
	v_mov_b32_e32 v81, v2
	v_mov_b32_e32 v82, v2
	v_mov_b32_e32 v83, v2
	v_mov_b32_e32 v84, v2
	v_mov_b32_e32 v85, v2
	v_mov_b32_e32 v86, v2
	v_mov_b32_e32 v87, v2
	v_mov_b32_e32 v88, v2
	v_mov_b32_e32 v89, v2
	v_mov_b32_e32 v90, v2
	v_mov_b32_e32 v91, v2
	v_mov_b32_e32 v92, v2
	v_mov_b32_e32 v93, v2
	v_mov_b32_e32 v94, v2
	v_mov_b32_e32 v95, v2
	v_mov_b32_e32 v96, v2
	v_mov_b32_e32 v97, v2
	v_mov_b32_e32 v98, v2
	v_mov_b32_e32 v99, v2
	v_mov_b32_e32 v100, v2
	v_mov_b32_e32 v101, v2
	v_mov_b32_e32 v102, v2
	v_mov_b32_e32 v103, v2
	v_mov_b32_e32 v104, v2
	v_mov_b32_e32 v105, v2
	v_mov_b32_e32 v106, v2
	v_mov_b32_e32 v107, v2
	v_mov_b32_e32 v108, v2
	v_mov_b32_e32 v109, v2
	v_mov_b32_e32 v110, v2
	v_mov_b32_e32 v111, v2
	v_mov_b32_e32 v112, v2
	v_mov_b32_e32 v113, v2
	v_mov_b32_e32 v114, v2
	v_mov_b32_e32 v115, v2
	v_mov_b32_e32 v116, v2
	v_mov_b32_e32 v117, v2
	v_mov_b32_e32 v118, v2
	v_mov_b32_e32 v119, v2
	v_mov_b32_e32 v120, v2
	v_mov_b32_e32 v121, v2
	v_mov_b32_e32 v122, v2
	v_mov_b32_e32 v123, v2
	v_mov_b32_e32 v124, v2
	v_mov_b32_e32 v125, v2
	v_mov_b32_e32 v126, v2
	v_mov_b32_e32 v127, v2
	v_mov_b32_e32 v128, v2
	v_mov_b32_e32 v129, v2
	s_mul_i32 s0, s42, 0x6000
	v_add_u32_e32 v214, s0, v185
	v_lshl_add_u64 v[210:211], v[182:183], 0, v[0:1]
	v_readfirstlane_b32 s0, v214
	v_lshl_add_u64 v[212:213], v[210:211], 0, s[84:85]
	s_mov_b32 m0, s0
	v_lshl_add_u64 v[210:211], v[210:211], 0, s[12:13]
	s_nop 0
	v_readfirstlane_b32 s100, v212
	v_readfirstlane_b32 s101, v213
	s_nop 1
	v_subrev_u32_e32 v226, s100, v212
	v_add_u32_e32 v212, 0x1000, v214
	v_add_u32_e32 v215, 0x2000, v214
	v_readfirstlane_b32 s0, v212
	s_mov_b32 m0, s0
	s_mov_b64 s[0:1], 0x43d6000
	v_subrev_u32_e32 v227, s100, v210
	v_lshl_add_u64 v[210:211], v[180:181], 0, v[0:1]
	v_lshl_add_u64 v[212:213], v[210:211], 0, s[0:1]
	v_readfirstlane_b32 s0, v215
	s_mov_b32 m0, s0
	s_mov_b64 s[0:1], 0x43d7000
	v_add_u32_e32 v215, 0x3000, v214
	s_nop 0
	v_readfirstlane_b32 vcc_lo, v212
	v_readfirstlane_b32 vcc_hi, v213
	s_nop 1
	v_subrev_u32_e32 v228, vcc_lo, v212
	v_lshl_add_u64 v[212:213], v[210:211], 0, s[0:1]
	v_readfirstlane_b32 s0, v215
	s_mov_b32 m0, s0
	s_mov_b64 s[0:1], 0x43d8000
	v_add_u32_e32 v215, 0x4000, v214
	v_subrev_u32_e32 v229, vcc_lo, v212
	v_lshl_add_u64 v[212:213], v[210:211], 0, s[0:1]
	v_readfirstlane_b32 s0, v215
	s_mov_b32 m0, s0
	s_mov_b64 s[0:1], 0x43d9000
	v_subrev_u32_e32 v230, vcc_lo, v212
	v_add_u32_e32 v212, 0x5000, v214
	v_lshl_add_u64 v[210:211], v[210:211], 0, s[0:1]
	v_readfirstlane_b32 s0, v212
	s_mov_b32 m0, s0
	s_nop 0
	v_subrev_u32_e32 v231, vcc_lo, v210
	v_mov_b32_e32 v182, v226
	v_mov_b32_e32 v183, v227
	v_mov_b32_e32 v180, v228
	v_mov_b32_e32 v181, v229
	v_mov_b32_e32 v253, v230
	v_mov_b32_e32 v254, v231
	v_readfirstlane_b32 s0, v185
	s_branch .LBB0_1421

; DEVI int otid() { int t = threadIdx.x; asm volatile("" : "+v"(t)); return t; }
; #define RAW_BARRIER() do { asm volatile("s_waitcnt lgkmcnt(0)" ::: "memory"); __builtin_amdgcn_s_barrier(); } while (0)
; template <int EPI, int NB>
; DEVI void gemm_tile(const GemmJob& J, int m0, int n0, unsigned char* smem) {
;     ...
;   const int tid = otid(), lane = tid & 63, wid = tid >> 6, wm = wid >> 1, wn = wid & 1;
;   const int l16 = lane & 15, g = lane >> 4;
;   f32x4 acc[4][NB];
; #pragma unroll
;   for (int i = 0; i < 4; ++i)
; #pragma unroll
;     for (int j = 0; j < NB; ++j) acc[i][j] = (f32x4){0.f, 0.f, 0.f, 0.f};
;   const int srow = tid >> 2, sch = tid & 3;
;   const int gch = sch ^ ((0 - (tid >> 4)) & 3);
;   const bf16_t* Ag = J.A + (size_t)(m0 + srow) * (J.ablk ? 32 : J.lda) + gch * 8;
;   const bf16_t* Bg = J.Bt + (size_t)(n0 + srow) * 32 + gch * 8;
;   const size_t Astep = (size_t)64 * (J.ablk ? 32 : J.lda), Ak = J.ablk ? (size_t)MROWS * 32 : (size_t)32, Bstep = (size_t)64 * 32, Bk = (size_t)J.NR * 32;
;   const int nk = J.K >> 5;
;   unsigned char* lds_t = smem + tid * 16;
;   const unsigned lbase = (unsigned)(uintptr_t)(__attribute__((address_space(3))) unsigned char*)smem;
;     ...
;   asm volatile("s_waitcnt vmcnt(0)" ::: "memory");
;   RAW_BARRIER();
; #pragma unroll
;   for (int st = 0; st < S - 1; ++st) GEMM_ISSUE(st, st);
;   const int fsl = (g ^ ((0 - (l16 >> 2)) & 3)) << 4;
;   const int aofs = (wm * 64 + l16) * 64 + fsl;
;   const int bofs = A_BYTES + (wn * NB * 16 + l16) * 64 + fsl;
;   int cs = 0, is = S - 1;
; template <int EPI, int NB>
; DEVI void gemm_run(const GemmJob& J, unsigned char* smem, int rot) {
;     ...
;     for (int t = b; t < ntiles; t += G) {
;       const int mt = t / J.ntn, nt = J.nt0 + (t - mt * J.ntn);
;       gemm_tile<EPI, NB>(J, mt * 128, nt * BN, smem);
.LBB0_1623:
	s_mul_hi_i32 s0, s9, 0x55555556
	s_lshr_b32 s1, s0, 31
	s_add_i32 s40, s0, s1
	s_mul_i32 s0, s40, -3
	s_add_i32 s0, s0, s9
	v_mov_b32_e32 v184, v177
	s_lshl_b32 s2, s0, 8
	s_lshl_b32 s3, s40, 7
	v_ashrrev_i32_e32 v8, 2, v184
	v_lshrrev_b32_e32 v0, 4, v184
	v_sub_u32_e32 v9, 0, v0
	v_add_u32_e32 v4, s2, v8
	v_xor_b32_e32 v0, v184, v9
	v_add_u32_e32 v10, s3, v8
	s_movk_i32 s28, 0x840
	v_ashrrev_i32_e32 v5, 31, v4
	v_mad_i64_i32 v[2:3], s[0:1], v10, s28, v[152:153]
	v_lshlrev_b32_e32 v0, 4, v0
	v_lshlrev_b64 v[4:5], 6, v[4:5]
	v_lshlrev_b32_e32 v185, 4, v184
	v_and_b32_e32 v0, 48, v0
	v_lshl_add_u64 v[4:5], v[136:137], 0, v[4:5]
	v_readfirstlane_b32 s0, v185
	v_lshl_add_u64 v[2:3], v[2:3], 0, v[0:1]
	v_lshl_add_u64 v[4:5], v[4:5], 0, v[0:1]
	s_mov_b32 m0, s0
	s_mov_b64 s[0:1], 0x21000
	v_add_u32_e32 v0, 0x1000, v185
	s_nop 0
	v_lshl_add_u64 v[6:7], v[2:3], 0, s[0:1]
	v_readfirstlane_b32 s0, v0
	v_add_u32_e32 v0, 0x2000, v185
	s_waitcnt lgkmcnt(0)
	s_barrier
	global_load_lds_dwordx4 v[2:3], off
	s_mov_b32 m0, s0
	v_readfirstlane_b32 s0, v0
	v_add_u32_e32 v0, 0x3000, v185
	global_load_lds_dwordx4 v[6:7], off
	s_mov_b32 m0, s0
	v_readfirstlane_b32 s0, v0
	global_load_lds_dwordx4 v[4:5], off
	v_lshl_add_u64 v[6:7], v[4:5], 0, s[30:31]
	s_mov_b32 m0, s0
	s_mov_b64 s[0:1], 0x2000
	v_add_u32_e32 v0, 0x4000, v185
	global_load_lds_dwordx4 v[6:7], off
	v_lshl_add_u64 v[6:7], v[4:5], 0, s[0:1]
	v_readfirstlane_b32 s0, v0
	s_mov_b32 m0, s0
	s_mov_b64 s[0:1], 0x3000
	v_add_u32_e32 v0, 0x5000, v185
	global_load_lds_dwordx4 v[6:7], off
	v_lshl_add_u64 v[6:7], v[4:5], 0, s[0:1]
	v_readfirstlane_b32 s0, v0
	v_add_u32_e32 v0, 0x6000, v185
	s_mov_b32 m0, s0
	v_readfirstlane_b32 s0, v0
	global_load_lds_dwordx4 v[6:7], off
	s_mov_b32 m0, s0
	s_mov_b64 s[0:1], 0x21040
	v_add_u32_e32 v0, 0x7000, v185
	v_lshl_add_u64 v[6:7], v[2:3], 0, 64
	v_lshl_add_u64 v[2:3], v[2:3], 0, s[0:1]
	v_readfirstlane_b32 s0, v0
	v_add_u32_e32 v0, 0x8000, v185
	global_load_lds_dwordx4 v[6:7], off
	s_mov_b32 m0, s0
	v_readfirstlane_b32 s0, v0
	global_load_lds_dwordx4 v[2:3], off
	v_lshl_add_u64 v[2:3], v[4:5], 0, s[86:87]
	s_mov_b32 m0, s0
	s_mov_b64 s[0:1], 0xd000
	v_add_u32_e32 v0, 0x9000, v185
	global_load_lds_dwordx4 v[2:3], off
	v_lshl_add_u64 v[2:3], v[4:5], 0, s[0:1]
	v_readfirstlane_b32 s0, v0
	s_mov_b32 m0, s0
	s_mov_b64 s[0:1], 0xe000
	v_add_u32_e32 v0, 0xa000, v185
	global_load_lds_dwordx4 v[2:3], off
	v_lshl_add_u64 v[2:3], v[4:5], 0, s[0:1]
	v_readfirstlane_b32 s0, v0
	s_mov_b32 m0, s0
	s_mov_b64 s[0:1], 0xf000
	v_add_u32_e32 v0, 0xb000, v185
	global_load_lds_dwordx4 v[2:3], off
	v_lshl_add_u64 v[2:3], v[4:5], 0, s[0:1]
	v_readfirstlane_b32 s0, v0
	s_mov_b32 m0, s0
	v_lshlrev_b32_e32 v0, 2, v184
	global_load_lds_dwordx4 v[2:3], off
	v_and_b32_e32 v0, 48, v0
	v_ashrrev_i32_e32 v2, 1, v184
	v_and_b32_e32 v187, 15, v184
	v_sub_u32_e32 v0, 0, v0
	v_and_b32_e32 v208, 0xffffffc0, v2
	v_bitop3_b32 v0, v184, 48, v0 bitop3:0x48
	v_or_b32_e32 v2, v208, v187
	v_lshl_or_b32 v209, v2, 6, v0
	v_lshlrev_b32_e32 v2, 1, v184
	v_and_b32_e32 v186, 0x80, v2
	v_or_b32_e32 v2, v186, v187
	v_lshl_or_b32 v0, v2, 6, v0
	v_add_u32_e32 v2, s8, v8
	s_mulk_i32 s40, 0x300
	v_subrev_u32_e32 v2, s40, v2
	v_ashrrev_i32_e32 v3, 31, v2
	v_lshlrev_b64 v[2:3], 6, v[2:3]
	v_add_u32_e32 v210, 0x2000, v0
	v_bitop3_b32 v0, v184, 3, v9 bitop3:0x48
	v_lshl_add_u64 v[180:181], v[130:131], 0, v[2:3]
	v_mov_b32_e32 v2, 0
	s_mov_b32 s42, 2
	s_mov_b32 s20, 0
	v_lshlrev_b32_e32 v0, 4, v0
	v_mad_i64_i32 v[182:183], s[0:1], v10, s28, v[130:131]
	s_mov_b32 s43, 0
	v_mov_b32_e32 v3, v2
	v_mov_b32_e32 v4, v2
	v_mov_b32_e32 v5, v2
	v_mov_b32_e32 v6, v2
	v_mov_b32_e32 v7, v2
	v_mov_b32_e32 v8, v2
	v_mov_b32_e32 v9, v2
	v_mov_b32_e32 v10, v2
	v_mov_b32_e32 v11, v2
	v_mov_b32_e32 v12, v2
	v_mov_b32_e32 v13, v2
	v_mov_b32_e32 v14, v2
	v_mov_b32_e32 v15, v2
	v_mov_b32_e32 v16, v2
	v_mov_b32_e32 v17, v2
	v_mov_b32_e32 v18, v2
	v_mov_b32_e32 v19, v2
	v_mov_b32_e32 v20, v2
	v_mov_b32_e32 v21, v2
	v_mov_b32_e32 v22, v2
	v_mov_b32_e32 v23, v2
	v_mov_b32_e32 v24, v2
	v_mov_b32_e32 v25, v2
	v_mov_b32_e32 v26, v2
; #define RAW_BARRIER() do { asm volatile("s_waitcnt lgkmcnt(0)" ::: "memory"); __builtin_amdgcn_s_barrier(); } while (0)
; template <int EPI, int NB>
; DEVI void gemm_tile(const GemmJob& J, int m0, int n0, unsigned char* smem) {
;     ...
;   f32x4 acc[4][NB];
; #pragma unroll
;   for (int i = 0; i < 4; ++i)
; #pragma unroll
;     for (int j = 0; j < NB; ++j) acc[i][j] = (f32x4){0.f, 0.f, 0.f, 0.f};
;   const int srow = tid >> 2, sch = tid & 3;
;   const int gch = sch ^ ((0 - (tid >> 4)) & 3);
;   const bf16_t* Ag = J.A + (size_t)(m0 + srow) * (J.ablk ? 32 : J.lda) + gch * 8;
;   const bf16_t* Bg = J.Bt + (size_t)(n0 + srow) * 32 + gch * 8;
;   const size_t Astep = (size_t)64 * (J.ablk ? 32 : J.lda), Ak = J.ablk ? (size_t)MROWS * 32 : (size_t)32, Bstep = (size_t)64 * 32, Bk = (size_t)J.NR * 32;
;   const int nk = J.K >> 5;
;   unsigned char* lds_t = smem + tid * 16;
;   const unsigned lbase = (unsigned)(uintptr_t)(__attribute__((address_space(3))) unsigned char*)smem;
;     ...
;   asm volatile("s_waitcnt vmcnt(0)" ::: "memory");
;   RAW_BARRIER();
; #pragma unroll
;   for (int st = 0; st < S - 1; ++st) GEMM_ISSUE(st, st);
;   const int fsl = (g ^ ((0 - (l16 >> 2)) & 3)) << 4;
;   const int aofs = (wm * 64 + l16) * 64 + fsl;
;   const int bofs = A_BYTES + (wn * NB * 16 + l16) * 64 + fsl;
;   int cs = 0, is = S - 1;
; #pragma clang loop unroll(disable)
;   for (int kt = 0; kt < nk; ++kt) {
;     if (nk - 1 - kt >= S - 2) {
;       if constexpr (NB == 8) asm volatile("s_waitcnt vmcnt(6)" ::: "memory");
;       else                   asm volatile("s_waitcnt vmcnt(8)" ::: "memory");
;     } else {
;       asm volatile("s_waitcnt vmcnt(0)" ::: "memory");
;     }
;     RAW_BARRIER();
;     if (kt + S - 1 < nk) GEMM_ISSUE(kt + S - 1, is);
;     is = (is + 1 == S) ? 0 : is + 1;
;     const unsigned cur = lbase + cs * STG;
;     cs = (cs + 1 == S) ? 0 : cs + 1;
	v_mov_b32_e32 v27, v2
	v_mov_b32_e32 v28, v2
	v_mov_b32_e32 v29, v2
	v_mov_b32_e32 v30, v2
	v_mov_b32_e32 v31, v2
	v_mov_b32_e32 v32, v2
	v_mov_b32_e32 v33, v2
	v_mov_b32_e32 v34, v2
	v_mov_b32_e32 v35, v2
	v_mov_b32_e32 v36, v2
	v_mov_b32_e32 v37, v2
	v_mov_b32_e32 v38, v2
	v_mov_b32_e32 v39, v2
	v_mov_b32_e32 v40, v2
	v_mov_b32_e32 v41, v2
	v_mov_b32_e32 v42, v2
	v_mov_b32_e32 v43, v2
	v_mov_b32_e32 v44, v2
	v_mov_b32_e32 v45, v2
	v_mov_b32_e32 v46, v2
	v_mov_b32_e32 v47, v2
	v_mov_b32_e32 v48, v2
	v_mov_b32_e32 v49, v2
	v_mov_b32_e32 v50, v2
	v_mov_b32_e32 v51, v2
	v_mov_b32_e32 v52, v2
	v_mov_b32_e32 v53, v2
	v_mov_b32_e32 v54, v2
	v_mov_b32_e32 v55, v2
	v_mov_b32_e32 v56, v2
	v_mov_b32_e32 v57, v2
	v_mov_b32_e32 v58, v2
	v_mov_b32_e32 v59, v2
	v_mov_b32_e32 v60, v2
	v_mov_b32_e32 v61, v2
	v_mov_b32_e32 v62, v2
	v_mov_b32_e32 v63, v2
	v_mov_b32_e32 v64, v2
	v_mov_b32_e32 v65, v2
	v_mov_b32_e32 v66, v2
	v_mov_b32_e32 v67, v2
	v_mov_b32_e32 v68, v2
	v_mov_b32_e32 v69, v2
	v_mov_b32_e32 v70, v2
	v_mov_b32_e32 v71, v2
	v_mov_b32_e32 v72, v2
	v_mov_b32_e32 v73, v2
	v_mov_b32_e32 v74, v2
	v_mov_b32_e32 v75, v2
	v_mov_b32_e32 v76, v2
	v_mov_b32_e32 v77, v2
	v_mov_b32_e32 v78, v2
	v_mov_b32_e32 v79, v2
	v_mov_b32_e32 v80, v2
	v_mov_b32_e32 v81, v2
	v_mov_b32_e32 v82, v2
	v_mov_b32_e32 v83, v2
	v_mov_b32_e32 v84, v2
	v_mov_b32_e32 v85, v2
	v_mov_b32_e32 v86, v2
	v_mov_b32_e32 v87, v2
	v_mov_b32_e32 v88, v2
	v_mov_b32_e32 v89, v2
	v_mov_b32_e32 v90, v2
	v_mov_b32_e32 v91, v2
	v_mov_b32_e32 v92, v2
	v_mov_b32_e32 v93, v2
	v_mov_b32_e32 v94, v2
	v_mov_b32_e32 v95, v2
	v_mov_b32_e32 v96, v2
	v_mov_b32_e32 v97, v2
	v_mov_b32_e32 v98, v2
	v_mov_b32_e32 v99, v2
	v_mov_b32_e32 v100, v2
	v_mov_b32_e32 v101, v2
	v_mov_b32_e32 v102, v2
	v_mov_b32_e32 v103, v2
	v_mov_b32_e32 v104, v2
	v_mov_b32_e32 v105, v2
	v_mov_b32_e32 v106, v2
	v_mov_b32_e32 v107, v2
	v_mov_b32_e32 v108, v2
	v_mov_b32_e32 v109, v2
	v_mov_b32_e32 v110, v2
	v_mov_b32_e32 v111, v2
	v_mov_b32_e32 v112, v2
	v_mov_b32_e32 v113, v2
	v_mov_b32_e32 v114, v2
	v_mov_b32_e32 v115, v2
	v_mov_b32_e32 v116, v2
	v_mov_b32_e32 v117, v2
	v_mov_b32_e32 v118, v2
	v_mov_b32_e32 v119, v2
	v_mov_b32_e32 v120, v2
	v_mov_b32_e32 v121, v2
	v_mov_b32_e32 v122, v2
	v_mov_b32_e32 v123, v2
	v_mov_b32_e32 v124, v2
	v_mov_b32_e32 v125, v2
	v_mov_b32_e32 v126, v2
	v_mov_b32_e32 v127, v2
	v_mov_b32_e32 v128, v2
	v_mov_b32_e32 v129, v2
	s_mul_i32 s0, s42, 0x6000
	v_add_u32_e32 v211, s0, v185
	v_lshl_add_u64 v[212:213], v[182:183], 0, v[0:1]
	s_mov_b64 s[0:1], 0xb286080
	v_lshl_add_u64 v[214:215], v[212:213], 0, s[0:1]
	v_readfirstlane_b32 s0, v211
	s_mov_b32 m0, s0
	s_mov_b64 s[0:1], 0xb2a7080
	s_nop 0
	v_readfirstlane_b32 s100, v214
	v_readfirstlane_b32 s101, v215
	s_nop 1
	v_subrev_u32_e32 v228, s100, v214
	v_add_u32_e32 v214, 0x1000, v211
	v_lshl_add_u64 v[212:213], v[212:213], 0, s[0:1]
	v_readfirstlane_b32 s0, v214
	s_mov_b32 m0, s0
	s_mov_b64 s[0:1], 0x46be000
	v_subrev_u32_e32 v229, s100, v212
	v_lshl_add_u64 v[212:213], v[180:181], 0, v[0:1]
	v_add_u32_e32 v216, 0x2000, v211
	v_lshl_add_u64 v[214:215], v[212:213], 0, s[0:1]
	v_readfirstlane_b32 s0, v216
	s_mov_b32 m0, s0
	s_mov_b64 s[0:1], 0x46bf000
	v_add_u32_e32 v216, 0x3000, v211
	s_nop 0
	v_readfirstlane_b32 vcc_lo, v214
	v_readfirstlane_b32 vcc_hi, v215
	s_nop 1
	v_subrev_u32_e32 v230, vcc_lo, v214
	v_lshl_add_u64 v[214:215], v[212:213], 0, s[0:1]
	v_readfirstlane_b32 s0, v216
	s_mov_b32 m0, s0
	s_mov_b64 s[0:1], 0x46c0000
	v_add_u32_e32 v216, 0x4000, v211
	v_subrev_u32_e32 v231, vcc_lo, v214
	v_lshl_add_u64 v[214:215], v[212:213], 0, s[0:1]
	v_readfirstlane_b32 s0, v216
	s_mov_b32 m0, s0
	s_mov_b64 s[0:1], 0x46c1000
	v_add_u32_e32 v211, 0x5000, v211
	v_lshl_add_u64 v[212:213], v[212:213], 0, s[0:1]
	v_readfirstlane_b32 s0, v211
	v_subrev_u32_e32 v232, vcc_lo, v214
	s_mov_b32 m0, s0
	s_nop 0
	v_subrev_u32_e32 v233, vcc_lo, v212
	v_mov_b32_e32 v182, v228
	v_mov_b32_e32 v183, v229
	v_mov_b32_e32 v180, v230
	v_mov_b32_e32 v181, v231
	v_mov_b32_e32 v253, v232
	v_mov_b32_e32 v254, v233
	v_readfirstlane_b32 s0, v185
	s_branch .LBB0_1625

; DEVI int otid() { int t = threadIdx.x; asm volatile("" : "+v"(t)); return t; }
; #define RAW_BARRIER() do { asm volatile("s_waitcnt lgkmcnt(0)" ::: "memory"); __builtin_amdgcn_s_barrier(); } while (0)
; template <int EPI, int NB>
; DEVI void gemm_tile(const GemmJob& J, int m0, int n0, unsigned char* smem) {
;     ...
;   const int tid = otid(), lane = tid & 63, wid = tid >> 6, wm = wid >> 1, wn = wid & 1;
;   const int l16 = lane & 15, g = lane >> 4;
;   f32x4 acc[4][NB];
; #pragma unroll
;   for (int i = 0; i < 4; ++i)
; #pragma unroll
;     for (int j = 0; j < NB; ++j) acc[i][j] = (f32x4){0.f, 0.f, 0.f, 0.f};
;   const int srow = tid >> 2, sch = tid & 3;
;   const int gch = sch ^ ((0 - (tid >> 4)) & 3);
;   const bf16_t* Ag = J.A + (size_t)(m0 + srow) * (J.ablk ? 32 : J.lda) + gch * 8;
;   const bf16_t* Bg = J.Bt + (size_t)(n0 + srow) * 32 + gch * 8;
;   const size_t Astep = (size_t)64 * (J.ablk ? 32 : J.lda), Ak = J.ablk ? (size_t)MROWS * 32 : (size_t)32, Bstep = (size_t)64 * 32, Bk = (size_t)J.NR * 32;
;   const int nk = J.K >> 5;
;   unsigned char* lds_t = smem + tid * 16;
;   const unsigned lbase = (unsigned)(uintptr_t)(__attribute__((address_space(3))) unsigned char*)smem;
;     ...
;   asm volatile("s_waitcnt vmcnt(0)" ::: "memory");
;   RAW_BARRIER();
; #pragma unroll
;   for (int st = 0; st < S - 1; ++st) GEMM_ISSUE(st, st);
;   const int fsl = (g ^ ((0 - (l16 >> 2)) & 3)) << 4;
;   const int aofs = (wm * 64 + l16) * 64 + fsl;
;   const int bofs = A_BYTES + (wn * NB * 16 + l16) * 64 + fsl;
;   int cs = 0, is = S - 1;
; template <int EPI, int NB>
; DEVI void gemm_run(const GemmJob& J, unsigned char* smem, int rot) {
;     ...
;     for (int t = b; t < ntiles; t += G) {
;       const int mt = t / J.ntn, nt = J.nt0 + (t - mt * J.ntn);
;       gemm_tile<EPI, NB>(J, mt * 128, nt * BN, smem);
.LBB0_1749:
	s_lshr_b32 s0, s9, 31
	s_add_i32 s0, s9, s0
	s_ashr_i32 s0, s0, 1
	s_lshl_b32 s3, s0, 7
	s_lshl_b32 s40, s0, 9
	s_lshl_b32 s0, s9, 8
	v_mov_b32_e32 v184, v177
	s_sub_i32 s2, s0, s40
	s_movk_i32 s28, 0x840
	v_ashrrev_i32_e32 v8, 2, v184
	v_lshrrev_b32_e32 v0, 4, v184
	v_sub_u32_e32 v9, 0, v0
	v_add_u32_e32 v4, s2, v8
	v_xor_b32_e32 v0, v184, v9
	v_add_u32_e32 v10, s3, v8
	v_ashrrev_i32_e32 v5, 31, v4
	v_mad_i64_i32 v[2:3], s[0:1], v10, s28, v[170:171]
	v_lshlrev_b32_e32 v0, 4, v0
	v_lshlrev_b64 v[4:5], 6, v[4:5]
	v_lshlrev_b32_e32 v185, 4, v184
	v_and_b32_e32 v0, 48, v0
	v_lshl_add_u64 v[4:5], v[138:139], 0, v[4:5]
	v_readfirstlane_b32 s0, v185
	v_lshl_add_u64 v[2:3], v[2:3], 0, v[0:1]
	v_lshl_add_u64 v[4:5], v[4:5], 0, v[0:1]
	s_mov_b32 m0, s0
	s_mov_b64 s[0:1], 0x21000
	v_add_u32_e32 v0, 0x1000, v185
	s_nop 0
	v_lshl_add_u64 v[6:7], v[2:3], 0, s[0:1]
	v_readfirstlane_b32 s0, v0
	v_add_u32_e32 v0, 0x2000, v185
	s_waitcnt lgkmcnt(0)
	s_barrier
	global_load_lds_dwordx4 v[2:3], off
	s_mov_b32 m0, s0
	v_readfirstlane_b32 s0, v0
	v_add_u32_e32 v0, 0x3000, v185
	global_load_lds_dwordx4 v[6:7], off
	s_mov_b32 m0, s0
	v_readfirstlane_b32 s0, v0
	global_load_lds_dwordx4 v[4:5], off
	v_lshl_add_u64 v[6:7], v[4:5], 0, s[30:31]
	s_mov_b32 m0, s0
	s_mov_b64 s[0:1], 0x2000
	v_add_u32_e32 v0, 0x4000, v185
	global_load_lds_dwordx4 v[6:7], off
	v_lshl_add_u64 v[6:7], v[4:5], 0, s[0:1]
	v_readfirstlane_b32 s0, v0
	s_mov_b32 m0, s0
	s_mov_b64 s[0:1], 0x3000
	v_add_u32_e32 v0, 0x5000, v185
	global_load_lds_dwordx4 v[6:7], off
	v_lshl_add_u64 v[6:7], v[4:5], 0, s[0:1]
	v_readfirstlane_b32 s0, v0
	v_add_u32_e32 v0, 0x6000, v185
	s_mov_b32 m0, s0
	v_readfirstlane_b32 s0, v0
	global_load_lds_dwordx4 v[6:7], off
	s_mov_b32 m0, s0
	s_mov_b64 s[0:1], 0x21040
	v_add_u32_e32 v0, 0x7000, v185
	v_lshl_add_u64 v[6:7], v[2:3], 0, 64
	v_lshl_add_u64 v[2:3], v[2:3], 0, s[0:1]
	v_readfirstlane_b32 s0, v0
	v_add_u32_e32 v0, 0x8000, v185
	global_load_lds_dwordx4 v[6:7], off
	s_mov_b32 m0, s0
	v_readfirstlane_b32 s0, v0
	global_load_lds_dwordx4 v[2:3], off
	v_lshl_add_u64 v[2:3], v[4:5], 0, s[22:23]
	s_mov_b32 m0, s0
	s_mov_b64 s[0:1], 0x11000
	v_add_u32_e32 v0, 0x9000, v185
	global_load_lds_dwordx4 v[2:3], off
	v_lshl_add_u64 v[2:3], v[4:5], 0, s[0:1]
	v_readfirstlane_b32 s0, v0
	s_mov_b32 m0, s0
	s_mov_b64 s[0:1], 0x12000
	v_add_u32_e32 v0, 0xa000, v185
	global_load_lds_dwordx4 v[2:3], off
	v_lshl_add_u64 v[2:3], v[4:5], 0, s[0:1]
	v_readfirstlane_b32 s0, v0
	s_mov_b32 m0, s0
	s_mov_b64 s[0:1], 0x13000
	v_add_u32_e32 v0, 0xb000, v185
	global_load_lds_dwordx4 v[2:3], off
	v_lshl_add_u64 v[2:3], v[4:5], 0, s[0:1]
	v_readfirstlane_b32 s0, v0
	s_mov_b32 m0, s0
	v_lshlrev_b32_e32 v0, 2, v184
	global_load_lds_dwordx4 v[2:3], off
	v_and_b32_e32 v0, 48, v0
	v_ashrrev_i32_e32 v2, 1, v184
	v_and_b32_e32 v186, 15, v184
	v_sub_u32_e32 v0, 0, v0
	v_and_b32_e32 v187, 0xffffffc0, v2
	v_bitop3_b32 v0, v184, 48, v0 bitop3:0x48
	v_or_b32_e32 v2, v187, v186
	v_lshl_or_b32 v209, v2, 6, v0
	v_lshlrev_b32_e32 v2, 1, v184
	v_and_b32_e32 v208, 0x80, v2
	v_or_b32_e32 v2, v208, v186
	v_lshl_or_b32 v0, v2, 6, v0
	v_add_u32_e32 v2, s8, v8
	v_subrev_u32_e32 v2, s40, v2
	v_ashrrev_i32_e32 v3, 31, v2
	v_lshlrev_b64 v[2:3], 6, v[2:3]
	v_add_u32_e32 v210, 0x2000, v0
	v_bitop3_b32 v0, v184, 3, v9 bitop3:0x48
	v_lshl_add_u64 v[180:181], v[130:131], 0, v[2:3]
	v_mov_b32_e32 v2, 0
	s_mov_b32 s42, 2
	s_mov_b32 s20, 0
	v_lshlrev_b32_e32 v0, 4, v0
	v_mad_i64_i32 v[182:183], s[0:1], v10, s28, v[130:131]
	s_mov_b32 s43, 0
	v_mov_b32_e32 v3, v2
	v_mov_b32_e32 v4, v2
	v_mov_b32_e32 v5, v2
	v_mov_b32_e32 v6, v2
	v_mov_b32_e32 v7, v2
	v_mov_b32_e32 v8, v2
	v_mov_b32_e32 v9, v2
	v_mov_b32_e32 v10, v2
	v_mov_b32_e32 v11, v2
	v_mov_b32_e32 v12, v2
	v_mov_b32_e32 v13, v2
	v_mov_b32_e32 v14, v2
	v_mov_b32_e32 v15, v2
	v_mov_b32_e32 v16, v2
	v_mov_b32_e32 v17, v2
	v_mov_b32_e32 v18, v2
	v_mov_b32_e32 v19, v2
	v_mov_b32_e32 v20, v2
	v_mov_b32_e32 v21, v2
	v_mov_b32_e32 v22, v2
	v_mov_b32_e32 v23, v2
	v_mov_b32_e32 v24, v2
	v_mov_b32_e32 v25, v2
	v_mov_b32_e32 v26, v2
; #define RAW_BARRIER() do { asm volatile("s_waitcnt lgkmcnt(0)" ::: "memory"); __builtin_amdgcn_s_barrier(); } while (0)
; template <int EPI, int NB>
; DEVI void gemm_tile(const GemmJob& J, int m0, int n0, unsigned char* smem) {
;     ...
;   f32x4 acc[4][NB];
; #pragma unroll
;   for (int i = 0; i < 4; ++i)
; #pragma unroll
;     for (int j = 0; j < NB; ++j) acc[i][j] = (f32x4){0.f, 0.f, 0.f, 0.f};
;   const int srow = tid >> 2, sch = tid & 3;
;   const int gch = sch ^ ((0 - (tid >> 4)) & 3);
;   const bf16_t* Ag = J.A + (size_t)(m0 + srow) * (J.ablk ? 32 : J.lda) + gch * 8;
;   const bf16_t* Bg = J.Bt + (size_t)(n0 + srow) * 32 + gch * 8;
;   const size_t Astep = (size_t)64 * (J.ablk ? 32 : J.lda), Ak = J.ablk ? (size_t)MROWS * 32 : (size_t)32, Bstep = (size_t)64 * 32, Bk = (size_t)J.NR * 32;
;   const int nk = J.K >> 5;
;   unsigned char* lds_t = smem + tid * 16;
;   const unsigned lbase = (unsigned)(uintptr_t)(__attribute__((address_space(3))) unsigned char*)smem;
;     ...
;   asm volatile("s_waitcnt vmcnt(0)" ::: "memory");
;   RAW_BARRIER();
; #pragma unroll
;   for (int st = 0; st < S - 1; ++st) GEMM_ISSUE(st, st);
;   const int fsl = (g ^ ((0 - (l16 >> 2)) & 3)) << 4;
;   const int aofs = (wm * 64 + l16) * 64 + fsl;
;   const int bofs = A_BYTES + (wn * NB * 16 + l16) * 64 + fsl;
;   int cs = 0, is = S - 1;
; #pragma clang loop unroll(disable)
;   for (int kt = 0; kt < nk; ++kt) {
;     if (nk - 1 - kt >= S - 2) {
;       if constexpr (NB == 8) asm volatile("s_waitcnt vmcnt(6)" ::: "memory");
;       else                   asm volatile("s_waitcnt vmcnt(8)" ::: "memory");
;     } else {
;       asm volatile("s_waitcnt vmcnt(0)" ::: "memory");
;     }
;     RAW_BARRIER();
;     if (kt + S - 1 < nk) GEMM_ISSUE(kt + S - 1, is);
;     is = (is + 1 == S) ? 0 : is + 1;
;     const unsigned cur = lbase + cs * STG;
;     cs = (cs + 1 == S) ? 0 : cs + 1;
	v_mov_b32_e32 v27, v2
	v_mov_b32_e32 v28, v2
	v_mov_b32_e32 v29, v2
	v_mov_b32_e32 v30, v2
	v_mov_b32_e32 v31, v2
	v_mov_b32_e32 v32, v2
	v_mov_b32_e32 v33, v2
	v_mov_b32_e32 v34, v2
	v_mov_b32_e32 v35, v2
	v_mov_b32_e32 v36, v2
	v_mov_b32_e32 v37, v2
	v_mov_b32_e32 v38, v2
	v_mov_b32_e32 v39, v2
	v_mov_b32_e32 v40, v2
	v_mov_b32_e32 v41, v2
	v_mov_b32_e32 v42, v2
	v_mov_b32_e32 v43, v2
	v_mov_b32_e32 v44, v2
	v_mov_b32_e32 v45, v2
	v_mov_b32_e32 v46, v2
	v_mov_b32_e32 v47, v2
	v_mov_b32_e32 v48, v2
	v_mov_b32_e32 v49, v2
	v_mov_b32_e32 v50, v2
	v_mov_b32_e32 v51, v2
	v_mov_b32_e32 v52, v2
	v_mov_b32_e32 v53, v2
	v_mov_b32_e32 v54, v2
	v_mov_b32_e32 v55, v2
	v_mov_b32_e32 v56, v2
	v_mov_b32_e32 v57, v2
	v_mov_b32_e32 v58, v2
	v_mov_b32_e32 v59, v2
	v_mov_b32_e32 v60, v2
	v_mov_b32_e32 v61, v2
	v_mov_b32_e32 v62, v2
	v_mov_b32_e32 v63, v2
	v_mov_b32_e32 v64, v2
	v_mov_b32_e32 v65, v2
	v_mov_b32_e32 v66, v2
	v_mov_b32_e32 v67, v2
	v_mov_b32_e32 v68, v2
	v_mov_b32_e32 v69, v2
	v_mov_b32_e32 v70, v2
	v_mov_b32_e32 v71, v2
	v_mov_b32_e32 v72, v2
	v_mov_b32_e32 v73, v2
	v_mov_b32_e32 v74, v2
	v_mov_b32_e32 v75, v2
	v_mov_b32_e32 v76, v2
	v_mov_b32_e32 v77, v2
	v_mov_b32_e32 v78, v2
	v_mov_b32_e32 v79, v2
	v_mov_b32_e32 v80, v2
	v_mov_b32_e32 v81, v2
	v_mov_b32_e32 v82, v2
	v_mov_b32_e32 v83, v2
	v_mov_b32_e32 v84, v2
	v_mov_b32_e32 v85, v2
	v_mov_b32_e32 v86, v2
	v_mov_b32_e32 v87, v2
	v_mov_b32_e32 v88, v2
	v_mov_b32_e32 v89, v2
	v_mov_b32_e32 v90, v2
	v_mov_b32_e32 v91, v2
	v_mov_b32_e32 v92, v2
	v_mov_b32_e32 v93, v2
	v_mov_b32_e32 v94, v2
	v_mov_b32_e32 v95, v2
	v_mov_b32_e32 v96, v2
	v_mov_b32_e32 v97, v2
	v_mov_b32_e32 v98, v2
	v_mov_b32_e32 v99, v2
	v_mov_b32_e32 v100, v2
	v_mov_b32_e32 v101, v2
	v_mov_b32_e32 v102, v2
	v_mov_b32_e32 v103, v2
	v_mov_b32_e32 v104, v2
	v_mov_b32_e32 v105, v2
	v_mov_b32_e32 v106, v2
	v_mov_b32_e32 v107, v2
	v_mov_b32_e32 v108, v2
	v_mov_b32_e32 v109, v2
	v_mov_b32_e32 v110, v2
	v_mov_b32_e32 v111, v2
	v_mov_b32_e32 v112, v2
	v_mov_b32_e32 v113, v2
	v_mov_b32_e32 v114, v2
	v_mov_b32_e32 v115, v2
	v_mov_b32_e32 v116, v2
	v_mov_b32_e32 v117, v2
	v_mov_b32_e32 v118, v2
	v_mov_b32_e32 v119, v2
	v_mov_b32_e32 v120, v2
	v_mov_b32_e32 v121, v2
	v_mov_b32_e32 v122, v2
	v_mov_b32_e32 v123, v2
	v_mov_b32_e32 v124, v2
	v_mov_b32_e32 v125, v2
	v_mov_b32_e32 v126, v2
	v_mov_b32_e32 v127, v2
	v_mov_b32_e32 v128, v2
	v_mov_b32_e32 v129, v2
	s_mul_i32 s0, s42, 0x6000
	v_add_u32_e32 v211, s0, v185
	v_lshl_add_u64 v[212:213], v[182:183], 0, v[0:1]
	s_mov_b64 s[0:1], 0xb286280
	v_lshl_add_u64 v[214:215], v[212:213], 0, s[0:1]
	v_readfirstlane_b32 s0, v211
	s_mov_b32 m0, s0
	s_mov_b64 s[0:1], 0xb2a7280
	s_nop 0
	v_readfirstlane_b32 s100, v214
	v_readfirstlane_b32 s101, v215
	s_nop 1
	v_subrev_u32_e32 v228, s100, v214
	v_add_u32_e32 v214, 0x1000, v211
	v_lshl_add_u64 v[212:213], v[212:213], 0, s[0:1]
	v_readfirstlane_b32 s0, v214
	s_mov_b32 m0, s0
	s_mov_b64 s[0:1], 0x4726000
	v_subrev_u32_e32 v229, s100, v212
	v_lshl_add_u64 v[212:213], v[180:181], 0, v[0:1]
	v_add_u32_e32 v216, 0x2000, v211
	v_lshl_add_u64 v[214:215], v[212:213], 0, s[0:1]
	v_readfirstlane_b32 s0, v216
	s_mov_b32 m0, s0
	s_mov_b64 s[0:1], 0x4727000
	v_add_u32_e32 v216, 0x3000, v211
	s_nop 0
	v_readfirstlane_b32 vcc_lo, v214
	v_readfirstlane_b32 vcc_hi, v215
	s_nop 1
	v_subrev_u32_e32 v230, vcc_lo, v214
	v_lshl_add_u64 v[214:215], v[212:213], 0, s[0:1]
	v_readfirstlane_b32 s0, v216
	s_mov_b32 m0, s0
	s_mov_b64 s[0:1], 0x4728000
	v_add_u32_e32 v216, 0x4000, v211
	v_subrev_u32_e32 v231, vcc_lo, v214
	v_lshl_add_u64 v[214:215], v[212:213], 0, s[0:1]
	v_readfirstlane_b32 s0, v216
	s_mov_b32 m0, s0
	s_mov_b64 s[0:1], 0x4729000
	v_add_u32_e32 v211, 0x5000, v211
	v_lshl_add_u64 v[212:213], v[212:213], 0, s[0:1]
	v_readfirstlane_b32 s0, v211
	v_subrev_u32_e32 v232, vcc_lo, v214
	s_mov_b32 m0, s0
	s_nop 0
	v_subrev_u32_e32 v233, vcc_lo, v212
	v_mov_b32_e32 v182, v228
	v_mov_b32_e32 v183, v229
	v_mov_b32_e32 v180, v230
	v_mov_b32_e32 v181, v231
	v_mov_b32_e32 v253, v232
	v_mov_b32_e32 v254, v233
	v_readfirstlane_b32 s0, v185
	s_branch .LBB0_1751

; DEVI int otid() { int t = threadIdx.x; asm volatile("" : "+v"(t)); return t; }
; #define RAW_BARRIER() do { asm volatile("s_waitcnt lgkmcnt(0)" ::: "memory"); __builtin_amdgcn_s_barrier(); } while (0)
; template <int EPI, int NB>
; DEVI void gemm_tile(const GemmJob& J, int m0, int n0, unsigned char* smem) {
;     ...
;   const int tid = otid(), lane = tid & 63, wid = tid >> 6, wm = wid >> 1, wn = wid & 1;
;   const int l16 = lane & 15, g = lane >> 4;
;   f32x4 acc[4][NB];
; #pragma unroll
;   for (int i = 0; i < 4; ++i)
; #pragma unroll
;     for (int j = 0; j < NB; ++j) acc[i][j] = (f32x4){0.f, 0.f, 0.f, 0.f};
;   const int srow = tid >> 2, sch = tid & 3;
;   const int gch = sch ^ ((0 - (tid >> 4)) & 3);
;   const bf16_t* Ag = J.A + (size_t)(m0 + srow) * (J.ablk ? 32 : J.lda) + gch * 8;
;   const bf16_t* Bg = J.Bt + (size_t)(n0 + srow) * 32 + gch * 8;
;   const size_t Astep = (size_t)64 * (J.ablk ? 32 : J.lda), Ak = J.ablk ? (size_t)MROWS * 32 : (size_t)32, Bstep = (size_t)64 * 32, Bk = (size_t)J.NR * 32;
;   const int nk = J.K >> 5;
;   unsigned char* lds_t = smem + tid * 16;
;   const unsigned lbase = (unsigned)(uintptr_t)(__attribute__((address_space(3))) unsigned char*)smem;
;     ...
;   asm volatile("s_waitcnt vmcnt(0)" ::: "memory");
;   RAW_BARRIER();
; #pragma unroll
;   for (int st = 0; st < S - 1; ++st) GEMM_ISSUE(st, st);
;   const int fsl = (g ^ ((0 - (l16 >> 2)) & 3)) << 4;
;   const int aofs = (wm * 64 + l16) * 64 + fsl;
;   const int bofs = A_BYTES + (wn * NB * 16 + l16) * 64 + fsl;
;   int cs = 0, is = S - 1;
; template <int EPI, int NB>
; DEVI void gemm_run(const GemmJob& J, unsigned char* smem, int rot) {
;     ...
;     for (int q0 = lb; q0 < ntot; q0 += nlb) {
;       const int q = J.rev ? ntot - 1 - q0 : q0;
;       int grp = q / gsz; const int qq = q - grp * gsz;
;       const int mg = min(8, mcnt - grp * 8);
;       const int nt = qq / mg, mi = qq - nt * mg;
;       gemm_tile<EPI, NB>(J, (mlo + grp * 8 + mi) * 128, (J.nt0 + nt) * BN, smem);
.LBB0_1822:
	s_mul_hi_i32 s0, s9, 0x2aaaaaab
	s_lshr_b32 s1, s0, 31
	s_ashr_i32 s0, s0, 2
	s_add_i32 s40, s0, s1
	s_lshl_b32 s0, s40, 3
	v_readlane_b32 s1, v251, 48
	s_sub_i32 s1, s1, s0
	s_min_i32 s1, s1, 8
	s_abs_i32 s2, s1
	v_cvt_f32_u32_e32 v0, s2
	s_sub_i32 s44, 0, s2
	s_mul_i32 s20, s40, 0xffffffe8
	s_add_i32 s20, s20, s9
	v_rcp_iflag_f32_e32 v0, v0
	s_abs_i32 s41, s20
	s_xor_b32 s43, s20, s1
	s_ashr_i32 s43, s43, 31
	v_mul_f32_e32 v0, 0x4f7ffffe, v0
	v_cvt_u32_f32_e32 v0, v0
	v_mov_b32_e32 v184, v177
	s_movk_i32 s28, 0x840
	v_readfirstlane_b32 s45, v0
	s_mul_i32 s44, s44, s45
	s_mul_hi_u32 s44, s45, s44
	s_add_i32 s45, s45, s44
	s_mul_hi_u32 s44, s41, s45
	s_mul_i32 s45, s44, s2
	s_sub_i32 s41, s41, s45
	s_add_i32 s45, s44, 1
	s_sub_i32 s46, s41, s2
	s_cmp_ge_u32 s41, s2
	s_cselect_b32 s44, s45, s44
	s_cselect_b32 s41, s46, s41
	s_add_i32 s45, s44, 1
	s_cmp_ge_u32 s41, s2
	s_cselect_b32 s2, s45, s44
	s_xor_b32 s2, s2, s43
	s_sub_i32 s2, s2, s43
	s_mul_i32 s41, s1, s2
	v_readlane_b32 s1, v250, 37
	s_add_i32 s0, s0, s1
	s_add_i32 s0, s0, s20
	s_sub_i32 s0, s0, s41
	s_lshl_b32 s2, s2, 8
	v_ashrrev_i32_e32 v10, 2, v184
	v_lshrrev_b32_e32 v0, 4, v184
	s_lshl_b32 s20, s0, 7
	v_sub_u32_e32 v11, 0, v0
	v_add_u32_e32 v4, s2, v10
	v_xor_b32_e32 v0, v184, v11
	v_add_u32_e32 v2, s20, v10
	v_ashrrev_i32_e32 v5, 31, v4
	v_mad_i64_i32 v[2:3], s[0:1], v2, s28, v[152:153]
	v_lshlrev_b32_e32 v0, 4, v0
	v_lshlrev_b64 v[4:5], 6, v[4:5]
	v_lshlrev_b32_e32 v185, 4, v184
	v_and_b32_e32 v0, 48, v0
	v_lshl_add_u64 v[6:7], v[136:137], 0, v[4:5]
	v_readfirstlane_b32 s0, v185
	v_lshl_add_u64 v[2:3], v[2:3], 0, v[0:1]
	v_lshl_add_u64 v[6:7], v[6:7], 0, v[0:1]
	s_mov_b32 m0, s0
	s_mov_b64 s[0:1], 0x21000
	v_add_u32_e32 v0, 0x1000, v185
	s_nop 0
	v_lshl_add_u64 v[8:9], v[2:3], 0, s[0:1]
	v_readfirstlane_b32 s0, v0
	v_add_u32_e32 v0, 0x2000, v185
	s_waitcnt lgkmcnt(0)
	s_barrier
	global_load_lds_dwordx4 v[2:3], off
	s_mov_b32 m0, s0
	v_readfirstlane_b32 s0, v0
	v_add_u32_e32 v0, 0x3000, v185
	global_load_lds_dwordx4 v[8:9], off
	s_mov_b32 m0, s0
	v_readfirstlane_b32 s0, v0
	global_load_lds_dwordx4 v[6:7], off
	v_lshl_add_u64 v[8:9], v[6:7], 0, s[30:31]
	s_mov_b32 m0, s0
	s_mov_b64 s[0:1], 0x2000
	v_add_u32_e32 v0, 0x4000, v185
	global_load_lds_dwordx4 v[8:9], off
	v_lshl_add_u64 v[8:9], v[6:7], 0, s[0:1]
	v_readfirstlane_b32 s0, v0
	s_mov_b32 m0, s0
	s_mov_b64 s[0:1], 0x3000
	v_add_u32_e32 v0, 0x5000, v185
	global_load_lds_dwordx4 v[8:9], off
	v_lshl_add_u64 v[8:9], v[6:7], 0, s[0:1]
	v_readfirstlane_b32 s0, v0
	v_add_u32_e32 v0, 0x6000, v185
	s_mov_b32 m0, s0
	v_readfirstlane_b32 s0, v0
	global_load_lds_dwordx4 v[8:9], off
	s_mov_b32 m0, s0
	s_mov_b64 s[0:1], 0x21040
	v_add_u32_e32 v0, 0x7000, v185
	v_lshl_add_u64 v[8:9], v[2:3], 0, 64
	v_lshl_add_u64 v[2:3], v[2:3], 0, s[0:1]
	v_readfirstlane_b32 s0, v0
	v_add_u32_e32 v0, 0x8000, v185
	global_load_lds_dwordx4 v[8:9], off
	s_mov_b32 m0, s0
	v_readfirstlane_b32 s0, v0
	global_load_lds_dwordx4 v[2:3], off
	v_lshl_add_u64 v[2:3], v[6:7], 0, s[86:87]
	s_mov_b32 m0, s0
	s_mov_b64 s[0:1], 0xd000
	v_add_u32_e32 v0, 0x9000, v185
	global_load_lds_dwordx4 v[2:3], off
	v_lshl_add_u64 v[2:3], v[6:7], 0, s[0:1]
	v_readfirstlane_b32 s0, v0
	s_mov_b32 m0, s0
	s_mov_b64 s[0:1], 0xe000
	v_add_u32_e32 v0, 0xa000, v185
	global_load_lds_dwordx4 v[2:3], off
	v_lshl_add_u64 v[2:3], v[6:7], 0, s[0:1]
	v_readfirstlane_b32 s0, v0
	s_mov_b32 m0, s0
	s_mov_b64 s[0:1], 0xf000
	v_add_u32_e32 v0, 0xb000, v185
	global_load_lds_dwordx4 v[2:3], off
	v_lshl_add_u64 v[2:3], v[6:7], 0, s[0:1]
	v_readfirstlane_b32 s0, v0
	s_mov_b32 m0, s0
	v_lshlrev_b32_e32 v0, 2, v184
	global_load_lds_dwordx4 v[2:3], off
	v_and_b32_e32 v0, 48, v0
	v_ashrrev_i32_e32 v2, 1, v184
	v_and_b32_e32 v187, 15, v184
	v_sub_u32_e32 v0, 0, v0
	v_and_b32_e32 v208, 0xffffffc0, v2
	v_bitop3_b32 v0, v184, 48, v0 bitop3:0x48
	v_or_b32_e32 v2, v208, v187
	v_lshl_or_b32 v209, v2, 6, v0
	v_lshlrev_b32_e32 v2, 1, v184
	v_and_b32_e32 v186, 0x80, v2
	s_sub_i32 s0, s8, s41
	s_lshl_b32 s1, s40, 4
	v_or_b32_e32 v2, v186, v187
	s_sub_i32 s0, s0, s1
	v_lshl_or_b32 v0, v2, 6, v0
	v_lshl_add_u32 v2, s0, 7, v10
	v_add_u32_e32 v210, 0x2000, v0
	v_bitop3_b32 v0, v184, 3, v11 bitop3:0x48
	v_mad_i64_i32 v[182:183], s[0:1], v2, s28, v[130:131]
	v_mov_b32_e32 v2, 0
	s_mov_b32 s42, 2
	s_mov_b32 s3, 0
	v_lshlrev_b32_e32 v0, 4, v0
	v_lshl_add_u64 v[180:181], v[130:131], 0, v[4:5]
	s_mov_b32 s43, 0
	v_mov_b32_e32 v3, v2
	v_mov_b32_e32 v4, v2
	v_mov_b32_e32 v5, v2
	v_mov_b32_e32 v6, v2
	v_mov_b32_e32 v7, v2
; #define RAW_BARRIER() do { asm volatile("s_waitcnt lgkmcnt(0)" ::: "memory"); __builtin_amdgcn_s_barrier(); } while (0)
; template <int EPI, int NB>
; DEVI void gemm_tile(const GemmJob& J, int m0, int n0, unsigned char* smem) {
;     ...
;   f32x4 acc[4][NB];
; #pragma unroll
;   for (int i = 0; i < 4; ++i)
; #pragma unroll
;     for (int j = 0; j < NB; ++j) acc[i][j] = (f32x4){0.f, 0.f, 0.f, 0.f};
;   const int srow = tid >> 2, sch = tid & 3;
;   const int gch = sch ^ ((0 - (tid >> 4)) & 3);
;   const bf16_t* Ag = J.A + (size_t)(m0 + srow) * (J.ablk ? 32 : J.lda) + gch * 8;
;   const bf16_t* Bg = J.Bt + (size_t)(n0 + srow) * 32 + gch * 8;
;   const size_t Astep = (size_t)64 * (J.ablk ? 32 : J.lda), Ak = J.ablk ? (size_t)MROWS * 32 : (size_t)32, Bstep = (size_t)64 * 32, Bk = (size_t)J.NR * 32;
;   const int nk = J.K >> 5;
;   unsigned char* lds_t = smem + tid * 16;
;   const unsigned lbase = (unsigned)(uintptr_t)(__attribute__((address_space(3))) unsigned char*)smem;
;     ...
;   asm volatile("s_waitcnt vmcnt(0)" ::: "memory");
;   RAW_BARRIER();
; #pragma unroll
;   for (int st = 0; st < S - 1; ++st) GEMM_ISSUE(st, st);
;   const int fsl = (g ^ ((0 - (l16 >> 2)) & 3)) << 4;
;   const int aofs = (wm * 64 + l16) * 64 + fsl;
;   const int bofs = A_BYTES + (wn * NB * 16 + l16) * 64 + fsl;
;   int cs = 0, is = S - 1;
; #pragma clang loop unroll(disable)
;   for (int kt = 0; kt < nk; ++kt) {
;     if (nk - 1 - kt >= S - 2) {
;       if constexpr (NB == 8) asm volatile("s_waitcnt vmcnt(6)" ::: "memory");
;       else                   asm volatile("s_waitcnt vmcnt(8)" ::: "memory");
;     } else {
;       asm volatile("s_waitcnt vmcnt(0)" ::: "memory");
;     }
;     RAW_BARRIER();
;     if (kt + S - 1 < nk) GEMM_ISSUE(kt + S - 1, is);
;     is = (is + 1 == S) ? 0 : is + 1;
;     const unsigned cur = lbase + cs * STG;
;     cs = (cs + 1 == S) ? 0 : cs + 1;
	v_mov_b32_e32 v8, v2
	v_mov_b32_e32 v9, v2
	v_mov_b32_e32 v10, v2
	v_mov_b32_e32 v11, v2
	v_mov_b32_e32 v12, v2
	v_mov_b32_e32 v13, v2
	v_mov_b32_e32 v14, v2
	v_mov_b32_e32 v15, v2
	v_mov_b32_e32 v16, v2
	v_mov_b32_e32 v17, v2
	v_mov_b32_e32 v18, v2
	v_mov_b32_e32 v19, v2
	v_mov_b32_e32 v20, v2
	v_mov_b32_e32 v21, v2
	v_mov_b32_e32 v22, v2
	v_mov_b32_e32 v23, v2
	v_mov_b32_e32 v24, v2
	v_mov_b32_e32 v25, v2
	v_mov_b32_e32 v26, v2
	v_mov_b32_e32 v27, v2
	v_mov_b32_e32 v28, v2
	v_mov_b32_e32 v29, v2
	v_mov_b32_e32 v30, v2
	v_mov_b32_e32 v31, v2
	v_mov_b32_e32 v32, v2
	v_mov_b32_e32 v33, v2
	v_mov_b32_e32 v34, v2
	v_mov_b32_e32 v35, v2
	v_mov_b32_e32 v36, v2
	v_mov_b32_e32 v37, v2
	v_mov_b32_e32 v38, v2
	v_mov_b32_e32 v39, v2
	v_mov_b32_e32 v40, v2
	v_mov_b32_e32 v41, v2
	v_mov_b32_e32 v42, v2
	v_mov_b32_e32 v43, v2
	v_mov_b32_e32 v44, v2
	v_mov_b32_e32 v45, v2
	v_mov_b32_e32 v46, v2
	v_mov_b32_e32 v47, v2
	v_mov_b32_e32 v48, v2
	v_mov_b32_e32 v49, v2
	v_mov_b32_e32 v50, v2
	v_mov_b32_e32 v51, v2
	v_mov_b32_e32 v52, v2
	v_mov_b32_e32 v53, v2
	v_mov_b32_e32 v54, v2
	v_mov_b32_e32 v55, v2
	v_mov_b32_e32 v56, v2
	v_mov_b32_e32 v57, v2
	v_mov_b32_e32 v58, v2
	v_mov_b32_e32 v59, v2
	v_mov_b32_e32 v60, v2
	v_mov_b32_e32 v61, v2
	v_mov_b32_e32 v62, v2
	v_mov_b32_e32 v63, v2
	v_mov_b32_e32 v64, v2
	v_mov_b32_e32 v65, v2
	v_mov_b32_e32 v66, v2
	v_mov_b32_e32 v67, v2
	v_mov_b32_e32 v68, v2
	v_mov_b32_e32 v69, v2
	v_mov_b32_e32 v70, v2
	v_mov_b32_e32 v71, v2
	v_mov_b32_e32 v72, v2
	v_mov_b32_e32 v73, v2
	v_mov_b32_e32 v74, v2
	v_mov_b32_e32 v75, v2
	v_mov_b32_e32 v76, v2
	v_mov_b32_e32 v77, v2
	v_mov_b32_e32 v78, v2
	v_mov_b32_e32 v79, v2
	v_mov_b32_e32 v80, v2
	v_mov_b32_e32 v81, v2
	v_mov_b32_e32 v82, v2
	v_mov_b32_e32 v83, v2
	v_mov_b32_e32 v84, v2
	v_mov_b32_e32 v85, v2
	v_mov_b32_e32 v86, v2
	v_mov_b32_e32 v87, v2
	v_mov_b32_e32 v88, v2
	v_mov_b32_e32 v89, v2
	v_mov_b32_e32 v90, v2
	v_mov_b32_e32 v91, v2
	v_mov_b32_e32 v92, v2
	v_mov_b32_e32 v93, v2
	v_mov_b32_e32 v94, v2
	v_mov_b32_e32 v95, v2
	v_mov_b32_e32 v96, v2
	v_mov_b32_e32 v97, v2
	v_mov_b32_e32 v98, v2
	v_mov_b32_e32 v99, v2
	v_mov_b32_e32 v100, v2
	v_mov_b32_e32 v101, v2
	v_mov_b32_e32 v102, v2
	v_mov_b32_e32 v103, v2
	v_mov_b32_e32 v104, v2
	v_mov_b32_e32 v105, v2
	v_mov_b32_e32 v106, v2
	v_mov_b32_e32 v107, v2
	v_mov_b32_e32 v108, v2
	v_mov_b32_e32 v109, v2
	v_mov_b32_e32 v110, v2
	v_mov_b32_e32 v111, v2
	v_mov_b32_e32 v112, v2
	v_mov_b32_e32 v113, v2
	v_mov_b32_e32 v114, v2
	v_mov_b32_e32 v115, v2
	v_mov_b32_e32 v116, v2
	v_mov_b32_e32 v117, v2
	v_mov_b32_e32 v118, v2
	v_mov_b32_e32 v119, v2
	v_mov_b32_e32 v120, v2
	v_mov_b32_e32 v121, v2
	v_mov_b32_e32 v122, v2
	v_mov_b32_e32 v123, v2
	v_mov_b32_e32 v124, v2
	v_mov_b32_e32 v125, v2
	v_mov_b32_e32 v126, v2
	v_mov_b32_e32 v127, v2
	v_mov_b32_e32 v128, v2
	v_mov_b32_e32 v129, v2
	s_mul_i32 s0, s42, 0x6000
	v_add_u32_e32 v211, s0, v185
	v_lshl_add_u64 v[212:213], v[182:183], 0, v[0:1]
	s_mov_b64 s[0:1], 0xb286080
	v_lshl_add_u64 v[214:215], v[212:213], 0, s[0:1]
	v_readfirstlane_b32 s0, v211
	s_mov_b32 m0, s0
	s_mov_b64 s[0:1], 0xb2a7080
	s_nop 0
	v_readfirstlane_b32 s100, v214
	v_readfirstlane_b32 s101, v215
	s_nop 1
	v_subrev_u32_e32 v228, s100, v214
	v_add_u32_e32 v214, 0x1000, v211
	v_lshl_add_u64 v[212:213], v[212:213], 0, s[0:1]
	v_readfirstlane_b32 s0, v214
	s_mov_b32 m0, s0
	s_mov_b64 s[0:1], 0x46be000
	v_subrev_u32_e32 v229, s100, v212
	v_lshl_add_u64 v[212:213], v[180:181], 0, v[0:1]
	v_add_u32_e32 v216, 0x2000, v211
	v_lshl_add_u64 v[214:215], v[212:213], 0, s[0:1]
	v_readfirstlane_b32 s0, v216
	s_mov_b32 m0, s0
	s_mov_b64 s[0:1], 0x46bf000
	v_add_u32_e32 v216, 0x3000, v211
	s_nop 0
	v_readfirstlane_b32 vcc_lo, v214
	v_readfirstlane_b32 vcc_hi, v215
	s_nop 1
	v_subrev_u32_e32 v230, vcc_lo, v214
	v_lshl_add_u64 v[214:215], v[212:213], 0, s[0:1]
	v_readfirstlane_b32 s0, v216
	s_mov_b32 m0, s0
	s_mov_b64 s[0:1], 0x46c0000
	v_add_u32_e32 v216, 0x4000, v211
	v_subrev_u32_e32 v231, vcc_lo, v214
	v_lshl_add_u64 v[214:215], v[212:213], 0, s[0:1]
	v_readfirstlane_b32 s0, v216
	s_mov_b32 m0, s0
	s_mov_b64 s[0:1], 0x46c1000
	v_add_u32_e32 v211, 0x5000, v211
	v_lshl_add_u64 v[212:213], v[212:213], 0, s[0:1]
	v_readfirstlane_b32 s0, v211
	v_subrev_u32_e32 v232, vcc_lo, v214
	s_mov_b32 m0, s0
	s_nop 0
	v_subrev_u32_e32 v233, vcc_lo, v212
	v_mov_b32_e32 v182, v228
	v_mov_b32_e32 v183, v229
	v_mov_b32_e32 v180, v230
	v_mov_b32_e32 v181, v231
	v_mov_b32_e32 v253, v232
	v_mov_b32_e32 v254, v233
	v_readfirstlane_b32 s0, v185
	s_branch .LBB0_1824

; DEVI int otid() { int t = threadIdx.x; asm volatile("" : "+v"(t)); return t; }
; #define RAW_BARRIER() do { asm volatile("s_waitcnt lgkmcnt(0)" ::: "memory"); __builtin_amdgcn_s_barrier(); } while (0)
; template <int EPI, int NB>
; DEVI void gemm_tile(const GemmJob& J, int m0, int n0, unsigned char* smem) {
;     ...
;   const int tid = otid(), lane = tid & 63, wid = tid >> 6, wm = wid >> 1, wn = wid & 1;
;   const int l16 = lane & 15, g = lane >> 4;
;   f32x4 acc[4][NB];
; #pragma unroll
;   for (int i = 0; i < 4; ++i)
; #pragma unroll
;     for (int j = 0; j < NB; ++j) acc[i][j] = (f32x4){0.f, 0.f, 0.f, 0.f};
;   const int srow = tid >> 2, sch = tid & 3;
;   const int gch = sch ^ ((0 - (tid >> 4)) & 3);
;   const bf16_t* Ag = J.A + (size_t)(m0 + srow) * (J.ablk ? 32 : J.lda) + gch * 8;
;   const bf16_t* Bg = J.Bt + (size_t)(n0 + srow) * 32 + gch * 8;
;   const size_t Astep = (size_t)64 * (J.ablk ? 32 : J.lda), Ak = J.ablk ? (size_t)MROWS * 32 : (size_t)32, Bstep = (size_t)64 * 32, Bk = (size_t)J.NR * 32;
;   const int nk = J.K >> 5;
;   unsigned char* lds_t = smem + tid * 16;
;   const unsigned lbase = (unsigned)(uintptr_t)(__attribute__((address_space(3))) unsigned char*)smem;
;     ...
;   asm volatile("s_waitcnt vmcnt(0)" ::: "memory");
;   RAW_BARRIER();
; #pragma unroll
;   for (int st = 0; st < S - 1; ++st) GEMM_ISSUE(st, st);
;   const int fsl = (g ^ ((0 - (l16 >> 2)) & 3)) << 4;
;   const int aofs = (wm * 64 + l16) * 64 + fsl;
;   const int bofs = A_BYTES + (wn * NB * 16 + l16) * 64 + fsl;
;   int cs = 0, is = S - 1;
; template <int EPI, int NB>
; DEVI void gemm_run(const GemmJob& J, unsigned char* smem, int rot) {
;     ...
;     for (int t = b; t < ntiles; t += G) {
;       const int mt = t / J.ntn, nt = J.nt0 + (t - mt * J.ntn);
;       gemm_tile<EPI, NB>(J, mt * 128, nt * BN, smem);
.LBB0_1948:
	s_lshr_b32 s0, s9, 31
	s_add_i32 s0, s9, s0
	s_ashr_i32 s0, s0, 1
	s_lshl_b32 s1, s9, 8
	s_lshl_b32 s40, s0, 9
	s_sub_i32 s2, s1, s40
	v_mov_b32_e32 v184, v177
	s_addk_i32 s2, 0x200
	s_lshl_b32 s3, s0, 7
	v_ashrrev_i32_e32 v8, 2, v184
	v_lshrrev_b32_e32 v0, 4, v184
	v_sub_u32_e32 v9, 0, v0
	v_add_u32_e32 v4, s2, v8
	v_xor_b32_e32 v0, v184, v9
	v_add_u32_e32 v10, s3, v8
	s_movk_i32 s28, 0x840
	v_ashrrev_i32_e32 v5, 31, v4
	v_mad_i64_i32 v[2:3], s[0:1], v10, s28, v[170:171]
	v_lshlrev_b32_e32 v0, 4, v0
	v_lshlrev_b64 v[4:5], 6, v[4:5]
	v_lshlrev_b32_e32 v185, 4, v184
	v_and_b32_e32 v0, 48, v0
	v_lshl_add_u64 v[4:5], v[138:139], 0, v[4:5]
	v_readfirstlane_b32 s0, v185
	v_lshl_add_u64 v[2:3], v[2:3], 0, v[0:1]
	v_lshl_add_u64 v[4:5], v[4:5], 0, v[0:1]
	s_mov_b32 m0, s0
	s_mov_b64 s[0:1], 0x21000
	v_add_u32_e32 v0, 0x1000, v185
	s_nop 0
	v_lshl_add_u64 v[6:7], v[2:3], 0, s[0:1]
	v_readfirstlane_b32 s0, v0
	v_add_u32_e32 v0, 0x2000, v185
	s_waitcnt lgkmcnt(0)
	s_barrier
	global_load_lds_dwordx4 v[2:3], off
	s_mov_b32 m0, s0
	v_readfirstlane_b32 s0, v0
	v_add_u32_e32 v0, 0x3000, v185
	global_load_lds_dwordx4 v[6:7], off
	s_mov_b32 m0, s0
	v_readfirstlane_b32 s0, v0
	global_load_lds_dwordx4 v[4:5], off
	v_lshl_add_u64 v[6:7], v[4:5], 0, s[30:31]
	s_mov_b32 m0, s0
	s_mov_b64 s[0:1], 0x2000
	v_add_u32_e32 v0, 0x4000, v185
	global_load_lds_dwordx4 v[6:7], off
	v_lshl_add_u64 v[6:7], v[4:5], 0, s[0:1]
	v_readfirstlane_b32 s0, v0
	s_mov_b32 m0, s0
	s_mov_b64 s[0:1], 0x3000
	v_add_u32_e32 v0, 0x5000, v185
	global_load_lds_dwordx4 v[6:7], off
	v_lshl_add_u64 v[6:7], v[4:5], 0, s[0:1]
	v_readfirstlane_b32 s0, v0
	v_add_u32_e32 v0, 0x6000, v185
	s_mov_b32 m0, s0
	v_readfirstlane_b32 s0, v0
	global_load_lds_dwordx4 v[6:7], off
	s_mov_b32 m0, s0
	s_mov_b64 s[0:1], 0x21040
	v_add_u32_e32 v0, 0x7000, v185
	v_lshl_add_u64 v[6:7], v[2:3], 0, 64
	v_lshl_add_u64 v[2:3], v[2:3], 0, s[0:1]
	v_readfirstlane_b32 s0, v0
	v_add_u32_e32 v0, 0x8000, v185
	global_load_lds_dwordx4 v[6:7], off
	s_mov_b32 m0, s0
	v_readfirstlane_b32 s0, v0
	global_load_lds_dwordx4 v[2:3], off
	v_lshl_add_u64 v[2:3], v[4:5], 0, s[22:23]
	s_mov_b32 m0, s0
	s_mov_b64 s[0:1], 0x11000
	v_add_u32_e32 v0, 0x9000, v185
	global_load_lds_dwordx4 v[2:3], off
	v_lshl_add_u64 v[2:3], v[4:5], 0, s[0:1]
	v_readfirstlane_b32 s0, v0
	s_mov_b32 m0, s0
	s_mov_b64 s[0:1], 0x12000
	v_add_u32_e32 v0, 0xa000, v185
	global_load_lds_dwordx4 v[2:3], off
	v_lshl_add_u64 v[2:3], v[4:5], 0, s[0:1]
	v_readfirstlane_b32 s0, v0
	s_mov_b32 m0, s0
	s_mov_b64 s[0:1], 0x13000
	v_add_u32_e32 v0, 0xb000, v185
	global_load_lds_dwordx4 v[2:3], off
	v_lshl_add_u64 v[2:3], v[4:5], 0, s[0:1]
	v_readfirstlane_b32 s0, v0
	s_mov_b32 m0, s0
	v_and_b32_e32 v0, 15, v184
	global_load_lds_dwordx4 v[2:3], off
	v_lshlrev_b32_e32 v2, 2, v184
	v_and_b32_e32 v2, 48, v2
	v_ashrrev_i32_e32 v3, 1, v184
	v_sub_u32_e32 v2, 0, v2
	v_and_b32_e32 v187, 0xffffffc0, v3
	v_bitop3_b32 v2, v184, 48, v2 bitop3:0x48
	v_or_b32_e32 v3, v187, v0
	v_lshl_or_b32 v208, v3, 6, v2
	v_lshlrev_b32_e32 v3, 1, v184
	s_movk_i32 s0, 0x80
	v_and_or_b32 v186, v3, s0, v0
	v_lshl_or_b32 v0, v186, 6, v2
	v_add_u32_e32 v2, s8, v8
	v_subrev_u32_e32 v2, s40, v2
	v_ashrrev_i32_e32 v3, 31, v2
	v_lshlrev_b64 v[2:3], 6, v[2:3]
	v_add_u32_e32 v209, 0x2000, v0
	v_bitop3_b32 v0, v184, 3, v9 bitop3:0x48
	v_lshl_add_u64 v[180:181], v[130:131], 0, v[2:3]
	v_mov_b32_e32 v2, 0
	s_mov_b32 s42, 2
	s_mov_b32 s20, 0
	v_lshlrev_b32_e32 v0, 4, v0
	v_mad_i64_i32 v[182:183], s[0:1], v10, s28, v[130:131]
	s_mov_b32 s43, 0
	v_mov_b32_e32 v3, v2
	v_mov_b32_e32 v4, v2
	v_mov_b32_e32 v5, v2
	v_mov_b32_e32 v6, v2
	v_mov_b32_e32 v7, v2
	v_mov_b32_e32 v8, v2
	v_mov_b32_e32 v9, v2
	v_mov_b32_e32 v10, v2
	v_mov_b32_e32 v11, v2
	v_mov_b32_e32 v12, v2
	v_mov_b32_e32 v13, v2
	v_mov_b32_e32 v14, v2
	v_mov_b32_e32 v15, v2
	v_mov_b32_e32 v16, v2
	v_mov_b32_e32 v17, v2
	v_mov_b32_e32 v18, v2
	v_mov_b32_e32 v19, v2
	v_mov_b32_e32 v20, v2
	v_mov_b32_e32 v21, v2
	v_mov_b32_e32 v22, v2
	v_mov_b32_e32 v23, v2
	v_mov_b32_e32 v24, v2
	v_mov_b32_e32 v25, v2
	v_mov_b32_e32 v26, v2
; #define RAW_BARRIER() do { asm volatile("s_waitcnt lgkmcnt(0)" ::: "memory"); __builtin_amdgcn_s_barrier(); } while (0)
; template <int EPI, int NB>
; DEVI void gemm_tile(const GemmJob& J, int m0, int n0, unsigned char* smem) {
;     ...
;   f32x4 acc[4][NB];
; #pragma unroll
;   for (int i = 0; i < 4; ++i)
; #pragma unroll
;     for (int j = 0; j < NB; ++j) acc[i][j] = (f32x4){0.f, 0.f, 0.f, 0.f};
;   const int srow = tid >> 2, sch = tid & 3;
;   const int gch = sch ^ ((0 - (tid >> 4)) & 3);
;   const bf16_t* Ag = J.A + (size_t)(m0 + srow) * (J.ablk ? 32 : J.lda) + gch * 8;
;   const bf16_t* Bg = J.Bt + (size_t)(n0 + srow) * 32 + gch * 8;
;   const size_t Astep = (size_t)64 * (J.ablk ? 32 : J.lda), Ak = J.ablk ? (size_t)MROWS * 32 : (size_t)32, Bstep = (size_t)64 * 32, Bk = (size_t)J.NR * 32;
;   const int nk = J.K >> 5;
;   unsigned char* lds_t = smem + tid * 16;
;   const unsigned lbase = (unsigned)(uintptr_t)(__attribute__((address_space(3))) unsigned char*)smem;
;     ...
;   asm volatile("s_waitcnt vmcnt(0)" ::: "memory");
;   RAW_BARRIER();
; #pragma unroll
;   for (int st = 0; st < S - 1; ++st) GEMM_ISSUE(st, st);
;   const int fsl = (g ^ ((0 - (l16 >> 2)) & 3)) << 4;
;   const int aofs = (wm * 64 + l16) * 64 + fsl;
;   const int bofs = A_BYTES + (wn * NB * 16 + l16) * 64 + fsl;
;   int cs = 0, is = S - 1;
; #pragma clang loop unroll(disable)
;   for (int kt = 0; kt < nk; ++kt) {
;     if (nk - 1 - kt >= S - 2) {
;       if constexpr (NB == 8) asm volatile("s_waitcnt vmcnt(6)" ::: "memory");
;       else                   asm volatile("s_waitcnt vmcnt(8)" ::: "memory");
;     } else {
;       asm volatile("s_waitcnt vmcnt(0)" ::: "memory");
;     }
;     RAW_BARRIER();
;     if (kt + S - 1 < nk) GEMM_ISSUE(kt + S - 1, is);
;     is = (is + 1 == S) ? 0 : is + 1;
;     const unsigned cur = lbase + cs * STG;
;     cs = (cs + 1 == S) ? 0 : cs + 1;
	v_mov_b32_e32 v27, v2
	v_mov_b32_e32 v28, v2
	v_mov_b32_e32 v29, v2
	v_mov_b32_e32 v30, v2
	v_mov_b32_e32 v31, v2
	v_mov_b32_e32 v32, v2
	v_mov_b32_e32 v33, v2
	v_mov_b32_e32 v34, v2
	v_mov_b32_e32 v35, v2
	v_mov_b32_e32 v36, v2
	v_mov_b32_e32 v37, v2
	v_mov_b32_e32 v38, v2
	v_mov_b32_e32 v39, v2
	v_mov_b32_e32 v40, v2
	v_mov_b32_e32 v41, v2
	v_mov_b32_e32 v42, v2
	v_mov_b32_e32 v43, v2
	v_mov_b32_e32 v44, v2
	v_mov_b32_e32 v45, v2
	v_mov_b32_e32 v46, v2
	v_mov_b32_e32 v47, v2
	v_mov_b32_e32 v48, v2
	v_mov_b32_e32 v49, v2
	v_mov_b32_e32 v50, v2
	v_mov_b32_e32 v51, v2
	v_mov_b32_e32 v52, v2
	v_mov_b32_e32 v53, v2
	v_mov_b32_e32 v54, v2
	v_mov_b32_e32 v55, v2
	v_mov_b32_e32 v56, v2
	v_mov_b32_e32 v57, v2
	v_mov_b32_e32 v58, v2
	v_mov_b32_e32 v59, v2
	v_mov_b32_e32 v60, v2
	v_mov_b32_e32 v61, v2
	v_mov_b32_e32 v62, v2
	v_mov_b32_e32 v63, v2
	v_mov_b32_e32 v64, v2
	v_mov_b32_e32 v65, v2
	v_mov_b32_e32 v66, v2
	v_mov_b32_e32 v67, v2
	v_mov_b32_e32 v68, v2
	v_mov_b32_e32 v69, v2
	v_mov_b32_e32 v70, v2
	v_mov_b32_e32 v71, v2
	v_mov_b32_e32 v72, v2
	v_mov_b32_e32 v73, v2
	v_mov_b32_e32 v74, v2
	v_mov_b32_e32 v75, v2
	v_mov_b32_e32 v76, v2
	v_mov_b32_e32 v77, v2
	v_mov_b32_e32 v78, v2
	v_mov_b32_e32 v79, v2
	v_mov_b32_e32 v80, v2
	v_mov_b32_e32 v81, v2
	v_mov_b32_e32 v82, v2
	v_mov_b32_e32 v83, v2
	v_mov_b32_e32 v84, v2
	v_mov_b32_e32 v85, v2
	v_mov_b32_e32 v86, v2
	v_mov_b32_e32 v87, v2
	v_mov_b32_e32 v88, v2
	v_mov_b32_e32 v89, v2
	v_mov_b32_e32 v90, v2
	v_mov_b32_e32 v91, v2
	v_mov_b32_e32 v92, v2
	v_mov_b32_e32 v93, v2
	v_mov_b32_e32 v94, v2
	v_mov_b32_e32 v95, v2
	v_mov_b32_e32 v96, v2
	v_mov_b32_e32 v97, v2
	v_mov_b32_e32 v98, v2
	v_mov_b32_e32 v99, v2
	v_mov_b32_e32 v100, v2
	v_mov_b32_e32 v101, v2
	v_mov_b32_e32 v102, v2
	v_mov_b32_e32 v103, v2
	v_mov_b32_e32 v104, v2
	v_mov_b32_e32 v105, v2
	v_mov_b32_e32 v106, v2
	v_mov_b32_e32 v107, v2
	v_mov_b32_e32 v108, v2
	v_mov_b32_e32 v109, v2
	v_mov_b32_e32 v110, v2
	v_mov_b32_e32 v111, v2
	v_mov_b32_e32 v112, v2
	v_mov_b32_e32 v113, v2
	v_mov_b32_e32 v114, v2
	v_mov_b32_e32 v115, v2
	v_mov_b32_e32 v116, v2
	v_mov_b32_e32 v117, v2
	v_mov_b32_e32 v118, v2
	v_mov_b32_e32 v119, v2
	v_mov_b32_e32 v120, v2
	v_mov_b32_e32 v121, v2
	v_mov_b32_e32 v122, v2
	v_mov_b32_e32 v123, v2
	v_mov_b32_e32 v124, v2
	v_mov_b32_e32 v125, v2
	v_mov_b32_e32 v126, v2
	v_mov_b32_e32 v127, v2
	v_mov_b32_e32 v128, v2
	v_mov_b32_e32 v129, v2
	s_mul_i32 s0, s42, 0x6000
	v_add_u32_e32 v214, s0, v185
	v_lshl_add_u64 v[210:211], v[182:183], 0, v[0:1]
	s_mov_b64 s[0:1], 0xb286280
	v_lshl_add_u64 v[212:213], v[210:211], 0, s[0:1]
	v_readfirstlane_b32 s0, v214
	s_mov_b32 m0, s0
	s_mov_b64 s[0:1], 0xb2a7280
	s_nop 0
	v_readfirstlane_b32 s100, v212
	v_readfirstlane_b32 s101, v213
	s_nop 1
	v_subrev_u32_e32 v226, s100, v212
	v_add_u32_e32 v212, 0x1000, v214
	v_lshl_add_u64 v[210:211], v[210:211], 0, s[0:1]
	v_readfirstlane_b32 s0, v212
	s_mov_b32 m0, s0
	s_mov_b64 s[0:1], 0x4726000
	v_subrev_u32_e32 v227, s100, v210
	v_lshl_add_u64 v[210:211], v[180:181], 0, v[0:1]
	v_add_u32_e32 v215, 0x2000, v214
	v_lshl_add_u64 v[212:213], v[210:211], 0, s[0:1]
	v_readfirstlane_b32 s0, v215
	s_mov_b32 m0, s0
	s_mov_b64 s[0:1], 0x4727000
	v_add_u32_e32 v215, 0x3000, v214
	s_nop 0
	v_readfirstlane_b32 vcc_lo, v212
	v_readfirstlane_b32 vcc_hi, v213
	s_nop 1
	v_subrev_u32_e32 v228, vcc_lo, v212
	v_lshl_add_u64 v[212:213], v[210:211], 0, s[0:1]
	v_readfirstlane_b32 s0, v215
	s_mov_b32 m0, s0
	s_mov_b64 s[0:1], 0x4728000
	v_add_u32_e32 v215, 0x4000, v214
	v_subrev_u32_e32 v229, vcc_lo, v212
	v_lshl_add_u64 v[212:213], v[210:211], 0, s[0:1]
	v_readfirstlane_b32 s0, v215
	s_mov_b32 m0, s0
	s_mov_b64 s[0:1], 0x4729000
	v_subrev_u32_e32 v230, vcc_lo, v212
	v_add_u32_e32 v212, 0x5000, v214
	v_lshl_add_u64 v[210:211], v[210:211], 0, s[0:1]
	v_readfirstlane_b32 s0, v212
	s_mov_b32 m0, s0
	s_nop 0
	v_subrev_u32_e32 v231, vcc_lo, v210
	v_mov_b32_e32 v182, v226
	v_mov_b32_e32 v183, v227
	v_mov_b32_e32 v180, v228
	v_mov_b32_e32 v181, v229
	v_mov_b32_e32 v253, v230
	v_mov_b32_e32 v254, v231
	v_readfirstlane_b32 s0, v185
	s_branch .LBB0_1950

; DEVI int otid() { int t = threadIdx.x; asm volatile("" : "+v"(t)); return t; }
; #define RAW_BARRIER() do { asm volatile("s_waitcnt lgkmcnt(0)" ::: "memory"); __builtin_amdgcn_s_barrier(); } while (0)
; template <int EPI, int NB>
; DEVI void gemm_tile(const GemmJob& J, int m0, int n0, unsigned char* smem) {
;     ...
;   const int tid = otid(), lane = tid & 63, wid = tid >> 6, wm = wid >> 1, wn = wid & 1;
;   const int l16 = lane & 15, g = lane >> 4;
;   f32x4 acc[4][NB];
; #pragma unroll
;   for (int i = 0; i < 4; ++i)
; #pragma unroll
;     for (int j = 0; j < NB; ++j) acc[i][j] = (f32x4){0.f, 0.f, 0.f, 0.f};
;   const int srow = tid >> 2, sch = tid & 3;
;   const int gch = sch ^ ((0 - (tid >> 4)) & 3);
;   const bf16_t* Ag = J.A + (size_t)(m0 + srow) * (J.ablk ? 32 : J.lda) + gch * 8;
;   const bf16_t* Bg = J.Bt + (size_t)(n0 + srow) * 32 + gch * 8;
;   const size_t Astep = (size_t)64 * (J.ablk ? 32 : J.lda), Ak = J.ablk ? (size_t)MROWS * 32 : (size_t)32, Bstep = (size_t)64 * 32, Bk = (size_t)J.NR * 32;
;   const int nk = J.K >> 5;
;   unsigned char* lds_t = smem + tid * 16;
;   const unsigned lbase = (unsigned)(uintptr_t)(__attribute__((address_space(3))) unsigned char*)smem;
;     ...
;   asm volatile("s_waitcnt vmcnt(0)" ::: "memory");
;   RAW_BARRIER();
; #pragma unroll
;   for (int st = 0; st < S - 1; ++st) GEMM_ISSUE(st, st);
;   const int fsl = (g ^ ((0 - (l16 >> 2)) & 3)) << 4;
;   const int aofs = (wm * 64 + l16) * 64 + fsl;
;   const int bofs = A_BYTES + (wn * NB * 16 + l16) * 64 + fsl;
;   int cs = 0, is = S - 1;
; template <int EPI, int NB>
; DEVI void gemm_run(const GemmJob& J, unsigned char* smem, int rot) {
;     ...
;     for (int q0 = lb; q0 < ntot; q0 += nlb) {
;       const int q = J.rev ? ntot - 1 - q0 : q0;
;       int grp = q / gsz; const int qq = q - grp * gsz;
;       const int mg = min(8, mcnt - grp * 8);
;       const int nt = qq / mg, mi = qq - nt * mg;
;       gemm_tile<EPI, NB>(J, (mlo + grp * 8 + mi) * 128, (J.nt0 + nt) * BN, smem);
.LBB0_2037:
	s_ashr_i32 s0, s9, 31
	s_lshr_b32 s0, s0, 28
	s_add_i32 s0, s9, s0
	s_ashr_i32 s1, s0, 4
	s_lshl_b32 s40, s1, 3
	v_readlane_b32 s1, v250, 16
	s_sub_i32 s1, s1, s40
	s_min_i32 s1, s1, 8
	s_abs_i32 s3, s1
	v_cvt_f32_u32_e32 v0, s3
	s_sub_i32 s42, 0, s3
	s_and_b32 s0, s0, -16
	s_sub_i32 s0, s9, s0
	v_rcp_iflag_f32_e32 v0, v0
	s_abs_i32 s20, s0
	s_xor_b32 s41, s0, s1
	s_ashr_i32 s41, s41, 31
	v_mul_f32_e32 v0, 0x4f7ffffe, v0
	v_cvt_u32_f32_e32 v0, v0
	v_mov_b32_e32 v184, v177
	s_movk_i32 s28, 0x840
	v_readfirstlane_b32 s43, v0
	s_mul_i32 s42, s42, s43
	s_mul_hi_u32 s42, s43, s42
	s_add_i32 s43, s43, s42
	s_mul_hi_u32 s42, s20, s43
	s_mul_i32 s43, s42, s3
	s_sub_i32 s20, s20, s43
	s_add_i32 s44, s42, 1
	s_sub_i32 s43, s20, s3
	s_cmp_ge_u32 s20, s3
	s_cselect_b32 s42, s44, s42
	s_cselect_b32 s20, s43, s20
	s_add_i32 s43, s42, 1
	s_cmp_ge_u32 s20, s3
	s_cselect_b32 s3, s43, s42
	s_xor_b32 s3, s3, s41
	s_sub_i32 s3, s3, s41
	s_mul_i32 s41, s1, s3
	v_readlane_b32 s1, v250, 48
	s_add_i32 s1, s40, s1
	s_add_i32 s1, s1, s0
	s_sub_i32 s0, s1, s41
	s_lshl_b32 s3, s3, 8
	v_ashrrev_i32_e32 v10, 2, v184
	v_lshrrev_b32_e32 v0, 4, v184
	s_lshl_b32 s20, s0, 7
	v_sub_u32_e32 v11, 0, v0
	v_add_u32_e32 v4, s3, v10
	v_xor_b32_e32 v0, v184, v11
	v_add_u32_e32 v2, s20, v10
	v_ashrrev_i32_e32 v5, 31, v4
	v_mad_i64_i32 v[2:3], s[0:1], v2, s28, v[170:171]
	v_lshlrev_b32_e32 v0, 4, v0
	v_lshlrev_b64 v[4:5], 6, v[4:5]
	v_lshlrev_b32_e32 v185, 4, v184
	v_and_b32_e32 v0, 48, v0
	v_lshl_add_u64 v[6:7], v[138:139], 0, v[4:5]
	v_readfirstlane_b32 s0, v185
	v_lshl_add_u64 v[2:3], v[2:3], 0, v[0:1]
	v_lshl_add_u64 v[6:7], v[6:7], 0, v[0:1]
	s_mov_b32 m0, s0
	s_mov_b64 s[0:1], 0x21000
	v_add_u32_e32 v0, 0x1000, v185
	s_nop 0
	v_lshl_add_u64 v[8:9], v[2:3], 0, s[0:1]
	v_readfirstlane_b32 s0, v0
	v_add_u32_e32 v0, 0x2000, v185
	s_waitcnt lgkmcnt(0)
	s_barrier
	global_load_lds_dwordx4 v[2:3], off
	s_mov_b32 m0, s0
	v_readfirstlane_b32 s0, v0
	v_add_u32_e32 v0, 0x3000, v185
	global_load_lds_dwordx4 v[8:9], off
	s_mov_b32 m0, s0
	v_readfirstlane_b32 s0, v0
	global_load_lds_dwordx4 v[6:7], off
	v_lshl_add_u64 v[8:9], v[6:7], 0, s[30:31]
	s_mov_b32 m0, s0
	s_mov_b64 s[0:1], 0x2000
	v_add_u32_e32 v0, 0x4000, v185
	global_load_lds_dwordx4 v[8:9], off
	v_lshl_add_u64 v[8:9], v[6:7], 0, s[0:1]
	v_readfirstlane_b32 s0, v0
	s_mov_b32 m0, s0
	s_mov_b64 s[0:1], 0x3000
	v_add_u32_e32 v0, 0x5000, v185
	global_load_lds_dwordx4 v[8:9], off
	v_lshl_add_u64 v[8:9], v[6:7], 0, s[0:1]
	v_readfirstlane_b32 s0, v0
	v_add_u32_e32 v0, 0x6000, v185
	s_mov_b32 m0, s0
	v_readfirstlane_b32 s0, v0
	global_load_lds_dwordx4 v[8:9], off
	s_mov_b32 m0, s0
	s_mov_b64 s[0:1], 0x21040
	v_add_u32_e32 v0, 0x7000, v185
	v_lshl_add_u64 v[8:9], v[2:3], 0, 64
	v_lshl_add_u64 v[2:3], v[2:3], 0, s[0:1]
	v_readfirstlane_b32 s0, v0
	v_add_u32_e32 v0, 0x8000, v185
	global_load_lds_dwordx4 v[8:9], off
	s_mov_b32 m0, s0
	v_readfirstlane_b32 s0, v0
	global_load_lds_dwordx4 v[2:3], off
	v_lshl_add_u64 v[2:3], v[6:7], 0, s[22:23]
	s_mov_b32 m0, s0
	s_mov_b64 s[0:1], 0x11000
	v_add_u32_e32 v0, 0x9000, v185
	global_load_lds_dwordx4 v[2:3], off
	v_lshl_add_u64 v[2:3], v[6:7], 0, s[0:1]
	v_readfirstlane_b32 s0, v0
	s_mov_b32 m0, s0
	s_mov_b64 s[0:1], 0x12000
	v_add_u32_e32 v0, 0xa000, v185
	global_load_lds_dwordx4 v[2:3], off
	v_lshl_add_u64 v[2:3], v[6:7], 0, s[0:1]
	v_readfirstlane_b32 s0, v0
	s_mov_b32 m0, s0
	s_mov_b64 s[0:1], 0x13000
	v_add_u32_e32 v0, 0xb000, v185
	global_load_lds_dwordx4 v[2:3], off
	v_lshl_add_u64 v[2:3], v[6:7], 0, s[0:1]
	v_readfirstlane_b32 s0, v0
	s_mov_b32 m0, s0
	v_lshlrev_b32_e32 v0, 2, v184
	global_load_lds_dwordx4 v[2:3], off
	v_and_b32_e32 v0, 48, v0
	v_ashrrev_i32_e32 v2, 1, v184
	v_and_b32_e32 v186, 15, v184
	v_sub_u32_e32 v0, 0, v0
	v_and_b32_e32 v187, 0xffffffc0, v2
	v_bitop3_b32 v0, v184, 48, v0 bitop3:0x48
	v_or_b32_e32 v2, v187, v186
	v_lshl_or_b32 v209, v2, 6, v0
	v_lshlrev_b32_e32 v2, 1, v184
	v_and_b32_e32 v208, 0x80, v2
	s_sub_i32 s0, s8, s41
	v_or_b32_e32 v2, v208, v186
	s_sub_i32 s0, s0, s40
	v_lshl_or_b32 v0, v2, 6, v0
	v_lshl_add_u32 v2, s0, 7, v10
	v_add_u32_e32 v210, 0x2000, v0
	v_bitop3_b32 v0, v184, 3, v11 bitop3:0x48
	v_mad_i64_i32 v[182:183], s[0:1], v2, s28, v[130:131]
	v_mov_b32_e32 v2, 0
	s_mov_b32 s2, 0
	s_mov_b32 s42, 2
	v_lshlrev_b32_e32 v0, 4, v0
	v_lshl_add_u64 v[180:181], v[130:131], 0, v[4:5]
	s_mov_b32 s43, 0
	v_mov_b32_e32 v3, v2
	v_mov_b32_e32 v4, v2
	v_mov_b32_e32 v5, v2
	v_mov_b32_e32 v6, v2
	v_mov_b32_e32 v7, v2
	v_mov_b32_e32 v8, v2
; #define RAW_BARRIER() do { asm volatile("s_waitcnt lgkmcnt(0)" ::: "memory"); __builtin_amdgcn_s_barrier(); } while (0)
; template <int EPI, int NB>
; DEVI void gemm_tile(const GemmJob& J, int m0, int n0, unsigned char* smem) {
;     ...
;   f32x4 acc[4][NB];
; #pragma unroll
;   for (int i = 0; i < 4; ++i)
; #pragma unroll
;     for (int j = 0; j < NB; ++j) acc[i][j] = (f32x4){0.f, 0.f, 0.f, 0.f};
;   const int srow = tid >> 2, sch = tid & 3;
;   const int gch = sch ^ ((0 - (tid >> 4)) & 3);
;   const bf16_t* Ag = J.A + (size_t)(m0 + srow) * (J.ablk ? 32 : J.lda) + gch * 8;
;   const bf16_t* Bg = J.Bt + (size_t)(n0 + srow) * 32 + gch * 8;
;   const size_t Astep = (size_t)64 * (J.ablk ? 32 : J.lda), Ak = J.ablk ? (size_t)MROWS * 32 : (size_t)32, Bstep = (size_t)64 * 32, Bk = (size_t)J.NR * 32;
;   const int nk = J.K >> 5;
;   unsigned char* lds_t = smem + tid * 16;
;   const unsigned lbase = (unsigned)(uintptr_t)(__attribute__((address_space(3))) unsigned char*)smem;
;     ...
;   asm volatile("s_waitcnt vmcnt(0)" ::: "memory");
;   RAW_BARRIER();
; #pragma unroll
;   for (int st = 0; st < S - 1; ++st) GEMM_ISSUE(st, st);
;   const int fsl = (g ^ ((0 - (l16 >> 2)) & 3)) << 4;
;   const int aofs = (wm * 64 + l16) * 64 + fsl;
;   const int bofs = A_BYTES + (wn * NB * 16 + l16) * 64 + fsl;
;   int cs = 0, is = S - 1;
; #pragma clang loop unroll(disable)
;   for (int kt = 0; kt < nk; ++kt) {
;     if (nk - 1 - kt >= S - 2) {
;       if constexpr (NB == 8) asm volatile("s_waitcnt vmcnt(6)" ::: "memory");
;       else                   asm volatile("s_waitcnt vmcnt(8)" ::: "memory");
;     } else {
;       asm volatile("s_waitcnt vmcnt(0)" ::: "memory");
;     }
;     RAW_BARRIER();
;     if (kt + S - 1 < nk) GEMM_ISSUE(kt + S - 1, is);
;     is = (is + 1 == S) ? 0 : is + 1;
;     const unsigned cur = lbase + cs * STG;
;     cs = (cs + 1 == S) ? 0 : cs + 1;
	v_mov_b32_e32 v9, v2
	v_mov_b32_e32 v10, v2
	v_mov_b32_e32 v11, v2
	v_mov_b32_e32 v12, v2
	v_mov_b32_e32 v13, v2
	v_mov_b32_e32 v14, v2
	v_mov_b32_e32 v15, v2
	v_mov_b32_e32 v16, v2
	v_mov_b32_e32 v17, v2
	v_mov_b32_e32 v18, v2
	v_mov_b32_e32 v19, v2
	v_mov_b32_e32 v20, v2
	v_mov_b32_e32 v21, v2
	v_mov_b32_e32 v22, v2
	v_mov_b32_e32 v23, v2
	v_mov_b32_e32 v24, v2
	v_mov_b32_e32 v25, v2
	v_mov_b32_e32 v26, v2
	v_mov_b32_e32 v27, v2
	v_mov_b32_e32 v28, v2
	v_mov_b32_e32 v29, v2
	v_mov_b32_e32 v30, v2
	v_mov_b32_e32 v31, v2
	v_mov_b32_e32 v32, v2
	v_mov_b32_e32 v33, v2
	v_mov_b32_e32 v34, v2
	v_mov_b32_e32 v35, v2
	v_mov_b32_e32 v36, v2
	v_mov_b32_e32 v37, v2
	v_mov_b32_e32 v38, v2
	v_mov_b32_e32 v39, v2
	v_mov_b32_e32 v40, v2
	v_mov_b32_e32 v41, v2
	v_mov_b32_e32 v42, v2
	v_mov_b32_e32 v43, v2
	v_mov_b32_e32 v44, v2
	v_mov_b32_e32 v45, v2
	v_mov_b32_e32 v46, v2
	v_mov_b32_e32 v47, v2
	v_mov_b32_e32 v48, v2
	v_mov_b32_e32 v49, v2
	v_mov_b32_e32 v50, v2
	v_mov_b32_e32 v51, v2
	v_mov_b32_e32 v52, v2
	v_mov_b32_e32 v53, v2
	v_mov_b32_e32 v54, v2
	v_mov_b32_e32 v55, v2
	v_mov_b32_e32 v56, v2
	v_mov_b32_e32 v57, v2
	v_mov_b32_e32 v58, v2
	v_mov_b32_e32 v59, v2
	v_mov_b32_e32 v60, v2
	v_mov_b32_e32 v61, v2
	v_mov_b32_e32 v62, v2
	v_mov_b32_e32 v63, v2
	v_mov_b32_e32 v64, v2
	v_mov_b32_e32 v65, v2
	v_mov_b32_e32 v66, v2
	v_mov_b32_e32 v67, v2
	v_mov_b32_e32 v68, v2
	v_mov_b32_e32 v69, v2
	v_mov_b32_e32 v70, v2
	v_mov_b32_e32 v71, v2
	v_mov_b32_e32 v72, v2
	v_mov_b32_e32 v73, v2
	v_mov_b32_e32 v74, v2
	v_mov_b32_e32 v75, v2
	v_mov_b32_e32 v76, v2
	v_mov_b32_e32 v77, v2
	v_mov_b32_e32 v78, v2
	v_mov_b32_e32 v79, v2
	v_mov_b32_e32 v80, v2
	v_mov_b32_e32 v81, v2
	v_mov_b32_e32 v82, v2
	v_mov_b32_e32 v83, v2
	v_mov_b32_e32 v84, v2
	v_mov_b32_e32 v85, v2
	v_mov_b32_e32 v86, v2
	v_mov_b32_e32 v87, v2
	v_mov_b32_e32 v88, v2
	v_mov_b32_e32 v89, v2
	v_mov_b32_e32 v90, v2
	v_mov_b32_e32 v91, v2
	v_mov_b32_e32 v92, v2
	v_mov_b32_e32 v93, v2
	v_mov_b32_e32 v94, v2
	v_mov_b32_e32 v95, v2
	v_mov_b32_e32 v96, v2
	v_mov_b32_e32 v97, v2
	v_mov_b32_e32 v98, v2
	v_mov_b32_e32 v99, v2
	v_mov_b32_e32 v100, v2
	v_mov_b32_e32 v101, v2
	v_mov_b32_e32 v102, v2
	v_mov_b32_e32 v103, v2
	v_mov_b32_e32 v104, v2
	v_mov_b32_e32 v105, v2
	v_mov_b32_e32 v106, v2
	v_mov_b32_e32 v107, v2
	v_mov_b32_e32 v108, v2
	v_mov_b32_e32 v109, v2
	v_mov_b32_e32 v110, v2
	v_mov_b32_e32 v111, v2
	v_mov_b32_e32 v112, v2
	v_mov_b32_e32 v113, v2
	v_mov_b32_e32 v114, v2
	v_mov_b32_e32 v115, v2
	v_mov_b32_e32 v116, v2
	v_mov_b32_e32 v117, v2
	v_mov_b32_e32 v118, v2
	v_mov_b32_e32 v119, v2
	v_mov_b32_e32 v120, v2
	v_mov_b32_e32 v121, v2
	v_mov_b32_e32 v122, v2
	v_mov_b32_e32 v123, v2
	v_mov_b32_e32 v124, v2
	v_mov_b32_e32 v125, v2
	v_mov_b32_e32 v126, v2
	v_mov_b32_e32 v127, v2
	v_mov_b32_e32 v128, v2
	v_mov_b32_e32 v129, v2
	s_mul_i32 s0, s42, 0x6000
	v_add_u32_e32 v211, s0, v185
	v_lshl_add_u64 v[212:213], v[182:183], 0, v[0:1]
	s_mov_b64 s[0:1], 0xb286280
	v_lshl_add_u64 v[214:215], v[212:213], 0, s[0:1]
	v_readfirstlane_b32 s0, v211
	s_mov_b32 m0, s0
	s_mov_b64 s[0:1], 0xb2a7280
	s_nop 0
	v_readfirstlane_b32 s100, v214
	v_readfirstlane_b32 s101, v215
	s_nop 1
	v_subrev_u32_e32 v228, s100, v214
	v_add_u32_e32 v214, 0x1000, v211
	v_lshl_add_u64 v[212:213], v[212:213], 0, s[0:1]
	v_readfirstlane_b32 s0, v214
	s_mov_b32 m0, s0
	s_mov_b64 s[0:1], 0x4726000
	v_subrev_u32_e32 v229, s100, v212
	v_lshl_add_u64 v[212:213], v[180:181], 0, v[0:1]
	v_add_u32_e32 v216, 0x2000, v211
	v_lshl_add_u64 v[214:215], v[212:213], 0, s[0:1]
	v_readfirstlane_b32 s0, v216
	s_mov_b32 m0, s0
	s_mov_b64 s[0:1], 0x4727000
	v_add_u32_e32 v216, 0x3000, v211
	s_nop 0
	v_readfirstlane_b32 vcc_lo, v214
	v_readfirstlane_b32 vcc_hi, v215
	s_nop 1
	v_subrev_u32_e32 v230, vcc_lo, v214
	v_lshl_add_u64 v[214:215], v[212:213], 0, s[0:1]
	v_readfirstlane_b32 s0, v216
	s_mov_b32 m0, s0
	s_mov_b64 s[0:1], 0x4728000
	v_add_u32_e32 v216, 0x4000, v211
	v_subrev_u32_e32 v231, vcc_lo, v214
	v_lshl_add_u64 v[214:215], v[212:213], 0, s[0:1]
	v_readfirstlane_b32 s0, v216
	s_mov_b32 m0, s0
	s_mov_b64 s[0:1], 0x4729000
	v_add_u32_e32 v211, 0x5000, v211
	v_lshl_add_u64 v[212:213], v[212:213], 0, s[0:1]
	v_readfirstlane_b32 s0, v211
	v_subrev_u32_e32 v232, vcc_lo, v214
	s_mov_b32 m0, s0
	s_nop 0
	v_subrev_u32_e32 v233, vcc_lo, v212
	v_mov_b32_e32 v182, v228
	v_mov_b32_e32 v183, v229
	v_mov_b32_e32 v180, v230
	v_mov_b32_e32 v181, v231
	v_mov_b32_e32 v253, v232
	v_mov_b32_e32 v254, v233
	v_readfirstlane_b32 s0, v185
	s_branch .LBB0_2039

; DEVI int otid() { int t = threadIdx.x; asm volatile("" : "+v"(t)); return t; }
; #define RAW_BARRIER() do { asm volatile("s_waitcnt lgkmcnt(0)" ::: "memory"); __builtin_amdgcn_s_barrier(); } while (0)
; template <int EPI, int NB>
; DEVI void gemm_tile(const GemmJob& J, int m0, int n0, unsigned char* smem) {
;     ...
;   const int tid = otid(), lane = tid & 63, wid = tid >> 6, wm = wid >> 1, wn = wid & 1;
;   const int l16 = lane & 15, g = lane >> 4;
;   f32x4 acc[4][NB];
; #pragma unroll
;   for (int i = 0; i < 4; ++i)
; #pragma unroll
;     for (int j = 0; j < NB; ++j) acc[i][j] = (f32x4){0.f, 0.f, 0.f, 0.f};
;   const int srow = tid >> 2, sch = tid & 3;
;   const int gch = sch ^ ((0 - (tid >> 4)) & 3);
;   const bf16_t* Ag = J.A + (size_t)(m0 + srow) * (J.ablk ? 32 : J.lda) + gch * 8;
;   const bf16_t* Bg = J.Bt + (size_t)(n0 + srow) * 32 + gch * 8;
;   const size_t Astep = (size_t)64 * (J.ablk ? 32 : J.lda), Ak = J.ablk ? (size_t)MROWS * 32 : (size_t)32, Bstep = (size_t)64 * 32, Bk = (size_t)J.NR * 32;
;   const int nk = J.K >> 5;
;   unsigned char* lds_t = smem + tid * 16;
;   const unsigned lbase = (unsigned)(uintptr_t)(__attribute__((address_space(3))) unsigned char*)smem;
;     ...
;   asm volatile("s_waitcnt vmcnt(0)" ::: "memory");
;   RAW_BARRIER();
; #pragma unroll
;   for (int st = 0; st < S - 1; ++st) GEMM_ISSUE(st, st);
;   const int fsl = (g ^ ((0 - (l16 >> 2)) & 3)) << 4;
;   const int aofs = (wm * 64 + l16) * 64 + fsl;
;   const int bofs = A_BYTES + (wn * NB * 16 + l16) * 64 + fsl;
;   int cs = 0, is = S - 1;
; template <int EPI, int NB>
; DEVI void gemm_run(const GemmJob& J, unsigned char* smem, int rot) {
;     ...
;     for (int q0 = lb; q0 < ntot; q0 += nlb) {
;       const int q = J.rev ? ntot - 1 - q0 : q0;
;       int grp = q / gsz; const int qq = q - grp * gsz;
;       const int mg = min(8, mcnt - grp * 8);
;       const int nt = qq / mg, mi = qq - nt * mg;
;       gemm_tile<EPI, NB>(J, (mlo + grp * 8 + mi) * 128, (J.nt0 + nt) * BN, smem);
.LBB0_2115:
	s_ashr_i32 s0, s9, 31
	s_lshr_b32 s0, s0, 28
	s_add_i32 s0, s9, s0
	s_ashr_i32 s1, s0, 4
	s_lshl_b32 s40, s1, 3
	v_readlane_b32 s1, v250, 22
	s_sub_i32 s1, s1, s40
	s_min_i32 s1, s1, 8
	s_abs_i32 s2, s1
	v_cvt_f32_u32_e32 v0, s2
	s_sub_i32 s42, 0, s2
	s_and_b32 s0, s0, -16
	s_sub_i32 s0, s9, s0
	v_rcp_iflag_f32_e32 v0, v0
	s_abs_i32 s20, s0
	s_xor_b32 s41, s0, s1
	s_ashr_i32 s41, s41, 31
	v_mul_f32_e32 v0, 0x4f7ffffe, v0
	v_cvt_u32_f32_e32 v0, v0
	v_mov_b32_e32 v184, v177
	s_movk_i32 s28, 0x840
	v_readfirstlane_b32 s43, v0
	s_mul_i32 s42, s42, s43
	s_mul_hi_u32 s42, s43, s42
	s_add_i32 s43, s43, s42
	s_mul_hi_u32 s42, s20, s43
	s_mul_i32 s43, s42, s2
	s_sub_i32 s20, s20, s43
	s_add_i32 s44, s42, 1
	s_sub_i32 s43, s20, s2
	s_cmp_ge_u32 s20, s2
	s_cselect_b32 s42, s44, s42
	s_cselect_b32 s20, s43, s20
	s_add_i32 s43, s42, 1
	s_cmp_ge_u32 s20, s2
	s_cselect_b32 s2, s43, s42
	s_xor_b32 s2, s2, s41
	s_sub_i32 s2, s2, s41
	s_mul_i32 s41, s1, s2
	v_readlane_b32 s1, v250, 53
	s_add_i32 s1, s40, s1
	s_add_i32 s1, s1, s0
	s_lshl_b32 s2, s2, 8
	s_sub_i32 s0, s1, s41
	s_addk_i32 s2, 0x200
	v_ashrrev_i32_e32 v10, 2, v184
	v_lshrrev_b32_e32 v0, 4, v184
	s_lshl_b32 s20, s0, 7
	v_sub_u32_e32 v11, 0, v0
	v_add_u32_e32 v4, s2, v10
	v_xor_b32_e32 v0, v184, v11
	v_add_u32_e32 v2, s20, v10
	v_ashrrev_i32_e32 v5, 31, v4
	v_mad_i64_i32 v[2:3], s[0:1], v2, s28, v[170:171]
	v_lshlrev_b32_e32 v0, 4, v0
	v_lshlrev_b64 v[4:5], 6, v[4:5]
	v_lshlrev_b32_e32 v185, 4, v184
	v_and_b32_e32 v0, 48, v0
	v_lshl_add_u64 v[6:7], v[138:139], 0, v[4:5]
	v_readfirstlane_b32 s0, v185
	v_lshl_add_u64 v[2:3], v[2:3], 0, v[0:1]
	v_lshl_add_u64 v[6:7], v[6:7], 0, v[0:1]
	s_mov_b32 m0, s0
	s_mov_b64 s[0:1], 0x21000
	v_add_u32_e32 v0, 0x1000, v185
	s_nop 0
	v_lshl_add_u64 v[8:9], v[2:3], 0, s[0:1]
	v_readfirstlane_b32 s0, v0
	v_add_u32_e32 v0, 0x2000, v185
	s_waitcnt lgkmcnt(0)
	s_barrier
	global_load_lds_dwordx4 v[2:3], off
	s_mov_b32 m0, s0
	v_readfirstlane_b32 s0, v0
	v_add_u32_e32 v0, 0x3000, v185
	global_load_lds_dwordx4 v[8:9], off
	s_mov_b32 m0, s0
	v_readfirstlane_b32 s0, v0
	global_load_lds_dwordx4 v[6:7], off
	v_lshl_add_u64 v[8:9], v[6:7], 0, s[30:31]
	s_mov_b32 m0, s0
	s_mov_b64 s[0:1], 0x2000
	v_add_u32_e32 v0, 0x4000, v185
	global_load_lds_dwordx4 v[8:9], off
	v_lshl_add_u64 v[8:9], v[6:7], 0, s[0:1]
	v_readfirstlane_b32 s0, v0
	s_mov_b32 m0, s0
	s_mov_b64 s[0:1], 0x3000
	v_add_u32_e32 v0, 0x5000, v185
	global_load_lds_dwordx4 v[8:9], off
	v_lshl_add_u64 v[8:9], v[6:7], 0, s[0:1]
	v_readfirstlane_b32 s0, v0
	v_add_u32_e32 v0, 0x6000, v185
	s_mov_b32 m0, s0
	v_readfirstlane_b32 s0, v0
	global_load_lds_dwordx4 v[8:9], off
	s_mov_b32 m0, s0
	s_mov_b64 s[0:1], 0x21040
	v_add_u32_e32 v0, 0x7000, v185
	v_lshl_add_u64 v[8:9], v[2:3], 0, 64
	v_lshl_add_u64 v[2:3], v[2:3], 0, s[0:1]
	v_readfirstlane_b32 s0, v0
	v_add_u32_e32 v0, 0x8000, v185
	global_load_lds_dwordx4 v[8:9], off
	s_mov_b32 m0, s0
	v_readfirstlane_b32 s0, v0
	global_load_lds_dwordx4 v[2:3], off
	v_lshl_add_u64 v[2:3], v[6:7], 0, s[22:23]
	s_mov_b32 m0, s0
	s_mov_b64 s[0:1], 0x11000
	v_add_u32_e32 v0, 0x9000, v185
	global_load_lds_dwordx4 v[2:3], off
	v_lshl_add_u64 v[2:3], v[6:7], 0, s[0:1]
	v_readfirstlane_b32 s0, v0
	s_mov_b32 m0, s0
	s_mov_b64 s[0:1], 0x12000
	v_add_u32_e32 v0, 0xa000, v185
	global_load_lds_dwordx4 v[2:3], off
	v_lshl_add_u64 v[2:3], v[6:7], 0, s[0:1]
	v_readfirstlane_b32 s0, v0
	s_mov_b32 m0, s0
	s_mov_b64 s[0:1], 0x13000
	v_add_u32_e32 v0, 0xb000, v185
	global_load_lds_dwordx4 v[2:3], off
	v_lshl_add_u64 v[2:3], v[6:7], 0, s[0:1]
	v_readfirstlane_b32 s0, v0
	s_mov_b32 m0, s0
	v_and_b32_e32 v0, 15, v184
	global_load_lds_dwordx4 v[2:3], off
	v_lshlrev_b32_e32 v2, 2, v184
	v_and_b32_e32 v2, 48, v2
	v_ashrrev_i32_e32 v3, 1, v184
	v_sub_u32_e32 v2, 0, v2
	v_and_b32_e32 v187, 0xffffffc0, v3
	v_bitop3_b32 v2, v184, 48, v2 bitop3:0x48
	v_or_b32_e32 v3, v187, v0
	v_lshl_or_b32 v208, v3, 6, v2
	v_lshlrev_b32_e32 v3, 1, v184
	s_movk_i32 s0, 0x80
	v_and_or_b32 v186, v3, s0, v0
	s_sub_i32 s0, s8, s41
	s_sub_i32 s0, s0, s40
	v_lshl_or_b32 v0, v186, 6, v2
	v_lshl_add_u32 v2, s0, 7, v10
	v_add_u32_e32 v209, 0x2000, v0
	v_bitop3_b32 v0, v184, 3, v11 bitop3:0x48
	v_mad_i64_i32 v[182:183], s[0:1], v2, s28, v[130:131]
	v_mov_b32_e32 v2, 0
	s_mov_b32 s3, 0
	s_mov_b32 s42, 2
	v_lshlrev_b32_e32 v0, 4, v0
	v_lshl_add_u64 v[180:181], v[130:131], 0, v[4:5]
	s_mov_b32 s43, 0
	v_mov_b32_e32 v3, v2
	v_mov_b32_e32 v4, v2
	v_mov_b32_e32 v5, v2
	v_mov_b32_e32 v6, v2
	v_mov_b32_e32 v7, v2
	v_mov_b32_e32 v8, v2
; #define RAW_BARRIER() do { asm volatile("s_waitcnt lgkmcnt(0)" ::: "memory"); __builtin_amdgcn_s_barrier(); } while (0)
; template <int EPI, int NB>
; DEVI void gemm_tile(const GemmJob& J, int m0, int n0, unsigned char* smem) {
;     ...
;   f32x4 acc[4][NB];
; #pragma unroll
;   for (int i = 0; i < 4; ++i)
; #pragma unroll
;     for (int j = 0; j < NB; ++j) acc[i][j] = (f32x4){0.f, 0.f, 0.f, 0.f};
;   const int srow = tid >> 2, sch = tid & 3;
;   const int gch = sch ^ ((0 - (tid >> 4)) & 3);
;   const bf16_t* Ag = J.A + (size_t)(m0 + srow) * (J.ablk ? 32 : J.lda) + gch * 8;
;   const bf16_t* Bg = J.Bt + (size_t)(n0 + srow) * 32 + gch * 8;
;   const size_t Astep = (size_t)64 * (J.ablk ? 32 : J.lda), Ak = J.ablk ? (size_t)MROWS * 32 : (size_t)32, Bstep = (size_t)64 * 32, Bk = (size_t)J.NR * 32;
;   const int nk = J.K >> 5;
;   unsigned char* lds_t = smem + tid * 16;
;   const unsigned lbase = (unsigned)(uintptr_t)(__attribute__((address_space(3))) unsigned char*)smem;
;     ...
;   asm volatile("s_waitcnt vmcnt(0)" ::: "memory");
;   RAW_BARRIER();
; #pragma unroll
;   for (int st = 0; st < S - 1; ++st) GEMM_ISSUE(st, st);
;   const int fsl = (g ^ ((0 - (l16 >> 2)) & 3)) << 4;
;   const int aofs = (wm * 64 + l16) * 64 + fsl;
;   const int bofs = A_BYTES + (wn * NB * 16 + l16) * 64 + fsl;
;   int cs = 0, is = S - 1;
; #pragma clang loop unroll(disable)
;   for (int kt = 0; kt < nk; ++kt) {
;     if (nk - 1 - kt >= S - 2) {
;       if constexpr (NB == 8) asm volatile("s_waitcnt vmcnt(6)" ::: "memory");
;       else                   asm volatile("s_waitcnt vmcnt(8)" ::: "memory");
;     } else {
;       asm volatile("s_waitcnt vmcnt(0)" ::: "memory");
;     }
;     RAW_BARRIER();
;     if (kt + S - 1 < nk) GEMM_ISSUE(kt + S - 1, is);
;     is = (is + 1 == S) ? 0 : is + 1;
;     const unsigned cur = lbase + cs * STG;
;     cs = (cs + 1 == S) ? 0 : cs + 1;
	v_mov_b32_e32 v9, v2
	v_mov_b32_e32 v10, v2
	v_mov_b32_e32 v11, v2
	v_mov_b32_e32 v12, v2
	v_mov_b32_e32 v13, v2
	v_mov_b32_e32 v14, v2
	v_mov_b32_e32 v15, v2
	v_mov_b32_e32 v16, v2
	v_mov_b32_e32 v17, v2
	v_mov_b32_e32 v18, v2
	v_mov_b32_e32 v19, v2
	v_mov_b32_e32 v20, v2
	v_mov_b32_e32 v21, v2
	v_mov_b32_e32 v22, v2
	v_mov_b32_e32 v23, v2
	v_mov_b32_e32 v24, v2
	v_mov_b32_e32 v25, v2
	v_mov_b32_e32 v26, v2
	v_mov_b32_e32 v27, v2
	v_mov_b32_e32 v28, v2
	v_mov_b32_e32 v29, v2
	v_mov_b32_e32 v30, v2
	v_mov_b32_e32 v31, v2
	v_mov_b32_e32 v32, v2
	v_mov_b32_e32 v33, v2
	v_mov_b32_e32 v34, v2
	v_mov_b32_e32 v35, v2
	v_mov_b32_e32 v36, v2
	v_mov_b32_e32 v37, v2
	v_mov_b32_e32 v38, v2
	v_mov_b32_e32 v39, v2
	v_mov_b32_e32 v40, v2
	v_mov_b32_e32 v41, v2
	v_mov_b32_e32 v42, v2
	v_mov_b32_e32 v43, v2
	v_mov_b32_e32 v44, v2
	v_mov_b32_e32 v45, v2
	v_mov_b32_e32 v46, v2
	v_mov_b32_e32 v47, v2
	v_mov_b32_e32 v48, v2
	v_mov_b32_e32 v49, v2
	v_mov_b32_e32 v50, v2
	v_mov_b32_e32 v51, v2
	v_mov_b32_e32 v52, v2
	v_mov_b32_e32 v53, v2
	v_mov_b32_e32 v54, v2
	v_mov_b32_e32 v55, v2
	v_mov_b32_e32 v56, v2
	v_mov_b32_e32 v57, v2
	v_mov_b32_e32 v58, v2
	v_mov_b32_e32 v59, v2
	v_mov_b32_e32 v60, v2
	v_mov_b32_e32 v61, v2
	v_mov_b32_e32 v62, v2
	v_mov_b32_e32 v63, v2
	v_mov_b32_e32 v64, v2
	v_mov_b32_e32 v65, v2
	v_mov_b32_e32 v66, v2
	v_mov_b32_e32 v67, v2
	v_mov_b32_e32 v68, v2
	v_mov_b32_e32 v69, v2
	v_mov_b32_e32 v70, v2
	v_mov_b32_e32 v71, v2
	v_mov_b32_e32 v72, v2
	v_mov_b32_e32 v73, v2
	v_mov_b32_e32 v74, v2
	v_mov_b32_e32 v75, v2
	v_mov_b32_e32 v76, v2
	v_mov_b32_e32 v77, v2
	v_mov_b32_e32 v78, v2
	v_mov_b32_e32 v79, v2
	v_mov_b32_e32 v80, v2
	v_mov_b32_e32 v81, v2
	v_mov_b32_e32 v82, v2
	v_mov_b32_e32 v83, v2
	v_mov_b32_e32 v84, v2
	v_mov_b32_e32 v85, v2
	v_mov_b32_e32 v86, v2
	v_mov_b32_e32 v87, v2
	v_mov_b32_e32 v88, v2
	v_mov_b32_e32 v89, v2
	v_mov_b32_e32 v90, v2
	v_mov_b32_e32 v91, v2
	v_mov_b32_e32 v92, v2
	v_mov_b32_e32 v93, v2
	v_mov_b32_e32 v94, v2
	v_mov_b32_e32 v95, v2
	v_mov_b32_e32 v96, v2
	v_mov_b32_e32 v97, v2
	v_mov_b32_e32 v98, v2
	v_mov_b32_e32 v99, v2
	v_mov_b32_e32 v100, v2
	v_mov_b32_e32 v101, v2
	v_mov_b32_e32 v102, v2
	v_mov_b32_e32 v103, v2
	v_mov_b32_e32 v104, v2
	v_mov_b32_e32 v105, v2
	v_mov_b32_e32 v106, v2
	v_mov_b32_e32 v107, v2
	v_mov_b32_e32 v108, v2
	v_mov_b32_e32 v109, v2
	v_mov_b32_e32 v110, v2
	v_mov_b32_e32 v111, v2
	v_mov_b32_e32 v112, v2
	v_mov_b32_e32 v113, v2
	v_mov_b32_e32 v114, v2
	v_mov_b32_e32 v115, v2
	v_mov_b32_e32 v116, v2
	v_mov_b32_e32 v117, v2
	v_mov_b32_e32 v118, v2
	v_mov_b32_e32 v119, v2
	v_mov_b32_e32 v120, v2
	v_mov_b32_e32 v121, v2
	v_mov_b32_e32 v122, v2
	v_mov_b32_e32 v123, v2
	v_mov_b32_e32 v124, v2
	v_mov_b32_e32 v125, v2
	v_mov_b32_e32 v126, v2
	v_mov_b32_e32 v127, v2
	v_mov_b32_e32 v128, v2
	v_mov_b32_e32 v129, v2
	s_mul_i32 s0, s42, 0x6000
	v_add_u32_e32 v214, s0, v185
	v_lshl_add_u64 v[210:211], v[182:183], 0, v[0:1]
	s_mov_b64 s[0:1], 0xb286280
	v_lshl_add_u64 v[212:213], v[210:211], 0, s[0:1]
	v_readfirstlane_b32 s0, v214
	s_mov_b32 m0, s0
	s_mov_b64 s[0:1], 0xb2a7280
	s_nop 0
	v_readfirstlane_b32 s100, v212
	v_readfirstlane_b32 s101, v213
	s_nop 1
	v_subrev_u32_e32 v226, s100, v212
	v_add_u32_e32 v212, 0x1000, v214
	v_lshl_add_u64 v[210:211], v[210:211], 0, s[0:1]
	v_readfirstlane_b32 s0, v212
	s_mov_b32 m0, s0
	s_mov_b64 s[0:1], 0x4726000
	v_subrev_u32_e32 v227, s100, v210
	v_lshl_add_u64 v[210:211], v[180:181], 0, v[0:1]
	v_add_u32_e32 v215, 0x2000, v214
	v_lshl_add_u64 v[212:213], v[210:211], 0, s[0:1]
	v_readfirstlane_b32 s0, v215
	s_mov_b32 m0, s0
	s_mov_b64 s[0:1], 0x4727000
	v_add_u32_e32 v215, 0x3000, v214
	s_nop 0
	v_readfirstlane_b32 vcc_lo, v212
	v_readfirstlane_b32 vcc_hi, v213
	s_nop 1
	v_subrev_u32_e32 v228, vcc_lo, v212
	v_lshl_add_u64 v[212:213], v[210:211], 0, s[0:1]
	v_readfirstlane_b32 s0, v215
	s_mov_b32 m0, s0
	s_mov_b64 s[0:1], 0x4728000
	v_add_u32_e32 v215, 0x4000, v214
	v_subrev_u32_e32 v229, vcc_lo, v212
	v_lshl_add_u64 v[212:213], v[210:211], 0, s[0:1]
	v_readfirstlane_b32 s0, v215
	s_mov_b32 m0, s0
	s_mov_b64 s[0:1], 0x4729000
	v_subrev_u32_e32 v230, vcc_lo, v212
	v_add_u32_e32 v212, 0x5000, v214
	v_lshl_add_u64 v[210:211], v[210:211], 0, s[0:1]
	v_readfirstlane_b32 s0, v212
	s_mov_b32 m0, s0
	s_nop 0
	v_subrev_u32_e32 v231, vcc_lo, v210
	v_mov_b32_e32 v182, v226
	v_mov_b32_e32 v183, v227
	v_mov_b32_e32 v180, v228
	v_mov_b32_e32 v181, v229
	v_mov_b32_e32 v253, v230
	v_mov_b32_e32 v254, v231
	v_readfirstlane_b32 s0, v185
	s_branch .LBB0_2117

; DEVI int otid() { int t = threadIdx.x; asm volatile("" : "+v"(t)); return t; }
; #define RAW_BARRIER() do { asm volatile("s_waitcnt lgkmcnt(0)" ::: "memory"); __builtin_amdgcn_s_barrier(); } while (0)
; template <int DK, int QB, bool NA>
; DEVI void attn_item(const AttnArgs& a, unsigned char* smem) {
;     ...
;   const int tid = otid(), lane = tid & 63, w = tid >> 6;
;   const int l16 = lane & 15, g = lane >> 4;
;   const bool wact = (w * QB * 16) < a.nq;
;   const int nt = a.nreg + 1;
;   const unsigned lbase = (unsigned)(uintptr_t)(__attribute__((address_space(3))) unsigned char*)smem;
;   bf16x8 qf[QB][KS];
; #pragma unroll
;   for (int qb = 0; qb < QB; ++qb) {
;     const bf16_t* qp = a.Q + (size_t)((wact ? w * QB * 16 : 0) + qb * 16 + l16) * a.ldq + g * 8;
; #pragma unroll
;     for (int ks = 0; ks < KS; ++ks) qf[qb][ks] = *(const bf16x8*)(qp + ks * 32);
;   }
;   float m[QB], l[QB];
;   f32x4 o[4][QB];
; #pragma unroll
;   for (int qb = 0; qb < QB; ++qb) {
;     m[qb] = NA ? -1e30f : 0.f; l[qb] = 0.f;
; #pragma unroll
;     for (int db = 0; db < 4; ++db) o[db][qb] = (f32x4){0.f, 0.f, 0.f, 0.f};
;   }
;   const int r8 = tid >> 3, c8 = (tid & 7) ^ ((tid >> 4) & 7);
;   const bf16_t* Kn = a.K + (size_t)r8 * a.ldk + c8 * 8;
;   const bf16_t* Kr = a.K + (size_t)(tid >> 2) * a.ldk + 64 + (((tid & 3) ^ ((0 - (tid >> 4)) & 3)) * 8);
;   const bf16_t* Vg = a.Vt + (size_t)r8 * a.Lk + c8 * 8;
;   const size_t kstep = (size_t)32 * a.ldk, vstep = (size_t)32 * a.Lk;
;   unsigned char* lds_t = smem + tid * 16;
;     ...
;   asm volatile("s_waitcnt vmcnt(0)" ::: "memory");
;   RAW_BARRIER();
;   ATT_ISSUE(0, 0);
;   if (nt > 1) ATT_ISSUE(1, 1);
;   const int sw8 = (l16 >> 1) & 7, vsw = sw8 << 1;
;   const unsigned ka0 = l16 * 128 + ((g ^ sw8) << 4), ka1 = l16 * 128 + (((4 + g) ^ sw8) << 4);
;   const unsigned kr = 8192 + l16 * 64 + ((g ^ ((0 - (l16 >> 2)) & 3)) << 4);
;   const unsigned vb00 = 12288 + l16 * 128 + (((0 + g) ^ vsw) << 3), vb01 = 12288 + l16 * 128 + (((4 + g) ^ vsw) << 3);
;   const unsigned vb10 = 12288 + l16 * 128 + (((8 + g) ^ vsw) << 3), vb11 = 12288 + l16 * 128 + (((12 + g) ^ vsw) << 3);
;   const unsigned biasA = lbase + ATT_BIAS_OFF;
;   const int qc = w * 16 + l16;
;   const int cs0 = min(max(qc - 8, 0), 48);
;   int cs = 0, is = 2;
.LBB0_2263:
	s_or_b32 s62, s60, 64
	s_lshl_b32 s0, s8, 7
	s_cmp_lt_i32 s8, 0
	s_cselect_b32 s0, s60, s0
	s_add_i32 s59, s2, s0
	s_lshr_b32 s61, s60, 6
	s_lshl_b32 s56, s58, 6
	s_cmp_gt_u32 s58, 7
	s_cbranch_scc0 .LBB0_2289
	s_add_i32 s0, s58, -8
	s_mul_i32 s3, s59, 0x840
	v_readlane_b32 s28, v251, 52
	s_mul_hi_i32 s1, s59, 0x840
	s_add_u32 s3, s28, s3
	v_readlane_b32 s29, v251, 53
	s_addc_u32 s1, s29, s1
	s_lshl_b32 s8, s0, 7
	s_add_u32 s8, s3, s8
	s_addc_u32 s9, s1, 0
	s_ashr_i32 s3, s2, 31
	s_mul_i32 s20, s2, 0x840
	s_mul_hi_i32 s1, s2, 0x840
	s_add_u32 s20, s28, s20
	s_addc_u32 s1, s29, s1
	s_lshl_b32 s0, s0, 4
	s_and_b32 s42, s0, 0x7fffffc0
	s_lshl_b32 s0, s42, 1
	s_add_u32 s40, s20, s0
	s_addc_u32 s41, s1, 0
	s_lshl_b64 s[0:1], s[2:3], 8
	v_readlane_b32 s3, v251, 56
	s_add_u32 s3, s3, s0
	v_readlane_b32 s0, v251, 57
	s_addc_u32 s20, s0, s1
	s_mul_hi_u32 s1, s62, s42
	s_mul_i32 s0, s62, s42
	v_mov_b32_e32 v3, v177
	s_lshl_b64 s[0:1], s[0:1], 1
	s_add_u32 s42, s3, s0
	v_ashrrev_i32_e32 v0, 1, v3
	v_and_b32_e32 v128, 0xffffffe0, v0
	s_addc_u32 s43, s20, s1
	v_cmp_gt_i32_e64 s[0:1], s57, v128
	v_and_b32_e32 v126, 15, v3
	v_bfe_u32 v127, v3, 4, 2
	v_cndmask_b32_e64 v0, 0, v128, s[0:1]
	v_or_b32_e32 v12, v0, v126
	v_lshlrev_b32_e32 v0, 4, v127
	v_lshrrev_b32_e32 v2, 4, v3
	v_lshl_add_u64 v[4:5], s[8:9], 0, v[0:1]
	s_movk_i32 s3, 0x840
	v_or_b32_e32 v0, 16, v12
	v_mad_i64_i32 v[6:7], s[8:9], v12, s3, v[4:5]
	v_mad_i64_i32 v[4:5], s[8:9], v0, s3, v[4:5]
	v_xor_b32_e32 v0, v2, v3
	v_ashrrev_i32_e32 v22, 3, v3
	v_mov_b64_e32 v[20:21], s[40:41]
	v_lshlrev_b32_e32 v0, 4, v0
	v_mad_i64_i32 v[20:21], s[8:9], v22, s3, v[20:21]
	v_and_b32_e32 v0, 0x70, v0
	v_lshl_add_u64 v[106:107], v[20:21], 0, v[0:1]
	s_mov_b64 s[8:9], 0x700
	v_lshl_add_u64 v[20:21], v[106:107], 0, s[8:9]
	v_mad_i64_i32 v[22:23], s[8:9], v22, s62, 0
	v_lshl_add_u64 v[22:23], v[22:23], 1, s[42:43]
	v_lshlrev_b32_e32 v185, 4, v3
	v_lshl_add_u64 v[104:105], v[22:23], 0, v[0:1]
	v_readfirstlane_b32 s3, v185
	v_add_u32_e32 v0, 0x1000, v185
	global_load_dwordx4 v[16:19], v[6:7], off offset:768
	global_load_dwordx4 v[8:11], v[6:7], off offset:832
	global_load_dwordx4 v[12:15], v[4:5], off offset:768
	s_nop 0
	global_load_dwordx4 v[4:7], v[4:5], off offset:832
	s_waitcnt vmcnt(0)
	s_mov_b32 m0, s3
	s_mov_b64 s[8:9], 0x10f00
	v_readfirstlane_b32 s3, v0
	v_add_u32_e32 v0, 0x3000, v185
	s_waitcnt lgkmcnt(0)
	s_barrier
	global_load_lds_dwordx4 v[20:21], off
	v_lshl_add_u64 v[20:21], v[106:107], 0, s[8:9]
	s_mov_b32 m0, s3
	v_readfirstlane_b32 s3, v0
	v_add_u32_e32 v0, 0x4000, v185
	global_load_lds_dwordx4 v[20:21], off
	s_mov_b32 m0, s3
	s_lshl_b32 s20, s62, 6
	v_readfirstlane_b32 s3, v0
	v_add_u32_e32 v0, 0x5000, v185
	global_load_lds_dwordx4 v[104:105], off
	v_lshl_add_u64 v[108:109], v[104:105], 0, s[20:21]
	s_mov_b32 m0, s3
	s_mov_b64 s[8:9], 0x21700
	v_readfirstlane_b32 s3, v0
	v_add_u32_e32 v0, 0x6000, v185
	global_load_lds_dwordx4 v[108:109], off
	v_lshl_add_u64 v[20:21], v[106:107], 0, s[8:9]
	s_mov_b32 m0, s3
	s_mov_b64 s[8:9], 0x31f00
	v_readfirstlane_b32 s3, v0
	v_add_u32_e32 v0, 0x8000, v185
	global_load_lds_dwordx4 v[20:21], off
	v_lshl_add_u64 v[20:21], v[106:107], 0, s[8:9]
	s_mov_b32 m0, s3
	s_mov_b64 s[8:9], 0x80
	v_readfirstlane_b32 s3, v0
	v_add_u32_e32 v0, 0x9000, v185
	global_load_lds_dwordx4 v[20:21], off
	v_lshl_add_u64 v[20:21], v[104:105], 0, s[8:9]
	s_mov_b32 m0, s3
	v_readfirstlane_b32 s3, v0
	global_load_lds_dwordx4 v[20:21], off
	v_lshl_add_u64 v[20:21], v[108:109], 0, s[8:9]
	s_mov_b32 m0, s3
	v_add_u32_e32 v0, 0xa000, v185
	global_load_lds_dwordx4 v[20:21], off
	s_mov_b64 s[8:9], 0x42700
	v_readfirstlane_b32 s3, v0
	v_add_u32_e32 v0, 0xb000, v185
	s_waitcnt vmcnt(4)
	v_lshl_add_u64 v[20:21], v[106:107], 0, s[8:9]
	s_mov_b32 m0, s3
	s_mov_b64 s[8:9], 0x52f00
	v_readfirstlane_b32 s3, v0
	v_add_u32_e32 v0, 0xd000, v185
	s_waitcnt lgkmcnt(0)
	s_barrier
	global_load_lds_dwordx4 v[20:21], off
	v_lshl_add_u64 v[20:21], v[106:107], 0, s[8:9]
	s_mov_b32 m0, s3
	s_mov_b64 s[8:9], 0x100
	v_readfirstlane_b32 s3, v0
	v_add_u32_e32 v0, 0xe000, v185
	global_load_lds_dwordx4 v[20:21], off
	v_lshl_add_u64 v[20:21], v[104:105], 0, s[8:9]
	s_mov_b32 m0, s3
	v_readfirstlane_b32 s3, v0
	global_load_lds_dwordx4 v[20:21], off
	v_lshl_add_u64 v[20:21], v[108:109], 0, s[8:9]
	s_mov_b32 m0, s3
	v_cmp_le_i32_e32 vcc, s57, v128
	global_load_lds_dwordx4 v[20:21], off
	s_and_saveexec_b64 s[8:9], vcc
	s_xor_b64 s[8:9], exec, s[8:9]
	s_or_saveexec_b64 s[42:43], s[8:9]
	v_bfe_u32 v0, v3, 1, 3
	v_lshlrev_b32_e32 v3, 1, v0
	v_lshlrev_b32_e32 v20, 7, v126
	v_bitop3_b32 v21, v2, v0, 3 bitop3:0x6c
	v_bitop3_b32 v0, v127, v0, 4 bitop3:0x36
	v_lshl_or_b32 v184, v0, 4, v20
	v_or_b32_e32 v0, 0x3000, v20
	v_bitop3_b32 v2, v3, v2, 3 bitop3:0x78
	v_lshl_or_b32 v129, v2, 3, v0
	v_bitop3_b32 v2, v127, v3, 4 bitop3:0x36
	v_lshl_or_b32 v180, v2, 3, v0
	v_bitop3_b32 v2, v127, v3, 8 bitop3:0x36
	v_lshl_or_b32 v181, v2, 3, v0
	v_bitop3_b32 v2, v127, v3, 12 bitop3:0x36
	v_lshl_or_b32 v182, v2, 3, v0
	v_mov_b32_e32 v2, v1
	v_mov_b32_e32 v3, v1
	v_lshl_or_b32 v183, v21, 4, v20
	v_mov_b32_e32 v0, v1
	v_mov_b64_e32 v[22:23], v[2:3]
	v_mov_b64_e32 v[26:27], v[2:3]
	v_mov_b64_e32 v[30:31], v[2:3]
	v_mov_b64_e32 v[34:35], v[2:3]
	v_mov_b64_e32 v[38:39], v[2:3]
	v_mov_b64_e32 v[42:43], v[2:3]
	v_mov_b64_e32 v[46:47], v[2:3]
	v_mov_b64_e32 v[50:51], v[2:3]
	s_mov_b32 s8, 0
	v_mov_b32_e32 v100, 0
	v_mov_b64_e32 v[20:21], v[0:1]
	v_mov_b64_e32 v[24:25], v[0:1]
	v_mov_b64_e32 v[28:29], v[0:1]
	v_mov_b64_e32 v[32:33], v[0:1]
	v_mov_b64_e32 v[36:37], v[0:1]
	v_mov_b64_e32 v[40:41], v[0:1]
	v_mov_b64_e32 v[44:45], v[0:1]
	v_mov_b64_e32 v[48:49], v[0:1]
	v_mov_b32_e32 v101, 0
	v_mov_b32_e32 v102, 0
	v_mov_b32_e32 v103, 0
	s_xor_b64 exec, exec, s[42:43]
	s_cbranch_execz .LBB0_2266
; template <int DK, int QB, bool NA>
; DEVI void attn_item(const AttnArgs& a, unsigned char* smem) {
;     ...
;         bf16x8 k0[4], k1[4], k2[4];
;         const unsigned a0 = cur + ka0, a1 = cur + ka1, a2 = cur + kr;
;         k0[0] = ldsr<0>(a0); k0[1] = ldsr<2048>(a0); k0[2] = ldsr<4096>(a0); k0[3] = ldsr<6144>(a0);
;         k1[0] = ldsr<0>(a1); k1[1] = ldsr<2048>(a1); k1[2] = ldsr<4096>(a1); k1[3] = ldsr<6144>(a1);
;         if constexpr (KS == 3) { k2[0] = ldsr<0>(a2); k2[1] = ldsr<1024>(a2); k2[2] = ldsr<2048>(a2); k2[3] = ldsr<3072>(a2); }
;         if constexpr (KS == 3) asm volatile("s_waitcnt lgkmcnt(8)" : "+v"(k0[0]), "+v"(k0[1]), "+v"(k0[2]), "+v"(k0[3]) :: "memory");
;         else                   asm volatile("s_waitcnt lgkmcnt(4)" : "+v"(k0[0]), "+v"(k0[1]), "+v"(k0[2]), "+v"(k0[3]) :: "memory");
;         __builtin_amdgcn_sched_barrier(0);
; #pragma unroll
;         for (int kb = 0; kb < 4; ++kb)
; #pragma unroll
;           for (int qb = 0; qb < QB; ++qb) s[kb][qb] = __builtin_amdgcn_mfma_f32_16x16x32_bf16(k0[kb], qf[qb][0], s[kb][qb], 0, 0, 0);
;         if constexpr (KS == 3) asm volatile("s_waitcnt lgkmcnt(4)" : "+v"(k1[0]), "+v"(k1[1]), "+v"(k1[2]), "+v"(k1[3]) :: "memory");
;         else                   asm volatile("s_waitcnt lgkmcnt(0)" : "+v"(k1[0]), "+v"(k1[1]), "+v"(k1[2]), "+v"(k1[3]) :: "memory");
;         __builtin_amdgcn_sched_barrier(0);
; #pragma unroll
;         for (int kb = 0; kb < 4; ++kb)
; #pragma unroll
;           for (int qb = 0; qb < QB; ++qb) s[kb][qb] = __builtin_amdgcn_mfma_f32_16x16x32_bf16(k1[kb], qf[qb][1], s[kb][qb], 0, 0, 0);
;         if constexpr (KS == 3) {
;           asm volatile("s_waitcnt lgkmcnt(0)" : "+v"(k2[0]), "+v"(k2[1]), "+v"(k2[2]), "+v"(k2[3]) :: "memory");
;           __builtin_amdgcn_sched_barrier(0);
; #pragma unroll
;           for (int kb = 0; kb < 4; ++kb)
; #pragma unroll
;             for (int qb = 0; qb < QB; ++qb) s[kb][qb] = __builtin_amdgcn_mfma_f32_16x16x32_bf16(k2[kb], qf[qb][2], s[kb][qb], 0, 0, 0);
;         }
;       }
;       u32x2 va[2][4], vbq[2][4];
;       {
;         const unsigned p00 = cur + vb00, p01 = cur + vb01, p10 = cur + vb10, p11 = cur + vb11;
;         va[0][0] = ldsr64<0>(p00); vbq[0][0] = ldsr64<0>(p01); va[0][1] = ldsr64<2048>(p00); vbq[0][1] = ldsr64<2048>(p01);
	ds_read_b128 v[20:23], v183 offset:0
	ds_read_b128 v[24:27], v183 offset:0x800
	ds_read_b128 v[28:31], v183 offset:0x1000
	ds_read_b128 v[32:35], v183 offset:0x1800
	ds_read_b128 v[36:39], v184 offset:0
	ds_read_b128 v[40:43], v184 offset:0x800
	ds_read_b128 v[44:47], v184 offset:0x1000
	ds_read_b128 v[48:51], v184 offset:0x1800
	s_nop 0
	s_waitcnt lgkmcnt(4)
	s_waitcnt vmcnt(0)
	s_setprio 1
	v_mfma_f32_16x16x32_bf16 v[52:55], v[20:23], v[16:19], 0
	s_waitcnt lgkmcnt(0)
	v_mfma_f32_16x16x32_bf16 v[20:23], v[20:23], v[12:15], 0
	v_mfma_f32_16x16x32_bf16 v[56:59], v[24:27], v[16:19], 0
	v_mfma_f32_16x16x32_bf16 v[24:27], v[24:27], v[12:15], 0
	v_mfma_f32_16x16x32_bf16 v[68:71], v[28:31], v[16:19], 0
	v_mfma_f32_16x16x32_bf16 v[28:31], v[28:31], v[12:15], 0
	v_mfma_f32_16x16x32_bf16 v[72:75], v[32:35], v[16:19], 0
	v_mfma_f32_16x16x32_bf16 v[32:35], v[32:35], v[12:15], 0
	v_mfma_f32_16x16x32_bf16 v[52:55], v[36:39], v[8:11], v[52:55]
	v_mfma_f32_16x16x32_bf16 v[56:59], v[40:43], v[8:11], v[56:59]
	v_mfma_f32_16x16x32_bf16 v[76:79], v[44:47], v[8:11], v[68:71]
	s_nop 5
	v_mul_f32_e64 v84, v54, s92
	v_mul_f32_e64 v85, v55, s92
	v_pk_mul_f32 v[2:3], v[52:53], s[92:93] op_sel_hi:[1,0]
	v_max_f32_e32 v0, v84, v85
	v_max3_f32 v0, v2, v3, v0
	v_pk_mul_f32 v[2:3], v[56:57], s[92:93] op_sel_hi:[1,0]
	v_mfma_f32_16x16x32_bf16 v[80:83], v[48:51], v[8:11], v[72:75]
	v_max_f32_e32 v84, v2, v3
	v_pk_mul_f32 v[2:3], v[58:59], s[92:93] op_sel_hi:[1,0]
	s_nop 0
	v_max_f32_e32 v2, v2, v3
	v_max3_f32 v0, v0, v84, v2
	v_pk_mul_f32 v[2:3], v[76:77], s[92:93] op_sel_hi:[1,0]
	v_mfma_f32_16x16x32_bf16 v[60:63], v[36:39], v[4:7], v[20:23]
	v_max_f32_e32 v84, v2, v3
	v_pk_mul_f32 v[2:3], v[78:79], s[92:93] op_sel_hi:[1,0]
	s_nop 0
	v_max_f32_e32 v2, v2, v3
	v_max3_f32 v0, v0, v84, v2
	v_pk_mul_f32 v[2:3], v[80:81], s[92:93] op_sel_hi:[1,0]
	v_mfma_f32_16x16x32_bf16 v[64:67], v[40:43], v[4:7], v[24:27]
	s_setprio 0
	v_max_f32_e32 v84, v2, v3
	v_pk_mul_f32 v[2:3], v[82:83], s[92:93] op_sel_hi:[1,0]
	s_nop 0
	v_max_f32_e32 v2, v2, v3
	v_max3_f32 v0, v0, v84, v2
	v_mov_b32_e32 v2, v0
	s_nop 1
	v_permlane16_swap_b32_e32 v0, v2
	v_max_f32_e32 v2, v2, v2
	v_max_f32_e32 v0, v0, v0
	v_max_f32_e32 v0, v0, v2
	v_mov_b32_e32 v2, v0
	s_nop 1
	v_permlane32_swap_b32_e32 v0, v2
	v_max_f32_e32 v2, v2, v2
	v_max_f32_e32 v0, v0, v0
	v_max_f32_e32 v84, v0, v2
	v_pk_fma_f32 v[52:53], v[52:53], s[92:93], v[84:85] op_sel_hi:[1,0,0] neg_lo:[0,0,1] neg_hi:[0,0,1]
	v_pk_fma_f32 v[54:55], v[54:55], s[92:93], v[84:85] op_sel_hi:[1,0,0] neg_lo:[0,0,1] neg_hi:[0,0,1]
	v_exp_f32_e32 v52, v52
	v_exp_f32_e32 v53, v53
	v_exp_f32_e32 v54, v54
	v_exp_f32_e32 v55, v55
	v_pk_fma_f32 v[56:57], v[56:57], s[92:93], v[84:85] op_sel_hi:[1,0,0] neg_lo:[0,0,1] neg_hi:[0,0,1]
	v_pk_add_f32 v[86:87], v[52:53], 0 op_sel_hi:[1,0]
	v_pk_fma_f32 v[58:59], v[58:59], s[92:93], v[84:85] op_sel_hi:[1,0,0] neg_lo:[0,0,1] neg_hi:[0,0,1]
	v_cvt_pk_bf16_f32 v52, v52, v53
	v_pk_add_f32 v[86:87], v[54:55], v[86:87]
	v_cvt_pk_bf16_f32 v53, v54, v55
	v_exp_f32_e32 v54, v56
	v_exp_f32_e32 v55, v57
	v_exp_f32_e32 v58, v58
	v_exp_f32_e32 v59, v59
	v_pk_fma_f32 v[76:77], v[76:77], s[92:93], v[84:85] op_sel_hi:[1,0,0] neg_lo:[0,0,1] neg_hi:[0,0,1]
	v_pk_add_f32 v[56:57], v[54:55], v[86:87]
	v_cvt_pk_bf16_f32 v54, v54, v55
	v_pk_add_f32 v[56:57], v[58:59], v[56:57]
	v_cvt_pk_bf16_f32 v55, v58, v59
	v_exp_f32_e32 v58, v76
	v_exp_f32_e32 v59, v77
	v_pk_fma_f32 v[78:79], v[78:79], s[92:93], v[84:85] op_sel_hi:[1,0,0] neg_lo:[0,0,1] neg_hi:[0,0,1]
	v_pk_fma_f32 v[80:81], v[80:81], s[92:93], v[84:85] op_sel_hi:[1,0,0] neg_lo:[0,0,1] neg_hi:[0,0,1]
	v_pk_fma_f32 v[82:83], v[82:83], s[92:93], v[84:85] op_sel_hi:[1,0,0] neg_lo:[0,0,1] neg_hi:[0,0,1]
	v_pk_add_f32 v[76:77], v[58:59], v[56:57]
	v_cvt_pk_bf16_f32 v56, v58, v59
	v_exp_f32_e32 v58, v78
	v_exp_f32_e32 v59, v79
	v_exp_f32_e32 v78, v82
	v_exp_f32_e32 v79, v83
	s_setprio 1
	v_mfma_f32_16x16x32_bf16 v[68:71], v[44:47], v[4:7], v[28:31]
	v_add_f32_e64 v76, v58, v76
	v_add_f32_e64 v77, v59, v77
	v_cvt_pk_bf16_f32 v57, v58, v59
	v_exp_f32_e32 v58, v80
	v_exp_f32_e32 v59, v81
	v_pk_mul_f32 v[80:81], v[62:63], s[92:93] op_sel_hi:[1,0]
	v_mfma_f32_16x16x32_bf16 v[72:75], v[48:51], v[4:7], v[32:35]
	s_setprio 0
	v_max_f32_e32 v0, v80, v81
	v_pk_add_f32 v[76:77], v[58:59], v[76:77]
	v_cvt_pk_bf16_f32 v58, v58, v59
	v_pk_add_f32 v[76:77], v[78:79], v[76:77]
	v_cvt_pk_bf16_f32 v59, v78, v79
	v_pk_mul_f32 v[78:79], v[60:61], s[92:93] op_sel_hi:[1,0]
	v_exp_f32_e64 v3, -v84
	v_max3_f32 v0, v78, v79, v0
	v_pk_mul_f32 v[78:79], v[64:65], s[92:93] op_sel_hi:[1,0]
	ds_read_b64 v[48:49], v129 offset:0
	ds_read_b64 v[50:51], v180 offset:0
	ds_read_b64 v[44:45], v129 offset:0x800
	ds_read_b64 v[46:47], v180 offset:0x800
	ds_read_b64 v[40:41], v129 offset:0x1000
	s_nop 0
	v_max_f32_e32 v2, v78, v79
	v_pk_mul_f32 v[78:79], v[66:67], s[92:93] op_sel_hi:[1,0]
	ds_read_b64 v[42:43], v180 offset:0x1000
	ds_read_b64 v[36:37], v129 offset:0x1800
	ds_read_b64 v[38:39], v180 offset:0x1800
	ds_read_b64 v[32:33], v181 offset:0
	ds_read_b64 v[34:35], v182 offset:0
	s_nop 0
	v_max_f32_e32 v78, v78, v79
	v_max3_f32 v0, v0, v2, v78
	v_pk_mul_f32 v[78:79], v[68:69], s[92:93] op_sel_hi:[1,0]
	ds_read_b64 v[28:29], v181 offset:0x800
	ds_read_b64 v[30:31], v182 offset:0x800
	ds_read_b64 v[24:25], v181 offset:0x1000
	ds_read_b64 v[26:27], v182 offset:0x1000
	ds_read_b64 v[20:21], v181 offset:0x1800
	s_nop 0
	v_max_f32_e32 v2, v78, v79
	v_pk_mul_f32 v[78:79], v[70:71], s[92:93] op_sel_hi:[1,0]
	ds_read_b64 v[22:23], v182 offset:0x1800
	s_nop 0
	v_max_f32_e32 v78, v78, v79
	v_max3_f32 v0, v0, v2, v78
	v_pk_mul_f32 v[78:79], v[72:73], s[92:93] op_sel_hi:[1,0]
	s_waitcnt lgkmcnt(0)
; DEVI unsigned pk2(float lo, float hi) { const f32x2_t v = {lo, hi}; const bf16x2_t b = __builtin_convertvector(v, bf16x2_t); return __builtin_bit_cast(unsigned, b); }
; template <int DK, int QB, bool NA>
; DEVI void attn_item(const AttnArgs& a, unsigned char* smem) {
;     ...
;           if (j == 0 || __any(mx > 6.f)) {
;             mx = xmax32(xmax16(mx));
;             const float d = (j == 0) ? mx : fmaxf(mx, 0.f);
;             const float alpha = __builtin_amdgcn_exp2f(-d);
;             const f32x2 dv = {d, d};
; #pragma unroll
;             for (int kb = 0; kb < 4; ++kb)
; #pragma unroll
;               for (int h = 0; h < 2; ++h) t[kb][h] -= dv;
;             m[qb] += d;
;             l[qb] *= alpha;
; #pragma unroll
;             for (int db = 0; db < 4; ++db) o[db][qb] *= alpha;
;           }
;           f32x2 ls2 = {0.f, 0.f};
;           unsigned pw[2][4];
; #pragma unroll
;           for (int kb = 0; kb < 4; ++kb)
; #pragma unroll
;             for (int h = 0; h < 2; ++h) {
;               const f32x2 pe = {__builtin_amdgcn_exp2f(t[kb][h].x), __builtin_amdgcn_exp2f(t[kb][h].y)};
;               ls2 += pe;
;               pw[kb >> 1][(kb & 1) * 2 + h] = pk2(pe.x, pe.y);
;             }
;           l[qb] += ls2.x + ls2.y;
; #pragma unroll
;           for (int c = 0; c < 2; ++c) {
;             const u32x4 pv = (u32x4){pw[c][0], pw[c][1], pw[c][2], pw[c][3]};
;             pf[qb][c] = __builtin_bit_cast(bf16x8, pv);
;           }
;     ...
;       asm volatile("s_waitcnt lgkmcnt(0)"
;                    : "+v"(va[0][0]), "+v"(va[0][1]), "+v"(va[0][2]), "+v"(va[0][3]), "+v"(va[1][0]), "+v"(va[1][1]), "+v"(va[1][2]), "+v"(va[1][3]),
;                      "+v"(vbq[0][0]), "+v"(vbq[0][1]), "+v"(vbq[0][2]), "+v"(vbq[0][3]), "+v"(vbq[1][0]), "+v"(vbq[1][1]), "+v"(vbq[1][2]), "+v"(vbq[1][3])
;                    :: "memory");
;       __builtin_amdgcn_sched_barrier(0);
; #pragma unroll
;       for (int c = 0; c < 2; ++c)
; #pragma unroll
;         for (int db = 0; db < 4; ++db) {
;           const u32x4 vw = (u32x4){va[c][db].x, va[c][db].y, vbq[c][db].x, vbq[c][db].y};
;           const bf16x8 vf = __builtin_bit_cast(bf16x8, vw);
; #pragma unroll
;           for (int qb = 0; qb < QB; ++qb) o[db][qb] = __builtin_amdgcn_mfma_f32_16x16x32_bf16(vf, pf[qb][c], o[db][qb], 0, 0, 0);
;         }
	s_nop 0
	v_max_f32_e32 v2, v78, v79
	v_pk_mul_f32 v[78:79], v[74:75], s[92:93] op_sel_hi:[1,0]
	s_nop 0
	v_max_f32_e32 v78, v78, v79
	v_max3_f32 v0, v0, v2, v78
	v_mov_b32_e32 v2, v0
	s_nop 1
	v_permlane16_swap_b32_e32 v0, v2
	v_max_f32_e32 v2, v2, v2
	v_max_f32_e32 v0, v0, v0
	v_max_f32_e32 v0, v0, v2
	v_mov_b32_e32 v2, v0
	s_nop 1
	v_permlane32_swap_b32_e32 v0, v2
	v_max_f32_e32 v2, v2, v2
	v_max_f32_e32 v0, v0, v0
	v_max_f32_e32 v85, v0, v2
	v_mov_b32_e32 v0, v85
	v_pk_fma_f32 v[60:61], v[60:61], s[92:93], v[0:1] op_sel_hi:[1,0,0] neg_lo:[0,0,1] neg_hi:[0,0,1]
	v_pk_fma_f32 v[62:63], v[62:63], s[92:93], v[0:1] op_sel_hi:[1,0,0] neg_lo:[0,0,1] neg_hi:[0,0,1]
	v_exp_f32_e32 v60, v60
	v_exp_f32_e32 v61, v61
	v_exp_f32_e32 v62, v62
	v_exp_f32_e32 v63, v63
	v_pk_fma_f32 v[64:65], v[64:65], s[92:93], v[0:1] op_sel_hi:[1,0,0] neg_lo:[0,0,1] neg_hi:[0,0,1]
	v_pk_add_f32 v[78:79], v[60:61], 0 op_sel_hi:[1,0]
	v_pk_fma_f32 v[66:67], v[66:67], s[92:93], v[0:1] op_sel_hi:[1,0,0] neg_lo:[0,0,1] neg_hi:[0,0,1]
	v_cvt_pk_bf16_f32 v60, v60, v61
	v_pk_add_f32 v[78:79], v[62:63], v[78:79]
	v_cvt_pk_bf16_f32 v61, v62, v63
	v_exp_f32_e32 v62, v64
	v_exp_f32_e32 v63, v65
	v_exp_f32_e32 v66, v66
	v_exp_f32_e32 v67, v67
	v_pk_fma_f32 v[68:69], v[68:69], s[92:93], v[0:1] op_sel_hi:[1,0,0] neg_lo:[0,0,1] neg_hi:[0,0,1]
	v_pk_add_f32 v[64:65], v[62:63], v[78:79]
	v_cvt_pk_bf16_f32 v62, v62, v63
	v_pk_add_f32 v[64:65], v[66:67], v[64:65]
	v_cvt_pk_bf16_f32 v63, v66, v67
	v_exp_f32_e32 v66, v68
	v_exp_f32_e32 v67, v69
	v_pk_fma_f32 v[70:71], v[70:71], s[92:93], v[0:1] op_sel_hi:[1,0,0] neg_lo:[0,0,1] neg_hi:[0,0,1]
	v_pk_fma_f32 v[72:73], v[72:73], s[92:93], v[0:1] op_sel_hi:[1,0,0] neg_lo:[0,0,1] neg_hi:[0,0,1]
	v_pk_fma_f32 v[74:75], v[74:75], s[92:93], v[0:1] op_sel_hi:[1,0,0] neg_lo:[0,0,1] neg_hi:[0,0,1]
	v_pk_add_f32 v[68:69], v[66:67], v[64:65]
	v_cvt_pk_bf16_f32 v64, v66, v67
	v_exp_f32_e32 v66, v70
	v_exp_f32_e32 v67, v71
	v_exp_f32_e32 v70, v74
	v_exp_f32_e32 v71, v75
	v_exp_f32_e64 v2, -v85
	v_pk_add_f32 v[68:69], v[66:67], v[68:69]
	v_cvt_pk_bf16_f32 v65, v66, v67
	v_exp_f32_e32 v66, v72
	v_exp_f32_e32 v67, v73
	v_pk_add_f32 v[102:103], v[84:85], 0 op_sel_hi:[1,0]
	v_pk_add_f32 v[68:69], v[66:67], v[68:69]
	s_nop 0
	v_pk_add_f32 v[78:79], v[70:71], v[68:69]
	v_cvt_pk_bf16_f32 v66, v66, v67
	v_cvt_pk_bf16_f32 v67, v70, v71
	v_mov_b32_e32 v70, v78
	v_mov_b32_e32 v71, v76
	v_mov_b32_e32 v76, v79
	v_pk_add_f32 v[76:77], v[70:71], v[76:77]
	v_pk_mul_f32 v[68:69], v[2:3], 0 op_sel_hi:[1,0]
	v_pk_fma_f32 v[100:101], v[2:3], 0, v[76:77] op_sel_hi:[1,0,1]
	v_mov_b32_e32 v72, v69
	v_mov_b32_e32 v73, v69
	v_mov_b32_e32 v74, v69
	v_mov_b32_e32 v75, v69
	v_mov_b32_e32 v69, v68
	v_mov_b32_e32 v70, v68
	v_mov_b32_e32 v71, v68
	s_setprio 1
	v_mfma_f32_16x16x32_bf16 v[76:79], v[48:51], v[52:55], v[72:75]
	s_nop 0
	v_mfma_f32_16x16x32_bf16 v[80:83], v[48:51], v[60:63], v[68:71]
	v_mfma_f32_16x16x32_bf16 v[84:87], v[44:47], v[52:55], v[72:75]
	v_mfma_f32_16x16x32_bf16 v[88:91], v[44:47], v[60:63], v[68:71]
	v_mfma_f32_16x16x32_bf16 v[92:95], v[40:43], v[52:55], v[72:75]
	v_mfma_f32_16x16x32_bf16 v[96:99], v[40:43], v[60:63], v[68:71]
	v_mfma_f32_16x16x32_bf16 v[52:55], v[36:39], v[52:55], v[72:75]
	v_mfma_f32_16x16x32_bf16 v[60:63], v[36:39], v[60:63], v[68:71]
	v_mfma_f32_16x16x32_bf16 v[48:51], v[32:35], v[56:59], v[76:79]
	v_mfma_f32_16x16x32_bf16 v[44:47], v[32:35], v[64:67], v[80:83]
	v_mfma_f32_16x16x32_bf16 v[40:43], v[28:31], v[56:59], v[84:87]
	v_mfma_f32_16x16x32_bf16 v[36:39], v[28:31], v[64:67], v[88:91]
	v_mfma_f32_16x16x32_bf16 v[32:35], v[24:27], v[56:59], v[92:95]
	v_mfma_f32_16x16x32_bf16 v[28:31], v[24:27], v[64:67], v[96:99]
	v_mfma_f32_16x16x32_bf16 v[24:27], v[20:23], v[56:59], v[52:55]
	v_mfma_f32_16x16x32_bf16 v[20:23], v[20:23], v[64:67], v[60:63]
	s_setprio 0

; DEVI unsigned pk2(float lo, float hi) { const f32x2_t v = {lo, hi}; const bf16x2_t b = __builtin_convertvector(v, bf16x2_t); return __builtin_bit_cast(unsigned, b); }
; template <int DK, int QB, bool NA>
; DEVI void attn_item(const AttnArgs& a, unsigned char* smem) {
;     ...
;           f32x2 ls2 = {0.f, 0.f};
;           unsigned pw[2][4];
; #pragma unroll
;           for (int kb = 0; kb < 4; ++kb)
; #pragma unroll
;             for (int h = 0; h < 2; ++h) {
;               const f32x2 pe = {__builtin_amdgcn_exp2f(t[kb][h].x), __builtin_amdgcn_exp2f(t[kb][h].y)};
;               ls2 += pe;
;               pw[kb >> 1][(kb & 1) * 2 + h] = pk2(pe.x, pe.y);
;             }
;           l[qb] += ls2.x + ls2.y;
; #pragma unroll
;           for (int c = 0; c < 2; ++c) {
;             const u32x4 pv = (u32x4){pw[c][0], pw[c][1], pw[c][2], pw[c][3]};
;             pf[qb][c] = __builtin_bit_cast(bf16x8, pv);
;           }
;     ...
;       asm volatile("s_waitcnt lgkmcnt(0)"
;                    : "+v"(va[0][0]), "+v"(va[0][1]), "+v"(va[0][2]), "+v"(va[0][3]), "+v"(va[1][0]), "+v"(va[1][1]), "+v"(va[1][2]), "+v"(va[1][3]),
;                      "+v"(vbq[0][0]), "+v"(vbq[0][1]), "+v"(vbq[0][2]), "+v"(vbq[0][3]), "+v"(vbq[1][0]), "+v"(vbq[1][1]), "+v"(vbq[1][2]), "+v"(vbq[1][3])
;                    :: "memory");
;       __builtin_amdgcn_sched_barrier(0);
; #pragma unroll
;       for (int c = 0; c < 2; ++c)
; #pragma unroll
;         for (int db = 0; db < 4; ++db) {
;           const u32x4 vw = (u32x4){va[c][db].x, va[c][db].y, vbq[c][db].x, vbq[c][db].y};
;           const bf16x8 vf = __builtin_bit_cast(bf16x8, vw);
; #pragma unroll
;           for (int qb = 0; qb < QB; ++qb) o[db][qb] = __builtin_amdgcn_mfma_f32_16x16x32_bf16(vf, pf[qb][c], o[db][qb], 0, 0, 0);
;         }
.LBB0_2267:
	v_exp_f32_e32 v86, v122
	v_exp_f32_e32 v87, v123
	v_exp_f32_e32 v122, v120
	v_exp_f32_e32 v123, v121
	v_exp_f32_e32 v116, v116
	v_exp_f32_e32 v117, v117
	v_pk_add_f32 v[186:187], v[86:87], 0 op_sel_hi:[1,0]
	v_exp_f32_e32 v118, v118
	v_exp_f32_e32 v119, v119
	v_cvt_pk_bf16_f32 v120, v86, v87
	v_pk_add_f32 v[86:87], v[122:123], v[186:187]
	v_exp_f32_e32 v114, v114
	v_exp_f32_e32 v115, v115
	v_cvt_pk_bf16_f32 v121, v122, v123
	v_pk_add_f32 v[86:87], v[116:117], v[86:87]
	v_cvt_pk_bf16_f32 v122, v116, v117
	v_exp_f32_e32 v116, v112
	v_exp_f32_e32 v117, v113
	v_exp_f32_e32 v110, v110
	v_exp_f32_e32 v111, v111
	v_pk_add_f32 v[86:87], v[118:119], v[86:87]
	v_exp_f32_e32 v2, v2
	v_exp_f32_e32 v3, v3
	v_pk_add_f32 v[86:87], v[114:115], v[86:87]
	v_cvt_pk_bf16_f32 v112, v114, v115
	v_pk_add_f32 v[86:87], v[116:117], v[86:87]
	v_cvt_pk_bf16_f32 v115, v2, v3
	v_pk_add_f32 v[86:87], v[110:111], v[86:87]
	v_exp_f32_e32 v96, v96
	v_pk_add_f32 v[86:87], v[2:3], v[86:87]
	v_exp_f32_e32 v2, v124
	v_exp_f32_e32 v3, v125
	v_add_f32_e32 v0, v86, v87
	v_exp_f32_e32 v86, v98
	v_exp_f32_e32 v87, v99
	v_exp_f32_e32 v97, v97
	v_pk_add_f32 v[98:99], v[2:3], 0 op_sel_hi:[1,0]
	v_exp_f32_e32 v94, v94
	v_exp_f32_e32 v95, v95
	v_cvt_pk_bf16_f32 v113, v116, v117
	v_cvt_pk_bf16_f32 v116, v2, v3
	v_pk_add_f32 v[2:3], v[86:87], v[98:99]
	v_cvt_pk_bf16_f32 v117, v86, v87
	v_exp_f32_e32 v86, v92
	v_exp_f32_e32 v87, v93
	v_exp_f32_e32 v90, v90
	v_exp_f32_e32 v91, v91
	v_pk_add_f32 v[2:3], v[96:97], v[2:3]
	v_exp_f32_e32 v88, v88
	v_exp_f32_e32 v89, v89
	v_pk_add_f32 v[2:3], v[94:95], v[2:3]
	v_exp_f32_e32 v84, v84
	v_exp_f32_e32 v85, v85
	v_pk_add_f32 v[2:3], v[86:87], v[2:3]
	s_waitcnt lgkmcnt(0)
	v_add_f32_e32 v101, v101, v0
	v_pk_add_f32 v[2:3], v[90:91], v[2:3]
	v_cvt_pk_bf16_f32 v123, v118, v119
	v_pk_add_f32 v[2:3], v[88:89], v[2:3]
	v_cvt_pk_bf16_f32 v114, v110, v111
	v_pk_add_f32 v[2:3], v[84:85], v[2:3]
	v_cvt_pk_bf16_f32 v118, v96, v97
	v_add_f32_e32 v0, v2, v3
	v_add_f32_e32 v100, v100, v0
	v_cvt_pk_bf16_f32 v119, v94, v95
	v_cvt_pk_bf16_f32 v86, v86, v87
	v_cvt_pk_bf16_f32 v87, v90, v91
	v_cvt_pk_bf16_f32 v88, v88, v89
	v_cvt_pk_bf16_f32 v89, v84, v85
	s_setprio 1
	v_mfma_f32_16x16x32_bf16 v[48:51], v[80:83], v[120:123], v[48:51]
	v_mfma_f32_16x16x32_bf16 v[44:47], v[80:83], v[116:119], v[44:47]
	v_mfma_f32_16x16x32_bf16 v[40:43], v[76:79], v[120:123], v[40:43]
	v_mfma_f32_16x16x32_bf16 v[36:39], v[76:79], v[116:119], v[36:39]
	v_mfma_f32_16x16x32_bf16 v[32:35], v[72:75], v[120:123], v[32:35]
	v_mfma_f32_16x16x32_bf16 v[28:31], v[72:75], v[116:119], v[28:31]
	v_mfma_f32_16x16x32_bf16 v[24:27], v[68:71], v[120:123], v[24:27]
	v_mfma_f32_16x16x32_bf16 v[20:23], v[68:71], v[116:119], v[20:23]
	v_mfma_f32_16x16x32_bf16 v[48:51], v[64:67], v[112:115], v[48:51]
	v_mfma_f32_16x16x32_bf16 v[44:47], v[64:67], v[86:89], v[44:47]
	v_mfma_f32_16x16x32_bf16 v[40:43], v[60:63], v[112:115], v[40:43]
	v_mfma_f32_16x16x32_bf16 v[36:39], v[60:63], v[86:89], v[36:39]
	v_mfma_f32_16x16x32_bf16 v[32:35], v[56:59], v[112:115], v[32:35]
	v_mfma_f32_16x16x32_bf16 v[28:31], v[56:59], v[86:89], v[28:31]
	v_mfma_f32_16x16x32_bf16 v[24:27], v[52:55], v[112:115], v[24:27]
	v_mfma_f32_16x16x32_bf16 v[20:23], v[52:55], v[86:89], v[20:23]
	s_setprio 0

; template <int DK, int QB, bool NA>
; DEVI void attn_item(const AttnArgs& a, unsigned char* smem) {
;     ...
;   for (int j = 0; j < nt; ++j) {
;     if (j + 1 < nt) {
;       if constexpr (DK == 96) asm volatile("s_waitcnt vmcnt(5)" ::: "memory");
;       else                    asm volatile("s_waitcnt vmcnt(4)" ::: "memory");
;     } else {
;       asm volatile("s_waitcnt vmcnt(0)" ::: "memory");
;     }
;     RAW_BARRIER();
;     if (j + 2 < nt) ATT_ISSUE(j + 2, is);
;     is = (is + 1 == S) ? 0 : is + 1;
;     const unsigned cur = lbase + cs * ATT_STAGE;
;     cs = (cs + 1 == S) ? 0 : cs + 1;
;     if (wact) {
;       f32x4 s[4][QB];
; #pragma unroll
;       for (int kb = 0; kb < 4; ++kb)
; #pragma unroll
;         for (int qb = 0; qb < QB; ++qb) s[kb][qb] = (f32x4){0.f, 0.f, 0.f, 0.f};
;       {
;         bf16x8 k0[4], k1[4], k2[4];
;         const unsigned a0 = cur + ka0, a1 = cur + ka1, a2 = cur + kr;
;         k0[0] = ldsr<0>(a0); k0[1] = ldsr<2048>(a0); k0[2] = ldsr<4096>(a0); k0[3] = ldsr<6144>(a0);
;         k1[0] = ldsr<0>(a1); k1[1] = ldsr<2048>(a1); k1[2] = ldsr<4096>(a1); k1[3] = ldsr<6144>(a1);
;         if constexpr (KS == 3) { k2[0] = ldsr<0>(a2); k2[1] = ldsr<1024>(a2); k2[2] = ldsr<2048>(a2); k2[3] = ldsr<3072>(a2); }
;         if constexpr (KS == 3) asm volatile("s_waitcnt lgkmcnt(8)" : "+v"(k0[0]), "+v"(k0[1]), "+v"(k0[2]), "+v"(k0[3]) :: "memory");
;         else                   asm volatile("s_waitcnt lgkmcnt(4)" : "+v"(k0[0]), "+v"(k0[1]), "+v"(k0[2]), "+v"(k0[3]) :: "memory");
;         __builtin_amdgcn_sched_barrier(0);
; #pragma unroll
;         for (int kb = 0; kb < 4; ++kb)
; #pragma unroll
;           for (int qb = 0; qb < QB; ++qb) s[kb][qb] = __builtin_amdgcn_mfma_f32_16x16x32_bf16(k0[kb], qf[qb][0], s[kb][qb], 0, 0, 0);
;         if constexpr (KS == 3) asm volatile("s_waitcnt lgkmcnt(4)" : "+v"(k1[0]), "+v"(k1[1]), "+v"(k1[2]), "+v"(k1[3]) :: "memory");
;         else                   asm volatile("s_waitcnt lgkmcnt(0)" : "+v"(k1[0]), "+v"(k1[1]), "+v"(k1[2]), "+v"(k1[3]) :: "memory");
;         __builtin_amdgcn_sched_barrier(0);
; #pragma unroll
;         for (int kb = 0; kb < 4; ++kb)
; #pragma unroll
;           for (int qb = 0; qb < QB; ++qb) s[kb][qb] = __builtin_amdgcn_mfma_f32_16x16x32_bf16(k1[kb], qf[qb][1], s[kb][qb], 0, 0, 0);
;         if constexpr (KS == 3) {
.LBB0_2269:
	s_add_i32 s9, s9, 1
	s_cmp_lt_u32 s9, s61
	s_cselect_b32 s20, s44, s60
	s_mul_i32 s40, s8, 0x5000
	v_add_u32_e32 v0, s40, v185
	v_mad_u64_u32 v[2:3], s[40:41], s20, v205, v[106:107]
	s_mov_b64 s[28:29], 0x700
	v_readfirstlane_b32 s40, v0
	s_waitcnt vmcnt(4)
	v_lshl_add_u64 v[52:53], v[2:3], 0, s[28:29]
	s_mov_b32 m0, s40
	s_waitcnt lgkmcnt(0)
	s_barrier
	global_load_lds_dwordx4 v[52:53], off
	v_add_u32_e32 v52, 0x1000, v0
	s_mov_b64 s[28:29], 0x10f00
	v_readfirstlane_b32 s40, v52
	v_add_u32_e32 v52, 0x3000, v0
	v_lshl_add_u64 v[2:3], v[2:3], 0, s[28:29]
	s_mov_b32 m0, s40
	s_lshl_b64 s[40:41], s[20:21], 1
	v_readfirstlane_b32 s20, v52
	v_add_u32_e32 v0, 0x4000, v0
	global_load_lds_dwordx4 v[2:3], off
	v_lshl_add_u64 v[2:3], v[104:105], 0, s[40:41]
	s_mov_b32 m0, s20
	v_readfirstlane_b32 s20, v0
	global_load_lds_dwordx4 v[2:3], off
	v_lshl_add_u64 v[2:3], v[108:109], 0, s[40:41]
	s_mov_b32 m0, s20
	s_nop 0
	global_load_lds_dwordx4 v[2:3], off
	s_and_saveexec_b64 s[42:43], s[0:1]
	s_cbranch_execz .LBB0_2268
	s_mul_i32 s20, s3, 0x5000
	v_or_b32_e32 v0, s20, v183
	ds_read_b128 v[52:55], v0 offset:0
	ds_read_b128 v[56:59], v0 offset:0x800
	ds_read_b128 v[60:63], v0 offset:0x1000
	ds_read_b128 v[64:67], v0 offset:0x1800
	v_or_b32_e32 v2, s20, v184
	ds_read_b128 v[68:71], v2 offset:0
	ds_read_b128 v[72:75], v2 offset:0x800
	ds_read_b128 v[76:79], v2 offset:0x1000
	ds_read_b128 v[80:83], v2 offset:0x1800
	s_waitcnt lgkmcnt(4)
	s_nop 0
	s_setprio 1
	v_mfma_f32_16x16x32_bf16 v[84:87], v[52:55], v[16:19], 0
	s_waitcnt lgkmcnt(0)
	v_mfma_f32_16x16x32_bf16 v[52:55], v[52:55], v[12:15], 0
	v_mfma_f32_16x16x32_bf16 v[88:91], v[56:59], v[16:19], 0
	v_mfma_f32_16x16x32_bf16 v[56:59], v[56:59], v[12:15], 0
	v_mfma_f32_16x16x32_bf16 v[110:113], v[60:63], v[16:19], 0
	v_mfma_f32_16x16x32_bf16 v[60:63], v[60:63], v[12:15], 0
	v_mfma_f32_16x16x32_bf16 v[114:117], v[64:67], v[16:19], 0
	v_mfma_f32_16x16x32_bf16 v[64:67], v[64:67], v[12:15], 0
	v_mfma_f32_16x16x32_bf16 v[118:121], v[68:71], v[8:11], v[84:87]
	v_add_u32_e32 v0, s20, v129
	v_add_u32_e32 v2, s20, v180
	v_add_u32_e32 v3, s20, v181
	v_mfma_f32_16x16x32_bf16 v[208:211], v[72:75], v[8:11], v[88:91]
	v_mfma_f32_16x16x32_bf16 v[110:113], v[76:79], v[8:11], v[110:113]
	s_nop 2
	v_fma_f32 v120, v120, s92, -v102
	v_fma_f32 v121, v121, s92, -v102
	v_pk_fma_f32 v[122:123], v[118:119], s[92:93], v[102:103] op_sel_hi:[1,0,0] neg_lo:[0,0,1] neg_hi:[0,0,1]
	s_nop 0
	v_pk_fma_f32 v[118:119], v[210:211], s[92:93], v[102:103] op_sel_hi:[1,0,0] neg_lo:[0,0,1] neg_hi:[0,0,1]
	v_mfma_f32_16x16x32_bf16 v[212:215], v[80:83], v[8:11], v[114:117]
	v_max_f32_e32 v125, v118, v119
	v_pk_fma_f32 v[112:113], v[112:113], s[92:93], v[102:103] op_sel_hi:[1,0,0] neg_lo:[0,0,1] neg_hi:[0,0,1]
	v_mfma_f32_16x16x32_bf16 v[96:99], v[68:71], v[4:7], v[52:55]
	v_fma_f32 v116, v208, s92, -v102
	v_fma_f32 v117, v209, s92, -v102
	v_pk_fma_f32 v[114:115], v[110:111], s[92:93], v[102:103] op_sel_hi:[1,0,0] neg_lo:[0,0,1] neg_hi:[0,0,1]
	v_max_f32_e32 v124, v116, v117
	v_mfma_f32_16x16x32_bf16 v[92:95], v[72:75], v[4:7], v[56:59]
	v_add_u32_e32 v54, s20, v182
	v_pk_fma_f32 v[110:111], v[212:213], s[92:93], v[102:103] op_sel_hi:[1,0,0] neg_lo:[0,0,1] neg_hi:[0,0,1]
	s_mov_b32 s20, 0x40c00000
	v_mfma_f32_16x16x32_bf16 v[88:91], v[76:79], v[4:7], v[60:63]
	v_mfma_f32_16x16x32_bf16 v[84:87], v[80:83], v[4:7], v[64:67]
	s_setprio 0
	ds_read_b64 v[80:81], v0 offset:0
	ds_read_b64 v[82:83], v2 offset:0
	ds_read_b64 v[76:77], v0 offset:0x800
	ds_read_b64 v[78:79], v2 offset:0x800
	ds_read_b64 v[72:73], v0 offset:0x1000
	ds_read_b64 v[74:75], v2 offset:0x1000
	ds_read_b64 v[68:69], v0 offset:0x1800
	v_max_f32_e32 v0, v120, v121
	v_max3_f32 v0, v122, v123, v0
	ds_read_b64 v[70:71], v2 offset:0x1800
	ds_read_b64 v[64:65], v3 offset:0
	ds_read_b64 v[66:67], v54 offset:0
	ds_read_b64 v[60:61], v3 offset:0x800
	ds_read_b64 v[62:63], v54 offset:0x800
	ds_read_b64 v[56:57], v3 offset:0x1000
	ds_read_b64 v[58:59], v54 offset:0x1000
	ds_read_b64 v[52:53], v3 offset:0x1800
	v_pk_fma_f32 v[2:3], v[214:215], s[92:93], v[102:103] op_sel_hi:[1,0,0] neg_lo:[0,0,1] neg_hi:[0,0,1]
	v_max3_f32 v0, v0, v124, v125
	v_max_f32_e32 v124, v114, v115
	v_max_f32_e32 v125, v112, v113
	v_max3_f32 v0, v0, v124, v125
	v_max_f32_e32 v124, v110, v111
	v_max_f32_e32 v125, v2, v3
	v_max3_f32 v0, v0, v124, v125
	v_cmp_lt_f32_e32 vcc, s20, v0
	ds_read_b64 v[54:55], v54 offset:0x1800
	s_cbranch_vccz .LBB0_2272
	v_mov_b32_e32 v124, v0
	s_nop 1
	v_permlane16_swap_b32_e32 v0, v124
	v_max_f32_e32 v124, v124, v124
	v_max_f32_e32 v0, v0, v0
	v_max_f32_e32 v0, v0, v124
	v_mov_b32_e32 v124, v0
	s_nop 1
	v_permlane32_swap_b32_e32 v0, v124
	v_max3_f32 v0, v0, v124, 0
	v_exp_f32_e64 v124, -v0
	v_pk_add_f32 v[122:123], v[122:123], v[0:1] op_sel_hi:[1,0] neg_lo:[0,1] neg_hi:[0,1]
	v_pk_add_f32 v[120:121], v[120:121], v[0:1] op_sel_hi:[1,0] neg_lo:[0,1] neg_hi:[0,1]
	v_pk_add_f32 v[116:117], v[116:117], v[0:1] op_sel_hi:[1,0] neg_lo:[0,1] neg_hi:[0,1]
	v_pk_add_f32 v[118:119], v[118:119], v[0:1] op_sel_hi:[1,0] neg_lo:[0,1] neg_hi:[0,1]
	v_pk_add_f32 v[114:115], v[114:115], v[0:1] op_sel_hi:[1,0] neg_lo:[0,1] neg_hi:[0,1]
	v_pk_add_f32 v[112:113], v[112:113], v[0:1] op_sel_hi:[1,0] neg_lo:[0,1] neg_hi:[0,1]
	v_pk_add_f32 v[110:111], v[110:111], v[0:1] op_sel_hi:[1,0] neg_lo:[0,1] neg_hi:[0,1]
	v_pk_add_f32 v[2:3], v[2:3], v[0:1] op_sel_hi:[1,0] neg_lo:[0,1] neg_hi:[0,1]
	v_add_f32_e32 v102, v102, v0
	v_mul_f32_e32 v101, v101, v124
	v_pk_mul_f32 v[50:51], v[50:51], v[124:125] op_sel_hi:[1,0]
	v_pk_mul_f32 v[48:49], v[48:49], v[124:125] op_sel_hi:[1,0]
	v_pk_mul_f32 v[42:43], v[42:43], v[124:125] op_sel_hi:[1,0]
	v_pk_mul_f32 v[40:41], v[40:41], v[124:125] op_sel_hi:[1,0]
	v_pk_mul_f32 v[34:35], v[34:35], v[124:125] op_sel_hi:[1,0]
	v_pk_mul_f32 v[32:33], v[32:33], v[124:125] op_sel_hi:[1,0]
	v_pk_mul_f32 v[26:27], v[26:27], v[124:125] op_sel_hi:[1,0]
	v_pk_mul_f32 v[24:25], v[24:25], v[124:125] op_sel_hi:[1,0]

; template <int DK, int QB, bool NA>
; DEVI void attn_item(const AttnArgs& a, unsigned char* smem) {
;     ...
;     if (wact) {
;       f32x4 s[4][QB];
; #pragma unroll
;       for (int kb = 0; kb < 4; ++kb)
; #pragma unroll
;         for (int qb = 0; qb < QB; ++qb) s[kb][qb] = (f32x4){0.f, 0.f, 0.f, 0.f};
;       {
;         bf16x8 k0[4], k1[4], k2[4];
;         const unsigned a0 = cur + ka0, a1 = cur + ka1, a2 = cur + kr;
;         k0[0] = ldsr<0>(a0); k0[1] = ldsr<2048>(a0); k0[2] = ldsr<4096>(a0); k0[3] = ldsr<6144>(a0);
;         k1[0] = ldsr<0>(a1); k1[1] = ldsr<2048>(a1); k1[2] = ldsr<4096>(a1); k1[3] = ldsr<6144>(a1);
;         if constexpr (KS == 3) { k2[0] = ldsr<0>(a2); k2[1] = ldsr<1024>(a2); k2[2] = ldsr<2048>(a2); k2[3] = ldsr<3072>(a2); }
;         if constexpr (KS == 3) asm volatile("s_waitcnt lgkmcnt(8)" : "+v"(k0[0]), "+v"(k0[1]), "+v"(k0[2]), "+v"(k0[3]) :: "memory");
;         else                   asm volatile("s_waitcnt lgkmcnt(4)" : "+v"(k0[0]), "+v"(k0[1]), "+v"(k0[2]), "+v"(k0[3]) :: "memory");
;         __builtin_amdgcn_sched_barrier(0);
; #pragma unroll
;         for (int kb = 0; kb < 4; ++kb)
; #pragma unroll
;           for (int qb = 0; qb < QB; ++qb) s[kb][qb] = __builtin_amdgcn_mfma_f32_16x16x32_bf16(k0[kb], qf[qb][0], s[kb][qb], 0, 0, 0);
;         if constexpr (KS == 3) asm volatile("s_waitcnt lgkmcnt(4)" : "+v"(k1[0]), "+v"(k1[1]), "+v"(k1[2]), "+v"(k1[3]) :: "memory");
;         else                   asm volatile("s_waitcnt lgkmcnt(0)" : "+v"(k1[0]), "+v"(k1[1]), "+v"(k1[2]), "+v"(k1[3]) :: "memory");
;         __builtin_amdgcn_sched_barrier(0);
; #pragma unroll
;         for (int kb = 0; kb < 4; ++kb)
; #pragma unroll
;           for (int qb = 0; qb < QB; ++qb) s[kb][qb] = __builtin_amdgcn_mfma_f32_16x16x32_bf16(k1[kb], qf[qb][1], s[kb][qb], 0, 0, 0);
;         if constexpr (KS == 3) {
;           asm volatile("s_waitcnt lgkmcnt(0)" : "+v"(k2[0]), "+v"(k2[1]), "+v"(k2[2]), "+v"(k2[3]) :: "memory");
;           __builtin_amdgcn_sched_barrier(0);
; #pragma unroll
;           for (int kb = 0; kb < 4; ++kb)
; #pragma unroll
;             for (int qb = 0; qb < QB; ++qb) s[kb][qb] = __builtin_amdgcn_mfma_f32_16x16x32_bf16(k2[kb], qf[qb][2], s[kb][qb], 0, 0, 0);
;         }
;       }
;       u32x2 va[2][4], vbq[2][4];
;       {
;         const unsigned p00 = cur + vb00, p01 = cur + vb01, p10 = cur + vb10, p11 = cur + vb11;
.LBB0_2292:
	s_and_saveexec_b64 s[42:43], s[0:1]
	s_cbranch_execz .LBB0_2298
	s_mul_i32 s8, s3, 0x5000
	v_or_b32_e32 v0, s8, v183
	ds_read_b128 v[52:55], v0 offset:0
	ds_read_b128 v[56:59], v0 offset:0x800
	ds_read_b128 v[60:63], v0 offset:0x1000
	ds_read_b128 v[64:67], v0 offset:0x1800
	v_or_b32_e32 v2, s8, v184
	ds_read_b128 v[68:71], v2 offset:0
	ds_read_b128 v[72:75], v2 offset:0x800
	ds_read_b128 v[76:79], v2 offset:0x1000
	ds_read_b128 v[80:83], v2 offset:0x1800
	s_waitcnt lgkmcnt(4)
	s_nop 0
	s_setprio 1
	v_mfma_f32_16x16x32_bf16 v[84:87], v[52:55], v[16:19], 0
	s_waitcnt lgkmcnt(0)
	v_mfma_f32_16x16x32_bf16 v[52:55], v[52:55], v[12:15], 0
	v_mfma_f32_16x16x32_bf16 v[88:91], v[56:59], v[16:19], 0
	v_mfma_f32_16x16x32_bf16 v[56:59], v[56:59], v[12:15], 0
	v_mfma_f32_16x16x32_bf16 v[104:107], v[60:63], v[16:19], 0
	v_mfma_f32_16x16x32_bf16 v[60:63], v[60:63], v[12:15], 0
	v_mfma_f32_16x16x32_bf16 v[108:111], v[64:67], v[16:19], 0
	v_mfma_f32_16x16x32_bf16 v[64:67], v[64:67], v[12:15], 0
	v_mfma_f32_16x16x32_bf16 v[112:115], v[68:71], v[8:11], v[84:87]
	v_add_u32_e32 v0, s8, v129
	v_add_u32_e32 v2, s8, v180
	v_add_u32_e32 v3, s8, v181
	v_mfma_f32_16x16x32_bf16 v[118:121], v[72:75], v[8:11], v[88:91]
	v_mfma_f32_16x16x32_bf16 v[104:107], v[76:79], v[8:11], v[104:107]
	s_nop 2
	v_fma_f32 v114, v114, s92, -v102
	v_fma_f32 v115, v115, s92, -v102
	v_pk_fma_f32 v[116:117], v[112:113], s[92:93], v[102:103] op_sel_hi:[1,0,0] neg_lo:[0,0,1] neg_hi:[0,0,1]
	s_nop 0
	v_pk_fma_f32 v[112:113], v[120:121], s[92:93], v[102:103] op_sel_hi:[1,0,0] neg_lo:[0,0,1] neg_hi:[0,0,1]
	v_mfma_f32_16x16x32_bf16 v[122:125], v[80:83], v[8:11], v[108:111]
	v_mfma_f32_16x16x32_bf16 v[96:99], v[68:71], v[4:7], v[52:55]
	s_nop 1
	v_fma_f32 v110, v118, s92, -v102
	v_fma_f32 v111, v119, s92, -v102
	v_pk_fma_f32 v[108:109], v[104:105], s[92:93], v[102:103] op_sel_hi:[1,0,0] neg_lo:[0,0,1] neg_hi:[0,0,1]
	v_pk_fma_f32 v[106:107], v[106:107], s[92:93], v[102:103] op_sel_hi:[1,0,0] neg_lo:[0,0,1] neg_hi:[0,0,1]
	v_mfma_f32_16x16x32_bf16 v[92:95], v[72:75], v[4:7], v[56:59]
	v_max_f32_e32 v118, v110, v111
	v_max_f32_e32 v119, v112, v113
	v_add_u32_e32 v54, s8, v182
	v_mfma_f32_16x16x32_bf16 v[88:91], v[76:79], v[4:7], v[60:63]
	v_fma_f32 v104, v122, s92, -v102
	v_fma_f32 v105, v123, s92, -v102
	s_mov_b32 s8, 0x40c00000
	v_mfma_f32_16x16x32_bf16 v[84:87], v[80:83], v[4:7], v[64:67]
	s_setprio 0
	ds_read_b64 v[80:81], v0 offset:0
	ds_read_b64 v[82:83], v2 offset:0
	ds_read_b64 v[76:77], v0 offset:0x800
	ds_read_b64 v[78:79], v2 offset:0x800
	ds_read_b64 v[72:73], v0 offset:0x1000
	ds_read_b64 v[74:75], v2 offset:0x1000
	ds_read_b64 v[68:69], v0 offset:0x1800
	v_max_f32_e32 v0, v114, v115
	v_max3_f32 v0, v116, v117, v0
	ds_read_b64 v[70:71], v2 offset:0x1800
	ds_read_b64 v[64:65], v3 offset:0
	ds_read_b64 v[66:67], v54 offset:0
	ds_read_b64 v[60:61], v3 offset:0x800
	ds_read_b64 v[62:63], v54 offset:0x800
	ds_read_b64 v[56:57], v3 offset:0x1000
	ds_read_b64 v[58:59], v54 offset:0x1000
	ds_read_b64 v[52:53], v3 offset:0x1800
	v_pk_fma_f32 v[2:3], v[124:125], s[92:93], v[102:103] op_sel_hi:[1,0,0] neg_lo:[0,0,1] neg_hi:[0,0,1]
	v_max3_f32 v0, v0, v118, v119
	v_max_f32_e32 v118, v108, v109
	v_max_f32_e32 v119, v106, v107
	v_max3_f32 v0, v0, v118, v119
	v_max_f32_e32 v118, v104, v105
	v_max_f32_e32 v119, v2, v3
	v_max3_f32 v0, v0, v118, v119
	v_cmp_lt_f32_e32 vcc, s8, v0
	ds_read_b64 v[54:55], v54 offset:0x1800
	s_cbranch_vccz .LBB0_2295
	v_mov_b32_e32 v118, v0
	s_nop 1
	v_permlane16_swap_b32_e32 v0, v118
	v_max_f32_e32 v118, v118, v118
	v_max_f32_e32 v0, v0, v0
	v_max_f32_e32 v0, v0, v118
	v_mov_b32_e32 v118, v0
	s_nop 1
	v_permlane32_swap_b32_e32 v0, v118
	v_max3_f32 v0, v0, v118, 0
	v_exp_f32_e64 v118, -v0
	v_pk_add_f32 v[116:117], v[116:117], v[0:1] op_sel_hi:[1,0] neg_lo:[0,1] neg_hi:[0,1]
	v_pk_add_f32 v[114:115], v[114:115], v[0:1] op_sel_hi:[1,0] neg_lo:[0,1] neg_hi:[0,1]
	v_pk_add_f32 v[110:111], v[110:111], v[0:1] op_sel_hi:[1,0] neg_lo:[0,1] neg_hi:[0,1]
	v_pk_add_f32 v[112:113], v[112:113], v[0:1] op_sel_hi:[1,0] neg_lo:[0,1] neg_hi:[0,1]
	v_pk_add_f32 v[108:109], v[108:109], v[0:1] op_sel_hi:[1,0] neg_lo:[0,1] neg_hi:[0,1]
	v_pk_add_f32 v[106:107], v[106:107], v[0:1] op_sel_hi:[1,0] neg_lo:[0,1] neg_hi:[0,1]
	v_pk_add_f32 v[104:105], v[104:105], v[0:1] op_sel_hi:[1,0] neg_lo:[0,1] neg_hi:[0,1]
	v_pk_add_f32 v[2:3], v[2:3], v[0:1] op_sel_hi:[1,0] neg_lo:[0,1] neg_hi:[0,1]
	v_add_f32_e32 v102, v102, v0
	v_mul_f32_e32 v101, v101, v118
	v_pk_mul_f32 v[50:51], v[50:51], v[118:119] op_sel_hi:[1,0]
	v_pk_mul_f32 v[48:49], v[48:49], v[118:119] op_sel_hi:[1,0]
	v_pk_mul_f32 v[42:43], v[42:43], v[118:119] op_sel_hi:[1,0]
	v_pk_mul_f32 v[40:41], v[40:41], v[118:119] op_sel_hi:[1,0]
	v_pk_mul_f32 v[34:35], v[34:35], v[118:119] op_sel_hi:[1,0]
	v_pk_mul_f32 v[32:33], v[32:33], v[118:119] op_sel_hi:[1,0]
	v_pk_mul_f32 v[26:27], v[26:27], v[118:119] op_sel_hi:[1,0]
	v_pk_mul_f32 v[24:25], v[24:25], v[118:119] op_sel_hi:[1,0]

; template <int DK, int QB, bool NA>
; DEVI void attn_item(const AttnArgs& a, unsigned char* smem) {
;     ...
;     if (j + 1 < nt) {
;       if constexpr (DK == 96) asm volatile("s_waitcnt vmcnt(5)" ::: "memory");
;       else                    asm volatile("s_waitcnt vmcnt(4)" ::: "memory");
;     } else {
;       asm volatile("s_waitcnt vmcnt(0)" ::: "memory");
;     }
;     RAW_BARRIER();
;     if (j + 2 < nt) ATT_ISSUE(j + 2, is);
;     is = (is + 1 == S) ? 0 : is + 1;
;     const unsigned cur = lbase + cs * ATT_STAGE;
;     cs = (cs + 1 == S) ? 0 : cs + 1;
;     if (wact) {
;       f32x4 s[4][QB];
; #pragma unroll
;       for (int kb = 0; kb < 4; ++kb)
; #pragma unroll
;         for (int qb = 0; qb < QB; ++qb) s[kb][qb] = (f32x4){0.f, 0.f, 0.f, 0.f};
;       {
;         bf16x8 k0[4], k1[4], k2[4];
;         const unsigned a0 = cur + ka0, a1 = cur + ka1, a2 = cur + kr;
;         k0[0] = ldsr<0>(a0); k0[1] = ldsr<2048>(a0); k0[2] = ldsr<4096>(a0); k0[3] = ldsr<6144>(a0);
;         k1[0] = ldsr<0>(a1); k1[1] = ldsr<2048>(a1); k1[2] = ldsr<4096>(a1); k1[3] = ldsr<6144>(a1);
;         if constexpr (KS == 3) { k2[0] = ldsr<0>(a2); k2[1] = ldsr<1024>(a2); k2[2] = ldsr<2048>(a2); k2[3] = ldsr<3072>(a2); }
;         if constexpr (KS == 3) asm volatile("s_waitcnt lgkmcnt(8)" : "+v"(k0[0]), "+v"(k0[1]), "+v"(k0[2]), "+v"(k0[3]) :: "memory");
;         else                   asm volatile("s_waitcnt lgkmcnt(4)" : "+v"(k0[0]), "+v"(k0[1]), "+v"(k0[2]), "+v"(k0[3]) :: "memory");
;         __builtin_amdgcn_sched_barrier(0);
; #pragma unroll
;         for (int kb = 0; kb < 4; ++kb)
; #pragma unroll
;           for (int qb = 0; qb < QB; ++qb) s[kb][qb] = __builtin_amdgcn_mfma_f32_16x16x32_bf16(k0[kb], qf[qb][0], s[kb][qb], 0, 0, 0);
;     ...
;           f32x2 ls2 = {0.f, 0.f};
;           unsigned pw[2][4];
; #pragma unroll
;           for (int kb = 0; kb < 4; ++kb)
; #pragma unroll
;             for (int h = 0; h < 2; ++h) {
;               const f32x2 pe = {__builtin_amdgcn_exp2f(t[kb][h].x), __builtin_amdgcn_exp2f(t[kb][h].y)};
;               ls2 += pe;
;               pw[kb >> 1][(kb & 1) * 2 + h] = pk2(pe.x, pe.y);
;             }
;           l[qb] += ls2.x + ls2.y;
; #pragma unroll
;           for (int c = 0; c < 2; ++c) {
;             const u32x4 pv = (u32x4){pw[c][0], pw[c][1], pw[c][2], pw[c][3]};
;             pf[qb][c] = __builtin_bit_cast(bf16x8, pv);
;           }
.LBB0_2297:
	v_exp_f32_e32 v86, v116
	v_exp_f32_e32 v87, v117
	v_exp_f32_e32 v116, v114
	v_exp_f32_e32 v117, v115
	v_exp_f32_e32 v110, v110
	v_exp_f32_e32 v111, v111
	v_pk_add_f32 v[120:121], v[86:87], 0 op_sel_hi:[1,0]
	v_exp_f32_e32 v112, v112
	v_exp_f32_e32 v113, v113
	v_cvt_pk_bf16_f32 v114, v86, v87
	v_pk_add_f32 v[86:87], v[116:117], v[120:121]
	v_exp_f32_e32 v108, v108
	v_exp_f32_e32 v109, v109
	v_cvt_pk_bf16_f32 v115, v116, v117
	v_pk_add_f32 v[86:87], v[110:111], v[86:87]
	v_cvt_pk_bf16_f32 v116, v110, v111
	v_exp_f32_e32 v110, v106
	v_exp_f32_e32 v111, v107
	v_exp_f32_e32 v104, v104
	v_exp_f32_e32 v105, v105
	v_pk_add_f32 v[86:87], v[112:113], v[86:87]
	v_exp_f32_e32 v2, v2
	v_exp_f32_e32 v3, v3
	v_pk_add_f32 v[86:87], v[108:109], v[86:87]
	v_cvt_pk_bf16_f32 v106, v108, v109
	v_pk_add_f32 v[86:87], v[110:111], v[86:87]
	v_cvt_pk_bf16_f32 v109, v2, v3
	v_pk_add_f32 v[86:87], v[104:105], v[86:87]
	v_exp_f32_e32 v96, v96
	v_pk_add_f32 v[86:87], v[2:3], v[86:87]
	v_exp_f32_e32 v2, v118
	v_exp_f32_e32 v3, v119
	v_add_f32_e32 v0, v86, v87
	v_exp_f32_e32 v86, v98
	v_exp_f32_e32 v87, v99
	v_exp_f32_e32 v97, v97
	v_pk_add_f32 v[98:99], v[2:3], 0 op_sel_hi:[1,0]
	v_exp_f32_e32 v94, v94
	v_exp_f32_e32 v95, v95
	v_cvt_pk_bf16_f32 v107, v110, v111
	v_cvt_pk_bf16_f32 v110, v2, v3
	v_pk_add_f32 v[2:3], v[86:87], v[98:99]
	v_cvt_pk_bf16_f32 v111, v86, v87
	v_exp_f32_e32 v86, v92
	v_exp_f32_e32 v87, v93
	v_exp_f32_e32 v90, v90
	v_exp_f32_e32 v91, v91
	v_pk_add_f32 v[2:3], v[96:97], v[2:3]
	v_exp_f32_e32 v88, v88
	v_exp_f32_e32 v89, v89
	v_pk_add_f32 v[2:3], v[94:95], v[2:3]
	v_exp_f32_e32 v84, v84
	v_exp_f32_e32 v85, v85
	v_pk_add_f32 v[2:3], v[86:87], v[2:3]
	s_waitcnt lgkmcnt(0)
	v_add_f32_e32 v101, v101, v0
	v_pk_add_f32 v[2:3], v[90:91], v[2:3]
	v_cvt_pk_bf16_f32 v117, v112, v113
	v_pk_add_f32 v[2:3], v[88:89], v[2:3]
	v_cvt_pk_bf16_f32 v108, v104, v105
	v_pk_add_f32 v[2:3], v[84:85], v[2:3]
	v_cvt_pk_bf16_f32 v112, v96, v97
	v_add_f32_e32 v0, v2, v3
	v_add_f32_e32 v100, v100, v0
	v_cvt_pk_bf16_f32 v113, v94, v95
	v_cvt_pk_bf16_f32 v86, v86, v87
	v_cvt_pk_bf16_f32 v87, v90, v91
	v_cvt_pk_bf16_f32 v88, v88, v89
	v_cvt_pk_bf16_f32 v89, v84, v85
	s_setprio 1
	v_mfma_f32_16x16x32_bf16 v[48:51], v[80:83], v[114:117], v[48:51]
	v_mfma_f32_16x16x32_bf16 v[44:47], v[80:83], v[110:113], v[44:47]
	v_mfma_f32_16x16x32_bf16 v[40:43], v[76:79], v[114:117], v[40:43]
	v_mfma_f32_16x16x32_bf16 v[36:39], v[76:79], v[110:113], v[36:39]
	v_mfma_f32_16x16x32_bf16 v[32:35], v[72:75], v[114:117], v[32:35]
	v_mfma_f32_16x16x32_bf16 v[28:31], v[72:75], v[110:113], v[28:31]
	v_mfma_f32_16x16x32_bf16 v[24:27], v[68:71], v[114:117], v[24:27]
	v_mfma_f32_16x16x32_bf16 v[20:23], v[68:71], v[110:113], v[20:23]
	v_mfma_f32_16x16x32_bf16 v[48:51], v[64:67], v[106:109], v[48:51]
	v_mfma_f32_16x16x32_bf16 v[44:47], v[64:67], v[86:89], v[44:47]
	v_mfma_f32_16x16x32_bf16 v[40:43], v[60:63], v[106:109], v[40:43]
	v_mfma_f32_16x16x32_bf16 v[36:39], v[60:63], v[86:89], v[36:39]
	v_mfma_f32_16x16x32_bf16 v[32:35], v[56:59], v[106:109], v[32:35]
	v_mfma_f32_16x16x32_bf16 v[28:31], v[56:59], v[86:89], v[28:31]
	v_mfma_f32_16x16x32_bf16 v[24:27], v[52:55], v[106:109], v[24:27]
	v_mfma_f32_16x16x32_bf16 v[20:23], v[52:55], v[86:89], v[20:23]
	s_setprio 0
.LBB0_2298:
	s_or_b64 exec, exec, s[42:43]
	s_waitcnt vmcnt(0)
	s_waitcnt lgkmcnt(0)
	s_mov_b64 s[42:43], 0
	s_mov_b64 s[52:53], 0
	s_barrier
	s_and_saveexec_b64 s[54:55], s[0:1]
	s_cbranch_execz .LBB0_2308
	s_add_i32 s0, s3, 1
	s_mul_i32 s1, s0, 0x5000
	s_cmp_lg_u32 s0, 3
	s_cselect_b32 s0, s1, 0
	v_or_b32_e32 v0, s0, v183
	ds_read_b128 v[52:55], v0 offset:0
	ds_read_b128 v[56:59], v0 offset:0x800
	ds_read_b128 v[60:63], v0 offset:0x1000
	ds_read_b128 v[64:67], v0 offset:0x1800
	v_or_b32_e32 v2, s0, v184
	ds_read_b128 v[68:71], v2 offset:0
	ds_read_b128 v[72:75], v2 offset:0x800
	ds_read_b128 v[76:79], v2 offset:0x1000
	ds_read_b128 v[80:83], v2 offset:0x1800
	s_waitcnt lgkmcnt(4)
	s_nop 0
	s_setprio 1
	v_mfma_f32_16x16x32_bf16 v[16:19], v[52:55], v[16:19], 0
	s_waitcnt lgkmcnt(0)
	v_mfma_f32_16x16x32_bf16 v[12:15], v[52:55], v[12:15], 0
	v_mfma_f32_16x16x32_bf16 v[74:77], v[68:71], v[8:11], v[16:19]
	v_add_u32_e32 v2, s0, v180
	v_add_u32_e32 v3, s0, v181
	v_add_u32_e32 v0, s0, v129
	s_nop 2
	v_add_u32_e32 v18, s0, v182
	ds_read_b64 v[64:65], v0 offset:0
	v_mfma_f32_16x16x32_bf16 v[68:71], v[68:71], v[4:7], v[12:15]
	s_setprio 0
	ds_read_b64 v[66:67], v2 offset:0
	ds_read_b64 v[60:61], v0 offset:0x800
	ds_read_b64 v[62:63], v2 offset:0x800
	ds_read_b64 v[56:57], v0 offset:0x1000
	ds_read_b64 v[58:59], v2 offset:0x1000
	ds_read_b64 v[52:53], v0 offset:0x1800
	ds_read_b64 v[54:55], v2 offset:0x1800
	ds_read_b64 v[14:15], v3 offset:0
	ds_read_b64 v[16:17], v18 offset:0
	ds_read_b64 v[10:11], v3 offset:0x800
	ds_read_b64 v[12:13], v18 offset:0x800
	ds_read_b64 v[6:7], v3 offset:0x1000
	ds_read_b64 v[8:9], v18 offset:0x1000
	ds_read_b64 v[2:3], v3 offset:0x1800
	ds_read_b64 v[4:5], v18 offset:0x1800
	v_fma_f32 v74, v74, s92, -v102
	v_fma_f32 v75, v75, s92, -v102
	v_pk_fma_f32 v[72:73], v[76:77], s[92:93], v[102:103] op_sel_hi:[1,0,0] neg_lo:[0,0,1] neg_hi:[0,0,1]
	v_sub_f32_e32 v18, 0xf011accb, v102
	v_max_f32_e32 v0, v74, v75
	v_max_f32_e32 v19, v72, v73
	v_max_f32_e32 v76, v18, v18
	v_max3_f32 v0, v0, v19, v76
	s_mov_b32 s0, 0x40c00000
	v_mov_b32_e32 v19, v18
	v_cmp_lt_f32_e32 vcc, s0, v0
	s_cbranch_vccz .LBB0_2301
	v_mov_b32_e32 v76, v0
	s_nop 1
	v_permlane16_swap_b32_e32 v0, v76
	v_max_f32_e32 v76, v76, v76
	v_max_f32_e32 v0, v0, v0
	v_max_f32_e32 v0, v0, v76
	v_mov_b32_e32 v76, v0
	s_nop 1
	v_permlane32_swap_b32_e32 v0, v76
	v_max3_f32 v0, v0, v76, 0
	v_exp_f32_e64 v76, -v0
	v_pk_add_f32 v[74:75], v[74:75], v[0:1] op_sel_hi:[1,0] neg_lo:[0,1] neg_hi:[0,1]
	v_pk_add_f32 v[72:73], v[72:73], v[0:1] op_sel_hi:[1,0] neg_lo:[0,1] neg_hi:[0,1]
	v_pk_add_f32 v[18:19], v[18:19], v[0:1] op_sel_hi:[1,0] neg_lo:[0,1] neg_hi:[0,1]
	v_mul_f32_e32 v101, v101, v76
	v_pk_mul_f32 v[50:51], v[50:51], v[76:77] op_sel_hi:[1,0]
	v_pk_mul_f32 v[48:49], v[48:49], v[76:77] op_sel_hi:[1,0]
	v_pk_mul_f32 v[42:43], v[42:43], v[76:77] op_sel_hi:[1,0]
	v_pk_mul_f32 v[40:41], v[40:41], v[76:77] op_sel_hi:[1,0]
	v_pk_mul_f32 v[34:35], v[34:35], v[76:77] op_sel_hi:[1,0]
	v_pk_mul_f32 v[32:33], v[32:33], v[76:77] op_sel_hi:[1,0]
	v_pk_mul_f32 v[26:27], v[26:27], v[76:77] op_sel_hi:[1,0]
	v_pk_mul_f32 v[24:25], v[24:25], v[76:77] op_sel_hi:[1,0]

; DEVI unsigned pk2(float lo, float hi) { const f32x2_t v = {lo, hi}; const bf16x2_t b = __builtin_convertvector(v, bf16x2_t); return __builtin_bit_cast(unsigned, b); }
; DEVI size_t blk_off(int row, int col) { return ((size_t)(col >> 5) * MROWS + row) * 32 + (col & 31); }
; DEVI float xsum16(float x) { auto r = __builtin_amdgcn_permlane16_swap(__float_as_uint(x), __float_as_uint(x), false, false); return __uint_as_float(r[0]) + __uint_as_float(r[1]); }
; DEVI float xsum32(float x) { auto r = __builtin_amdgcn_permlane32_swap(__float_as_uint(x), __float_as_uint(x), false, false); return __uint_as_float(r[0]) + __uint_as_float(r[1]); }
; template <int DK, int QB, bool NA>
; DEVI void attn_item(const AttnArgs& a, unsigned char* smem) {
;     ...
;       asm volatile("s_waitcnt lgkmcnt(0)"
;                    : "+v"(va[0][0]), "+v"(va[0][1]), "+v"(va[0][2]), "+v"(va[0][3]), "+v"(va[1][0]), "+v"(va[1][1]), "+v"(va[1][2]), "+v"(va[1][3]),
;                      "+v"(vbq[0][0]), "+v"(vbq[0][1]), "+v"(vbq[0][2]), "+v"(vbq[0][3]), "+v"(vbq[1][0]), "+v"(vbq[1][1]), "+v"(vbq[1][2]), "+v"(vbq[1][3])
;                    :: "memory");
;       __builtin_amdgcn_sched_barrier(0);
; #pragma unroll
;       for (int c = 0; c < 2; ++c)
; #pragma unroll
;         for (int db = 0; db < 4; ++db) {
;           const u32x4 vw = (u32x4){va[c][db].x, va[c][db].y, vbq[c][db].x, vbq[c][db].y};
;           const bf16x8 vf = __builtin_bit_cast(bf16x8, vw);
; #pragma unroll
;           for (int qb = 0; qb < QB; ++qb) o[db][qb] = __builtin_amdgcn_mfma_f32_16x16x32_bf16(vf, pf[qb][c], o[db][qb], 0, 0, 0);
;         }
;     }
;   }
;     ...
;   if (wact) {
; #pragma unroll
;     for (int qb = 0; qb < QB; ++qb) {
;       const float lt = xsum32(xsum16(l[qb]));
;       const float inv = 1.0f / lt;
;       const int qi = w * QB * 16 + qb * 16 + l16;
;       if (qi < a.nq) {
; #pragma unroll
;         for (int db = 0; db < 4; ++db) {
;           const f32x4 v = o[db][qb] * inv;
;           *(u32x2*)(a.O + blk_off(a.orow0 + qi, a.ocol0 + db * 16 + g * 4)) = (u32x2){pk2(v[0], v[1]), pk2(v[2], v[3])};
;         }
;       }
;     }
.LBB0_2303:
	v_exp_f32_e32 v74, v74
	v_exp_f32_e32 v75, v75
	v_exp_f32_e32 v72, v72
	v_exp_f32_e32 v73, v73
	v_exp_f32_e32 v18, v18
	v_exp_f32_e32 v19, v19
	v_pk_add_f32 v[80:81], v[74:75], 0 op_sel_hi:[1,0]
	v_cvt_pk_bf16_f32 v78, v74, v75
	v_pk_add_f32 v[74:75], v[72:73], v[80:81]
	v_cvt_pk_bf16_f32 v79, v72, v73
	v_pk_add_f32 v[72:73], v[18:19], v[74:75]
	v_exp_f32_e32 v70, v70
	v_pk_add_f32 v[72:73], v[18:19], v[72:73]
	v_exp_f32_e32 v71, v71
	v_pk_add_f32 v[72:73], v[18:19], v[72:73]
	v_cvt_pk_bf16_f32 v80, v18, v19
	v_pk_add_f32 v[72:73], v[18:19], v[72:73]
	v_exp_f32_e32 v68, v68
	v_pk_add_f32 v[72:73], v[18:19], v[72:73]
	v_exp_f32_e32 v69, v69
	v_pk_add_f32 v[18:19], v[18:19], v[72:73]
	v_exp_f32_e32 v72, v76
	v_exp_f32_e32 v73, v77
	s_waitcnt lgkmcnt(0)
	v_add_f32_e32 v0, v18, v19
	v_add_f32_e32 v0, v101, v0
	v_cvt_pk_bf16_f32 v76, v70, v71
	v_mov_b32_e32 v81, v80
	v_mov_b32_e32 v82, v80
	v_mov_b32_e32 v83, v80
	v_mov_b32_e32 v84, v80
	v_mov_b32_e32 v85, v80
	v_cvt_pk_bf16_f32 v74, v68, v69
	v_cvt_pk_bf16_f32 v75, v72, v73
	v_mov_b32_e32 v77, v76
	v_mov_b32_e32 v86, v76
	v_mov_b32_e32 v87, v76
	v_mov_b32_e32 v88, v76
	v_mov_b32_e32 v89, v76
	s_setprio 1
	v_mfma_f32_16x16x32_bf16 v[40:43], v[60:63], v[78:81], v[40:43]
	v_mfma_f32_16x16x32_bf16 v[36:39], v[60:63], v[74:77], v[36:39]
	v_mfma_f32_16x16x32_bf16 v[48:51], v[64:67], v[78:81], v[48:51]
	v_mfma_f32_16x16x32_bf16 v[44:47], v[64:67], v[74:77], v[44:47]
	v_mfma_f32_16x16x32_bf16 v[60:63], v[56:59], v[78:81], v[32:35]
	v_mfma_f32_16x16x32_bf16 v[56:59], v[56:59], v[74:77], v[28:31]
	s_nop 1
	v_or_b32_e32 v35, v128, v126
	v_lshlrev_b32_e32 v34, 2, v127
	v_cmp_gt_i32_e32 vcc, s57, v35
	v_mfma_f32_16x16x32_bf16 v[26:29], v[52:55], v[78:81], v[24:27]
	v_mfma_f32_16x16x32_bf16 v[52:55], v[52:55], v[74:77], v[20:23]
	v_mfma_f32_16x16x32_bf16 v[22:25], v[10:13], v[82:85], v[40:43]
	v_mfma_f32_16x16x32_bf16 v[10:13], v[10:13], v[86:89], v[36:39]
	s_nop 2
	v_mov_b32_e32 v36, v0
	v_mfma_f32_16x16x32_bf16 v[30:33], v[14:17], v[82:85], v[48:51]
	s_nop 0
	v_permlane16_swap_b32_e32 v0, v36
	v_add_f32_e32 v36, v0, v36
	v_mfma_f32_16x16x32_bf16 v[14:17], v[14:17], v[86:89], v[44:47]
	v_mov_b32_e32 v37, v36
	s_nop 1
	v_permlane32_swap_b32_e32 v36, v37
	v_mfma_f32_16x16x32_bf16 v[18:21], v[6:9], v[82:85], v[60:63]
	v_lshlrev_b32_e32 v0, 1, v34
	v_mfma_f32_16x16x32_bf16 v[6:9], v[6:9], v[86:89], v[56:59]
	v_mfma_f32_16x16x32_bf16 v[26:29], v[2:5], v[82:85], v[26:29]
	v_mfma_f32_16x16x32_bf16 v[2:5], v[2:5], v[86:89], v[52:55]
	s_setprio 0
	s_and_saveexec_b64 s[0:1], vcc
	s_cbranch_execz .LBB0_2305
	v_add_f32_e32 v36, v36, v37
	v_div_scale_f32 v37, s[8:9], v36, v36, 1.0
	v_rcp_f32_e32 v38, v37
	v_div_scale_f32 v39, vcc, 1.0, v36, 1.0
	s_lshl_b32 s3, s58, 1
	v_fma_f32 v40, -v37, v38, 1.0
	v_fmac_f32_e32 v38, v40, v38
	v_mul_f32_e32 v40, v39, v38
	v_fma_f32 v41, -v37, v40, v39
	v_fmac_f32_e32 v40, v41, v38
	v_fma_f32 v37, -v37, v40, v39
	v_div_fmas_f32 v37, v37, v38, v40
	v_div_fixup_f32 v36, v37, v36, 1.0
	v_pk_mul_f32 v[32:33], v[32:33], v[36:37] op_sel_hi:[1,0]
	v_pk_mul_f32 v[30:31], v[30:31], v[36:37] op_sel_hi:[1,0]
	v_pk_mul_f32 v[20:21], v[20:21], v[36:37] op_sel_hi:[1,0]
	v_cvt_pk_bf16_f32 v30, v30, v31
	v_cvt_pk_bf16_f32 v31, v32, v33
	v_add_u32_e32 v32, s59, v35
	v_ashrrev_i32_e32 v33, 31, v32
	v_mad_u64_u32 v[38:39], s[8:9], s3, v206, v[32:33]
	v_pk_mul_f32 v[18:19], v[18:19], v[36:37] op_sel_hi:[1,0]
	s_or_b32 s3, s3, 1
	v_readlane_b32 s28, v251, 54
	v_cvt_pk_bf16_f32 v18, v18, v19
	v_cvt_pk_bf16_f32 v19, v20, v21
	v_mad_u64_u32 v[20:21], s[8:9], s3, v206, v[32:33]
	v_lshlrev_b64 v[38:39], 6, v[38:39]
	v_readlane_b32 s29, v251, 55
	v_lshlrev_b64 v[20:21], 6, v[20:21]
	v_pk_mul_f32 v[24:25], v[24:25], v[36:37] op_sel_hi:[1,0]
	v_lshl_add_u64 v[38:39], s[28:29], 0, v[38:39]
	v_pk_mul_f32 v[22:23], v[22:23], v[36:37] op_sel_hi:[1,0]
	v_lshl_add_u64 v[20:21], s[28:29], 0, v[20:21]
	v_lshl_add_u64 v[38:39], v[38:39], 0, v[0:1]
	v_cvt_pk_bf16_f32 v22, v22, v23
	v_cvt_pk_bf16_f32 v23, v24, v25
	v_lshl_add_u64 v[20:21], v[20:21], 0, v[0:1]
	global_store_dwordx2 v[38:39], v[22:23], off offset:32
	global_store_dwordx2 v[20:21], v[18:19], off
	v_pk_mul_f32 v[18:19], v[28:29], v[36:37] op_sel_hi:[1,0]
	v_pk_mul_f32 v[20:21], v[26:27], v[36:37] op_sel_hi:[1,0]
	v_or_b32_e32 v22, s56, v34
	v_cvt_pk_bf16_f32 v20, v20, v21
	v_cvt_pk_bf16_f32 v21, v18, v19
	v_or_b32_e32 v18, 48, v22
	v_lshrrev_b32_e32 v18, 5, v18
	v_mad_u64_u32 v[18:19], s[8:9], v18, s93, v[32:33]
	v_bitop3_b32 v22, v22, 28, 48 bitop3:0xc8
	v_lshlrev_b64 v[18:19], 6, v[18:19]
	v_lshl_add_u64 v[18:19], s[28:29], 0, v[18:19]
	v_lshlrev_b32_e32 v22, 1, v22
	v_mov_b32_e32 v23, v1
	v_lshl_add_u64 v[18:19], v[18:19], 0, v[22:23]
	global_store_dwordx2 v[38:39], v[30:31], off
	global_store_dwordx2 v[18:19], v[20:21], off

; DEVI int otid() { int t = threadIdx.x; asm volatile("" : "+v"(t)); return t; }
; #define RAW_BARRIER() do { asm volatile("s_waitcnt lgkmcnt(0)" ::: "memory"); __builtin_amdgcn_s_barrier(); } while (0)
; template <int DK, int QB, bool NA>
; DEVI void attn_item(const AttnArgs& a, unsigned char* smem) {
;     ...
;   const int tid = otid(), lane = tid & 63, w = tid >> 6;
;   const int l16 = lane & 15, g = lane >> 4;
;   const bool wact = (w * QB * 16) < a.nq;
;   const int nt = a.nreg + 1;
;   const unsigned lbase = (unsigned)(uintptr_t)(__attribute__((address_space(3))) unsigned char*)smem;
;   bf16x8 qf[QB][KS];
; #pragma unroll
;   for (int qb = 0; qb < QB; ++qb) {
;     const bf16_t* qp = a.Q + (size_t)((wact ? w * QB * 16 : 0) + qb * 16 + l16) * a.ldq + g * 8;
; #pragma unroll
;     for (int ks = 0; ks < KS; ++ks) qf[qb][ks] = *(const bf16x8*)(qp + ks * 32);
;   }
;   float m[QB], l[QB];
;   f32x4 o[4][QB];
; #pragma unroll
;   for (int qb = 0; qb < QB; ++qb) {
;     m[qb] = NA ? -1e30f : 0.f; l[qb] = 0.f;
; #pragma unroll
;     for (int db = 0; db < 4; ++db) o[db][qb] = (f32x4){0.f, 0.f, 0.f, 0.f};
;   }
;   const int r8 = tid >> 3, c8 = (tid & 7) ^ ((tid >> 4) & 7);
;   const bf16_t* Kn = a.K + (size_t)r8 * a.ldk + c8 * 8;
;   const bf16_t* Kr = a.K + (size_t)(tid >> 2) * a.ldk + 64 + (((tid & 3) ^ ((0 - (tid >> 4)) & 3)) * 8);
;   const bf16_t* Vg = a.Vt + (size_t)r8 * a.Lk + c8 * 8;
;   const size_t kstep = (size_t)32 * a.ldk, vstep = (size_t)32 * a.Lk;
;   unsigned char* lds_t = smem + tid * 16;
;     ...
;   asm volatile("s_waitcnt vmcnt(0)" ::: "memory");
;   RAW_BARRIER();
;   ATT_ISSUE(0, 0);
;   if (nt > 1) ATT_ISSUE(1, 1);
;   const int sw8 = (l16 >> 1) & 7, vsw = sw8 << 1;
;   const unsigned ka0 = l16 * 128 + ((g ^ sw8) << 4), ka1 = l16 * 128 + (((4 + g) ^ sw8) << 4);
;   const unsigned kr = 8192 + l16 * 64 + ((g ^ ((0 - (l16 >> 2)) & 3)) << 4);
;   const unsigned vb00 = 12288 + l16 * 128 + (((0 + g) ^ vsw) << 3), vb01 = 12288 + l16 * 128 + (((4 + g) ^ vsw) << 3);
;   const unsigned vb10 = 12288 + l16 * 128 + (((8 + g) ^ vsw) << 3), vb11 = 12288 + l16 * 128 + (((12 + g) ^ vsw) << 3);
;   const unsigned biasA = lbase + ATT_BIAS_OFF;
;   const int qc = w * 16 + l16;
;   const int cs0 = min(max(qc - 8, 0), 48);
;   int cs = 0, is = 2;
.LBB0_2309:
	s_mul_i32 s1, s59, 0x600
	v_readlane_b32 s3, v251, 58
	s_mul_hi_i32 s0, s59, 0x600
	s_add_u32 s3, s3, s1
	v_readlane_b32 s1, v251, 59
	s_mul_i32 s20, s58, 0x60
	s_addc_u32 s9, s1, s0
	s_lshl_b64 s[0:1], s[20:21], 1
	s_add_u32 s8, s3, s0
	s_addc_u32 s9, s9, s1
	s_ashr_i32 s3, s2, 31
	s_mul_i32 s40, s2, 0x600
	v_readlane_b32 s28, v251, 60
	s_mul_hi_i32 s20, s2, 0x600
	s_add_u32 s40, s28, s40
	v_readlane_b32 s28, v251, 61
	s_addc_u32 s20, s28, s20
	s_add_u32 s40, s40, s0
	s_addc_u32 s41, s20, s1
	s_lshl_b64 s[0:1], s[2:3], 10
	v_readlane_b32 s2, v251, 62
	s_add_u32 s2, s2, s0
	v_readlane_b32 s0, v251, 63
	s_mul_i32 s20, s62, s56
	v_mov_b32_e32 v2, v177
	s_addc_u32 s3, s0, s1
	s_lshl_b64 s[0:1], s[20:21], 1
	s_add_u32 s2, s2, s0
	v_ashrrev_i32_e32 v0, 1, v2
	v_and_b32_e32 v208, 0xffffffe0, v0
	s_addc_u32 s3, s3, s1
	v_cmp_gt_i32_e64 s[0:1], s57, v208
	v_and_b32_e32 v186, 15, v2
	v_bfe_u32 v187, v2, 4, 2
	v_cndmask_b32_e64 v0, 0, v208, s[0:1]
	v_or_b32_e32 v3, v0, v186
	v_lshlrev_b32_e32 v0, 4, v187
	v_lshl_add_u64 v[4:5], s[8:9], 0, v[0:1]
	s_movk_i32 s20, 0x600
	v_or_b32_e32 v0, 16, v3
	v_ashrrev_i32_e32 v32, 4, v2
	v_mad_i64_i32 v[6:7], s[8:9], v3, s20, v[4:5]
	v_mad_i64_i32 v[4:5], s[8:9], v0, s20, v[4:5]
	v_xor_b32_e32 v0, v32, v2
	v_ashrrev_i32_e32 v3, 3, v2
	v_mov_b64_e32 v[28:29], s[40:41]
	v_lshlrev_b32_e32 v0, 4, v0
	v_mad_i64_i32 v[30:31], s[8:9], v3, s20, v[28:29]
	v_and_b32_e32 v0, 0x70, v0
	v_lshl_add_u64 v[114:115], v[30:31], 0, v[0:1]
	v_ashrrev_i32_e32 v30, 2, v2
	v_mad_i64_i32 v[28:29], s[8:9], v30, s20, v[28:29]
	v_sub_u32_e32 v30, 0, v32
	v_xor_b32_e32 v30, v2, v30
	v_lshlrev_b32_e32 v30, 4, v30
	v_and_b32_e32 v30, 48, v30
	v_mov_b32_e32 v31, v1
	v_lshl_add_u64 v[116:117], v[28:29], 0, v[30:31]
	v_mad_i64_i32 v[30:31], s[8:9], v3, s62, 0
	v_lshl_add_u64 v[30:31], v[30:31], 1, s[2:3]
	v_lshlrev_b32_e32 v216, 4, v2
	v_lshl_add_u64 v[112:113], v[30:31], 0, v[0:1]
	v_readfirstlane_b32 s2, v216
	v_add_u32_e32 v0, 0x1000, v216
	global_load_dwordx4 v[24:27], v[6:7], off
	global_load_dwordx4 v[16:19], v[6:7], off offset:64
	global_load_dwordx4 v[8:11], v[6:7], off offset:128
	global_load_dwordx4 v[20:23], v[4:5], off
	global_load_dwordx4 v[12:15], v[4:5], off offset:64
	s_nop 0
	global_load_dwordx4 v[4:7], v[4:5], off offset:128
	s_waitcnt vmcnt(0)
	s_mov_b32 m0, s2
	v_readfirstlane_b32 s2, v0
	v_add_u32_e32 v0, 0x2000, v216
	s_mov_b64 s[40:41], 0x80
	s_waitcnt lgkmcnt(0)
	s_barrier
	global_load_lds_dwordx4 v[114:115], off
	v_lshl_add_u64 v[30:31], v[114:115], 0, s[86:87]
	s_mov_b32 m0, s2
	v_readfirstlane_b32 s2, v0
	v_add_u32_e32 v0, 0x3000, v216
	v_lshl_add_u64 v[28:29], v[116:117], 0, s[40:41]
	global_load_lds_dwordx4 v[30:31], off
	s_mov_b32 m0, s2
	v_readfirstlane_b32 s2, v0
	v_add_u32_e32 v0, 0x4000, v216
	global_load_lds_dwordx4 v[28:29], off
	s_mov_b32 m0, s2
	s_lshl_b32 s20, s62, 6
	v_readfirstlane_b32 s2, v0
	v_add_u32_e32 v0, 0x5000, v216
	global_load_lds_dwordx4 v[112:113], off
	v_lshl_add_u64 v[118:119], v[112:113], 0, s[20:21]
	s_mov_b32 m0, s2
	v_readfirstlane_b32 s2, v0
	global_load_lds_dwordx4 v[118:119], off
	v_lshl_add_u64 v[28:29], v[114:115], 0, s[38:39]
	s_mov_b32 m0, s2
	s_mov_b64 s[2:3], 0x24000
	v_add_u32_e32 v0, 0x6000, v216
	global_load_lds_dwordx4 v[28:29], off
	v_lshl_add_u64 v[28:29], v[114:115], 0, s[2:3]
	v_readfirstlane_b32 s2, v0
	s_mov_b32 m0, s2
	s_mov_b64 s[2:3], 0x18080
	v_add_u32_e32 v0, 0x7000, v216
	global_load_lds_dwordx4 v[28:29], off
	v_lshl_add_u64 v[28:29], v[116:117], 0, s[2:3]
	v_readfirstlane_b32 s2, v0
	v_add_u32_e32 v0, 0x8000, v216
	s_mov_b32 m0, s2
	v_readfirstlane_b32 s2, v0
	v_add_u32_e32 v0, 0x9000, v216
	global_load_lds_dwordx4 v[28:29], off
	v_lshl_add_u64 v[28:29], v[112:113], 0, s[40:41]
	s_mov_b32 m0, s2
	v_readfirstlane_b32 s2, v0
	global_load_lds_dwordx4 v[28:29], off
	v_lshl_add_u64 v[28:29], v[118:119], 0, s[40:41]
	s_mov_b32 m0, s2
	v_add_u32_e32 v0, 0xa000, v216
	global_load_lds_dwordx4 v[28:29], off
	v_readfirstlane_b32 s2, v0
	s_waitcnt vmcnt(5)
	v_lshl_add_u64 v[28:29], v[114:115], 0, s[4:5]
	s_mov_b32 m0, s2
	s_mov_b64 s[2:3], 0x3c000
	v_add_u32_e32 v0, 0xb000, v216
	s_waitcnt lgkmcnt(0)
	s_barrier
	global_load_lds_dwordx4 v[28:29], off
	v_lshl_add_u64 v[28:29], v[114:115], 0, s[2:3]
	v_readfirstlane_b32 s2, v0
	s_mov_b32 m0, s2
	s_mov_b64 s[2:3], 0x30080
	v_add_u32_e32 v0, 0xc000, v216
	global_load_lds_dwordx4 v[28:29], off
	v_lshl_add_u64 v[28:29], v[116:117], 0, s[2:3]
	v_readfirstlane_b32 s2, v0
	v_add_u32_e32 v0, 0xd000, v216
	s_mov_b32 m0, s2
	s_mov_b64 s[8:9], 0x100
	v_readfirstlane_b32 s2, v0
	v_add_u32_e32 v0, 0xe000, v216
	global_load_lds_dwordx4 v[28:29], off
	v_lshl_add_u64 v[28:29], v[112:113], 0, s[8:9]
	s_mov_b32 m0, s2
	v_readfirstlane_b32 s2, v0
	global_load_lds_dwordx4 v[28:29], off
	v_lshl_add_u64 v[28:29], v[118:119], 0, s[8:9]
	s_mov_b32 m0, s2
	s_mov_b64 s[28:29], 0x80
	global_load_lds_dwordx4 v[28:29], off
	v_cmp_le_i32_e32 vcc, s57, v208
	s_and_saveexec_b64 s[2:3], vcc
	s_xor_b64 s[2:3], exec, s[2:3]
	s_or_saveexec_b64 s[2:3], s[2:3]
	v_lshrrev_b32_e32 v0, 4, v2
	v_bfe_u32 v3, v2, 1, 3
	v_lshrrev_b32_e32 v2, 2, v2
	v_lshlrev_b32_e32 v28, 1, v3
	v_lshlrev_b32_e32 v29, 7, v186
	v_bitop3_b32 v30, v0, v3, 3 bitop3:0x6c
	v_bitop3_b32 v3, v187, v3, 4 bitop3:0x36
	v_sub_u32_e32 v2, 0, v2
	v_lshl_or_b32 v213, v30, 4, v29
	v_lshl_or_b32 v214, v3, 4, v29
	v_or_b32_e32 v3, 0x3000, v29
	v_bitop3_b32 v29, v28, v0, 3 bitop3:0x78
	v_xor_b32_e32 v0, v0, v2
	v_lshl_or_b32 v209, v29, 3, v3
	v_bitop3_b32 v29, v187, v28, 4 bitop3:0x36
	v_lshlrev_b32_e32 v0, 4, v0
	v_lshl_or_b32 v210, v29, 3, v3
	v_bitop3_b32 v29, v187, v28, 8 bitop3:0x36
	v_bitop3_b32 v28, v187, v28, 12 bitop3:0x36
	v_and_b32_e32 v0, 48, v0
	v_lshlrev_b32_e32 v2, 6, v186
	s_movk_i32 s8, 0x2000
	v_lshl_or_b32 v211, v29, 3, v3
	v_lshl_or_b32 v212, v28, 3, v3
	v_or3_b32 v215, v0, v2, s8
	v_mov_b32_e32 v2, v1
	v_mov_b32_e32 v3, v1
	v_mov_b32_e32 v0, v1
	v_mov_b64_e32 v[30:31], v[2:3]
	v_mov_b64_e32 v[34:35], v[2:3]
	v_mov_b64_e32 v[38:39], v[2:3]
	v_mov_b64_e32 v[42:43], v[2:3]
	v_mov_b64_e32 v[46:47], v[2:3]
	v_mov_b64_e32 v[50:51], v[2:3]
	v_mov_b64_e32 v[54:55], v[2:3]
	v_mov_b64_e32 v[58:59], v[2:3]
	s_mov_b32 s9, 0
	v_mov_b32_e32 v108, 0
	v_mov_b64_e32 v[28:29], v[0:1]
	v_mov_b64_e32 v[32:33], v[0:1]
	v_mov_b64_e32 v[36:37], v[0:1]
	v_mov_b64_e32 v[40:41], v[0:1]
	v_mov_b64_e32 v[44:45], v[0:1]
	v_mov_b64_e32 v[48:49], v[0:1]
	v_mov_b64_e32 v[52:53], v[0:1]
	v_mov_b64_e32 v[56:57], v[0:1]
	v_mov_b32_e32 v109, 0
	v_mov_b32_e32 v110, 0
	v_mov_b32_e32 v111, 0
	s_xor_b64 exec, exec, s[2:3]
	s_cbranch_execz .LBB0_2311
; template <int DK, int QB, bool NA>
; DEVI void attn_item(const AttnArgs& a, unsigned char* smem) {
;     ...
;       {
;         bf16x8 k0[4], k1[4], k2[4];
;         const unsigned a0 = cur + ka0, a1 = cur + ka1, a2 = cur + kr;
;         k0[0] = ldsr<0>(a0); k0[1] = ldsr<2048>(a0); k0[2] = ldsr<4096>(a0); k0[3] = ldsr<6144>(a0);
;         k1[0] = ldsr<0>(a1); k1[1] = ldsr<2048>(a1); k1[2] = ldsr<4096>(a1); k1[3] = ldsr<6144>(a1);
;         if constexpr (KS == 3) { k2[0] = ldsr<0>(a2); k2[1] = ldsr<1024>(a2); k2[2] = ldsr<2048>(a2); k2[3] = ldsr<3072>(a2); }
;         if constexpr (KS == 3) asm volatile("s_waitcnt lgkmcnt(8)" : "+v"(k0[0]), "+v"(k0[1]), "+v"(k0[2]), "+v"(k0[3]) :: "memory");
;         else                   asm volatile("s_waitcnt lgkmcnt(4)" : "+v"(k0[0]), "+v"(k0[1]), "+v"(k0[2]), "+v"(k0[3]) :: "memory");
;         __builtin_amdgcn_sched_barrier(0);
; #pragma unroll
;         for (int kb = 0; kb < 4; ++kb)
; #pragma unroll
;           for (int qb = 0; qb < QB; ++qb) s[kb][qb] = __builtin_amdgcn_mfma_f32_16x16x32_bf16(k0[kb], qf[qb][0], s[kb][qb], 0, 0, 0);
;         if constexpr (KS == 3) asm volatile("s_waitcnt lgkmcnt(4)" : "+v"(k1[0]), "+v"(k1[1]), "+v"(k1[2]), "+v"(k1[3]) :: "memory");
;         else                   asm volatile("s_waitcnt lgkmcnt(0)" : "+v"(k1[0]), "+v"(k1[1]), "+v"(k1[2]), "+v"(k1[3]) :: "memory");
;         __builtin_amdgcn_sched_barrier(0);
; #pragma unroll
;         for (int kb = 0; kb < 4; ++kb)
; #pragma unroll
;           for (int qb = 0; qb < QB; ++qb) s[kb][qb] = __builtin_amdgcn_mfma_f32_16x16x32_bf16(k1[kb], qf[qb][1], s[kb][qb], 0, 0, 0);
;         if constexpr (KS == 3) {
;           asm volatile("s_waitcnt lgkmcnt(0)" : "+v"(k2[0]), "+v"(k2[1]), "+v"(k2[2]), "+v"(k2[3]) :: "memory");
;           __builtin_amdgcn_sched_barrier(0);
; #pragma unroll
;           for (int kb = 0; kb < 4; ++kb)
; #pragma unroll
;             for (int qb = 0; qb < QB; ++qb) s[kb][qb] = __builtin_amdgcn_mfma_f32_16x16x32_bf16(k2[kb], qf[qb][2], s[kb][qb], 0, 0, 0);
;         }
;       }
;       u32x2 va[2][4], vbq[2][4];
;       {
;         const unsigned p00 = cur + vb00, p01 = cur + vb01, p10 = cur + vb10, p11 = cur + vb11;
;         va[0][0] = ldsr64<0>(p00); vbq[0][0] = ldsr64<0>(p01); va[0][1] = ldsr64<2048>(p00); vbq[0][1] = ldsr64<2048>(p01);
	ds_read_b128 v[28:31], v213 offset:0
	ds_read_b128 v[32:35], v213 offset:0x800
	ds_read_b128 v[36:39], v213 offset:0x1000
	ds_read_b128 v[40:43], v213 offset:0x1800
	ds_read_b128 v[44:47], v214 offset:0
	ds_read_b128 v[48:51], v214 offset:0x800
	ds_read_b128 v[52:55], v214 offset:0x1000
	ds_read_b128 v[56:59], v214 offset:0x1800
	ds_read_b128 v[60:63], v215 offset:0
	ds_read_b128 v[64:67], v215 offset:0x400
	ds_read_b128 v[76:79], v215 offset:0x800
	ds_read_b128 v[80:83], v215 offset:0xc00
	s_nop 0
	s_waitcnt lgkmcnt(8)
	s_waitcnt vmcnt(0)
	s_setprio 1
	v_mfma_f32_16x16x32_bf16 v[68:71], v[28:31], v[24:27], 0
	s_waitcnt lgkmcnt(4)
	v_mfma_f32_16x16x32_bf16 v[28:31], v[28:31], v[20:23], 0
	v_mfma_f32_16x16x32_bf16 v[72:75], v[32:35], v[24:27], 0
	v_mfma_f32_16x16x32_bf16 v[32:35], v[32:35], v[20:23], 0
	v_mfma_f32_16x16x32_bf16 v[84:87], v[36:39], v[24:27], 0
	v_mfma_f32_16x16x32_bf16 v[36:39], v[36:39], v[20:23], 0
	v_mfma_f32_16x16x32_bf16 v[88:91], v[40:43], v[24:27], 0
	v_mfma_f32_16x16x32_bf16 v[40:43], v[40:43], v[20:23], 0
	v_mfma_f32_16x16x32_bf16 v[68:71], v[44:47], v[16:19], v[68:71]
	s_waitcnt lgkmcnt(0)
	v_mfma_f32_16x16x32_bf16 v[28:31], v[44:47], v[12:15], v[28:31]
	v_mfma_f32_16x16x32_bf16 v[44:47], v[48:51], v[16:19], v[72:75]
	v_mfma_f32_16x16x32_bf16 v[32:35], v[48:51], v[12:15], v[32:35]
	v_mfma_f32_16x16x32_bf16 v[48:51], v[52:55], v[16:19], v[84:87]
	v_mfma_f32_16x16x32_bf16 v[36:39], v[52:55], v[12:15], v[36:39]
	v_mfma_f32_16x16x32_bf16 v[52:55], v[56:59], v[16:19], v[88:91]
	v_mfma_f32_16x16x32_bf16 v[40:43], v[56:59], v[12:15], v[40:43]
	v_mfma_f32_16x16x32_bf16 v[84:87], v[60:63], v[8:11], v[68:71]
	ds_read_b64 v[56:57], v209 offset:0
	ds_read_b64 v[58:59], v210 offset:0
	v_mfma_f32_16x16x32_bf16 v[68:71], v[60:63], v[4:7], v[28:31]
	v_mfma_f32_16x16x32_bf16 v[60:63], v[64:67], v[8:11], v[44:47]
	s_nop 5
	v_mul_f32_e64 v92, v86, s34
	v_mul_f32_e64 v93, v87, s34
	v_pk_mul_f32 v[2:3], v[84:85], s[34:35] op_sel_hi:[1,0]
	v_max_f32_e32 v0, v92, v93
	v_mfma_f32_16x16x32_bf16 v[72:75], v[64:67], v[4:7], v[32:35]
	v_max3_f32 v0, v2, v3, v0
	v_pk_mul_f32 v[2:3], v[60:61], s[34:35] op_sel_hi:[1,0]
	v_mfma_f32_16x16x32_bf16 v[64:67], v[76:79], v[8:11], v[48:51]
	v_max_f32_e32 v92, v2, v3
	v_pk_mul_f32 v[2:3], v[62:63], s[34:35] op_sel_hi:[1,0]
	v_mfma_f32_16x16x32_bf16 v[88:91], v[80:83], v[8:11], v[52:55]
	v_max_f32_e32 v2, v2, v3
	v_max3_f32 v0, v0, v92, v2
	s_nop 2
	v_pk_mul_f32 v[2:3], v[64:65], s[34:35] op_sel_hi:[1,0]
	v_mfma_f32_16x16x32_bf16 v[76:79], v[76:79], v[4:7], v[36:39]
	v_max_f32_e32 v92, v2, v3
	v_pk_mul_f32 v[2:3], v[66:67], s[34:35] op_sel_hi:[1,0]
	ds_read_b64 v[52:53], v209 offset:0x800
	v_mfma_f32_16x16x32_bf16 v[80:83], v[80:83], v[4:7], v[40:43]
	s_setprio 0
	v_max_f32_e32 v2, v2, v3
	v_max3_f32 v0, v0, v92, v2
	v_pk_mul_f32 v[2:3], v[88:89], s[34:35] op_sel_hi:[1,0]
	ds_read_b64 v[54:55], v210 offset:0x800
	ds_read_b64 v[48:49], v209 offset:0x1000
	ds_read_b64 v[50:51], v210 offset:0x1000
	ds_read_b64 v[44:45], v209 offset:0x1800
	ds_read_b64 v[46:47], v210 offset:0x1800
	s_nop 0
	v_max_f32_e32 v92, v2, v3
	v_pk_mul_f32 v[2:3], v[90:91], s[34:35] op_sel_hi:[1,0]
	ds_read_b64 v[40:41], v211 offset:0
	ds_read_b64 v[42:43], v212 offset:0
	ds_read_b64 v[36:37], v211 offset:0x800
	ds_read_b64 v[38:39], v212 offset:0x800
	ds_read_b64 v[32:33], v211 offset:0x1000
	s_nop 0
	v_max_f32_e32 v2, v2, v3
	v_max3_f32 v0, v0, v92, v2
	v_mov_b32_e32 v2, v0
	s_nop 1
	v_permlane16_swap_b32_e32 v0, v2
	v_max_f32_e32 v2, v2, v2
	v_max_f32_e32 v0, v0, v0
	v_max_f32_e32 v0, v0, v2
	v_mov_b32_e32 v2, v0
	s_nop 1
	v_permlane32_swap_b32_e32 v0, v2
	v_max_f32_e32 v2, v2, v2
	v_max_f32_e32 v0, v0, v0
	v_max_f32_e32 v92, v0, v2
	v_pk_fma_f32 v[94:95], v[62:63], s[34:35], v[92:93] op_sel_hi:[1,0,0] neg_lo:[0,0,1] neg_hi:[0,0,1]
	v_pk_fma_f32 v[62:63], v[60:61], s[34:35], v[92:93] op_sel_hi:[1,0,0] neg_lo:[0,0,1] neg_hi:[0,0,1]
	v_pk_fma_f32 v[60:61], v[84:85], s[34:35], v[92:93] op_sel_hi:[1,0,0] neg_lo:[0,0,1] neg_hi:[0,0,1]
	v_pk_fma_f32 v[86:87], v[86:87], s[34:35], v[92:93] op_sel_hi:[1,0,0] neg_lo:[0,0,1] neg_hi:[0,0,1]
	v_exp_f32_e32 v60, v60
	v_exp_f32_e32 v61, v61
	v_exp_f32_e32 v86, v86
	v_exp_f32_e32 v87, v87
	v_exp_f32_e32 v62, v62
	v_pk_add_f32 v[84:85], v[60:61], 0 op_sel_hi:[1,0]
	v_exp_f32_e32 v63, v63
	v_pk_fma_f32 v[64:65], v[64:65], s[34:35], v[92:93] op_sel_hi:[1,0,0] neg_lo:[0,0,1] neg_hi:[0,0,1]
	v_cvt_pk_bf16_f32 v60, v60, v61
	v_pk_add_f32 v[84:85], v[86:87], v[84:85]
	v_cvt_pk_bf16_f32 v61, v86, v87
	v_exp_f32_e32 v86, v94
	v_exp_f32_e32 v87, v95
	v_pk_fma_f32 v[66:67], v[66:67], s[34:35], v[92:93] op_sel_hi:[1,0,0] neg_lo:[0,0,1] neg_hi:[0,0,1]
	v_exp_f32_e32 v64, v64
	v_exp_f32_e32 v65, v65
	v_exp_f32_e32 v66, v66
	v_exp_f32_e32 v67, v67
	v_pk_add_f32 v[84:85], v[62:63], v[84:85]
	v_pk_fma_f32 v[88:89], v[88:89], s[34:35], v[92:93] op_sel_hi:[1,0,0] neg_lo:[0,0,1] neg_hi:[0,0,1]
	v_pk_add_f32 v[84:85], v[86:87], v[84:85]
	v_pk_fma_f32 v[90:91], v[90:91], s[34:35], v[92:93] op_sel_hi:[1,0,0] neg_lo:[0,0,1] neg_hi:[0,0,1]
	v_pk_add_f32 v[84:85], v[64:65], v[84:85]
	v_cvt_pk_bf16_f32 v64, v64, v65
	v_pk_add_f32 v[84:85], v[66:67], v[84:85]
	v_cvt_pk_bf16_f32 v65, v66, v67
	v_exp_f32_e32 v66, v88
	v_exp_f32_e32 v67, v89
	v_cvt_pk_bf16_f32 v62, v62, v63
	v_cvt_pk_bf16_f32 v63, v86, v87
	v_exp_f32_e32 v86, v90
	v_exp_f32_e32 v87, v91
	v_pk_add_f32 v[84:85], v[66:67], v[84:85]
	v_pk_mul_f32 v[88:89], v[70:71], s[34:35] op_sel_hi:[1,0]
	v_cvt_pk_bf16_f32 v66, v66, v67
	v_pk_add_f32 v[84:85], v[86:87], v[84:85]
	v_cvt_pk_bf16_f32 v67, v86, v87
	v_pk_mul_f32 v[86:87], v[68:69], s[34:35] op_sel_hi:[1,0]
	v_max_f32_e32 v0, v88, v89
	v_max3_f32 v0, v86, v87, v0
	v_pk_mul_f32 v[86:87], v[72:73], s[34:35] op_sel_hi:[1,0]
	v_exp_f32_e64 v3, -v92
	v_max_f32_e32 v2, v86, v87
	v_pk_mul_f32 v[86:87], v[74:75], s[34:35] op_sel_hi:[1,0]
	ds_read_b64 v[34:35], v212 offset:0x1000
	ds_read_b64 v[28:29], v211 offset:0x1800
	ds_read_b64 v[30:31], v212 offset:0x1800
	s_nop 0
	v_max_f32_e32 v86, v86, v87
	v_max3_f32 v0, v0, v2, v86
	v_pk_mul_f32 v[86:87], v[76:77], s[34:35] op_sel_hi:[1,0]
	s_waitcnt lgkmcnt(0)
; DEVI unsigned pk2(float lo, float hi) { const f32x2_t v = {lo, hi}; const bf16x2_t b = __builtin_convertvector(v, bf16x2_t); return __builtin_bit_cast(unsigned, b); }
; template <int DK, int QB, bool NA>
; DEVI void attn_item(const AttnArgs& a, unsigned char* smem) {
;     ...
;           if (j == 0 || __any(mx > 6.f)) {
;             mx = xmax32(xmax16(mx));
;             const float d = (j == 0) ? mx : fmaxf(mx, 0.f);
;             const float alpha = __builtin_amdgcn_exp2f(-d);
;             const f32x2 dv = {d, d};
; #pragma unroll
;             for (int kb = 0; kb < 4; ++kb)
; #pragma unroll
;               for (int h = 0; h < 2; ++h) t[kb][h] -= dv;
;             m[qb] += d;
;             l[qb] *= alpha;
; #pragma unroll
;             for (int db = 0; db < 4; ++db) o[db][qb] *= alpha;
;           }
;           f32x2 ls2 = {0.f, 0.f};
;           unsigned pw[2][4];
; #pragma unroll
;           for (int kb = 0; kb < 4; ++kb)
; #pragma unroll
;             for (int h = 0; h < 2; ++h) {
;               const f32x2 pe = {__builtin_amdgcn_exp2f(t[kb][h].x), __builtin_amdgcn_exp2f(t[kb][h].y)};
;               ls2 += pe;
;               pw[kb >> 1][(kb & 1) * 2 + h] = pk2(pe.x, pe.y);
;             }
;           l[qb] += ls2.x + ls2.y;
; #pragma unroll
;           for (int c = 0; c < 2; ++c) {
;             const u32x4 pv = (u32x4){pw[c][0], pw[c][1], pw[c][2], pw[c][3]};
;             pf[qb][c] = __builtin_bit_cast(bf16x8, pv);
;           }
;     ...
;       asm volatile("s_waitcnt lgkmcnt(0)"
;                    : "+v"(va[0][0]), "+v"(va[0][1]), "+v"(va[0][2]), "+v"(va[0][3]), "+v"(va[1][0]), "+v"(va[1][1]), "+v"(va[1][2]), "+v"(va[1][3]),
;                      "+v"(vbq[0][0]), "+v"(vbq[0][1]), "+v"(vbq[0][2]), "+v"(vbq[0][3]), "+v"(vbq[1][0]), "+v"(vbq[1][1]), "+v"(vbq[1][2]), "+v"(vbq[1][3])
;                    :: "memory");
;       __builtin_amdgcn_sched_barrier(0);
; #pragma unroll
;       for (int c = 0; c < 2; ++c)
; #pragma unroll
;         for (int db = 0; db < 4; ++db) {
;           const u32x4 vw = (u32x4){va[c][db].x, va[c][db].y, vbq[c][db].x, vbq[c][db].y};
;           const bf16x8 vf = __builtin_bit_cast(bf16x8, vw);
; #pragma unroll
;           for (int qb = 0; qb < QB; ++qb) o[db][qb] = __builtin_amdgcn_mfma_f32_16x16x32_bf16(vf, pf[qb][c], o[db][qb], 0, 0, 0);
;         }
	s_nop 0
	v_max_f32_e32 v2, v86, v87
	v_pk_mul_f32 v[86:87], v[78:79], s[34:35] op_sel_hi:[1,0]
	s_nop 0
	v_max_f32_e32 v86, v86, v87
	v_max3_f32 v0, v0, v2, v86
	v_pk_mul_f32 v[86:87], v[80:81], s[34:35] op_sel_hi:[1,0]
	s_nop 0
	v_max_f32_e32 v2, v86, v87
	v_pk_mul_f32 v[86:87], v[82:83], s[34:35] op_sel_hi:[1,0]
	s_nop 0
	v_max_f32_e32 v86, v86, v87
	v_max3_f32 v0, v0, v2, v86
	v_mov_b32_e32 v2, v0
	s_nop 1
	v_permlane16_swap_b32_e32 v0, v2
	v_max_f32_e32 v2, v2, v2
	v_max_f32_e32 v0, v0, v0
	v_max_f32_e32 v0, v0, v2
	v_mov_b32_e32 v2, v0
	s_nop 1
	v_permlane32_swap_b32_e32 v0, v2
	v_max_f32_e32 v2, v2, v2
	v_max_f32_e32 v0, v0, v0
	v_max_f32_e32 v93, v0, v2
	v_mov_b32_e32 v0, v93
	v_pk_fma_f32 v[68:69], v[68:69], s[34:35], v[0:1] op_sel_hi:[1,0,0] neg_lo:[0,0,1] neg_hi:[0,0,1]
	v_pk_fma_f32 v[70:71], v[70:71], s[34:35], v[0:1] op_sel_hi:[1,0,0] neg_lo:[0,0,1] neg_hi:[0,0,1]
	v_exp_f32_e32 v68, v68
	v_exp_f32_e32 v69, v69
	v_exp_f32_e32 v70, v70
	v_exp_f32_e32 v71, v71
	v_pk_fma_f32 v[72:73], v[72:73], s[34:35], v[0:1] op_sel_hi:[1,0,0] neg_lo:[0,0,1] neg_hi:[0,0,1]
	v_pk_add_f32 v[86:87], v[68:69], 0 op_sel_hi:[1,0]
	v_pk_fma_f32 v[74:75], v[74:75], s[34:35], v[0:1] op_sel_hi:[1,0,0] neg_lo:[0,0,1] neg_hi:[0,0,1]
	v_cvt_pk_bf16_f32 v68, v68, v69
	v_pk_add_f32 v[86:87], v[70:71], v[86:87]
	v_cvt_pk_bf16_f32 v69, v70, v71
	v_exp_f32_e32 v70, v72
	v_exp_f32_e32 v71, v73
	v_exp_f32_e32 v74, v74
	v_exp_f32_e32 v75, v75
	v_pk_fma_f32 v[76:77], v[76:77], s[34:35], v[0:1] op_sel_hi:[1,0,0] neg_lo:[0,0,1] neg_hi:[0,0,1]
	v_pk_add_f32 v[72:73], v[70:71], v[86:87]
	v_cvt_pk_bf16_f32 v70, v70, v71
	v_pk_add_f32 v[72:73], v[74:75], v[72:73]
	v_cvt_pk_bf16_f32 v71, v74, v75
	v_exp_f32_e32 v74, v76
	v_exp_f32_e32 v75, v77
	v_pk_fma_f32 v[78:79], v[78:79], s[34:35], v[0:1] op_sel_hi:[1,0,0] neg_lo:[0,0,1] neg_hi:[0,0,1]
	v_pk_fma_f32 v[80:81], v[80:81], s[34:35], v[0:1] op_sel_hi:[1,0,0] neg_lo:[0,0,1] neg_hi:[0,0,1]
	v_pk_fma_f32 v[82:83], v[82:83], s[34:35], v[0:1] op_sel_hi:[1,0,0] neg_lo:[0,0,1] neg_hi:[0,0,1]
	v_pk_add_f32 v[76:77], v[74:75], v[72:73]
	v_cvt_pk_bf16_f32 v72, v74, v75
	v_exp_f32_e32 v74, v78
	v_exp_f32_e32 v75, v79
	v_exp_f32_e32 v78, v82
	v_exp_f32_e32 v79, v83
	v_exp_f32_e64 v2, -v93
	v_pk_add_f32 v[76:77], v[74:75], v[76:77]
	v_cvt_pk_bf16_f32 v73, v74, v75
	v_exp_f32_e32 v74, v80
	v_exp_f32_e32 v75, v81
	v_pk_add_f32 v[110:111], v[92:93], 0 op_sel_hi:[1,0]
	v_pk_add_f32 v[76:77], v[74:75], v[76:77]
	s_nop 0
	v_pk_add_f32 v[86:87], v[78:79], v[76:77]
	v_cvt_pk_bf16_f32 v74, v74, v75
	v_cvt_pk_bf16_f32 v75, v78, v79
	v_mov_b32_e32 v78, v86
	v_mov_b32_e32 v79, v84
	v_mov_b32_e32 v84, v87
	v_pk_add_f32 v[84:85], v[78:79], v[84:85]
	v_pk_mul_f32 v[76:77], v[2:3], 0 op_sel_hi:[1,0]
	v_pk_fma_f32 v[108:109], v[2:3], 0, v[84:85] op_sel_hi:[1,0,1]
	v_mov_b32_e32 v80, v77
	v_mov_b32_e32 v81, v77
	v_mov_b32_e32 v82, v77
	v_mov_b32_e32 v83, v77
	v_mov_b32_e32 v77, v76
	v_mov_b32_e32 v78, v76
	v_mov_b32_e32 v79, v76
	s_setprio 1
	v_mfma_f32_16x16x32_bf16 v[84:87], v[56:59], v[60:63], v[80:83]
	s_nop 0
	v_mfma_f32_16x16x32_bf16 v[88:91], v[56:59], v[68:71], v[76:79]
	v_mfma_f32_16x16x32_bf16 v[92:95], v[52:55], v[60:63], v[80:83]
	v_mfma_f32_16x16x32_bf16 v[96:99], v[52:55], v[68:71], v[76:79]
	v_mfma_f32_16x16x32_bf16 v[100:103], v[48:51], v[60:63], v[80:83]
	v_mfma_f32_16x16x32_bf16 v[104:107], v[48:51], v[68:71], v[76:79]
	v_mfma_f32_16x16x32_bf16 v[60:63], v[44:47], v[60:63], v[80:83]
	v_mfma_f32_16x16x32_bf16 v[68:71], v[44:47], v[68:71], v[76:79]
	v_mfma_f32_16x16x32_bf16 v[56:59], v[40:43], v[64:67], v[84:87]
	v_mfma_f32_16x16x32_bf16 v[52:55], v[40:43], v[72:75], v[88:91]
	v_mfma_f32_16x16x32_bf16 v[48:51], v[36:39], v[64:67], v[92:95]
	v_mfma_f32_16x16x32_bf16 v[44:47], v[36:39], v[72:75], v[96:99]
	v_mfma_f32_16x16x32_bf16 v[40:43], v[32:35], v[64:67], v[100:103]
	v_mfma_f32_16x16x32_bf16 v[36:39], v[32:35], v[72:75], v[104:107]
	v_mfma_f32_16x16x32_bf16 v[32:35], v[28:31], v[64:67], v[60:63]
	v_mfma_f32_16x16x32_bf16 v[28:31], v[28:31], v[72:75], v[68:71]
	s_setprio 0

; DEVI unsigned pk2(float lo, float hi) { const f32x2_t v = {lo, hi}; const bf16x2_t b = __builtin_convertvector(v, bf16x2_t); return __builtin_bit_cast(unsigned, b); }
; template <int DK, int QB, bool NA>
; DEVI void attn_item(const AttnArgs& a, unsigned char* smem) {
;     ...
;           f32x2 ls2 = {0.f, 0.f};
;           unsigned pw[2][4];
; #pragma unroll
;           for (int kb = 0; kb < 4; ++kb)
; #pragma unroll
;             for (int h = 0; h < 2; ++h) {
;               const f32x2 pe = {__builtin_amdgcn_exp2f(t[kb][h].x), __builtin_amdgcn_exp2f(t[kb][h].y)};
;               ls2 += pe;
;               pw[kb >> 1][(kb & 1) * 2 + h] = pk2(pe.x, pe.y);
;             }
;           l[qb] += ls2.x + ls2.y;
; #pragma unroll
;           for (int c = 0; c < 2; ++c) {
;             const u32x4 pv = (u32x4){pw[c][0], pw[c][1], pw[c][2], pw[c][3]};
;             pf[qb][c] = __builtin_bit_cast(bf16x8, pv);
;           }
;     ...
;       asm volatile("s_waitcnt lgkmcnt(0)"
;                    : "+v"(va[0][0]), "+v"(va[0][1]), "+v"(va[0][2]), "+v"(va[0][3]), "+v"(va[1][0]), "+v"(va[1][1]), "+v"(va[1][2]), "+v"(va[1][3]),
;                      "+v"(vbq[0][0]), "+v"(vbq[0][1]), "+v"(vbq[0][2]), "+v"(vbq[0][3]), "+v"(vbq[1][0]), "+v"(vbq[1][1]), "+v"(vbq[1][2]), "+v"(vbq[1][3])
;                    :: "memory");
;       __builtin_amdgcn_sched_barrier(0);
; #pragma unroll
;       for (int c = 0; c < 2; ++c)
; #pragma unroll
;         for (int db = 0; db < 4; ++db) {
;           const u32x4 vw = (u32x4){va[c][db].x, va[c][db].y, vbq[c][db].x, vbq[c][db].y};
;           const bf16x8 vf = __builtin_bit_cast(bf16x8, vw);
; #pragma unroll
;           for (int qb = 0; qb < QB; ++qb) o[db][qb] = __builtin_amdgcn_mfma_f32_16x16x32_bf16(vf, pf[qb][c], o[db][qb], 0, 0, 0);
;         }
.LBB0_2312:
	v_exp_f32_e32 v94, v182
	v_exp_f32_e32 v95, v183
	v_exp_f32_e32 v182, v180
	v_exp_f32_e32 v183, v181
	v_exp_f32_e32 v126, v126
	v_exp_f32_e32 v127, v127
	v_pk_add_f32 v[218:219], v[94:95], 0 op_sel_hi:[1,0]
	v_exp_f32_e32 v128, v128
	v_exp_f32_e32 v129, v129
	v_cvt_pk_bf16_f32 v180, v94, v95
	v_pk_add_f32 v[94:95], v[182:183], v[218:219]
	v_exp_f32_e32 v124, v124
	v_exp_f32_e32 v125, v125
	v_cvt_pk_bf16_f32 v181, v182, v183
	v_pk_add_f32 v[94:95], v[126:127], v[94:95]
	v_cvt_pk_bf16_f32 v182, v126, v127
	v_exp_f32_e32 v126, v122
	v_exp_f32_e32 v127, v123
	v_exp_f32_e32 v120, v120
	v_exp_f32_e32 v121, v121
	v_pk_add_f32 v[94:95], v[128:129], v[94:95]
	v_exp_f32_e32 v2, v2
	v_exp_f32_e32 v3, v3
	v_pk_add_f32 v[94:95], v[124:125], v[94:95]
	v_cvt_pk_bf16_f32 v122, v124, v125
	v_pk_add_f32 v[94:95], v[126:127], v[94:95]
	v_cvt_pk_bf16_f32 v125, v2, v3
	v_pk_add_f32 v[94:95], v[120:121], v[94:95]
	v_exp_f32_e32 v104, v104
	v_pk_add_f32 v[94:95], v[2:3], v[94:95]
	v_exp_f32_e32 v2, v184
	v_exp_f32_e32 v3, v185
	v_add_f32_e32 v0, v94, v95
	v_exp_f32_e32 v94, v106
	v_exp_f32_e32 v95, v107
	v_exp_f32_e32 v105, v105
	v_pk_add_f32 v[106:107], v[2:3], 0 op_sel_hi:[1,0]
	v_exp_f32_e32 v102, v102
	v_exp_f32_e32 v103, v103
	v_cvt_pk_bf16_f32 v123, v126, v127
	v_cvt_pk_bf16_f32 v126, v2, v3
	v_pk_add_f32 v[2:3], v[94:95], v[106:107]
	v_cvt_pk_bf16_f32 v127, v94, v95
	v_exp_f32_e32 v94, v100
	v_exp_f32_e32 v95, v101
	v_exp_f32_e32 v98, v98
	v_exp_f32_e32 v99, v99
	v_pk_add_f32 v[2:3], v[104:105], v[2:3]
	v_exp_f32_e32 v96, v96
	v_exp_f32_e32 v97, v97
	v_pk_add_f32 v[2:3], v[102:103], v[2:3]
	v_exp_f32_e32 v92, v92
	v_exp_f32_e32 v93, v93
	v_pk_add_f32 v[2:3], v[94:95], v[2:3]
	s_waitcnt lgkmcnt(0)
	v_add_f32_e32 v109, v109, v0
	v_pk_add_f32 v[2:3], v[98:99], v[2:3]
	v_cvt_pk_bf16_f32 v183, v128, v129
	v_pk_add_f32 v[2:3], v[96:97], v[2:3]
	v_cvt_pk_bf16_f32 v124, v120, v121
	v_pk_add_f32 v[2:3], v[92:93], v[2:3]
	v_cvt_pk_bf16_f32 v128, v104, v105
	v_add_f32_e32 v0, v2, v3
	v_add_f32_e32 v108, v108, v0
	v_cvt_pk_bf16_f32 v129, v102, v103
	v_cvt_pk_bf16_f32 v94, v94, v95
	v_cvt_pk_bf16_f32 v95, v98, v99
	v_cvt_pk_bf16_f32 v96, v96, v97
	v_cvt_pk_bf16_f32 v97, v92, v93
	s_setprio 1
	v_mfma_f32_16x16x32_bf16 v[56:59], v[88:91], v[180:183], v[56:59]
	v_mfma_f32_16x16x32_bf16 v[52:55], v[88:91], v[126:129], v[52:55]
	v_mfma_f32_16x16x32_bf16 v[48:51], v[84:87], v[180:183], v[48:51]
	v_mfma_f32_16x16x32_bf16 v[44:47], v[84:87], v[126:129], v[44:47]
	v_mfma_f32_16x16x32_bf16 v[40:43], v[80:83], v[180:183], v[40:43]
	v_mfma_f32_16x16x32_bf16 v[36:39], v[80:83], v[126:129], v[36:39]
	v_mfma_f32_16x16x32_bf16 v[32:35], v[76:79], v[180:183], v[32:35]
	v_mfma_f32_16x16x32_bf16 v[28:31], v[76:79], v[126:129], v[28:31]
	v_mfma_f32_16x16x32_bf16 v[56:59], v[72:75], v[122:125], v[56:59]
	v_mfma_f32_16x16x32_bf16 v[52:55], v[72:75], v[94:97], v[52:55]
	v_mfma_f32_16x16x32_bf16 v[48:51], v[68:71], v[122:125], v[48:51]
	v_mfma_f32_16x16x32_bf16 v[44:47], v[68:71], v[94:97], v[44:47]
	v_mfma_f32_16x16x32_bf16 v[40:43], v[64:67], v[122:125], v[40:43]
	v_mfma_f32_16x16x32_bf16 v[36:39], v[64:67], v[94:97], v[36:39]
	v_mfma_f32_16x16x32_bf16 v[32:35], v[60:63], v[122:125], v[32:35]
	v_mfma_f32_16x16x32_bf16 v[28:31], v[60:63], v[94:97], v[28:31]
	s_setprio 0

; template <int DK, int QB, bool NA>
; DEVI void attn_item(const AttnArgs& a, unsigned char* smem) {
;     ...
;   for (int j = 0; j < nt; ++j) {
;     if (j + 1 < nt) {
;       if constexpr (DK == 96) asm volatile("s_waitcnt vmcnt(5)" ::: "memory");
;       else                    asm volatile("s_waitcnt vmcnt(4)" ::: "memory");
;     } else {
;       asm volatile("s_waitcnt vmcnt(0)" ::: "memory");
;     }
;     RAW_BARRIER();
;     if (j + 2 < nt) ATT_ISSUE(j + 2, is);
;     is = (is + 1 == S) ? 0 : is + 1;
;     const unsigned cur = lbase + cs * ATT_STAGE;
;     cs = (cs + 1 == S) ? 0 : cs + 1;
;     if (wact) {
;       f32x4 s[4][QB];
; #pragma unroll
;       for (int kb = 0; kb < 4; ++kb)
; #pragma unroll
;         for (int qb = 0; qb < QB; ++qb) s[kb][qb] = (f32x4){0.f, 0.f, 0.f, 0.f};
;       {
;         bf16x8 k0[4], k1[4], k2[4];
;         const unsigned a0 = cur + ka0, a1 = cur + ka1, a2 = cur + kr;
;         k0[0] = ldsr<0>(a0); k0[1] = ldsr<2048>(a0); k0[2] = ldsr<4096>(a0); k0[3] = ldsr<6144>(a0);
;         k1[0] = ldsr<0>(a1); k1[1] = ldsr<2048>(a1); k1[2] = ldsr<4096>(a1); k1[3] = ldsr<6144>(a1);
;         if constexpr (KS == 3) { k2[0] = ldsr<0>(a2); k2[1] = ldsr<1024>(a2); k2[2] = ldsr<2048>(a2); k2[3] = ldsr<3072>(a2); }
;         if constexpr (KS == 3) asm volatile("s_waitcnt lgkmcnt(8)" : "+v"(k0[0]), "+v"(k0[1]), "+v"(k0[2]), "+v"(k0[3]) :: "memory");
;         else                   asm volatile("s_waitcnt lgkmcnt(4)" : "+v"(k0[0]), "+v"(k0[1]), "+v"(k0[2]), "+v"(k0[3]) :: "memory");
;         __builtin_amdgcn_sched_barrier(0);
; #pragma unroll
;         for (int kb = 0; kb < 4; ++kb)
; #pragma unroll
;           for (int qb = 0; qb < QB; ++qb) s[kb][qb] = __builtin_amdgcn_mfma_f32_16x16x32_bf16(k0[kb], qf[qb][0], s[kb][qb], 0, 0, 0);
;         if constexpr (KS == 3) asm volatile("s_waitcnt lgkmcnt(4)" : "+v"(k1[0]), "+v"(k1[1]), "+v"(k1[2]), "+v"(k1[3]) :: "memory");
;         else                   asm volatile("s_waitcnt lgkmcnt(0)" : "+v"(k1[0]), "+v"(k1[1]), "+v"(k1[2]), "+v"(k1[3]) :: "memory");
;         __builtin_amdgcn_sched_barrier(0);
; #pragma unroll
;         for (int kb = 0; kb < 4; ++kb)
; #pragma unroll
;           for (int qb = 0; qb < QB; ++qb) s[kb][qb] = __builtin_amdgcn_mfma_f32_16x16x32_bf16(k1[kb], qf[qb][1], s[kb][qb], 0, 0, 0);
;         if constexpr (KS == 3) {
.LBB0_2314:
	s_add_i32 s42, s42, 1
	s_cmp_lt_u32 s42, s61
	s_cselect_b32 s20, s43, s60
	s_mul_i32 s2, s9, 0x5000
	v_add_u32_e32 v0, s2, v216
	v_mad_u64_u32 v[2:3], s[2:3], s20, v207, v[114:115]
	v_readfirstlane_b32 s2, v0
	v_add_u32_e32 v60, 0x1000, v0
	s_waitcnt vmcnt(5)
	s_mov_b32 m0, s2
	v_readfirstlane_b32 s2, v60
	s_waitcnt lgkmcnt(0)
	s_barrier
	global_load_lds_dwordx4 v[2:3], off
	v_lshl_add_u64 v[2:3], v[2:3], 0, s[86:87]
	s_mov_b32 m0, s2
	v_add_u32_e32 v60, 0x2000, v0
	global_load_lds_dwordx4 v[2:3], off
	v_mad_u64_u32 v[2:3], s[2:3], s20, v207, v[116:117]
	v_readfirstlane_b32 s2, v60
	v_add_u32_e32 v60, 0x3000, v0
	v_lshl_add_u64 v[2:3], v[2:3], 0, s[28:29]
	s_mov_b32 m0, s2
	s_lshl_b64 s[2:3], s[20:21], 1
	v_readfirstlane_b32 s20, v60
	global_load_lds_dwordx4 v[2:3], off
	v_lshl_add_u64 v[2:3], v[112:113], 0, s[2:3]
	s_mov_b32 m0, s20
	v_add_u32_e32 v0, 0x4000, v0
	global_load_lds_dwordx4 v[2:3], off
	v_lshl_add_u64 v[2:3], v[118:119], 0, s[2:3]
	v_readfirstlane_b32 s2, v0
	s_mov_b32 m0, s2
	s_nop 0
	global_load_lds_dwordx4 v[2:3], off
	s_and_saveexec_b64 s[2:3], s[0:1]
	s_cbranch_execz .LBB0_2313
	s_mul_i32 s20, s8, 0x5000
	v_or_b32_e32 v0, s20, v213
	ds_read_b128 v[60:63], v0 offset:0
	ds_read_b128 v[64:67], v0 offset:0x800
	ds_read_b128 v[68:71], v0 offset:0x1000
	ds_read_b128 v[72:75], v0 offset:0x1800
	v_or_b32_e32 v2, s20, v214
	v_add_u32_e32 v3, s20, v215
	ds_read_b128 v[76:79], v2 offset:0
	ds_read_b128 v[80:83], v2 offset:0x800
	ds_read_b128 v[84:87], v2 offset:0x1000
	ds_read_b128 v[88:91], v2 offset:0x1800
	ds_read_b128 v[92:95], v3 offset:0
	ds_read_b128 v[96:99], v3 offset:0x400
	ds_read_b128 v[120:123], v3 offset:0x800
	ds_read_b128 v[124:127], v3 offset:0xc00
	s_waitcnt lgkmcnt(8)
	s_nop 0
	s_setprio 1
	v_mfma_f32_16x16x32_bf16 v[100:103], v[60:63], v[24:27], 0
	s_waitcnt lgkmcnt(4)
	v_mfma_f32_16x16x32_bf16 v[60:63], v[60:63], v[20:23], 0
	v_mfma_f32_16x16x32_bf16 v[104:107], v[64:67], v[24:27], 0
	v_mfma_f32_16x16x32_bf16 v[64:67], v[64:67], v[20:23], 0
	v_mfma_f32_16x16x32_bf16 v[180:183], v[68:71], v[24:27], 0
	v_mfma_f32_16x16x32_bf16 v[68:71], v[68:71], v[20:23], 0
	v_mfma_f32_16x16x32_bf16 v[218:221], v[72:75], v[24:27], 0
	v_mfma_f32_16x16x32_bf16 v[72:75], v[72:75], v[20:23], 0
	v_mfma_f32_16x16x32_bf16 v[100:103], v[76:79], v[16:19], v[100:103]
	s_waitcnt lgkmcnt(0)
	v_mfma_f32_16x16x32_bf16 v[60:63], v[76:79], v[12:15], v[60:63]
	v_mfma_f32_16x16x32_bf16 v[76:79], v[80:83], v[16:19], v[104:107]
	v_mfma_f32_16x16x32_bf16 v[64:67], v[80:83], v[12:15], v[64:67]
	v_mfma_f32_16x16x32_bf16 v[80:83], v[84:87], v[16:19], v[180:183]
	v_mfma_f32_16x16x32_bf16 v[68:71], v[84:87], v[12:15], v[68:71]
	v_mfma_f32_16x16x32_bf16 v[84:87], v[88:91], v[16:19], v[218:221]
	v_mfma_f32_16x16x32_bf16 v[72:75], v[88:91], v[12:15], v[72:75]
	v_mfma_f32_16x16x32_bf16 v[182:185], v[92:95], v[8:11], v[100:103]
	v_add_u32_e32 v0, s20, v209
	v_add_u32_e32 v2, s20, v210
	ds_read_b64 v[88:89], v0 offset:0
	v_mfma_f32_16x16x32_bf16 v[218:221], v[96:99], v[8:11], v[76:79]
	ds_read_b64 v[90:91], v2 offset:0
	s_nop 4
	v_fma_f32 v180, v184, s34, -v110
	v_fma_f32 v181, v185, s34, -v110
	v_pk_fma_f32 v[182:183], v[182:183], s[34:35], v[110:111] op_sel_hi:[1,0,0] neg_lo:[0,0,1] neg_hi:[0,0,1]
	v_mfma_f32_16x16x32_bf16 v[222:225], v[120:123], v[8:11], v[80:83]
	v_add_u32_e32 v3, s20, v211
	v_pk_fma_f32 v[128:129], v[220:221], s[34:35], v[110:111] op_sel_hi:[1,0,0] neg_lo:[0,0,1] neg_hi:[0,0,1]
	v_mfma_f32_16x16x32_bf16 v[226:229], v[124:127], v[8:11], v[84:87]
	ds_read_b64 v[84:85], v0 offset:0x800
	ds_read_b64 v[86:87], v2 offset:0x800
	ds_read_b64 v[80:81], v0 offset:0x1000
	v_mfma_f32_16x16x32_bf16 v[104:107], v[92:95], v[4:7], v[60:63]
	ds_read_b64 v[82:83], v2 offset:0x1000
	ds_read_b64 v[76:77], v0 offset:0x1800
	v_max_f32_e32 v0, v180, v181
	v_mfma_f32_16x16x32_bf16 v[92:95], v[124:127], v[4:7], v[72:75]
	v_fma_f32 v126, v218, s34, -v110
	v_fma_f32 v127, v219, s34, -v110
	v_pk_fma_f32 v[124:125], v[222:223], s[34:35], v[110:111] op_sel_hi:[1,0,0] neg_lo:[0,0,1] neg_hi:[0,0,1]
	v_max3_f32 v0, v182, v183, v0
	v_mfma_f32_16x16x32_bf16 v[100:103], v[96:99], v[4:7], v[64:67]
	v_max_f32_e32 v184, v126, v127
	v_max_f32_e32 v185, v128, v129
	v_add_u32_e32 v62, s20, v212
	v_mfma_f32_16x16x32_bf16 v[96:99], v[120:123], v[4:7], v[68:71]
	s_setprio 0
	v_fma_f32 v122, v224, s34, -v110
	v_fma_f32 v123, v225, s34, -v110
	ds_read_b64 v[78:79], v2 offset:0x1800
	ds_read_b64 v[72:73], v3 offset:0
	ds_read_b64 v[74:75], v62 offset:0
	ds_read_b64 v[68:69], v3 offset:0x800
	ds_read_b64 v[70:71], v62 offset:0x800
	ds_read_b64 v[64:65], v3 offset:0x1000
	ds_read_b64 v[66:67], v62 offset:0x1000
	ds_read_b64 v[60:61], v3 offset:0x1800
	v_pk_fma_f32 v[120:121], v[226:227], s[34:35], v[110:111] op_sel_hi:[1,0,0] neg_lo:[0,0,1] neg_hi:[0,0,1]
	v_pk_fma_f32 v[2:3], v[228:229], s[34:35], v[110:111] op_sel_hi:[1,0,0] neg_lo:[0,0,1] neg_hi:[0,0,1]
	v_max3_f32 v0, v0, v184, v185
	v_max_f32_e32 v184, v124, v125
	v_max_f32_e32 v185, v122, v123
	v_max3_f32 v0, v0, v184, v185
	v_max_f32_e32 v184, v120, v121
	v_max_f32_e32 v185, v2, v3
	v_max3_f32 v0, v0, v184, v185
	s_mov_b32 s20, 0x40c00000
	v_cmp_lt_f32_e32 vcc, s20, v0
	ds_read_b64 v[62:63], v62 offset:0x1800
	s_cbranch_vccz .LBB0_2317
	v_mov_b32_e32 v184, v0
	s_nop 1
	v_permlane16_swap_b32_e32 v0, v184
	v_max_f32_e32 v184, v184, v184
	v_max_f32_e32 v0, v0, v0
	v_max_f32_e32 v0, v0, v184
	v_mov_b32_e32 v184, v0
	s_nop 1
	v_permlane32_swap_b32_e32 v0, v184
	v_max3_f32 v0, v0, v184, 0
	v_exp_f32_e64 v184, -v0
	v_pk_add_f32 v[182:183], v[182:183], v[0:1] op_sel_hi:[1,0] neg_lo:[0,1] neg_hi:[0,1]
	v_pk_add_f32 v[180:181], v[180:181], v[0:1] op_sel_hi:[1,0] neg_lo:[0,1] neg_hi:[0,1]
	v_pk_add_f32 v[126:127], v[126:127], v[0:1] op_sel_hi:[1,0] neg_lo:[0,1] neg_hi:[0,1]
	v_pk_add_f32 v[128:129], v[128:129], v[0:1] op_sel_hi:[1,0] neg_lo:[0,1] neg_hi:[0,1]
	v_pk_add_f32 v[124:125], v[124:125], v[0:1] op_sel_hi:[1,0] neg_lo:[0,1] neg_hi:[0,1]
	v_pk_add_f32 v[122:123], v[122:123], v[0:1] op_sel_hi:[1,0] neg_lo:[0,1] neg_hi:[0,1]
	v_pk_add_f32 v[120:121], v[120:121], v[0:1] op_sel_hi:[1,0] neg_lo:[0,1] neg_hi:[0,1]
	v_pk_add_f32 v[2:3], v[2:3], v[0:1] op_sel_hi:[1,0] neg_lo:[0,1] neg_hi:[0,1]
	v_add_f32_e32 v110, v110, v0
	v_mul_f32_e32 v109, v109, v184
	v_pk_mul_f32 v[58:59], v[58:59], v[184:185] op_sel_hi:[1,0]
	v_pk_mul_f32 v[56:57], v[56:57], v[184:185] op_sel_hi:[1,0]
	v_pk_mul_f32 v[50:51], v[50:51], v[184:185] op_sel_hi:[1,0]
	v_pk_mul_f32 v[48:49], v[48:49], v[184:185] op_sel_hi:[1,0]
	v_pk_mul_f32 v[42:43], v[42:43], v[184:185] op_sel_hi:[1,0]
	v_pk_mul_f32 v[40:41], v[40:41], v[184:185] op_sel_hi:[1,0]
	v_pk_mul_f32 v[34:35], v[34:35], v[184:185] op_sel_hi:[1,0]
	v_pk_mul_f32 v[32:33], v[32:33], v[184:185] op_sel_hi:[1,0]

; template <int DK, int QB, bool NA>
; DEVI void attn_item(const AttnArgs& a, unsigned char* smem) {
;     ...
;       {
;         bf16x8 k0[4], k1[4], k2[4];
;         const unsigned a0 = cur + ka0, a1 = cur + ka1, a2 = cur + kr;
;         k0[0] = ldsr<0>(a0); k0[1] = ldsr<2048>(a0); k0[2] = ldsr<4096>(a0); k0[3] = ldsr<6144>(a0);
;         k1[0] = ldsr<0>(a1); k1[1] = ldsr<2048>(a1); k1[2] = ldsr<4096>(a1); k1[3] = ldsr<6144>(a1);
;         if constexpr (KS == 3) { k2[0] = ldsr<0>(a2); k2[1] = ldsr<1024>(a2); k2[2] = ldsr<2048>(a2); k2[3] = ldsr<3072>(a2); }
;         if constexpr (KS == 3) asm volatile("s_waitcnt lgkmcnt(8)" : "+v"(k0[0]), "+v"(k0[1]), "+v"(k0[2]), "+v"(k0[3]) :: "memory");
;         else                   asm volatile("s_waitcnt lgkmcnt(4)" : "+v"(k0[0]), "+v"(k0[1]), "+v"(k0[2]), "+v"(k0[3]) :: "memory");
;         __builtin_amdgcn_sched_barrier(0);
; #pragma unroll
;         for (int kb = 0; kb < 4; ++kb)
; #pragma unroll
;           for (int qb = 0; qb < QB; ++qb) s[kb][qb] = __builtin_amdgcn_mfma_f32_16x16x32_bf16(k0[kb], qf[qb][0], s[kb][qb], 0, 0, 0);
;         if constexpr (KS == 3) asm volatile("s_waitcnt lgkmcnt(4)" : "+v"(k1[0]), "+v"(k1[1]), "+v"(k1[2]), "+v"(k1[3]) :: "memory");
;         else                   asm volatile("s_waitcnt lgkmcnt(0)" : "+v"(k1[0]), "+v"(k1[1]), "+v"(k1[2]), "+v"(k1[3]) :: "memory");
;         __builtin_amdgcn_sched_barrier(0);
; #pragma unroll
;         for (int kb = 0; kb < 4; ++kb)
; #pragma unroll
;           for (int qb = 0; qb < QB; ++qb) s[kb][qb] = __builtin_amdgcn_mfma_f32_16x16x32_bf16(k1[kb], qf[qb][1], s[kb][qb], 0, 0, 0);
;         if constexpr (KS == 3) {
;           asm volatile("s_waitcnt lgkmcnt(0)" : "+v"(k2[0]), "+v"(k2[1]), "+v"(k2[2]), "+v"(k2[3]) :: "memory");
;           __builtin_amdgcn_sched_barrier(0);
; #pragma unroll
;           for (int kb = 0; kb < 4; ++kb)
; #pragma unroll
;             for (int qb = 0; qb < QB; ++qb) s[kb][qb] = __builtin_amdgcn_mfma_f32_16x16x32_bf16(k2[kb], qf[qb][2], s[kb][qb], 0, 0, 0);
;         }
;       }
;       u32x2 va[2][4], vbq[2][4];
;       {
;         const unsigned p00 = cur + vb00, p01 = cur + vb01, p10 = cur + vb10, p11 = cur + vb11;
;         va[0][0] = ldsr64<0>(p00); vbq[0][0] = ldsr64<0>(p01); va[0][1] = ldsr64<2048>(p00); vbq[0][1] = ldsr64<2048>(p01);
.LBB0_2321:
	s_and_saveexec_b64 s[2:3], s[0:1]
	s_cbranch_execz .LBB0_2327
	s_mul_i32 s9, s8, 0x5000
	v_or_b32_e32 v0, s9, v213
	ds_read_b128 v[60:63], v0 offset:0
	ds_read_b128 v[64:67], v0 offset:0x800
	ds_read_b128 v[68:71], v0 offset:0x1000
	ds_read_b128 v[72:75], v0 offset:0x1800
	v_or_b32_e32 v2, s9, v214
	v_add_u32_e32 v3, s9, v215
	ds_read_b128 v[76:79], v2 offset:0
	ds_read_b128 v[80:83], v2 offset:0x800
	ds_read_b128 v[84:87], v2 offset:0x1000
	ds_read_b128 v[88:91], v2 offset:0x1800
	ds_read_b128 v[92:95], v3 offset:0
	ds_read_b128 v[96:99], v3 offset:0x400
	ds_read_b128 v[112:115], v3 offset:0x800
	ds_read_b128 v[116:119], v3 offset:0xc00
	s_waitcnt lgkmcnt(8)
	s_nop 0
	s_setprio 1
	v_mfma_f32_16x16x32_bf16 v[100:103], v[60:63], v[24:27], 0
	s_waitcnt lgkmcnt(4)
	v_mfma_f32_16x16x32_bf16 v[60:63], v[60:63], v[20:23], 0
	v_mfma_f32_16x16x32_bf16 v[104:107], v[64:67], v[24:27], 0
	v_mfma_f32_16x16x32_bf16 v[64:67], v[64:67], v[20:23], 0
	v_mfma_f32_16x16x32_bf16 v[120:123], v[68:71], v[24:27], 0
	v_mfma_f32_16x16x32_bf16 v[68:71], v[68:71], v[20:23], 0
	v_mfma_f32_16x16x32_bf16 v[124:127], v[72:75], v[24:27], 0
	v_mfma_f32_16x16x32_bf16 v[72:75], v[72:75], v[20:23], 0
	v_mfma_f32_16x16x32_bf16 v[100:103], v[76:79], v[16:19], v[100:103]
	s_waitcnt lgkmcnt(0)
	v_mfma_f32_16x16x32_bf16 v[60:63], v[76:79], v[12:15], v[60:63]
	v_mfma_f32_16x16x32_bf16 v[76:79], v[80:83], v[16:19], v[104:107]
	v_mfma_f32_16x16x32_bf16 v[64:67], v[80:83], v[12:15], v[64:67]
	v_mfma_f32_16x16x32_bf16 v[80:83], v[84:87], v[16:19], v[120:123]
	v_mfma_f32_16x16x32_bf16 v[68:71], v[84:87], v[12:15], v[68:71]
	v_mfma_f32_16x16x32_bf16 v[84:87], v[88:91], v[16:19], v[124:127]
	v_mfma_f32_16x16x32_bf16 v[72:75], v[88:91], v[12:15], v[72:75]
	v_mfma_f32_16x16x32_bf16 v[120:123], v[92:95], v[8:11], v[100:103]
	v_add_u32_e32 v0, s9, v209
	v_add_u32_e32 v2, s9, v210
	ds_read_b64 v[88:89], v0 offset:0
	v_mfma_f32_16x16x32_bf16 v[126:129], v[96:99], v[8:11], v[76:79]
	ds_read_b64 v[90:91], v2 offset:0
	s_nop 4
	v_fma_f32 v122, v122, s34, -v110
	v_fma_f32 v123, v123, s34, -v110
	v_pk_fma_f32 v[124:125], v[120:121], s[34:35], v[110:111] op_sel_hi:[1,0,0] neg_lo:[0,0,1] neg_hi:[0,0,1]
	v_mfma_f32_16x16x32_bf16 v[180:183], v[112:115], v[8:11], v[80:83]
	v_add_u32_e32 v3, s9, v211
	v_pk_fma_f32 v[120:121], v[128:129], s[34:35], v[110:111] op_sel_hi:[1,0,0] neg_lo:[0,0,1] neg_hi:[0,0,1]
	v_mfma_f32_16x16x32_bf16 v[216:219], v[116:119], v[8:11], v[84:87]
	ds_read_b64 v[84:85], v0 offset:0x800
	ds_read_b64 v[86:87], v2 offset:0x800
	ds_read_b64 v[80:81], v0 offset:0x1000
	v_mfma_f32_16x16x32_bf16 v[104:107], v[92:95], v[4:7], v[60:63]
	ds_read_b64 v[82:83], v2 offset:0x1000
	ds_read_b64 v[76:77], v0 offset:0x1800
	v_max_f32_e32 v0, v122, v123
	v_mfma_f32_16x16x32_bf16 v[92:95], v[116:119], v[4:7], v[72:75]
	v_fma_f32 v118, v126, s34, -v110
	v_fma_f32 v119, v127, s34, -v110
	v_pk_fma_f32 v[116:117], v[180:181], s[34:35], v[110:111] op_sel_hi:[1,0,0] neg_lo:[0,0,1] neg_hi:[0,0,1]
	v_max3_f32 v0, v124, v125, v0
	v_mfma_f32_16x16x32_bf16 v[100:103], v[96:99], v[4:7], v[64:67]
	v_max_f32_e32 v126, v118, v119
	v_max_f32_e32 v127, v120, v121
	v_add_u32_e32 v62, s9, v212
	v_mfma_f32_16x16x32_bf16 v[96:99], v[112:115], v[4:7], v[68:71]
	s_setprio 0
	v_fma_f32 v114, v182, s34, -v110
	v_fma_f32 v115, v183, s34, -v110
	ds_read_b64 v[78:79], v2 offset:0x1800
	ds_read_b64 v[72:73], v3 offset:0
	ds_read_b64 v[74:75], v62 offset:0
	ds_read_b64 v[68:69], v3 offset:0x800
	ds_read_b64 v[70:71], v62 offset:0x800
	ds_read_b64 v[64:65], v3 offset:0x1000
	ds_read_b64 v[66:67], v62 offset:0x1000
	ds_read_b64 v[60:61], v3 offset:0x1800
	v_pk_fma_f32 v[112:113], v[216:217], s[34:35], v[110:111] op_sel_hi:[1,0,0] neg_lo:[0,0,1] neg_hi:[0,0,1]
	v_pk_fma_f32 v[2:3], v[218:219], s[34:35], v[110:111] op_sel_hi:[1,0,0] neg_lo:[0,0,1] neg_hi:[0,0,1]
	v_max3_f32 v0, v0, v126, v127
	v_max_f32_e32 v126, v116, v117
	v_max_f32_e32 v127, v114, v115
	v_max3_f32 v0, v0, v126, v127
	v_max_f32_e32 v126, v112, v113
	v_max_f32_e32 v127, v2, v3
	v_max3_f32 v0, v0, v126, v127
	s_mov_b32 s9, 0x40c00000
	v_cmp_lt_f32_e32 vcc, s9, v0
	ds_read_b64 v[62:63], v62 offset:0x1800
	s_cbranch_vccz .LBB0_2324
	v_mov_b32_e32 v126, v0
	s_nop 1
	v_permlane16_swap_b32_e32 v0, v126
	v_max_f32_e32 v126, v126, v126
	v_max_f32_e32 v0, v0, v0
	v_max_f32_e32 v0, v0, v126
	v_mov_b32_e32 v126, v0
	s_nop 1
	v_permlane32_swap_b32_e32 v0, v126
	v_max3_f32 v0, v0, v126, 0
	v_exp_f32_e64 v126, -v0
	v_pk_add_f32 v[124:125], v[124:125], v[0:1] op_sel_hi:[1,0] neg_lo:[0,1] neg_hi:[0,1]
	v_pk_add_f32 v[122:123], v[122:123], v[0:1] op_sel_hi:[1,0] neg_lo:[0,1] neg_hi:[0,1]
	v_pk_add_f32 v[118:119], v[118:119], v[0:1] op_sel_hi:[1,0] neg_lo:[0,1] neg_hi:[0,1]
	v_pk_add_f32 v[120:121], v[120:121], v[0:1] op_sel_hi:[1,0] neg_lo:[0,1] neg_hi:[0,1]
	v_pk_add_f32 v[116:117], v[116:117], v[0:1] op_sel_hi:[1,0] neg_lo:[0,1] neg_hi:[0,1]
	v_pk_add_f32 v[114:115], v[114:115], v[0:1] op_sel_hi:[1,0] neg_lo:[0,1] neg_hi:[0,1]
	v_pk_add_f32 v[112:113], v[112:113], v[0:1] op_sel_hi:[1,0] neg_lo:[0,1] neg_hi:[0,1]
	v_pk_add_f32 v[2:3], v[2:3], v[0:1] op_sel_hi:[1,0] neg_lo:[0,1] neg_hi:[0,1]
	v_add_f32_e32 v110, v110, v0
	v_mul_f32_e32 v109, v109, v126
	v_pk_mul_f32 v[58:59], v[58:59], v[126:127] op_sel_hi:[1,0]
	v_pk_mul_f32 v[56:57], v[56:57], v[126:127] op_sel_hi:[1,0]
	v_pk_mul_f32 v[50:51], v[50:51], v[126:127] op_sel_hi:[1,0]
	v_pk_mul_f32 v[48:49], v[48:49], v[126:127] op_sel_hi:[1,0]
	v_pk_mul_f32 v[42:43], v[42:43], v[126:127] op_sel_hi:[1,0]
	v_pk_mul_f32 v[40:41], v[40:41], v[126:127] op_sel_hi:[1,0]
	v_pk_mul_f32 v[34:35], v[34:35], v[126:127] op_sel_hi:[1,0]
	v_pk_mul_f32 v[32:33], v[32:33], v[126:127] op_sel_hi:[1,0]

; #define RAW_BARRIER() do { asm volatile("s_waitcnt lgkmcnt(0)" ::: "memory"); __builtin_amdgcn_s_barrier(); } while (0)
; template <int DK, int QB, bool NA>
; DEVI void attn_item(const AttnArgs& a, unsigned char* smem) {
;     ...
;   for (int j = 0; j < nt; ++j) {
;     if (j + 1 < nt) {
;       if constexpr (DK == 96) asm volatile("s_waitcnt vmcnt(5)" ::: "memory");
;       else                    asm volatile("s_waitcnt vmcnt(4)" ::: "memory");
;     } else {
;       asm volatile("s_waitcnt vmcnt(0)" ::: "memory");
;     }
;     RAW_BARRIER();
;     if (j + 2 < nt) ATT_ISSUE(j + 2, is);
;     is = (is + 1 == S) ? 0 : is + 1;
;     const unsigned cur = lbase + cs * ATT_STAGE;
;     cs = (cs + 1 == S) ? 0 : cs + 1;
;     if (wact) {
;       f32x4 s[4][QB];
; #pragma unroll
;       for (int kb = 0; kb < 4; ++kb)
; #pragma unroll
;         for (int qb = 0; qb < QB; ++qb) s[kb][qb] = (f32x4){0.f, 0.f, 0.f, 0.f};
;       {
;         bf16x8 k0[4], k1[4], k2[4];
;         const unsigned a0 = cur + ka0, a1 = cur + ka1, a2 = cur + kr;
;         k0[0] = ldsr<0>(a0); k0[1] = ldsr<2048>(a0); k0[2] = ldsr<4096>(a0); k0[3] = ldsr<6144>(a0);
;         k1[0] = ldsr<0>(a1); k1[1] = ldsr<2048>(a1); k1[2] = ldsr<4096>(a1); k1[3] = ldsr<6144>(a1);
;         if constexpr (KS == 3) { k2[0] = ldsr<0>(a2); k2[1] = ldsr<1024>(a2); k2[2] = ldsr<2048>(a2); k2[3] = ldsr<3072>(a2); }
;         if constexpr (KS == 3) asm volatile("s_waitcnt lgkmcnt(8)" : "+v"(k0[0]), "+v"(k0[1]), "+v"(k0[2]), "+v"(k0[3]) :: "memory");
;         else                   asm volatile("s_waitcnt lgkmcnt(4)" : "+v"(k0[0]), "+v"(k0[1]), "+v"(k0[2]), "+v"(k0[3]) :: "memory");
;         __builtin_amdgcn_sched_barrier(0);
; #pragma unroll
;         for (int kb = 0; kb < 4; ++kb)
; #pragma unroll
;     ...
;           f32x2 ls2 = {0.f, 0.f};
;           unsigned pw[2][4];
; #pragma unroll
;           for (int kb = 0; kb < 4; ++kb)
; #pragma unroll
;             for (int h = 0; h < 2; ++h) {
;               const f32x2 pe = {__builtin_amdgcn_exp2f(t[kb][h].x), __builtin_amdgcn_exp2f(t[kb][h].y)};
;               ls2 += pe;
;               pw[kb >> 1][(kb & 1) * 2 + h] = pk2(pe.x, pe.y);
;             }
;           l[qb] += ls2.x + ls2.y;
; #pragma unroll
;           for (int c = 0; c < 2; ++c) {
;             const u32x4 pv = (u32x4){pw[c][0], pw[c][1], pw[c][2], pw[c][3]};
;             pf[qb][c] = __builtin_bit_cast(bf16x8, pv);
.LBB0_2326:
	v_exp_f32_e32 v94, v124
	v_exp_f32_e32 v95, v125
	v_exp_f32_e32 v124, v122
	v_exp_f32_e32 v125, v123
	v_exp_f32_e32 v118, v118
	v_exp_f32_e32 v119, v119
	v_pk_add_f32 v[128:129], v[94:95], 0 op_sel_hi:[1,0]
	v_exp_f32_e32 v120, v120
	v_exp_f32_e32 v121, v121
	v_cvt_pk_bf16_f32 v122, v94, v95
	v_pk_add_f32 v[94:95], v[124:125], v[128:129]
	v_exp_f32_e32 v116, v116
	v_exp_f32_e32 v117, v117
	v_cvt_pk_bf16_f32 v123, v124, v125
	v_pk_add_f32 v[94:95], v[118:119], v[94:95]
	v_cvt_pk_bf16_f32 v124, v118, v119
	v_exp_f32_e32 v118, v114
	v_exp_f32_e32 v119, v115
	v_exp_f32_e32 v112, v112
	v_exp_f32_e32 v113, v113
	v_pk_add_f32 v[94:95], v[120:121], v[94:95]
	v_exp_f32_e32 v2, v2
	v_exp_f32_e32 v3, v3
	v_pk_add_f32 v[94:95], v[116:117], v[94:95]
	v_cvt_pk_bf16_f32 v114, v116, v117
	v_pk_add_f32 v[94:95], v[118:119], v[94:95]
	v_cvt_pk_bf16_f32 v117, v2, v3
	v_pk_add_f32 v[94:95], v[112:113], v[94:95]
	v_exp_f32_e32 v104, v104
	v_pk_add_f32 v[94:95], v[2:3], v[94:95]
	v_exp_f32_e32 v2, v126
	v_exp_f32_e32 v3, v127
	v_add_f32_e32 v0, v94, v95
	v_exp_f32_e32 v94, v106
	v_exp_f32_e32 v95, v107
	v_exp_f32_e32 v105, v105
	v_pk_add_f32 v[106:107], v[2:3], 0 op_sel_hi:[1,0]
	v_exp_f32_e32 v102, v102
	v_exp_f32_e32 v103, v103
	v_cvt_pk_bf16_f32 v115, v118, v119
	v_cvt_pk_bf16_f32 v118, v2, v3
	v_pk_add_f32 v[2:3], v[94:95], v[106:107]
	v_cvt_pk_bf16_f32 v119, v94, v95
	v_exp_f32_e32 v94, v100
	v_exp_f32_e32 v95, v101
	v_exp_f32_e32 v98, v98
	v_exp_f32_e32 v99, v99
	v_pk_add_f32 v[2:3], v[104:105], v[2:3]
	v_exp_f32_e32 v96, v96
	v_exp_f32_e32 v97, v97
	v_pk_add_f32 v[2:3], v[102:103], v[2:3]
	v_exp_f32_e32 v92, v92
	v_exp_f32_e32 v93, v93
	v_pk_add_f32 v[2:3], v[94:95], v[2:3]
	s_waitcnt lgkmcnt(0)
	v_add_f32_e32 v109, v109, v0
	v_pk_add_f32 v[2:3], v[98:99], v[2:3]
	v_cvt_pk_bf16_f32 v125, v120, v121
	v_pk_add_f32 v[2:3], v[96:97], v[2:3]
	v_cvt_pk_bf16_f32 v116, v112, v113
	v_pk_add_f32 v[2:3], v[92:93], v[2:3]
	v_cvt_pk_bf16_f32 v120, v104, v105
	v_add_f32_e32 v0, v2, v3
	v_add_f32_e32 v108, v108, v0
	v_cvt_pk_bf16_f32 v121, v102, v103
	v_cvt_pk_bf16_f32 v94, v94, v95
	v_cvt_pk_bf16_f32 v95, v98, v99
	v_cvt_pk_bf16_f32 v96, v96, v97
	v_cvt_pk_bf16_f32 v97, v92, v93
	s_setprio 1
	v_mfma_f32_16x16x32_bf16 v[56:59], v[88:91], v[122:125], v[56:59]
	v_mfma_f32_16x16x32_bf16 v[52:55], v[88:91], v[118:121], v[52:55]
	v_mfma_f32_16x16x32_bf16 v[48:51], v[84:87], v[122:125], v[48:51]
	v_mfma_f32_16x16x32_bf16 v[44:47], v[84:87], v[118:121], v[44:47]
	v_mfma_f32_16x16x32_bf16 v[40:43], v[80:83], v[122:125], v[40:43]
	v_mfma_f32_16x16x32_bf16 v[36:39], v[80:83], v[118:121], v[36:39]
	v_mfma_f32_16x16x32_bf16 v[32:35], v[76:79], v[122:125], v[32:35]
	v_mfma_f32_16x16x32_bf16 v[28:31], v[76:79], v[118:121], v[28:31]
	v_mfma_f32_16x16x32_bf16 v[56:59], v[72:75], v[114:117], v[56:59]
	v_mfma_f32_16x16x32_bf16 v[52:55], v[72:75], v[94:97], v[52:55]
	v_mfma_f32_16x16x32_bf16 v[48:51], v[68:71], v[114:117], v[48:51]
	v_mfma_f32_16x16x32_bf16 v[44:47], v[68:71], v[94:97], v[44:47]
	v_mfma_f32_16x16x32_bf16 v[40:43], v[64:67], v[114:117], v[40:43]
	v_mfma_f32_16x16x32_bf16 v[36:39], v[64:67], v[94:97], v[36:39]
	v_mfma_f32_16x16x32_bf16 v[32:35], v[60:63], v[114:117], v[32:35]
	v_mfma_f32_16x16x32_bf16 v[28:31], v[60:63], v[94:97], v[28:31]
	s_setprio 0
.LBB0_2327:
	s_or_b64 exec, exec, s[2:3]
	s_waitcnt vmcnt(0)
	s_waitcnt lgkmcnt(0)
	s_barrier
	s_and_saveexec_b64 s[2:3], s[0:1]
	s_cbranch_execz .LBB0_2337
	s_add_i32 s0, s8, 1
	s_mul_i32 s1, s0, 0x5000
	s_cmp_lg_u32 s0, 3
	s_cselect_b32 s0, s1, 0
	v_or_b32_e32 v0, s0, v213
	ds_read_b128 v[60:63], v0 offset:0
	ds_read_b128 v[64:67], v0 offset:0x800
	ds_read_b128 v[68:71], v0 offset:0x1000
	ds_read_b128 v[72:75], v0 offset:0x1800
	v_or_b32_e32 v2, s0, v214
	v_add_u32_e32 v3, s0, v215
	ds_read_b128 v[76:79], v2 offset:0
	ds_read_b128 v[80:83], v2 offset:0x800
	ds_read_b128 v[84:87], v2 offset:0x1000
	ds_read_b128 v[88:91], v2 offset:0x1800
	ds_read_b128 v[92:95], v3 offset:0
	ds_read_b128 v[96:99], v3 offset:0x400
	ds_read_b128 v[100:103], v3 offset:0x800
	ds_read_b128 v[104:107], v3 offset:0xc00
	s_waitcnt lgkmcnt(8)
	s_nop 0
	s_setprio 1
	v_mfma_f32_16x16x32_bf16 v[24:27], v[60:63], v[24:27], 0
	s_waitcnt lgkmcnt(4)
	v_mfma_f32_16x16x32_bf16 v[20:23], v[60:63], v[20:23], 0
	v_mfma_f32_16x16x32_bf16 v[16:19], v[76:79], v[16:19], v[24:27]
	s_waitcnt lgkmcnt(0)
	v_mfma_f32_16x16x32_bf16 v[12:15], v[76:79], v[12:15], v[20:23]
	v_mfma_f32_16x16x32_bf16 v[74:77], v[92:95], v[8:11], v[16:19]
	v_add_u32_e32 v2, s0, v210
	v_add_u32_e32 v3, s0, v211
	s_nop 1
	v_add_u32_e32 v26, s0, v212
	v_add_u32_e32 v0, s0, v209
	ds_read_b64 v[64:65], v0 offset:0
	v_mfma_f32_16x16x32_bf16 v[68:71], v[92:95], v[4:7], v[12:15]
	s_setprio 0
	ds_read_b64 v[66:67], v2 offset:0
	ds_read_b64 v[60:61], v0 offset:0x800
	ds_read_b64 v[62:63], v2 offset:0x800
	ds_read_b64 v[22:23], v0 offset:0x1000
	ds_read_b64 v[24:25], v2 offset:0x1000
	ds_read_b64 v[18:19], v0 offset:0x1800
	ds_read_b64 v[20:21], v2 offset:0x1800
	ds_read_b64 v[14:15], v3 offset:0
	ds_read_b64 v[16:17], v26 offset:0
	ds_read_b64 v[10:11], v3 offset:0x800
	ds_read_b64 v[12:13], v26 offset:0x800
	ds_read_b64 v[6:7], v3 offset:0x1000
	ds_read_b64 v[8:9], v26 offset:0x1000
	ds_read_b64 v[2:3], v3 offset:0x1800
	ds_read_b64 v[4:5], v26 offset:0x1800
	s_nop 0
	v_fma_f32 v74, v74, s34, -v110
	v_fma_f32 v75, v75, s34, -v110
	v_pk_fma_f32 v[72:73], v[76:77], s[34:35], v[110:111] op_sel_hi:[1,0,0] neg_lo:[0,0,1] neg_hi:[0,0,1]
	v_sub_f32_e32 v26, 0xefede2e1, v110
	v_max_f32_e32 v0, v74, v75
	v_max_f32_e32 v27, v72, v73
	v_max_f32_e32 v76, v26, v26
	v_max3_f32 v0, v0, v27, v76
	s_mov_b32 s0, 0x40c00000
	v_mov_b32_e32 v27, v26
	v_cmp_lt_f32_e32 vcc, s0, v0
	s_cbranch_vccz .LBB0_2330
	v_mov_b32_e32 v76, v0
	s_nop 1
	v_permlane16_swap_b32_e32 v0, v76
	v_max_f32_e32 v76, v76, v76
	v_max_f32_e32 v0, v0, v0
	v_max_f32_e32 v0, v0, v76
	v_mov_b32_e32 v76, v0
	s_nop 1
	v_permlane32_swap_b32_e32 v0, v76
	v_max3_f32 v0, v0, v76, 0
	v_exp_f32_e64 v76, -v0
	v_pk_add_f32 v[74:75], v[74:75], v[0:1] op_sel_hi:[1,0] neg_lo:[0,1] neg_hi:[0,1]
	v_pk_add_f32 v[72:73], v[72:73], v[0:1] op_sel_hi:[1,0] neg_lo:[0,1] neg_hi:[0,1]
	v_pk_add_f32 v[26:27], v[26:27], v[0:1] op_sel_hi:[1,0] neg_lo:[0,1] neg_hi:[0,1]
	v_mul_f32_e32 v109, v109, v76
	v_pk_mul_f32 v[58:59], v[58:59], v[76:77] op_sel_hi:[1,0]
	v_pk_mul_f32 v[56:57], v[56:57], v[76:77] op_sel_hi:[1,0]
	v_pk_mul_f32 v[50:51], v[50:51], v[76:77] op_sel_hi:[1,0]
	v_pk_mul_f32 v[48:49], v[48:49], v[76:77] op_sel_hi:[1,0]
	v_pk_mul_f32 v[42:43], v[42:43], v[76:77] op_sel_hi:[1,0]
	v_pk_mul_f32 v[40:41], v[40:41], v[76:77] op_sel_hi:[1,0]
	v_pk_mul_f32 v[34:35], v[34:35], v[76:77] op_sel_hi:[1,0]
	v_pk_mul_f32 v[32:33], v[32:33], v[76:77] op_sel_hi:[1,0]

; DEVI unsigned pk2(float lo, float hi) { const f32x2_t v = {lo, hi}; const bf16x2_t b = __builtin_convertvector(v, bf16x2_t); return __builtin_bit_cast(unsigned, b); }
; DEVI size_t blk_off(int row, int col) { return ((size_t)(col >> 5) * MROWS + row) * 32 + (col & 31); }
; template <int DK, int QB, bool NA>
; DEVI void attn_item(const AttnArgs& a, unsigned char* smem) {
;     ...
;           f32x2 ls2 = {0.f, 0.f};
;           unsigned pw[2][4];
; #pragma unroll
;           for (int kb = 0; kb < 4; ++kb)
; #pragma unroll
;             for (int h = 0; h < 2; ++h) {
;               const f32x2 pe = {__builtin_amdgcn_exp2f(t[kb][h].x), __builtin_amdgcn_exp2f(t[kb][h].y)};
;               ls2 += pe;
;               pw[kb >> 1][(kb & 1) * 2 + h] = pk2(pe.x, pe.y);
;             }
;           l[qb] += ls2.x + ls2.y;
; #pragma unroll
;           for (int c = 0; c < 2; ++c) {
;             const u32x4 pv = (u32x4){pw[c][0], pw[c][1], pw[c][2], pw[c][3]};
;             pf[qb][c] = __builtin_bit_cast(bf16x8, pv);
;     ...
;       asm volatile("s_waitcnt lgkmcnt(0)"
;                    : "+v"(va[0][0]), "+v"(va[0][1]), "+v"(va[0][2]), "+v"(va[0][3]), "+v"(va[1][0]), "+v"(va[1][1]), "+v"(va[1][2]), "+v"(va[1][3]),
;                      "+v"(vbq[0][0]), "+v"(vbq[0][1]), "+v"(vbq[0][2]), "+v"(vbq[0][3]), "+v"(vbq[1][0]), "+v"(vbq[1][1]), "+v"(vbq[1][2]), "+v"(vbq[1][3])
;                    :: "memory");
;       __builtin_amdgcn_sched_barrier(0);
; #pragma unroll
;       for (int c = 0; c < 2; ++c)
; #pragma unroll
;         for (int db = 0; db < 4; ++db) {
;           const u32x4 vw = (u32x4){va[c][db].x, va[c][db].y, vbq[c][db].x, vbq[c][db].y};
;           const bf16x8 vf = __builtin_bit_cast(bf16x8, vw);
; #pragma unroll
;           for (int qb = 0; qb < QB; ++qb) o[db][qb] = __builtin_amdgcn_mfma_f32_16x16x32_bf16(vf, pf[qb][c], o[db][qb], 0, 0, 0);
;         }
;     }
;   }
;     ...
;   if (wact) {
; #pragma unroll
;     for (int qb = 0; qb < QB; ++qb) {
;       const float lt = xsum32(xsum16(l[qb]));
;       const float inv = 1.0f / lt;
;       const int qi = w * QB * 16 + qb * 16 + l16;
;       if (qi < a.nq) {
; #pragma unroll
;         for (int db = 0; db < 4; ++db) {
;           const f32x4 v = o[db][qb] * inv;
;           *(u32x2*)(a.O + blk_off(a.orow0 + qi, a.ocol0 + db * 16 + g * 4)) = (u32x2){pk2(v[0], v[1]), pk2(v[2], v[3])};
;         }
;       }
;     }
.LBB0_2332:
	v_exp_f32_e32 v74, v74
	v_exp_f32_e32 v75, v75
	v_exp_f32_e32 v72, v72
	v_exp_f32_e32 v73, v73
	v_exp_f32_e32 v26, v26
	v_exp_f32_e32 v27, v27
	v_pk_add_f32 v[80:81], v[74:75], 0 op_sel_hi:[1,0]
	v_cvt_pk_bf16_f32 v78, v74, v75
	v_pk_add_f32 v[74:75], v[72:73], v[80:81]
	v_cvt_pk_bf16_f32 v79, v72, v73
	v_pk_add_f32 v[72:73], v[26:27], v[74:75]
	v_exp_f32_e32 v70, v70
	v_pk_add_f32 v[72:73], v[26:27], v[72:73]
	v_exp_f32_e32 v71, v71
	v_pk_add_f32 v[72:73], v[26:27], v[72:73]
	v_cvt_pk_bf16_f32 v80, v26, v27
	v_pk_add_f32 v[72:73], v[26:27], v[72:73]
	v_exp_f32_e32 v68, v68
	v_pk_add_f32 v[72:73], v[26:27], v[72:73]
	v_exp_f32_e32 v69, v69
	v_pk_add_f32 v[26:27], v[26:27], v[72:73]
	v_exp_f32_e32 v72, v76
	v_exp_f32_e32 v73, v77
	s_waitcnt lgkmcnt(0)
	v_add_f32_e32 v0, v26, v27
	v_add_f32_e32 v0, v109, v0
	v_cvt_pk_bf16_f32 v76, v70, v71
	v_mov_b32_e32 v81, v80
	v_mov_b32_e32 v82, v80
	v_mov_b32_e32 v83, v80
	v_mov_b32_e32 v84, v80
	v_mov_b32_e32 v85, v80
	v_cvt_pk_bf16_f32 v74, v68, v69
	v_cvt_pk_bf16_f32 v75, v72, v73
	v_mov_b32_e32 v77, v76
	v_mov_b32_e32 v86, v76
	v_mov_b32_e32 v87, v76
	v_mov_b32_e32 v88, v76
	v_mov_b32_e32 v89, v76
	s_setprio 1
	v_mfma_f32_16x16x32_bf16 v[56:59], v[64:67], v[78:81], v[56:59]
	s_mul_i32 s20, s58, 0x18500
	v_mfma_f32_16x16x32_bf16 v[52:55], v[64:67], v[74:77], v[52:55]
	v_mfma_f32_16x16x32_bf16 v[48:51], v[60:63], v[78:81], v[48:51]
	v_mfma_f32_16x16x32_bf16 v[44:47], v[60:63], v[74:77], v[44:47]
	v_mfma_f32_16x16x32_bf16 v[40:43], v[22:25], v[78:81], v[40:43]
	v_mfma_f32_16x16x32_bf16 v[22:25], v[22:25], v[74:77], v[36:39]
	v_mfma_f32_16x16x32_bf16 v[60:63], v[18:21], v[78:81], v[32:35]
	s_nop 1
	v_mov_b32_e32 v36, v0
	s_nop 1
	v_permlane16_swap_b32_e32 v0, v36
	v_mfma_f32_16x16x32_bf16 v[64:67], v[18:21], v[74:77], v[28:31]
	v_add_f32_e32 v36, v0, v36
	v_or_b32_e32 v35, v208, v186
	v_lshlrev_b32_e32 v34, 2, v187
	v_mfma_f32_16x16x32_bf16 v[30:33], v[14:17], v[82:85], v[56:59]
	v_mov_b32_e32 v37, v36
	s_nop 1
	v_permlane32_swap_b32_e32 v36, v37
	v_mfma_f32_16x16x32_bf16 v[14:17], v[14:17], v[86:89], v[52:55]
	v_cmp_gt_i32_e32 vcc, s57, v35
	v_lshlrev_b32_e32 v0, 1, v34
	v_mfma_f32_16x16x32_bf16 v[26:29], v[10:13], v[82:85], v[48:51]
	v_mfma_f32_16x16x32_bf16 v[10:13], v[10:13], v[86:89], v[44:47]
	v_mfma_f32_16x16x32_bf16 v[18:21], v[6:9], v[82:85], v[40:43]
	v_mfma_f32_16x16x32_bf16 v[6:9], v[6:9], v[86:89], v[22:25]
	v_mfma_f32_16x16x32_bf16 v[22:25], v[2:5], v[82:85], v[60:63]
	v_mfma_f32_16x16x32_bf16 v[2:5], v[2:5], v[86:89], v[64:67]
	s_setprio 0
	s_and_saveexec_b64 s[0:1], vcc
	s_cbranch_execz .LBB0_2334
	v_add_f32_e32 v36, v36, v37
	v_div_scale_f32 v37, s[8:9], v36, v36, 1.0
	v_rcp_f32_e32 v38, v37
	v_div_scale_f32 v39, vcc, 1.0, v36, 1.0
	s_add_i32 s8, s20, 0xc280
	v_fma_f32 v40, -v37, v38, 1.0
	v_fmac_f32_e32 v38, v40, v38
	v_mul_f32_e32 v40, v39, v38
	v_fma_f32 v41, -v37, v40, v39
	v_fmac_f32_e32 v40, v41, v38
	v_fma_f32 v37, -v37, v40, v39
	v_div_fmas_f32 v37, v37, v38, v40
	v_div_fixup_f32 v36, v37, v36, 1.0
	v_pk_mul_f32 v[32:33], v[32:33], v[36:37] op_sel_hi:[1,0]
	v_pk_mul_f32 v[30:31], v[30:31], v[36:37] op_sel_hi:[1,0]
	v_pk_mul_f32 v[20:21], v[20:21], v[36:37] op_sel_hi:[1,0]
	v_cvt_pk_bf16_f32 v30, v30, v31
	v_cvt_pk_bf16_f32 v31, v32, v33
	v_add_u32_e32 v32, s59, v35
	v_ashrrev_i32_e32 v33, 31, v32
	v_pk_mul_f32 v[18:19], v[18:19], v[36:37] op_sel_hi:[1,0]
	s_mov_b32 s9, s21
	v_readlane_b32 s28, v251, 54
	v_cvt_pk_bf16_f32 v18, v18, v19
	v_cvt_pk_bf16_f32 v19, v20, v21
	v_lshl_add_u64 v[20:21], v[32:33], 0, s[8:9]
	v_readlane_b32 s29, v251, 55
	v_lshlrev_b64 v[20:21], 6, v[20:21]
	v_lshl_add_u64 v[38:39], v[32:33], 0, s[20:21]
	v_lshl_add_u64 v[20:21], s[28:29], 0, v[20:21]
	v_lshl_add_u64 v[20:21], v[20:21], 0, v[0:1]
	global_store_dwordx2 v[20:21], v[18:19], off
	v_pk_mul_f32 v[18:19], v[24:25], v[36:37] op_sel_hi:[1,0]
	v_pk_mul_f32 v[20:21], v[22:23], v[36:37] op_sel_hi:[1,0]
	v_or_b32_e32 v22, s56, v34
	v_cvt_pk_bf16_f32 v20, v20, v21
	v_cvt_pk_bf16_f32 v21, v18, v19
	v_or_b32_e32 v18, 48, v22
	v_lshrrev_b32_e32 v18, 5, v18
	v_mul_lo_u32 v18, v18, s93
	v_mov_b32_e32 v19, v1
	v_lshl_add_u64 v[18:19], v[18:19], 0, v[32:33]
	v_lshlrev_b64 v[38:39], 6, v[38:39]
	v_bitop3_b32 v22, v22, 28, 48 bitop3:0xc8
	v_lshlrev_b64 v[18:19], 6, v[18:19]
	v_lshl_add_u64 v[38:39], s[28:29], 0, v[38:39]
	v_pk_mul_f32 v[28:29], v[28:29], v[36:37] op_sel_hi:[1,0]
	v_pk_mul_f32 v[26:27], v[26:27], v[36:37] op_sel_hi:[1,0]
	v_lshl_add_u64 v[18:19], s[28:29], 0, v[18:19]
	v_lshlrev_b32_e32 v22, 1, v22
	v_mov_b32_e32 v23, v1
	v_lshl_add_u64 v[38:39], v[38:39], 0, v[0:1]
	v_cvt_pk_bf16_f32 v26, v26, v27
	v_cvt_pk_bf16_f32 v27, v28, v29
	v_lshl_add_u64 v[18:19], v[18:19], 0, v[22:23]
	global_store_dwordx2 v[38:39], v[30:31], off
	global_store_dwordx2 v[38:39], v[26:27], off offset:32
	global_store_dwordx2 v[18:19], v[20:21], off

; DEVI int otid() { int t = threadIdx.x; asm volatile("" : "+v"(t)); return t; }
; #define RAW_BARRIER() do { asm volatile("s_waitcnt lgkmcnt(0)" ::: "memory"); __builtin_amdgcn_s_barrier(); } while (0)
; template <int EPI, int NB>
; DEVI void gemm_tile(const GemmJob& J, int m0, int n0, unsigned char* smem) {
;     ...
;   const int tid = otid(), lane = tid & 63, wid = tid >> 6, wm = wid >> 1, wn = wid & 1;
;   const int l16 = lane & 15, g = lane >> 4;
;   f32x4 acc[4][NB];
; #pragma unroll
;   for (int i = 0; i < 4; ++i)
; #pragma unroll
;     for (int j = 0; j < NB; ++j) acc[i][j] = (f32x4){0.f, 0.f, 0.f, 0.f};
;   const int srow = tid >> 2, sch = tid & 3;
;   const int gch = sch ^ ((0 - (tid >> 4)) & 3);
;   const bf16_t* Ag = J.A + (size_t)(m0 + srow) * (J.ablk ? 32 : J.lda) + gch * 8;
;   const bf16_t* Bg = J.Bt + (size_t)(n0 + srow) * 32 + gch * 8;
;   const size_t Astep = (size_t)64 * (J.ablk ? 32 : J.lda), Ak = J.ablk ? (size_t)MROWS * 32 : (size_t)32, Bstep = (size_t)64 * 32, Bk = (size_t)J.NR * 32;
;   const int nk = J.K >> 5;
;   unsigned char* lds_t = smem + tid * 16;
;   const unsigned lbase = (unsigned)(uintptr_t)(__attribute__((address_space(3))) unsigned char*)smem;
;     ...
;   asm volatile("s_waitcnt vmcnt(0)" ::: "memory");
;   RAW_BARRIER();
; #pragma unroll
;   for (int st = 0; st < S - 1; ++st) GEMM_ISSUE(st, st);
; template <int EPI, int NB>
; DEVI void gemm_run(const GemmJob& J, unsigned char* smem, int rot) {
;     ...
;     const int ntiles = MT128 * J.ntn;
;     for (int t = b; t < ntiles; t += G) {
;       const int mt = t / J.ntn, nt = J.nt0 + (t - mt * J.ntn);
;       gemm_tile<EPI, NB>(J, mt * 128, nt * BN, smem);
.LBB0_2396:
	s_ashr_i32 s0, s9, 31
	s_lshr_b32 s0, s0, 30
	s_add_i32 s0, s9, s0
	s_ashr_i32 s0, s0, 2
	s_lshl_b32 s3, s0, 7
	s_lshl_b32 s0, s0, 10
	s_lshl_b32 s1, s9, 8
	v_mov_b32_e32 v184, v177
	s_sub_i32 s2, s1, s0
	s_nop 0
	s_mov_b64 s[28:29], 0x1000
	v_ashrrev_i32_e32 v10, 2, v184
	v_lshrrev_b32_e32 v0, 4, v184
	v_sub_u32_e32 v11, 0, v0
	v_add_u32_e32 v2, s3, v10
	v_add_u32_e32 v6, s2, v10
	v_xor_b32_e32 v0, v184, v11
	v_ashrrev_i32_e32 v3, 31, v2
	v_ashrrev_i32_e32 v7, 31, v6
	v_lshlrev_b64 v[2:3], 6, v[2:3]
	v_lshlrev_b32_e32 v0, 4, v0
	v_lshlrev_b64 v[6:7], 6, v[6:7]
	v_lshl_add_u64 v[4:5], v[146:147], 0, v[2:3]
	v_and_b32_e32 v0, 48, v0
	v_lshl_add_u64 v[6:7], v[140:141], 0, v[6:7]
	v_lshlrev_b32_e32 v185, 4, v184
	v_lshl_add_u64 v[4:5], v[4:5], 0, v[0:1]
	v_lshl_add_u64 v[6:7], v[6:7], 0, v[0:1]
	v_readfirstlane_b32 s1, v185
	v_add_u32_e32 v0, 0x1000, v185
	s_mov_b32 m0, s1
	v_readfirstlane_b32 s1, v0
	v_add_u32_e32 v0, 0x2000, v185
	s_waitcnt lgkmcnt(0)
	s_barrier
	global_load_lds_dwordx4 v[4:5], off
	v_lshl_add_u64 v[8:9], v[4:5], 0, s[28:29]
	s_mov_b32 m0, s1
	v_readfirstlane_b32 s1, v0
	v_add_u32_e32 v0, 0x3000, v185
	global_load_lds_dwordx4 v[8:9], off
	s_mov_b32 m0, s1
	v_readfirstlane_b32 s1, v0
	v_add_u32_e32 v0, 0x4000, v185
	global_load_lds_dwordx4 v[6:7], off
	v_lshl_add_u64 v[8:9], v[6:7], 0, s[28:29]
	s_mov_b32 m0, s1
	s_mov_b64 s[28:29], 0x2000
	v_readfirstlane_b32 s1, v0
	v_add_u32_e32 v0, 0x5000, v185
	global_load_lds_dwordx4 v[8:9], off
	v_lshl_add_u64 v[8:9], v[6:7], 0, s[28:29]
	s_mov_b32 m0, s1
	s_mov_b64 s[28:29], 0x3000
	v_readfirstlane_b32 s1, v0
	v_add_u32_e32 v0, 0x6000, v185
	global_load_lds_dwordx4 v[8:9], off
	v_lshl_add_u64 v[8:9], v[6:7], 0, s[28:29]
	s_mov_b32 m0, s1
	v_readfirstlane_b32 s1, v0
	v_add_u32_e32 v0, 0x7000, v185
	global_load_lds_dwordx4 v[8:9], off
	v_lshl_add_u64 v[8:9], v[4:5], 0, s[94:95]
	s_mov_b32 m0, s1
	s_mov_b64 s[28:29], 0x30b000
	v_readfirstlane_b32 s1, v0
	v_add_u32_e32 v0, 0x8000, v185
	global_load_lds_dwordx4 v[8:9], off
	v_lshl_add_u64 v[4:5], v[4:5], 0, s[28:29]
	s_mov_b32 m0, s1
	v_readfirstlane_b32 s1, v0
	v_add_u32_e32 v0, 0x9000, v185
	global_load_lds_dwordx4 v[4:5], off
	v_lshl_add_u64 v[4:5], v[6:7], 0, s[22:23]
	s_mov_b32 m0, s1
	s_mov_b64 s[28:29], 0x11000
	v_readfirstlane_b32 s1, v0
	v_add_u32_e32 v0, 0xa000, v185
	global_load_lds_dwordx4 v[4:5], off
	v_lshl_add_u64 v[4:5], v[6:7], 0, s[28:29]
	s_mov_b32 m0, s1
	s_mov_b64 s[28:29], 0x12000
	v_readfirstlane_b32 s1, v0
	v_add_u32_e32 v0, 0xb000, v185
	global_load_lds_dwordx4 v[4:5], off
	v_lshl_add_u64 v[4:5], v[6:7], 0, s[28:29]
	s_mov_b32 m0, s1
	s_mov_b64 s[28:29], 0x13000
	v_readfirstlane_b32 s1, v0
	global_load_lds_dwordx4 v[4:5], off
	v_lshl_add_u64 v[4:5], v[6:7], 0, s[28:29]
	s_mov_b32 m0, s1
	v_lshlrev_b32_e32 v0, 2, v184
	global_load_lds_dwordx4 v[4:5], off
	v_and_b32_e32 v0, 48, v0
	v_ashrrev_i32_e32 v4, 1, v184
	v_and_b32_e32 v186, 15, v184
	v_sub_u32_e32 v0, 0, v0
	v_and_b32_e32 v187, 0xffffffc0, v4
	v_bitop3_b32 v0, v184, 48, v0 bitop3:0x48
	v_or_b32_e32 v4, v187, v186
	v_lshl_or_b32 v209, v4, 6, v0
	v_lshlrev_b32_e32 v4, 1, v184
	v_and_b32_e32 v208, 0x80, v4
	v_or_b32_e32 v4, v208, v186
	v_lshl_or_b32 v0, v4, 6, v0
	v_add_u32_e32 v4, s8, v10
	v_subrev_u32_e32 v4, s0, v4
	v_ashrrev_i32_e32 v5, 31, v4
	v_add_u32_e32 v210, 0x2000, v0
	v_bitop3_b32 v0, v184, 3, v11 bitop3:0x48
	v_lshlrev_b64 v[4:5], 6, v[4:5]
	v_lshl_add_u64 v[182:183], v[130:131], 0, v[2:3]
	v_mov_b32_e32 v2, 0
	s_mov_b32 s42, 2
	s_mov_b32 s20, 0
	s_mov_b64 s[30:31], 0x1000
	v_lshlrev_b32_e32 v0, 4, v0
	v_lshl_add_u64 v[180:181], v[130:131], 0, v[4:5]
	s_mov_b32 s43, 0
	v_mov_b32_e32 v3, v2
	v_mov_b32_e32 v4, v2
	v_mov_b32_e32 v5, v2
	v_mov_b32_e32 v6, v2
	v_mov_b32_e32 v7, v2
	v_mov_b32_e32 v8, v2
	v_mov_b32_e32 v9, v2
	v_mov_b32_e32 v10, v2
	v_mov_b32_e32 v11, v2
	v_mov_b32_e32 v12, v2
	v_mov_b32_e32 v13, v2
	v_mov_b32_e32 v14, v2
	v_mov_b32_e32 v15, v2
	v_mov_b32_e32 v16, v2
	v_mov_b32_e32 v17, v2
	v_mov_b32_e32 v18, v2
	v_mov_b32_e32 v19, v2
	v_mov_b32_e32 v20, v2
	v_mov_b32_e32 v21, v2
	v_mov_b32_e32 v22, v2
	v_mov_b32_e32 v23, v2
; #define RAW_BARRIER() do { asm volatile("s_waitcnt lgkmcnt(0)" ::: "memory"); __builtin_amdgcn_s_barrier(); } while (0)
; template <int EPI, int NB>
; DEVI void gemm_tile(const GemmJob& J, int m0, int n0, unsigned char* smem) {
;     ...
;   f32x4 acc[4][NB];
; #pragma unroll
;   for (int i = 0; i < 4; ++i)
; #pragma unroll
;     for (int j = 0; j < NB; ++j) acc[i][j] = (f32x4){0.f, 0.f, 0.f, 0.f};
;   const int srow = tid >> 2, sch = tid & 3;
;   const int gch = sch ^ ((0 - (tid >> 4)) & 3);
;   const bf16_t* Ag = J.A + (size_t)(m0 + srow) * (J.ablk ? 32 : J.lda) + gch * 8;
;   const bf16_t* Bg = J.Bt + (size_t)(n0 + srow) * 32 + gch * 8;
;   const size_t Astep = (size_t)64 * (J.ablk ? 32 : J.lda), Ak = J.ablk ? (size_t)MROWS * 32 : (size_t)32, Bstep = (size_t)64 * 32, Bk = (size_t)J.NR * 32;
;   const int nk = J.K >> 5;
;   unsigned char* lds_t = smem + tid * 16;
;   const unsigned lbase = (unsigned)(uintptr_t)(__attribute__((address_space(3))) unsigned char*)smem;
;     ...
;   asm volatile("s_waitcnt vmcnt(0)" ::: "memory");
;   RAW_BARRIER();
; #pragma unroll
;   for (int st = 0; st < S - 1; ++st) GEMM_ISSUE(st, st);
;   const int fsl = (g ^ ((0 - (l16 >> 2)) & 3)) << 4;
;   const int aofs = (wm * 64 + l16) * 64 + fsl;
;   const int bofs = A_BYTES + (wn * NB * 16 + l16) * 64 + fsl;
;   int cs = 0, is = S - 1;
; #pragma clang loop unroll(disable)
;   for (int kt = 0; kt < nk; ++kt) {
;     if (nk - 1 - kt >= S - 2) {
;       if constexpr (NB == 8) asm volatile("s_waitcnt vmcnt(6)" ::: "memory");
;       else                   asm volatile("s_waitcnt vmcnt(8)" ::: "memory");
;     } else {
;       asm volatile("s_waitcnt vmcnt(0)" ::: "memory");
;     }
;     RAW_BARRIER();
;     if (kt + S - 1 < nk) GEMM_ISSUE(kt + S - 1, is);
;     is = (is + 1 == S) ? 0 : is + 1;
	v_mov_b32_e32 v24, v2
	v_mov_b32_e32 v25, v2
	v_mov_b32_e32 v26, v2
	v_mov_b32_e32 v27, v2
	v_mov_b32_e32 v28, v2
	v_mov_b32_e32 v29, v2
	v_mov_b32_e32 v30, v2
	v_mov_b32_e32 v31, v2
	v_mov_b32_e32 v32, v2
	v_mov_b32_e32 v33, v2
	v_mov_b32_e32 v34, v2
	v_mov_b32_e32 v35, v2
	v_mov_b32_e32 v36, v2
	v_mov_b32_e32 v37, v2
	v_mov_b32_e32 v38, v2
	v_mov_b32_e32 v39, v2
	v_mov_b32_e32 v40, v2
	v_mov_b32_e32 v41, v2
	v_mov_b32_e32 v42, v2
	v_mov_b32_e32 v43, v2
	v_mov_b32_e32 v44, v2
	v_mov_b32_e32 v45, v2
	v_mov_b32_e32 v46, v2
	v_mov_b32_e32 v47, v2
	v_mov_b32_e32 v48, v2
	v_mov_b32_e32 v49, v2
	v_mov_b32_e32 v50, v2
	v_mov_b32_e32 v51, v2
	v_mov_b32_e32 v52, v2
	v_mov_b32_e32 v53, v2
	v_mov_b32_e32 v54, v2
	v_mov_b32_e32 v55, v2
	v_mov_b32_e32 v56, v2
	v_mov_b32_e32 v57, v2
	v_mov_b32_e32 v58, v2
	v_mov_b32_e32 v59, v2
	v_mov_b32_e32 v60, v2
	v_mov_b32_e32 v61, v2
	v_mov_b32_e32 v62, v2
	v_mov_b32_e32 v63, v2
	v_mov_b32_e32 v64, v2
	v_mov_b32_e32 v65, v2
	v_mov_b32_e32 v66, v2
	v_mov_b32_e32 v67, v2
	v_mov_b32_e32 v68, v2
	v_mov_b32_e32 v69, v2
	v_mov_b32_e32 v70, v2
	v_mov_b32_e32 v71, v2
	v_mov_b32_e32 v72, v2
	v_mov_b32_e32 v73, v2
	v_mov_b32_e32 v74, v2
	v_mov_b32_e32 v75, v2
	v_mov_b32_e32 v76, v2
	v_mov_b32_e32 v77, v2
	v_mov_b32_e32 v78, v2
	v_mov_b32_e32 v79, v2
	v_mov_b32_e32 v80, v2
	v_mov_b32_e32 v81, v2
	v_mov_b32_e32 v82, v2
	v_mov_b32_e32 v83, v2
	v_mov_b32_e32 v84, v2
	v_mov_b32_e32 v85, v2
	v_mov_b32_e32 v86, v2
	v_mov_b32_e32 v87, v2
	v_mov_b32_e32 v88, v2
	v_mov_b32_e32 v89, v2
	v_mov_b32_e32 v90, v2
	v_mov_b32_e32 v91, v2
	v_mov_b32_e32 v92, v2
	v_mov_b32_e32 v93, v2
	v_mov_b32_e32 v94, v2
	v_mov_b32_e32 v95, v2
	v_mov_b32_e32 v96, v2
	v_mov_b32_e32 v97, v2
	v_mov_b32_e32 v98, v2
	v_mov_b32_e32 v99, v2
	v_mov_b32_e32 v100, v2
	v_mov_b32_e32 v101, v2
	v_mov_b32_e32 v102, v2
	v_mov_b32_e32 v103, v2
	v_mov_b32_e32 v104, v2
	v_mov_b32_e32 v105, v2
	v_mov_b32_e32 v106, v2
	v_mov_b32_e32 v107, v2
	v_mov_b32_e32 v108, v2
	v_mov_b32_e32 v109, v2
	v_mov_b32_e32 v110, v2
	v_mov_b32_e32 v111, v2
	v_mov_b32_e32 v112, v2
	v_mov_b32_e32 v113, v2
	v_mov_b32_e32 v114, v2
	v_mov_b32_e32 v115, v2
	v_mov_b32_e32 v116, v2
	v_mov_b32_e32 v117, v2
	v_mov_b32_e32 v118, v2
	v_mov_b32_e32 v119, v2
	v_mov_b32_e32 v120, v2
	v_mov_b32_e32 v121, v2
	v_mov_b32_e32 v122, v2
	v_mov_b32_e32 v123, v2
	v_mov_b32_e32 v124, v2
	v_mov_b32_e32 v125, v2
	v_mov_b32_e32 v126, v2
	v_mov_b32_e32 v127, v2
	v_mov_b32_e32 v128, v2
	v_mov_b32_e32 v129, v2
	s_mul_i32 s0, s42, 0x6000
	v_add_u32_e32 v211, s0, v185
	v_lshl_add_u64 v[212:213], v[182:183], 0, v[0:1]
	v_readfirstlane_b32 s0, v211
	v_lshl_add_u64 v[214:215], v[212:213], 0, s[84:85]
	s_mov_b32 m0, s0
	v_lshl_add_u64 v[212:213], v[212:213], 0, s[12:13]
	s_nop 0
	v_readfirstlane_b32 s100, v214
	v_readfirstlane_b32 s101, v215
	s_nop 1
	v_subrev_u32_e32 v228, s100, v214
	v_add_u32_e32 v214, 0x1000, v211
	v_add_u32_e32 v216, 0x2000, v211
	v_readfirstlane_b32 s0, v214
	s_mov_b32 m0, s0
	s_mov_b64 s[0:1], 0x4766000
	v_subrev_u32_e32 v229, s100, v212
	v_lshl_add_u64 v[212:213], v[180:181], 0, v[0:1]
	v_lshl_add_u64 v[214:215], v[212:213], 0, s[0:1]
	v_readfirstlane_b32 s0, v216
	s_mov_b32 m0, s0
	s_mov_b64 s[0:1], 0x4767000
	v_add_u32_e32 v216, 0x3000, v211
	s_nop 0
	v_readfirstlane_b32 vcc_lo, v214
	v_readfirstlane_b32 vcc_hi, v215
	s_nop 1
	v_subrev_u32_e32 v230, vcc_lo, v214
	v_lshl_add_u64 v[214:215], v[212:213], 0, s[0:1]
	v_readfirstlane_b32 s0, v216
	s_mov_b32 m0, s0
	s_mov_b64 s[0:1], 0x4768000
	v_add_u32_e32 v216, 0x4000, v211
	v_subrev_u32_e32 v231, vcc_lo, v214
	v_lshl_add_u64 v[214:215], v[212:213], 0, s[0:1]
	v_readfirstlane_b32 s0, v216
	s_mov_b32 m0, s0
	s_mov_b64 s[0:1], 0x4769000
	v_add_u32_e32 v211, 0x5000, v211
	v_lshl_add_u64 v[212:213], v[212:213], 0, s[0:1]
	v_readfirstlane_b32 s0, v211
	v_subrev_u32_e32 v232, vcc_lo, v214
	s_mov_b32 m0, s0
	s_nop 0
	v_subrev_u32_e32 v233, vcc_lo, v212
	v_mov_b32_e32 v182, v228
	v_mov_b32_e32 v183, v229
	v_mov_b32_e32 v180, v230
	v_mov_b32_e32 v181, v231
	v_mov_b32_e32 v253, v232
	v_mov_b32_e32 v254, v233
	v_readfirstlane_b32 s0, v185
	s_branch .LBB0_2398

; DEVI int otid() { int t = threadIdx.x; asm volatile("" : "+v"(t)); return t; }
; #define RAW_BARRIER() do { asm volatile("s_waitcnt lgkmcnt(0)" ::: "memory"); __builtin_amdgcn_s_barrier(); } while (0)
; template <int EPI, int NB>
; DEVI void gemm_tile(const GemmJob& J, int m0, int n0, unsigned char* smem) {
;     ...
;   const int tid = otid(), lane = tid & 63, wid = tid >> 6, wm = wid >> 1, wn = wid & 1;
;   const int l16 = lane & 15, g = lane >> 4;
;   f32x4 acc[4][NB];
; #pragma unroll
;   for (int i = 0; i < 4; ++i)
; #pragma unroll
;     for (int j = 0; j < NB; ++j) acc[i][j] = (f32x4){0.f, 0.f, 0.f, 0.f};
;   const int srow = tid >> 2, sch = tid & 3;
;   const int gch = sch ^ ((0 - (tid >> 4)) & 3);
;   const bf16_t* Ag = J.A + (size_t)(m0 + srow) * (J.ablk ? 32 : J.lda) + gch * 8;
;   const bf16_t* Bg = J.Bt + (size_t)(n0 + srow) * 32 + gch * 8;
;   const size_t Astep = (size_t)64 * (J.ablk ? 32 : J.lda), Ak = J.ablk ? (size_t)MROWS * 32 : (size_t)32, Bstep = (size_t)64 * 32, Bk = (size_t)J.NR * 32;
;   const int nk = J.K >> 5;
;   unsigned char* lds_t = smem + tid * 16;
;   const unsigned lbase = (unsigned)(uintptr_t)(__attribute__((address_space(3))) unsigned char*)smem;
;     ...
;   asm volatile("s_waitcnt vmcnt(0)" ::: "memory");
;   RAW_BARRIER();
; #pragma unroll
;   for (int st = 0; st < S - 1; ++st) GEMM_ISSUE(st, st);
; template <int EPI, int NB>
; DEVI void gemm_run(const GemmJob& J, unsigned char* smem, int rot) {
;     ...
;     for (int q0 = lb; q0 < ntot; q0 += nlb) {
;       const int q = J.rev ? ntot - 1 - q0 : q0;
;       int grp = q / gsz; const int qq = q - grp * gsz;
;       const int mg = min(8, mcnt - grp * 8);
;       const int nt = qq / mg, mi = qq - nt * mg;
;       gemm_tile<EPI, NB>(J, (mlo + grp * 8 + mi) * 128, (J.nt0 + nt) * BN, smem);
.LBB0_2474:
	s_ashr_i32 s0, s9, 31
	s_lshr_b32 s0, s0, 27
	s_add_i32 s0, s9, s0
	s_ashr_i32 s1, s0, 5
	s_lshl_b32 s3, s1, 3
	v_readlane_b32 s2, v251, 48
	s_sub_i32 s2, s2, s3
	s_min_i32 s20, s2, 8
	s_abs_i32 s40, s20
	v_cvt_f32_u32_e32 v0, s40
	s_sub_i32 s43, 0, s40
	s_andn2_b32 s0, s0, 31
	s_sub_i32 s0, s9, s0
	v_rcp_iflag_f32_e32 v0, v0
	s_abs_i32 s41, s0
	s_xor_b32 s42, s0, s20
	s_ashr_i32 s42, s42, 31
	v_mul_f32_e32 v0, 0x4f7ffffe, v0
	v_cvt_u32_f32_e32 v0, v0
	v_mov_b32_e32 v184, v177
	s_nop 0
	v_readfirstlane_b32 s44, v0
	s_mul_i32 s43, s43, s44
	s_mul_hi_u32 s43, s44, s43
	s_add_i32 s44, s44, s43
	s_mul_hi_u32 s43, s41, s44
	s_mul_i32 s44, s43, s40
	s_sub_i32 s41, s41, s44
	s_add_i32 s45, s43, 1
	s_sub_i32 s44, s41, s40
	s_cmp_ge_u32 s41, s40
	s_cselect_b32 s43, s45, s43
	s_cselect_b32 s41, s44, s41
	s_add_i32 s44, s43, 1
	s_cmp_ge_u32 s41, s40
	s_cselect_b32 s40, s44, s43
	s_xor_b32 s40, s40, s42
	s_sub_i32 s40, s40, s42
	s_mul_i32 s41, s20, s40
	v_readlane_b32 s20, v250, 37
	s_add_i32 s3, s3, s20
	s_add_i32 s3, s3, s0
	s_sub_i32 s0, s3, s41
	s_lshl_b32 s20, s0, 7
	s_lshl_b32 s3, s40, 8
	v_ashrrev_i32_e32 v10, 2, v184
	v_lshrrev_b32_e32 v0, 4, v184
	v_sub_u32_e32 v11, 0, v0
	v_add_u32_e32 v2, s20, v10
	v_add_u32_e32 v4, s3, v10
	v_xor_b32_e32 v0, v184, v11
	v_ashrrev_i32_e32 v3, 31, v2
	v_ashrrev_i32_e32 v5, 31, v4
	v_lshlrev_b64 v[2:3], 6, v[2:3]
	v_lshlrev_b32_e32 v0, 4, v0
	v_lshlrev_b64 v[4:5], 6, v[4:5]
	v_lshl_add_u64 v[2:3], v[146:147], 0, v[2:3]
	v_and_b32_e32 v0, 48, v0
	v_lshl_add_u64 v[6:7], v[140:141], 0, v[4:5]
	v_lshlrev_b32_e32 v185, 4, v184
	v_lshl_add_u64 v[2:3], v[2:3], 0, v[0:1]
	v_lshl_add_u64 v[6:7], v[6:7], 0, v[0:1]
	v_readfirstlane_b32 s0, v185
	v_add_u32_e32 v0, 0x1000, v185
	s_mov_b32 m0, s0
	s_mov_b64 s[28:29], 0x1000
	v_readfirstlane_b32 s0, v0
	v_add_u32_e32 v0, 0x2000, v185
	s_waitcnt lgkmcnt(0)
	s_barrier
	global_load_lds_dwordx4 v[2:3], off
	v_lshl_add_u64 v[8:9], v[2:3], 0, s[28:29]
	s_mov_b32 m0, s0
	v_readfirstlane_b32 s0, v0
	v_add_u32_e32 v0, 0x3000, v185
	global_load_lds_dwordx4 v[8:9], off
	s_mov_b32 m0, s0
	v_readfirstlane_b32 s0, v0
	v_add_u32_e32 v0, 0x4000, v185
	global_load_lds_dwordx4 v[6:7], off
	v_lshl_add_u64 v[8:9], v[6:7], 0, s[28:29]
	s_mov_b32 m0, s0
	s_mov_b64 s[28:29], 0x2000
	v_readfirstlane_b32 s0, v0
	v_add_u32_e32 v0, 0x5000, v185
	global_load_lds_dwordx4 v[8:9], off
	v_lshl_add_u64 v[8:9], v[6:7], 0, s[28:29]
	s_mov_b32 m0, s0
	s_mov_b64 s[28:29], 0x3000
	v_readfirstlane_b32 s0, v0
	v_add_u32_e32 v0, 0x6000, v185
	global_load_lds_dwordx4 v[8:9], off
	v_lshl_add_u64 v[8:9], v[6:7], 0, s[28:29]
	s_mov_b32 m0, s0
	v_readfirstlane_b32 s0, v0
	v_add_u32_e32 v0, 0x7000, v185
	global_load_lds_dwordx4 v[8:9], off
	v_lshl_add_u64 v[8:9], v[2:3], 0, s[94:95]
	s_mov_b32 m0, s0
	s_mov_b64 s[28:29], 0x30b000
	v_readfirstlane_b32 s0, v0
	v_add_u32_e32 v0, 0x8000, v185
	global_load_lds_dwordx4 v[8:9], off
	v_lshl_add_u64 v[2:3], v[2:3], 0, s[28:29]
	s_mov_b32 m0, s0
	v_readfirstlane_b32 s0, v0
	v_add_u32_e32 v0, 0x9000, v185
	global_load_lds_dwordx4 v[2:3], off
	v_lshl_add_u64 v[2:3], v[6:7], 0, s[22:23]
	s_mov_b32 m0, s0
	s_mov_b64 s[28:29], 0x11000
	v_readfirstlane_b32 s0, v0
	v_add_u32_e32 v0, 0xa000, v185
	global_load_lds_dwordx4 v[2:3], off
	v_lshl_add_u64 v[2:3], v[6:7], 0, s[28:29]
	s_mov_b32 m0, s0
	s_mov_b64 s[28:29], 0x12000
	v_readfirstlane_b32 s0, v0
	v_add_u32_e32 v0, 0xb000, v185
	global_load_lds_dwordx4 v[2:3], off
	v_lshl_add_u64 v[2:3], v[6:7], 0, s[28:29]
	s_mov_b32 m0, s0
	s_mov_b64 s[28:29], 0x13000
	v_readfirstlane_b32 s0, v0
	global_load_lds_dwordx4 v[2:3], off
	v_lshl_add_u64 v[2:3], v[6:7], 0, s[28:29]
	s_mov_b32 m0, s0
	v_lshlrev_b32_e32 v0, 2, v184
	global_load_lds_dwordx4 v[2:3], off
	v_and_b32_e32 v0, 48, v0
	v_ashrrev_i32_e32 v2, 1, v184
	v_and_b32_e32 v186, 15, v184
	v_sub_u32_e32 v0, 0, v0
	v_and_b32_e32 v187, 0xffffffc0, v2
	v_bitop3_b32 v0, v184, 48, v0 bitop3:0x48
	v_or_b32_e32 v2, v187, v186
	v_lshl_or_b32 v209, v2, 6, v0
	v_lshlrev_b32_e32 v2, 1, v184
	v_and_b32_e32 v208, 0x80, v2
	s_sub_i32 s0, s8, s41
	s_mul_i32 s1, s1, 24
	v_or_b32_e32 v2, v208, v186
	s_sub_i32 s0, s0, s1
	v_lshl_or_b32 v0, v2, 6, v0
	v_lshl_add_u32 v2, s0, 7, v10
	v_ashrrev_i32_e32 v3, 31, v2
	v_lshlrev_b64 v[2:3], 6, v[2:3]
	v_add_u32_e32 v210, 0x2000, v0
	v_bitop3_b32 v0, v184, 3, v11 bitop3:0x48
	v_lshl_add_u64 v[182:183], v[130:131], 0, v[2:3]
	v_mov_b32_e32 v2, 0
	s_mov_b32 s2, 0
	s_mov_b32 s42, 2
	s_mov_b64 s[30:31], 0x1000
	v_lshlrev_b32_e32 v0, 4, v0
	v_lshl_add_u64 v[180:181], v[130:131], 0, v[4:5]
	s_mov_b32 s43, 0
; #define RAW_BARRIER() do { asm volatile("s_waitcnt lgkmcnt(0)" ::: "memory"); __builtin_amdgcn_s_barrier(); } while (0)
; template <int EPI, int NB>
; DEVI void gemm_tile(const GemmJob& J, int m0, int n0, unsigned char* smem) {
;     ...
;   f32x4 acc[4][NB];
; #pragma unroll
;   for (int i = 0; i < 4; ++i)
; #pragma unroll
;     for (int j = 0; j < NB; ++j) acc[i][j] = (f32x4){0.f, 0.f, 0.f, 0.f};
;   const int srow = tid >> 2, sch = tid & 3;
;   const int gch = sch ^ ((0 - (tid >> 4)) & 3);
;   const bf16_t* Ag = J.A + (size_t)(m0 + srow) * (J.ablk ? 32 : J.lda) + gch * 8;
;   const bf16_t* Bg = J.Bt + (size_t)(n0 + srow) * 32 + gch * 8;
;   const size_t Astep = (size_t)64 * (J.ablk ? 32 : J.lda), Ak = J.ablk ? (size_t)MROWS * 32 : (size_t)32, Bstep = (size_t)64 * 32, Bk = (size_t)J.NR * 32;
;   const int nk = J.K >> 5;
;   unsigned char* lds_t = smem + tid * 16;
;   const unsigned lbase = (unsigned)(uintptr_t)(__attribute__((address_space(3))) unsigned char*)smem;
;     ...
;   asm volatile("s_waitcnt vmcnt(0)" ::: "memory");
;   RAW_BARRIER();
; #pragma unroll
;   for (int st = 0; st < S - 1; ++st) GEMM_ISSUE(st, st);
;   const int fsl = (g ^ ((0 - (l16 >> 2)) & 3)) << 4;
;   const int aofs = (wm * 64 + l16) * 64 + fsl;
;   const int bofs = A_BYTES + (wn * NB * 16 + l16) * 64 + fsl;
;   int cs = 0, is = S - 1;
; #pragma clang loop unroll(disable)
;   for (int kt = 0; kt < nk; ++kt) {
;     if (nk - 1 - kt >= S - 2) {
;       if constexpr (NB == 8) asm volatile("s_waitcnt vmcnt(6)" ::: "memory");
;       else                   asm volatile("s_waitcnt vmcnt(8)" ::: "memory");
;     } else {
;       asm volatile("s_waitcnt vmcnt(0)" ::: "memory");
;     }
;     RAW_BARRIER();
;     if (kt + S - 1 < nk) GEMM_ISSUE(kt + S - 1, is);
;     is = (is + 1 == S) ? 0 : is + 1;
	v_mov_b32_e32 v3, v2
	v_mov_b32_e32 v4, v2
	v_mov_b32_e32 v5, v2
	v_mov_b32_e32 v6, v2
	v_mov_b32_e32 v7, v2
	v_mov_b32_e32 v8, v2
	v_mov_b32_e32 v9, v2
	v_mov_b32_e32 v10, v2
	v_mov_b32_e32 v11, v2
	v_mov_b32_e32 v12, v2
	v_mov_b32_e32 v13, v2
	v_mov_b32_e32 v14, v2
	v_mov_b32_e32 v15, v2
	v_mov_b32_e32 v16, v2
	v_mov_b32_e32 v17, v2
	v_mov_b32_e32 v18, v2
	v_mov_b32_e32 v19, v2
	v_mov_b32_e32 v20, v2
	v_mov_b32_e32 v21, v2
	v_mov_b32_e32 v22, v2
	v_mov_b32_e32 v23, v2
	v_mov_b32_e32 v24, v2
	v_mov_b32_e32 v25, v2
	v_mov_b32_e32 v26, v2
	v_mov_b32_e32 v27, v2
	v_mov_b32_e32 v28, v2
	v_mov_b32_e32 v29, v2
	v_mov_b32_e32 v30, v2
	v_mov_b32_e32 v31, v2
	v_mov_b32_e32 v32, v2
	v_mov_b32_e32 v33, v2
	v_mov_b32_e32 v34, v2
	v_mov_b32_e32 v35, v2
	v_mov_b32_e32 v36, v2
	v_mov_b32_e32 v37, v2
	v_mov_b32_e32 v38, v2
	v_mov_b32_e32 v39, v2
	v_mov_b32_e32 v40, v2
	v_mov_b32_e32 v41, v2
	v_mov_b32_e32 v42, v2
	v_mov_b32_e32 v43, v2
	v_mov_b32_e32 v44, v2
	v_mov_b32_e32 v45, v2
	v_mov_b32_e32 v46, v2
	v_mov_b32_e32 v47, v2
	v_mov_b32_e32 v48, v2
	v_mov_b32_e32 v49, v2
	v_mov_b32_e32 v50, v2
	v_mov_b32_e32 v51, v2
	v_mov_b32_e32 v52, v2
	v_mov_b32_e32 v53, v2
	v_mov_b32_e32 v54, v2
	v_mov_b32_e32 v55, v2
	v_mov_b32_e32 v56, v2
	v_mov_b32_e32 v57, v2
	v_mov_b32_e32 v58, v2
	v_mov_b32_e32 v59, v2
	v_mov_b32_e32 v60, v2
	v_mov_b32_e32 v61, v2
	v_mov_b32_e32 v62, v2
	v_mov_b32_e32 v63, v2
	v_mov_b32_e32 v64, v2
	v_mov_b32_e32 v65, v2
	v_mov_b32_e32 v66, v2
	v_mov_b32_e32 v67, v2
	v_mov_b32_e32 v68, v2
	v_mov_b32_e32 v69, v2
	v_mov_b32_e32 v70, v2
	v_mov_b32_e32 v71, v2
	v_mov_b32_e32 v72, v2
	v_mov_b32_e32 v73, v2
	v_mov_b32_e32 v74, v2
	v_mov_b32_e32 v75, v2
	v_mov_b32_e32 v76, v2
	v_mov_b32_e32 v77, v2
	v_mov_b32_e32 v78, v2
	v_mov_b32_e32 v79, v2
	v_mov_b32_e32 v80, v2
	v_mov_b32_e32 v81, v2
	v_mov_b32_e32 v82, v2
	v_mov_b32_e32 v83, v2
	v_mov_b32_e32 v84, v2
	v_mov_b32_e32 v85, v2
	v_mov_b32_e32 v86, v2
	v_mov_b32_e32 v87, v2
	v_mov_b32_e32 v88, v2
	v_mov_b32_e32 v89, v2
	v_mov_b32_e32 v90, v2
	v_mov_b32_e32 v91, v2
	v_mov_b32_e32 v92, v2
	v_mov_b32_e32 v93, v2
	v_mov_b32_e32 v94, v2
	v_mov_b32_e32 v95, v2
	v_mov_b32_e32 v96, v2
	v_mov_b32_e32 v97, v2
	v_mov_b32_e32 v98, v2
	v_mov_b32_e32 v99, v2
	v_mov_b32_e32 v100, v2
	v_mov_b32_e32 v101, v2
	v_mov_b32_e32 v102, v2
	v_mov_b32_e32 v103, v2
	v_mov_b32_e32 v104, v2
	v_mov_b32_e32 v105, v2
	v_mov_b32_e32 v106, v2
	v_mov_b32_e32 v107, v2
	v_mov_b32_e32 v108, v2
	v_mov_b32_e32 v109, v2
	v_mov_b32_e32 v110, v2
	v_mov_b32_e32 v111, v2
	v_mov_b32_e32 v112, v2
	v_mov_b32_e32 v113, v2
	v_mov_b32_e32 v114, v2
	v_mov_b32_e32 v115, v2
	v_mov_b32_e32 v116, v2
	v_mov_b32_e32 v117, v2
	v_mov_b32_e32 v118, v2
	v_mov_b32_e32 v119, v2
	v_mov_b32_e32 v120, v2
	v_mov_b32_e32 v121, v2
	v_mov_b32_e32 v122, v2
	v_mov_b32_e32 v123, v2
	v_mov_b32_e32 v124, v2
	v_mov_b32_e32 v125, v2
	v_mov_b32_e32 v126, v2
	v_mov_b32_e32 v127, v2
	v_mov_b32_e32 v128, v2
	v_mov_b32_e32 v129, v2
	s_mul_i32 s0, s42, 0x6000
	v_add_u32_e32 v211, s0, v185
	v_lshl_add_u64 v[212:213], v[182:183], 0, v[0:1]
	v_readfirstlane_b32 s0, v211
	v_lshl_add_u64 v[214:215], v[212:213], 0, s[84:85]
	s_mov_b32 m0, s0
	v_lshl_add_u64 v[212:213], v[212:213], 0, s[12:13]
	s_nop 0
	v_readfirstlane_b32 s100, v214
	v_readfirstlane_b32 s101, v215
	s_nop 1
	v_subrev_u32_e32 v228, s100, v214
	v_add_u32_e32 v214, 0x1000, v211
	v_add_u32_e32 v216, 0x2000, v211
	v_readfirstlane_b32 s0, v214
	s_mov_b32 m0, s0
	s_mov_b64 s[0:1], 0x4766000
	v_subrev_u32_e32 v229, s100, v212
	v_lshl_add_u64 v[212:213], v[180:181], 0, v[0:1]
	v_lshl_add_u64 v[214:215], v[212:213], 0, s[0:1]
	v_readfirstlane_b32 s0, v216
	s_mov_b32 m0, s0
	s_mov_b64 s[0:1], 0x4767000
	v_add_u32_e32 v216, 0x3000, v211
	s_nop 0
	v_readfirstlane_b32 vcc_lo, v214
	v_readfirstlane_b32 vcc_hi, v215
	s_nop 1
	v_subrev_u32_e32 v230, vcc_lo, v214
	v_lshl_add_u64 v[214:215], v[212:213], 0, s[0:1]
	v_readfirstlane_b32 s0, v216
	s_mov_b32 m0, s0
	s_mov_b64 s[0:1], 0x4768000
	v_add_u32_e32 v216, 0x4000, v211
	v_subrev_u32_e32 v231, vcc_lo, v214
	v_lshl_add_u64 v[214:215], v[212:213], 0, s[0:1]
	v_readfirstlane_b32 s0, v216
	s_mov_b32 m0, s0
	s_mov_b64 s[0:1], 0x4769000
	v_add_u32_e32 v211, 0x5000, v211
	v_lshl_add_u64 v[212:213], v[212:213], 0, s[0:1]
	v_readfirstlane_b32 s0, v211
	v_subrev_u32_e32 v232, vcc_lo, v214
	s_mov_b32 m0, s0
	s_nop 0
	v_subrev_u32_e32 v233, vcc_lo, v212
	v_mov_b32_e32 v182, v228
	v_mov_b32_e32 v183, v229
	v_mov_b32_e32 v180, v230
	v_mov_b32_e32 v181, v231
	v_mov_b32_e32 v253, v232
	v_mov_b32_e32 v254, v233
	v_readfirstlane_b32 s0, v185
	s_branch .LBB0_2476

; DEVI int otid() { int t = threadIdx.x; asm volatile("" : "+v"(t)); return t; }
; #define RAW_BARRIER() do { asm volatile("s_waitcnt lgkmcnt(0)" ::: "memory"); __builtin_amdgcn_s_barrier(); } while (0)
; template <int EPI, int NB>
; DEVI void gemm_tile(const GemmJob& J, int m0, int n0, unsigned char* smem) {
;     ...
;   const int tid = otid(), lane = tid & 63, wid = tid >> 6, wm = wid >> 1, wn = wid & 1;
;   const int l16 = lane & 15, g = lane >> 4;
;   f32x4 acc[4][NB];
; #pragma unroll
;   for (int i = 0; i < 4; ++i)
; #pragma unroll
;     for (int j = 0; j < NB; ++j) acc[i][j] = (f32x4){0.f, 0.f, 0.f, 0.f};
;   const int srow = tid >> 2, sch = tid & 3;
;   const int gch = sch ^ ((0 - (tid >> 4)) & 3);
;   const bf16_t* Ag = J.A + (size_t)(m0 + srow) * (J.ablk ? 32 : J.lda) + gch * 8;
;   const bf16_t* Bg = J.Bt + (size_t)(n0 + srow) * 32 + gch * 8;
;   const size_t Astep = (size_t)64 * (J.ablk ? 32 : J.lda), Ak = J.ablk ? (size_t)MROWS * 32 : (size_t)32, Bstep = (size_t)64 * 32, Bk = (size_t)J.NR * 32;
;   const int nk = J.K >> 5;
;   unsigned char* lds_t = smem + tid * 16;
;   const unsigned lbase = (unsigned)(uintptr_t)(__attribute__((address_space(3))) unsigned char*)smem;
;     ...
;   asm volatile("s_waitcnt vmcnt(0)" ::: "memory");
;   RAW_BARRIER();
; #pragma unroll
;   for (int st = 0; st < S - 1; ++st) GEMM_ISSUE(st, st);
; template <int EPI, int NB>
; DEVI void gemm_run(const GemmJob& J, unsigned char* smem, int rot) {
;     ...
;     const int ntiles = MT128 * J.ntn;
;     for (int t = b; t < ntiles; t += G) {
;       const int mt = t / J.ntn, nt = J.nt0 + (t - mt * J.ntn);
;       gemm_tile<EPI, NB>(J, mt * 128, nt * BN, smem);
.LBB0_2663:
	s_mul_hi_i32 s0, s3, 0x2e8ba2e9
	s_lshr_b32 s1, s0, 31
	s_ashr_i32 s0, s0, 2
	s_add_i32 s0, s0, s1
	s_mul_i32 s1, s0, 0xffffffea
	s_add_i32 s1, s1, s3
	v_mov_b32_e32 v208, v177
	s_lshl_b32 s8, s0, 7
	s_lshl_b32 s9, s1, 8
	s_nop 0
	s_mov_b64 s[28:29], 0x1000
	v_ashrrev_i32_e32 v10, 2, v208
	v_lshrrev_b32_e32 v0, 4, v208
	v_sub_u32_e32 v11, 0, v0
	v_add_u32_e32 v2, s8, v10
	v_add_u32_e32 v6, s9, v10
	v_xor_b32_e32 v0, v208, v11
	v_ashrrev_i32_e32 v3, 31, v2
	v_ashrrev_i32_e32 v7, 31, v6
	v_lshlrev_b64 v[2:3], 6, v[2:3]
	v_lshlrev_b32_e32 v0, 4, v0
	v_lshlrev_b64 v[6:7], 6, v[6:7]
	v_lshl_add_u64 v[4:5], v[146:147], 0, v[2:3]
	v_and_b32_e32 v0, 48, v0
	v_lshl_add_u64 v[6:7], v[180:181], 0, v[6:7]
	v_lshlrev_b32_e32 v209, 4, v208
	v_lshl_add_u64 v[4:5], v[4:5], 0, v[0:1]
	v_lshl_add_u64 v[6:7], v[6:7], 0, v[0:1]
	v_readfirstlane_b32 s1, v209
	v_add_u32_e32 v0, 0x1000, v209
	s_mov_b32 m0, s1
	v_readfirstlane_b32 s1, v0
	v_add_u32_e32 v0, 0x2000, v209
	s_waitcnt lgkmcnt(0)
	s_barrier
	global_load_lds_dwordx4 v[4:5], off
	v_lshl_add_u64 v[8:9], v[4:5], 0, s[28:29]
	s_mov_b32 m0, s1
	v_readfirstlane_b32 s1, v0
	v_add_u32_e32 v0, 0x3000, v209
	global_load_lds_dwordx4 v[8:9], off
	s_mov_b32 m0, s1
	v_readfirstlane_b32 s1, v0
	v_add_u32_e32 v0, 0x4000, v209
	global_load_lds_dwordx4 v[6:7], off
	v_lshl_add_u64 v[8:9], v[6:7], 0, s[28:29]
	s_mov_b32 m0, s1
	s_mov_b64 s[28:29], 0x2000
	v_readfirstlane_b32 s1, v0
	v_add_u32_e32 v0, 0x5000, v209
	global_load_lds_dwordx4 v[8:9], off
	v_lshl_add_u64 v[8:9], v[6:7], 0, s[28:29]
	s_mov_b32 m0, s1
	s_mov_b64 s[28:29], 0x3000
	v_readfirstlane_b32 s1, v0
	v_add_u32_e32 v0, 0x6000, v209
	global_load_lds_dwordx4 v[8:9], off
	v_lshl_add_u64 v[8:9], v[6:7], 0, s[28:29]
	s_mov_b32 m0, s1
	v_readfirstlane_b32 s1, v0
	v_add_u32_e32 v0, 0x7000, v209
	global_load_lds_dwordx4 v[8:9], off
	v_lshl_add_u64 v[8:9], v[4:5], 0, s[94:95]
	s_mov_b32 m0, s1
	s_mov_b64 s[28:29], 0x30b000
	v_readfirstlane_b32 s1, v0
	v_add_u32_e32 v0, 0x8000, v209
	global_load_lds_dwordx4 v[8:9], off
	v_lshl_add_u64 v[4:5], v[4:5], 0, s[28:29]
	s_mov_b32 m0, s1
	v_readfirstlane_b32 s1, v0
	v_add_u32_e32 v0, 0x9000, v209
	global_load_lds_dwordx4 v[4:5], off
	v_lshl_add_u64 v[4:5], v[6:7], 0, s[50:51]
	s_mov_b32 m0, s1
	s_mov_b64 s[28:29], 0x59000
	v_readfirstlane_b32 s1, v0
	v_add_u32_e32 v0, 0xa000, v209
	global_load_lds_dwordx4 v[4:5], off
	v_lshl_add_u64 v[4:5], v[6:7], 0, s[28:29]
	s_mov_b32 m0, s1
	s_mov_b64 s[28:29], 0x5a000
	v_readfirstlane_b32 s1, v0
	v_add_u32_e32 v0, 0xb000, v209
	global_load_lds_dwordx4 v[4:5], off
	v_lshl_add_u64 v[4:5], v[6:7], 0, s[28:29]
	s_mov_b32 m0, s1
	s_mov_b64 s[28:29], 0x5b000
	v_readfirstlane_b32 s1, v0
	global_load_lds_dwordx4 v[4:5], off
	v_lshl_add_u64 v[4:5], v[6:7], 0, s[28:29]
	s_mov_b32 m0, s1
	v_lshlrev_b32_e32 v0, 2, v208
	global_load_lds_dwordx4 v[4:5], off
	v_and_b32_e32 v0, 48, v0
	v_ashrrev_i32_e32 v4, 1, v208
	v_and_b32_e32 v210, 15, v208
	v_sub_u32_e32 v0, 0, v0
	v_and_b32_e32 v211, 0xffffffc0, v4
	v_bitop3_b32 v0, v208, 48, v0 bitop3:0x48
	v_or_b32_e32 v4, v211, v210
	v_lshl_or_b32 v212, v4, 6, v0
	v_lshlrev_b32_e32 v4, 1, v208
	v_and_b32_e32 v213, 0x80, v4
	v_or_b32_e32 v4, v213, v210
	v_lshl_or_b32 v0, v4, 6, v0
	v_add_u32_e32 v4, s2, v10
	s_mulk_i32 s0, 0x1600
	v_subrev_u32_e32 v4, s0, v4
	v_ashrrev_i32_e32 v5, 31, v4
	v_add_u32_e32 v214, 0x2000, v0
	v_bitop3_b32 v0, v208, 3, v11 bitop3:0x48
	v_lshlrev_b64 v[4:5], 6, v[4:5]
	v_mov_b32_e32 v6, 0
	s_mov_b32 s42, 2
	s_mov_b32 s20, 0
	s_mov_b64 s[30:31], 0x1000
	v_lshlrev_b32_e32 v0, 4, v0
	v_lshl_add_u64 v[184:185], v[182:183], 0, v[4:5]
	v_lshl_add_u64 v[186:187], v[130:131], 0, v[2:3]
	s_mov_b32 s43, 0
	v_mov_b32_e32 v7, v6
	v_mov_b32_e32 v8, v6
	v_mov_b32_e32 v9, v6
	v_mov_b32_e32 v14, v6
	v_mov_b32_e32 v15, v6
	v_mov_b32_e32 v16, v6
	v_mov_b32_e32 v17, v6
	v_mov_b32_e32 v2, v6
	v_mov_b32_e32 v3, v6
	v_mov_b32_e32 v4, v6
	v_mov_b32_e32 v5, v6
	v_mov_b32_e32 v10, v6
	v_mov_b32_e32 v11, v6
	v_mov_b32_e32 v12, v6
	v_mov_b32_e32 v13, v6
	v_mov_b32_e32 v22, v6
	v_mov_b32_e32 v23, v6
	v_mov_b32_e32 v24, v6
; #define RAW_BARRIER() do { asm volatile("s_waitcnt lgkmcnt(0)" ::: "memory"); __builtin_amdgcn_s_barrier(); } while (0)
; template <int EPI, int NB>
; DEVI void gemm_tile(const GemmJob& J, int m0, int n0, unsigned char* smem) {
;     ...
;   f32x4 acc[4][NB];
; #pragma unroll
;   for (int i = 0; i < 4; ++i)
; #pragma unroll
;     for (int j = 0; j < NB; ++j) acc[i][j] = (f32x4){0.f, 0.f, 0.f, 0.f};
;   const int srow = tid >> 2, sch = tid & 3;
;   const int gch = sch ^ ((0 - (tid >> 4)) & 3);
;   const bf16_t* Ag = J.A + (size_t)(m0 + srow) * (J.ablk ? 32 : J.lda) + gch * 8;
;   const bf16_t* Bg = J.Bt + (size_t)(n0 + srow) * 32 + gch * 8;
;   const size_t Astep = (size_t)64 * (J.ablk ? 32 : J.lda), Ak = J.ablk ? (size_t)MROWS * 32 : (size_t)32, Bstep = (size_t)64 * 32, Bk = (size_t)J.NR * 32;
;   const int nk = J.K >> 5;
;   unsigned char* lds_t = smem + tid * 16;
;   const unsigned lbase = (unsigned)(uintptr_t)(__attribute__((address_space(3))) unsigned char*)smem;
;     ...
;   asm volatile("s_waitcnt vmcnt(0)" ::: "memory");
;   RAW_BARRIER();
; #pragma unroll
;   for (int st = 0; st < S - 1; ++st) GEMM_ISSUE(st, st);
;   const int fsl = (g ^ ((0 - (l16 >> 2)) & 3)) << 4;
;   const int aofs = (wm * 64 + l16) * 64 + fsl;
;   const int bofs = A_BYTES + (wn * NB * 16 + l16) * 64 + fsl;
;   int cs = 0, is = S - 1;
; #pragma clang loop unroll(disable)
;   for (int kt = 0; kt < nk; ++kt) {
;     if (nk - 1 - kt >= S - 2) {
;       if constexpr (NB == 8) asm volatile("s_waitcnt vmcnt(6)" ::: "memory");
;       else                   asm volatile("s_waitcnt vmcnt(8)" ::: "memory");
;     } else {
;       asm volatile("s_waitcnt vmcnt(0)" ::: "memory");
;     }
;     RAW_BARRIER();
;     if (kt + S - 1 < nk) GEMM_ISSUE(kt + S - 1, is);
;     is = (is + 1 == S) ? 0 : is + 1;
	v_mov_b32_e32 v25, v6
	v_mov_b32_e32 v30, v6
	v_mov_b32_e32 v31, v6
	v_mov_b32_e32 v32, v6
	v_mov_b32_e32 v33, v6
	v_mov_b32_e32 v18, v6
	v_mov_b32_e32 v19, v6
	v_mov_b32_e32 v20, v6
	v_mov_b32_e32 v21, v6
	v_mov_b32_e32 v26, v6
	v_mov_b32_e32 v27, v6
	v_mov_b32_e32 v28, v6
	v_mov_b32_e32 v29, v6
	v_mov_b32_e32 v38, v6
	v_mov_b32_e32 v39, v6
	v_mov_b32_e32 v40, v6
	v_mov_b32_e32 v41, v6
	v_mov_b32_e32 v46, v6
	v_mov_b32_e32 v47, v6
	v_mov_b32_e32 v48, v6
	v_mov_b32_e32 v49, v6
	v_mov_b32_e32 v34, v6
	v_mov_b32_e32 v35, v6
	v_mov_b32_e32 v36, v6
	v_mov_b32_e32 v37, v6
	v_mov_b32_e32 v42, v6
	v_mov_b32_e32 v43, v6
	v_mov_b32_e32 v44, v6
	v_mov_b32_e32 v45, v6
	v_mov_b32_e32 v54, v6
	v_mov_b32_e32 v55, v6
	v_mov_b32_e32 v56, v6
	v_mov_b32_e32 v57, v6
	v_mov_b32_e32 v62, v6
	v_mov_b32_e32 v63, v6
	v_mov_b32_e32 v64, v6
	v_mov_b32_e32 v65, v6
	v_mov_b32_e32 v50, v6
	v_mov_b32_e32 v51, v6
	v_mov_b32_e32 v52, v6
	v_mov_b32_e32 v53, v6
	v_mov_b32_e32 v58, v6
	v_mov_b32_e32 v59, v6
	v_mov_b32_e32 v60, v6
	v_mov_b32_e32 v61, v6
	v_mov_b32_e32 v70, v6
	v_mov_b32_e32 v71, v6
	v_mov_b32_e32 v72, v6
	v_mov_b32_e32 v73, v6
	v_mov_b32_e32 v78, v6
	v_mov_b32_e32 v79, v6
	v_mov_b32_e32 v80, v6
	v_mov_b32_e32 v81, v6
	v_mov_b32_e32 v66, v6
	v_mov_b32_e32 v67, v6
	v_mov_b32_e32 v68, v6
	v_mov_b32_e32 v69, v6
	v_mov_b32_e32 v74, v6
	v_mov_b32_e32 v75, v6
	v_mov_b32_e32 v76, v6
	v_mov_b32_e32 v77, v6
	v_mov_b32_e32 v86, v6
	v_mov_b32_e32 v87, v6
	v_mov_b32_e32 v88, v6
	v_mov_b32_e32 v89, v6
	v_mov_b32_e32 v94, v6
	v_mov_b32_e32 v95, v6
	v_mov_b32_e32 v96, v6
	v_mov_b32_e32 v97, v6
	v_mov_b32_e32 v82, v6
	v_mov_b32_e32 v83, v6
	v_mov_b32_e32 v84, v6
	v_mov_b32_e32 v85, v6
	v_mov_b32_e32 v90, v6
	v_mov_b32_e32 v91, v6
	v_mov_b32_e32 v92, v6
	v_mov_b32_e32 v93, v6
	v_mov_b32_e32 v102, v6
	v_mov_b32_e32 v103, v6
	v_mov_b32_e32 v104, v6
	v_mov_b32_e32 v105, v6
	v_mov_b32_e32 v110, v6
	v_mov_b32_e32 v111, v6
	v_mov_b32_e32 v112, v6
	v_mov_b32_e32 v113, v6
	v_mov_b32_e32 v98, v6
	v_mov_b32_e32 v99, v6
	v_mov_b32_e32 v100, v6
	v_mov_b32_e32 v101, v6
	v_mov_b32_e32 v106, v6
	v_mov_b32_e32 v107, v6
	v_mov_b32_e32 v108, v6
	v_mov_b32_e32 v109, v6
	v_mov_b32_e32 v118, v6
	v_mov_b32_e32 v119, v6
	v_mov_b32_e32 v120, v6
	v_mov_b32_e32 v121, v6
	v_mov_b32_e32 v126, v6
	v_mov_b32_e32 v127, v6
	v_mov_b32_e32 v128, v6
	v_mov_b32_e32 v129, v6
	v_mov_b32_e32 v114, v6
	v_mov_b32_e32 v115, v6
	v_mov_b32_e32 v116, v6
	v_mov_b32_e32 v117, v6
	v_mov_b32_e32 v122, v6
	v_mov_b32_e32 v123, v6
	v_mov_b32_e32 v124, v6
	v_mov_b32_e32 v125, v6
	s_mul_i32 s0, s42, 0x6000
	v_add_u32_e32 v215, s0, v209
	v_lshl_add_u64 v[216:217], v[186:187], 0, v[0:1]
	v_readfirstlane_b32 s0, v215
	v_lshl_add_u64 v[218:219], v[216:217], 0, s[84:85]
	s_mov_b32 m0, s0
	v_lshl_add_u64 v[216:217], v[216:217], 0, s[12:13]
	s_nop 0
	v_readfirstlane_b32 s100, v218
	v_readfirstlane_b32 s101, v219
	s_nop 1
	v_subrev_u32_e32 v232, s100, v218
	v_add_u32_e32 v218, 0x1000, v215
	v_add_u32_e32 v220, 0x2000, v215
	v_readfirstlane_b32 s0, v218
	s_mov_b32 m0, s0
	v_readfirstlane_b32 s0, v220
	v_subrev_u32_e32 v233, s100, v216
	v_lshl_add_u64 v[216:217], v[184:185], 0, v[0:1]
	v_add_u32_e32 v220, 0x3000, v215
	v_lshl_add_u64 v[218:219], v[216:217], 0, s[36:37]
	s_mov_b32 m0, s0
	v_readfirstlane_b32 s0, v220
	v_add_u32_e32 v220, 0x4000, v215
	s_nop 0
	v_readfirstlane_b32 vcc_lo, v218
	v_readfirstlane_b32 vcc_hi, v219
	s_nop 1
	v_subrev_u32_e32 v234, vcc_lo, v218
	v_lshl_add_u64 v[218:219], v[216:217], 0, s[6:7]
	s_mov_b32 m0, s0
	v_readfirstlane_b32 s0, v220
	v_add_u32_e32 v215, 0x5000, v215
	v_subrev_u32_e32 v235, vcc_lo, v218
	v_lshl_add_u64 v[218:219], v[216:217], 0, s[88:89]
	s_mov_b32 m0, s0
	v_readfirstlane_b32 s0, v215
	v_subrev_u32_e32 v236, vcc_lo, v218
	v_lshl_add_u64 v[216:217], v[216:217], 0, s[90:91]
	s_mov_b32 m0, s0
	s_nop 0
	v_subrev_u32_e32 v237, vcc_lo, v216
	v_mov_b32_e32 v186, v232
	v_mov_b32_e32 v187, v233
	v_mov_b32_e32 v184, v234
	v_mov_b32_e32 v185, v235
	v_mov_b32_e32 v253, v236
	v_mov_b32_e32 v254, v237
	v_readfirstlane_b32 s0, v209
	s_branch .LBB0_2665

; DEVI int otid() { int t = threadIdx.x; asm volatile("" : "+v"(t)); return t; }
; #define RAW_BARRIER() do { asm volatile("s_waitcnt lgkmcnt(0)" ::: "memory"); __builtin_amdgcn_s_barrier(); } while (0)
; template <int EPI, int NB>
; DEVI void gemm_tile(const GemmJob& J, int m0, int n0, unsigned char* smem) {
;     ...
;   const int tid = otid(), lane = tid & 63, wid = tid >> 6, wm = wid >> 1, wn = wid & 1;
;   const int l16 = lane & 15, g = lane >> 4;
;   f32x4 acc[4][NB];
; #pragma unroll
;   for (int i = 0; i < 4; ++i)
; #pragma unroll
;     for (int j = 0; j < NB; ++j) acc[i][j] = (f32x4){0.f, 0.f, 0.f, 0.f};
;   const int srow = tid >> 2, sch = tid & 3;
;   const int gch = sch ^ ((0 - (tid >> 4)) & 3);
;   const bf16_t* Ag = J.A + (size_t)(m0 + srow) * (J.ablk ? 32 : J.lda) + gch * 8;
;   const bf16_t* Bg = J.Bt + (size_t)(n0 + srow) * 32 + gch * 8;
;   const size_t Astep = (size_t)64 * (J.ablk ? 32 : J.lda), Ak = J.ablk ? (size_t)MROWS * 32 : (size_t)32, Bstep = (size_t)64 * 32, Bk = (size_t)J.NR * 32;
;   const int nk = J.K >> 5;
;   unsigned char* lds_t = smem + tid * 16;
;   const unsigned lbase = (unsigned)(uintptr_t)(__attribute__((address_space(3))) unsigned char*)smem;
;     ...
;   asm volatile("s_waitcnt vmcnt(0)" ::: "memory");
;   RAW_BARRIER();
; #pragma unroll
;   for (int st = 0; st < S - 1; ++st) GEMM_ISSUE(st, st);
; template <int EPI, int NB>
; DEVI void gemm_run(const GemmJob& J, unsigned char* smem, int rot) {
;     ...
;     for (int q0 = lb; q0 < ntot; q0 += nlb) {
;       const int q = J.rev ? ntot - 1 - q0 : q0;
;       int grp = q / gsz; const int qq = q - grp * gsz;
;       const int mg = min(8, mcnt - grp * 8);
;       const int nt = qq / mg, mi = qq - nt * mg;
;       gemm_tile<EPI, NB>(J, (mlo + grp * 8 + mi) * 128, (J.nt0 + nt) * BN, smem);
.LBB0_2677:
	s_mul_hi_i32 s0, s3, 0x2e8ba2e9
	s_lshr_b32 s1, s0, 31
	s_ashr_i32 s0, s0, 5
	s_add_i32 s0, s0, s1
	s_lshl_b32 s1, s0, 3
	v_readlane_b32 s8, v251, 48
	s_sub_i32 s8, s8, s1
	s_min_i32 s9, s8, 8
	s_abs_i32 s20, s9
	v_cvt_f32_u32_e32 v0, s20
	s_sub_i32 s43, 0, s20
	s_mul_i32 s40, s0, 0xffffff50
	s_add_i32 s40, s40, s3
	v_rcp_iflag_f32_e32 v0, v0
	s_abs_i32 s41, s40
	s_xor_b32 s42, s40, s9
	s_ashr_i32 s42, s42, 31
	v_mul_f32_e32 v0, 0x4f7ffffe, v0
	v_cvt_u32_f32_e32 v0, v0
	v_mov_b32_e32 v208, v177
	s_nop 0
	v_readfirstlane_b32 s44, v0
	s_mul_i32 s43, s43, s44
	s_mul_hi_u32 s43, s44, s43
	s_add_i32 s44, s44, s43
	s_mul_hi_u32 s43, s41, s44
	s_mul_i32 s44, s43, s20
	s_sub_i32 s41, s41, s44
	s_add_i32 s45, s43, 1
	s_sub_i32 s44, s41, s20
	s_cmp_ge_u32 s41, s20
	s_cselect_b32 s43, s45, s43
	s_cselect_b32 s41, s44, s41
	s_add_i32 s44, s43, 1
	s_cmp_ge_u32 s41, s20
	s_cselect_b32 s20, s44, s43
	s_xor_b32 s20, s20, s42
	s_sub_i32 s20, s20, s42
	s_mul_i32 s41, s9, s20
	v_readlane_b32 s9, v250, 37
	s_add_i32 s1, s1, s9
	s_add_i32 s1, s1, s40
	s_sub_i32 s1, s1, s41
	s_lshl_b32 s9, s1, 7
	s_lshl_b32 s20, s20, 8
	v_ashrrev_i32_e32 v10, 2, v208
	v_lshrrev_b32_e32 v0, 4, v208
	v_sub_u32_e32 v11, 0, v0
	v_add_u32_e32 v2, s9, v10
	v_add_u32_e32 v4, s20, v10
	v_xor_b32_e32 v0, v208, v11
	v_ashrrev_i32_e32 v3, 31, v2
	v_ashrrev_i32_e32 v5, 31, v4
	v_lshlrev_b64 v[2:3], 6, v[2:3]
	v_lshlrev_b32_e32 v0, 4, v0
	v_lshlrev_b64 v[4:5], 6, v[4:5]
	v_lshl_add_u64 v[2:3], v[146:147], 0, v[2:3]
	v_and_b32_e32 v0, 48, v0
	v_lshl_add_u64 v[6:7], v[180:181], 0, v[4:5]
	v_lshlrev_b32_e32 v209, 4, v208
	v_lshl_add_u64 v[2:3], v[2:3], 0, v[0:1]
	v_lshl_add_u64 v[6:7], v[6:7], 0, v[0:1]
	v_readfirstlane_b32 s1, v209
	v_add_u32_e32 v0, 0x1000, v209
	s_mov_b32 m0, s1
	s_mov_b64 s[28:29], 0x1000
	v_readfirstlane_b32 s1, v0
	v_add_u32_e32 v0, 0x2000, v209
	s_waitcnt lgkmcnt(0)
	s_barrier
	global_load_lds_dwordx4 v[2:3], off
	v_lshl_add_u64 v[8:9], v[2:3], 0, s[28:29]
	s_mov_b32 m0, s1
	v_readfirstlane_b32 s1, v0
	v_add_u32_e32 v0, 0x3000, v209
	global_load_lds_dwordx4 v[8:9], off
	s_mov_b32 m0, s1
	v_readfirstlane_b32 s1, v0
	v_add_u32_e32 v0, 0x4000, v209
	global_load_lds_dwordx4 v[6:7], off
	v_lshl_add_u64 v[8:9], v[6:7], 0, s[28:29]
	s_mov_b32 m0, s1
	s_mov_b64 s[28:29], 0x2000
	v_readfirstlane_b32 s1, v0
	v_add_u32_e32 v0, 0x5000, v209
	global_load_lds_dwordx4 v[8:9], off
	v_lshl_add_u64 v[8:9], v[6:7], 0, s[28:29]
	s_mov_b32 m0, s1
	s_mov_b64 s[28:29], 0x3000
	v_readfirstlane_b32 s1, v0
	v_add_u32_e32 v0, 0x6000, v209
	global_load_lds_dwordx4 v[8:9], off
	v_lshl_add_u64 v[8:9], v[6:7], 0, s[28:29]
	s_mov_b32 m0, s1
	v_readfirstlane_b32 s1, v0
	v_add_u32_e32 v0, 0x7000, v209
	global_load_lds_dwordx4 v[8:9], off
	v_lshl_add_u64 v[8:9], v[2:3], 0, s[94:95]
	s_mov_b32 m0, s1
	s_mov_b64 s[28:29], 0x30b000
	v_readfirstlane_b32 s1, v0
	v_add_u32_e32 v0, 0x8000, v209
	global_load_lds_dwordx4 v[8:9], off
	v_lshl_add_u64 v[2:3], v[2:3], 0, s[28:29]
	s_mov_b32 m0, s1
	v_readfirstlane_b32 s1, v0
	v_add_u32_e32 v0, 0x9000, v209
	global_load_lds_dwordx4 v[2:3], off
	v_lshl_add_u64 v[2:3], v[6:7], 0, s[50:51]
	s_mov_b32 m0, s1
	s_mov_b64 s[28:29], 0x59000
	v_readfirstlane_b32 s1, v0
	v_add_u32_e32 v0, 0xa000, v209
	global_load_lds_dwordx4 v[2:3], off
	v_lshl_add_u64 v[2:3], v[6:7], 0, s[28:29]
	s_mov_b32 m0, s1
	s_mov_b64 s[28:29], 0x5a000
	v_readfirstlane_b32 s1, v0
	v_add_u32_e32 v0, 0xb000, v209
	global_load_lds_dwordx4 v[2:3], off
	v_lshl_add_u64 v[2:3], v[6:7], 0, s[28:29]
	s_mov_b32 m0, s1
	s_mov_b64 s[28:29], 0x5b000
	v_readfirstlane_b32 s1, v0
	global_load_lds_dwordx4 v[2:3], off
	v_lshl_add_u64 v[2:3], v[6:7], 0, s[28:29]
	s_mov_b32 m0, s1
	v_lshlrev_b32_e32 v0, 2, v208
	global_load_lds_dwordx4 v[2:3], off
	v_and_b32_e32 v0, 48, v0
	v_ashrrev_i32_e32 v2, 1, v208
	v_and_b32_e32 v210, 15, v208
	v_sub_u32_e32 v0, 0, v0
	v_and_b32_e32 v211, 0xffffffc0, v2
	v_bitop3_b32 v0, v208, 48, v0 bitop3:0x48
	v_or_b32_e32 v2, v211, v210
	v_lshl_or_b32 v212, v2, 6, v0
	v_lshlrev_b32_e32 v2, 1, v208
	v_and_b32_e32 v213, 0x80, v2
	s_sub_i32 s1, s2, s41
	s_mulk_i32 s0, 0xa8
	v_or_b32_e32 v2, v213, v210
	s_sub_i32 s0, s1, s0
	v_lshl_or_b32 v0, v2, 6, v0
	v_lshl_add_u32 v2, s0, 7, v10
	v_ashrrev_i32_e32 v3, 31, v2
	v_add_u32_e32 v214, 0x2000, v0
	v_bitop3_b32 v0, v208, 3, v11 bitop3:0x48
	v_lshlrev_b64 v[2:3], 6, v[2:3]
	v_mov_b32_e32 v6, 0
	s_mov_b32 s8, 0
	s_mov_b32 s42, 2
	s_mov_b64 s[30:31], 0x1000
	v_lshlrev_b32_e32 v0, 4, v0
	v_lshl_add_u64 v[184:185], v[182:183], 0, v[4:5]
; #define RAW_BARRIER() do { asm volatile("s_waitcnt lgkmcnt(0)" ::: "memory"); __builtin_amdgcn_s_barrier(); } while (0)
; template <int EPI, int NB>
; DEVI void gemm_tile(const GemmJob& J, int m0, int n0, unsigned char* smem) {
;     ...
;   f32x4 acc[4][NB];
; #pragma unroll
;   for (int i = 0; i < 4; ++i)
; #pragma unroll
;     for (int j = 0; j < NB; ++j) acc[i][j] = (f32x4){0.f, 0.f, 0.f, 0.f};
;   const int srow = tid >> 2, sch = tid & 3;
;   const int gch = sch ^ ((0 - (tid >> 4)) & 3);
;   const bf16_t* Ag = J.A + (size_t)(m0 + srow) * (J.ablk ? 32 : J.lda) + gch * 8;
;   const bf16_t* Bg = J.Bt + (size_t)(n0 + srow) * 32 + gch * 8;
;   const size_t Astep = (size_t)64 * (J.ablk ? 32 : J.lda), Ak = J.ablk ? (size_t)MROWS * 32 : (size_t)32, Bstep = (size_t)64 * 32, Bk = (size_t)J.NR * 32;
;   const int nk = J.K >> 5;
;   unsigned char* lds_t = smem + tid * 16;
;   const unsigned lbase = (unsigned)(uintptr_t)(__attribute__((address_space(3))) unsigned char*)smem;
;     ...
;   asm volatile("s_waitcnt vmcnt(0)" ::: "memory");
;   RAW_BARRIER();
; #pragma unroll
;   for (int st = 0; st < S - 1; ++st) GEMM_ISSUE(st, st);
;   const int fsl = (g ^ ((0 - (l16 >> 2)) & 3)) << 4;
;   const int aofs = (wm * 64 + l16) * 64 + fsl;
;   const int bofs = A_BYTES + (wn * NB * 16 + l16) * 64 + fsl;
;   int cs = 0, is = S - 1;
; #pragma clang loop unroll(disable)
;   for (int kt = 0; kt < nk; ++kt) {
;     if (nk - 1 - kt >= S - 2) {
;       if constexpr (NB == 8) asm volatile("s_waitcnt vmcnt(6)" ::: "memory");
;       else                   asm volatile("s_waitcnt vmcnt(8)" ::: "memory");
;     } else {
;       asm volatile("s_waitcnt vmcnt(0)" ::: "memory");
;     }
;     RAW_BARRIER();
;     if (kt + S - 1 < nk) GEMM_ISSUE(kt + S - 1, is);
;     is = (is + 1 == S) ? 0 : is + 1;
	v_lshl_add_u64 v[186:187], v[130:131], 0, v[2:3]
	s_mov_b32 s43, 0
	v_mov_b32_e32 v7, v6
	v_mov_b32_e32 v8, v6
	v_mov_b32_e32 v9, v6
	v_mov_b32_e32 v14, v6
	v_mov_b32_e32 v15, v6
	v_mov_b32_e32 v16, v6
	v_mov_b32_e32 v17, v6
	v_mov_b32_e32 v2, v6
	v_mov_b32_e32 v3, v6
	v_mov_b32_e32 v4, v6
	v_mov_b32_e32 v5, v6
	v_mov_b32_e32 v10, v6
	v_mov_b32_e32 v11, v6
	v_mov_b32_e32 v12, v6
	v_mov_b32_e32 v13, v6
	v_mov_b32_e32 v22, v6
	v_mov_b32_e32 v23, v6
	v_mov_b32_e32 v24, v6
	v_mov_b32_e32 v25, v6
	v_mov_b32_e32 v30, v6
	v_mov_b32_e32 v31, v6
	v_mov_b32_e32 v32, v6
	v_mov_b32_e32 v33, v6
	v_mov_b32_e32 v18, v6
	v_mov_b32_e32 v19, v6
	v_mov_b32_e32 v20, v6
	v_mov_b32_e32 v21, v6
	v_mov_b32_e32 v26, v6
	v_mov_b32_e32 v27, v6
	v_mov_b32_e32 v28, v6
	v_mov_b32_e32 v29, v6
	v_mov_b32_e32 v38, v6
	v_mov_b32_e32 v39, v6
	v_mov_b32_e32 v40, v6
	v_mov_b32_e32 v41, v6
	v_mov_b32_e32 v46, v6
	v_mov_b32_e32 v47, v6
	v_mov_b32_e32 v48, v6
	v_mov_b32_e32 v49, v6
	v_mov_b32_e32 v34, v6
	v_mov_b32_e32 v35, v6
	v_mov_b32_e32 v36, v6
	v_mov_b32_e32 v37, v6
	v_mov_b32_e32 v42, v6
	v_mov_b32_e32 v43, v6
	v_mov_b32_e32 v44, v6
	v_mov_b32_e32 v45, v6
	v_mov_b32_e32 v54, v6
	v_mov_b32_e32 v55, v6
	v_mov_b32_e32 v56, v6
	v_mov_b32_e32 v57, v6
	v_mov_b32_e32 v62, v6
	v_mov_b32_e32 v63, v6
	v_mov_b32_e32 v64, v6
	v_mov_b32_e32 v65, v6
	v_mov_b32_e32 v50, v6
	v_mov_b32_e32 v51, v6
	v_mov_b32_e32 v52, v6
	v_mov_b32_e32 v53, v6
	v_mov_b32_e32 v58, v6
	v_mov_b32_e32 v59, v6
	v_mov_b32_e32 v60, v6
	v_mov_b32_e32 v61, v6
	v_mov_b32_e32 v70, v6
	v_mov_b32_e32 v71, v6
	v_mov_b32_e32 v72, v6
	v_mov_b32_e32 v73, v6
	v_mov_b32_e32 v78, v6
	v_mov_b32_e32 v79, v6
	v_mov_b32_e32 v80, v6
	v_mov_b32_e32 v81, v6
	v_mov_b32_e32 v66, v6
	v_mov_b32_e32 v67, v6
	v_mov_b32_e32 v68, v6
	v_mov_b32_e32 v69, v6
	v_mov_b32_e32 v74, v6
	v_mov_b32_e32 v75, v6
	v_mov_b32_e32 v76, v6
	v_mov_b32_e32 v77, v6
	v_mov_b32_e32 v86, v6
	v_mov_b32_e32 v87, v6
	v_mov_b32_e32 v88, v6
	v_mov_b32_e32 v89, v6
	v_mov_b32_e32 v94, v6
	v_mov_b32_e32 v95, v6
	v_mov_b32_e32 v96, v6
	v_mov_b32_e32 v97, v6
	v_mov_b32_e32 v82, v6
	v_mov_b32_e32 v83, v6
	v_mov_b32_e32 v84, v6
	v_mov_b32_e32 v85, v6
	v_mov_b32_e32 v90, v6
	v_mov_b32_e32 v91, v6
	v_mov_b32_e32 v92, v6
	v_mov_b32_e32 v93, v6
	v_mov_b32_e32 v102, v6
	v_mov_b32_e32 v103, v6
	v_mov_b32_e32 v104, v6
	v_mov_b32_e32 v105, v6
	v_mov_b32_e32 v110, v6
	v_mov_b32_e32 v111, v6
	v_mov_b32_e32 v112, v6
	v_mov_b32_e32 v113, v6
	v_mov_b32_e32 v98, v6
	v_mov_b32_e32 v99, v6
	v_mov_b32_e32 v100, v6
	v_mov_b32_e32 v101, v6
	v_mov_b32_e32 v106, v6
	v_mov_b32_e32 v107, v6
	v_mov_b32_e32 v108, v6
	v_mov_b32_e32 v109, v6
	v_mov_b32_e32 v118, v6
	v_mov_b32_e32 v119, v6
	v_mov_b32_e32 v120, v6
	v_mov_b32_e32 v121, v6
	v_mov_b32_e32 v126, v6
	v_mov_b32_e32 v127, v6
	v_mov_b32_e32 v128, v6
	v_mov_b32_e32 v129, v6
	v_mov_b32_e32 v114, v6
	v_mov_b32_e32 v115, v6
	v_mov_b32_e32 v116, v6
	v_mov_b32_e32 v117, v6
	v_mov_b32_e32 v122, v6
	v_mov_b32_e32 v123, v6
	v_mov_b32_e32 v124, v6
	v_mov_b32_e32 v125, v6
	s_mul_i32 s0, s42, 0x6000
	v_add_u32_e32 v215, s0, v209
	v_lshl_add_u64 v[216:217], v[186:187], 0, v[0:1]
	v_readfirstlane_b32 s0, v215
	v_lshl_add_u64 v[218:219], v[216:217], 0, s[84:85]
	s_mov_b32 m0, s0
	v_lshl_add_u64 v[216:217], v[216:217], 0, s[12:13]
	s_nop 0
	v_readfirstlane_b32 s100, v218
	v_readfirstlane_b32 s101, v219
	s_nop 1
	v_subrev_u32_e32 v232, s100, v218
	v_add_u32_e32 v218, 0x1000, v215
	v_add_u32_e32 v220, 0x2000, v215
	v_readfirstlane_b32 s0, v218
	s_mov_b32 m0, s0
	v_readfirstlane_b32 s0, v220
	v_subrev_u32_e32 v233, s100, v216
	v_lshl_add_u64 v[216:217], v[184:185], 0, v[0:1]
	v_add_u32_e32 v220, 0x3000, v215
	v_lshl_add_u64 v[218:219], v[216:217], 0, s[36:37]
	s_mov_b32 m0, s0
	v_readfirstlane_b32 s0, v220
	v_add_u32_e32 v220, 0x4000, v215
	s_nop 0
	v_readfirstlane_b32 vcc_lo, v218
	v_readfirstlane_b32 vcc_hi, v219
	s_nop 1
	v_subrev_u32_e32 v234, vcc_lo, v218
	v_lshl_add_u64 v[218:219], v[216:217], 0, s[6:7]
	s_mov_b32 m0, s0
	v_readfirstlane_b32 s0, v220
	v_add_u32_e32 v215, 0x5000, v215
	v_subrev_u32_e32 v235, vcc_lo, v218
	v_lshl_add_u64 v[218:219], v[216:217], 0, s[88:89]
	s_mov_b32 m0, s0
	v_readfirstlane_b32 s0, v215
	v_subrev_u32_e32 v236, vcc_lo, v218
	v_lshl_add_u64 v[216:217], v[216:217], 0, s[90:91]
	s_mov_b32 m0, s0
	s_nop 0
	v_subrev_u32_e32 v237, vcc_lo, v216
	v_mov_b32_e32 v186, v232
	v_mov_b32_e32 v187, v233
	v_mov_b32_e32 v184, v234
	v_mov_b32_e32 v185, v235
	v_mov_b32_e32 v253, v236
	v_mov_b32_e32 v254, v237
	v_readfirstlane_b32 s0, v209
	s_branch .LBB0_2679

; DEVI int otid() { int t = threadIdx.x; asm volatile("" : "+v"(t)); return t; }
; #define RAW_BARRIER() do { asm volatile("s_waitcnt lgkmcnt(0)" ::: "memory"); __builtin_amdgcn_s_barrier(); } while (0)
; template <int EPI, int NB>
; DEVI void gemm_tile(const GemmJob& J, int m0, int n0, unsigned char* smem) {
;     ...
;   const int tid = otid(), lane = tid & 63, wid = tid >> 6, wm = wid >> 1, wn = wid & 1;
;   const int l16 = lane & 15, g = lane >> 4;
;   f32x4 acc[4][NB];
; #pragma unroll
;   for (int i = 0; i < 4; ++i)
; #pragma unroll
;     for (int j = 0; j < NB; ++j) acc[i][j] = (f32x4){0.f, 0.f, 0.f, 0.f};
;   const int srow = tid >> 2, sch = tid & 3;
;   const int gch = sch ^ ((0 - (tid >> 4)) & 3);
;   const bf16_t* Ag = J.A + (size_t)(m0 + srow) * (J.ablk ? 32 : J.lda) + gch * 8;
;   const bf16_t* Bg = J.Bt + (size_t)(n0 + srow) * 32 + gch * 8;
;   const size_t Astep = (size_t)64 * (J.ablk ? 32 : J.lda), Ak = J.ablk ? (size_t)MROWS * 32 : (size_t)32, Bstep = (size_t)64 * 32, Bk = (size_t)J.NR * 32;
;   const int nk = J.K >> 5;
;   unsigned char* lds_t = smem + tid * 16;
;   const unsigned lbase = (unsigned)(uintptr_t)(__attribute__((address_space(3))) unsigned char*)smem;
;     ...
;   asm volatile("s_waitcnt vmcnt(0)" ::: "memory");
;   RAW_BARRIER();
; #pragma unroll
;   for (int st = 0; st < S - 1; ++st) GEMM_ISSUE(st, st);
; template <int EPI, int NB>
; DEVI void gemm_run(const GemmJob& J, unsigned char* smem, int rot) {
;     ...
;     const int ntiles = MT128 * J.ntn;
;     for (int t = b; t < ntiles; t += G) {
;       const int mt = t / J.ntn, nt = J.nt0 + (t - mt * J.ntn);
;       gemm_tile<EPI, NB>(J, mt * 128, nt * BN, smem);
.LBB0_2742:
	s_ashr_i32 s0, s9, 31
	s_lshr_b32 s0, s0, 30
	s_add_i32 s0, s9, s0
	s_ashr_i32 s0, s0, 2
	s_lshl_b32 s3, s0, 7
	s_lshl_b32 s0, s0, 10
	s_lshl_b32 s1, s9, 8
	v_mov_b32_e32 v186, v177
	s_sub_i32 s2, s1, s0
	s_nop 0
	s_mov_b64 s[28:29], 0x1000
	v_ashrrev_i32_e32 v10, 2, v186
	v_lshrrev_b32_e32 v0, 4, v186
	v_sub_u32_e32 v11, 0, v0
	v_add_u32_e32 v2, s3, v10
	v_add_u32_e32 v6, s2, v10
	v_xor_b32_e32 v0, v186, v11
	v_ashrrev_i32_e32 v3, 31, v2
	v_ashrrev_i32_e32 v7, 31, v6
	v_lshlrev_b64 v[2:3], 6, v[2:3]
	v_lshlrev_b32_e32 v0, 4, v0
	v_lshlrev_b64 v[6:7], 6, v[6:7]
	v_lshl_add_u64 v[4:5], v[152:153], 0, v[2:3]
	v_and_b32_e32 v0, 48, v0
	v_lshl_add_u64 v[6:7], v[178:179], 0, v[6:7]
	v_lshlrev_b32_e32 v187, 4, v186
	v_lshl_add_u64 v[4:5], v[4:5], 0, v[0:1]
	v_lshl_add_u64 v[6:7], v[6:7], 0, v[0:1]
	v_readfirstlane_b32 s1, v187
	v_add_u32_e32 v0, 0x1000, v187
	s_mov_b32 m0, s1
	v_readfirstlane_b32 s1, v0
	v_add_u32_e32 v0, 0x2000, v187
	s_waitcnt lgkmcnt(0)
	s_barrier
	global_load_lds_dwordx4 v[4:5], off
	v_lshl_add_u64 v[8:9], v[4:5], 0, s[28:29]
	s_mov_b32 m0, s1
	v_readfirstlane_b32 s1, v0
	v_add_u32_e32 v0, 0x3000, v187
	global_load_lds_dwordx4 v[8:9], off
	s_mov_b32 m0, s1
	v_readfirstlane_b32 s1, v0
	v_add_u32_e32 v0, 0x4000, v187
	global_load_lds_dwordx4 v[6:7], off
	v_lshl_add_u64 v[8:9], v[6:7], 0, s[28:29]
	s_mov_b32 m0, s1
	s_mov_b64 s[28:29], 0x2000
	v_readfirstlane_b32 s1, v0
	v_add_u32_e32 v0, 0x5000, v187
	global_load_lds_dwordx4 v[8:9], off
	v_lshl_add_u64 v[8:9], v[6:7], 0, s[28:29]
	s_mov_b32 m0, s1
	s_mov_b64 s[28:29], 0x3000
	v_readfirstlane_b32 s1, v0
	v_add_u32_e32 v0, 0x6000, v187
	global_load_lds_dwordx4 v[8:9], off
	v_lshl_add_u64 v[8:9], v[6:7], 0, s[28:29]
	s_mov_b32 m0, s1
	v_readfirstlane_b32 s1, v0
	v_add_u32_e32 v0, 0x7000, v187
	global_load_lds_dwordx4 v[8:9], off
	v_lshl_add_u64 v[8:9], v[4:5], 0, s[94:95]
	s_mov_b32 m0, s1
	s_mov_b64 s[28:29], 0x30b000
	v_readfirstlane_b32 s1, v0
	v_add_u32_e32 v0, 0x8000, v187
	global_load_lds_dwordx4 v[8:9], off
	v_lshl_add_u64 v[4:5], v[4:5], 0, s[28:29]
	s_mov_b32 m0, s1
	v_readfirstlane_b32 s1, v0
	v_add_u32_e32 v0, 0x9000, v187
	global_load_lds_dwordx4 v[4:5], off
	v_lshl_add_u64 v[4:5], v[6:7], 0, s[22:23]
	s_mov_b32 m0, s1
	s_mov_b64 s[28:29], 0x11000
	v_readfirstlane_b32 s1, v0
	v_add_u32_e32 v0, 0xa000, v187
	global_load_lds_dwordx4 v[4:5], off
	v_lshl_add_u64 v[4:5], v[6:7], 0, s[28:29]
	s_mov_b32 m0, s1
	s_mov_b64 s[28:29], 0x12000
	v_readfirstlane_b32 s1, v0
	v_add_u32_e32 v0, 0xb000, v187
	global_load_lds_dwordx4 v[4:5], off
	v_lshl_add_u64 v[4:5], v[6:7], 0, s[28:29]
	s_mov_b32 m0, s1
	s_mov_b64 s[28:29], 0x13000
	v_readfirstlane_b32 s1, v0
	global_load_lds_dwordx4 v[4:5], off
	v_lshl_add_u64 v[4:5], v[6:7], 0, s[28:29]
	s_mov_b32 m0, s1
	v_lshlrev_b32_e32 v0, 2, v186
	global_load_lds_dwordx4 v[4:5], off
	v_and_b32_e32 v0, 48, v0
	v_ashrrev_i32_e32 v4, 1, v186
	v_and_b32_e32 v208, 15, v186
	v_sub_u32_e32 v0, 0, v0
	v_and_b32_e32 v209, 0xffffffc0, v4
	v_bitop3_b32 v0, v186, 48, v0 bitop3:0x48
	v_or_b32_e32 v4, v209, v208
	v_lshl_or_b32 v211, v4, 6, v0
	v_lshlrev_b32_e32 v4, 1, v186
	v_and_b32_e32 v210, 0x80, v4
	v_or_b32_e32 v4, v210, v208
	v_lshl_or_b32 v0, v4, 6, v0
	v_add_u32_e32 v4, s8, v10
	v_subrev_u32_e32 v4, s0, v4
	v_ashrrev_i32_e32 v5, 31, v4
	v_add_u32_e32 v212, 0x2000, v0
	v_bitop3_b32 v0, v186, 3, v11 bitop3:0x48
	v_lshlrev_b64 v[4:5], 6, v[4:5]
	v_lshl_add_u64 v[184:185], v[130:131], 0, v[2:3]
	v_mov_b32_e32 v2, 0
	s_mov_b32 s40, 2
	s_mov_b32 s20, 0
	s_mov_b64 s[30:31], 0x1000
	v_lshlrev_b32_e32 v0, 4, v0
	v_lshl_add_u64 v[182:183], v[180:181], 0, v[4:5]
	s_mov_b32 s41, 0
	v_mov_b32_e32 v3, v2
	v_mov_b32_e32 v4, v2
	v_mov_b32_e32 v5, v2
	v_mov_b32_e32 v6, v2
	v_mov_b32_e32 v7, v2
	v_mov_b32_e32 v8, v2
	v_mov_b32_e32 v9, v2
	v_mov_b32_e32 v10, v2
	v_mov_b32_e32 v11, v2
	v_mov_b32_e32 v12, v2
	v_mov_b32_e32 v13, v2
	v_mov_b32_e32 v14, v2
	v_mov_b32_e32 v15, v2
	v_mov_b32_e32 v16, v2
	v_mov_b32_e32 v17, v2
	v_mov_b32_e32 v18, v2
	v_mov_b32_e32 v19, v2
	v_mov_b32_e32 v20, v2
; #define RAW_BARRIER() do { asm volatile("s_waitcnt lgkmcnt(0)" ::: "memory"); __builtin_amdgcn_s_barrier(); } while (0)
; template <int EPI, int NB>
; DEVI void gemm_tile(const GemmJob& J, int m0, int n0, unsigned char* smem) {
;     ...
;   f32x4 acc[4][NB];
; #pragma unroll
;   for (int i = 0; i < 4; ++i)
; #pragma unroll
;     for (int j = 0; j < NB; ++j) acc[i][j] = (f32x4){0.f, 0.f, 0.f, 0.f};
;   const int srow = tid >> 2, sch = tid & 3;
;   const int gch = sch ^ ((0 - (tid >> 4)) & 3);
;   const bf16_t* Ag = J.A + (size_t)(m0 + srow) * (J.ablk ? 32 : J.lda) + gch * 8;
;   const bf16_t* Bg = J.Bt + (size_t)(n0 + srow) * 32 + gch * 8;
;   const size_t Astep = (size_t)64 * (J.ablk ? 32 : J.lda), Ak = J.ablk ? (size_t)MROWS * 32 : (size_t)32, Bstep = (size_t)64 * 32, Bk = (size_t)J.NR * 32;
;   const int nk = J.K >> 5;
;   unsigned char* lds_t = smem + tid * 16;
;   const unsigned lbase = (unsigned)(uintptr_t)(__attribute__((address_space(3))) unsigned char*)smem;
;     ...
;   asm volatile("s_waitcnt vmcnt(0)" ::: "memory");
;   RAW_BARRIER();
; #pragma unroll
;   for (int st = 0; st < S - 1; ++st) GEMM_ISSUE(st, st);
;   const int fsl = (g ^ ((0 - (l16 >> 2)) & 3)) << 4;
;   const int aofs = (wm * 64 + l16) * 64 + fsl;
;   const int bofs = A_BYTES + (wn * NB * 16 + l16) * 64 + fsl;
;   int cs = 0, is = S - 1;
; #pragma clang loop unroll(disable)
;   for (int kt = 0; kt < nk; ++kt) {
;     if (nk - 1 - kt >= S - 2) {
;       if constexpr (NB == 8) asm volatile("s_waitcnt vmcnt(6)" ::: "memory");
;       else                   asm volatile("s_waitcnt vmcnt(8)" ::: "memory");
;     } else {
;       asm volatile("s_waitcnt vmcnt(0)" ::: "memory");
;     }
;     RAW_BARRIER();
;     if (kt + S - 1 < nk) GEMM_ISSUE(kt + S - 1, is);
;     is = (is + 1 == S) ? 0 : is + 1;
	v_mov_b32_e32 v21, v2
	v_mov_b32_e32 v22, v2
	v_mov_b32_e32 v23, v2
	v_mov_b32_e32 v24, v2
	v_mov_b32_e32 v25, v2
	v_mov_b32_e32 v26, v2
	v_mov_b32_e32 v27, v2
	v_mov_b32_e32 v28, v2
	v_mov_b32_e32 v29, v2
	v_mov_b32_e32 v30, v2
	v_mov_b32_e32 v31, v2
	v_mov_b32_e32 v32, v2
	v_mov_b32_e32 v33, v2
	v_mov_b32_e32 v34, v2
	v_mov_b32_e32 v35, v2
	v_mov_b32_e32 v36, v2
	v_mov_b32_e32 v37, v2
	v_mov_b32_e32 v38, v2
	v_mov_b32_e32 v39, v2
	v_mov_b32_e32 v40, v2
	v_mov_b32_e32 v41, v2
	v_mov_b32_e32 v42, v2
	v_mov_b32_e32 v43, v2
	v_mov_b32_e32 v44, v2
	v_mov_b32_e32 v45, v2
	v_mov_b32_e32 v46, v2
	v_mov_b32_e32 v47, v2
	v_mov_b32_e32 v48, v2
	v_mov_b32_e32 v49, v2
	v_mov_b32_e32 v50, v2
	v_mov_b32_e32 v51, v2
	v_mov_b32_e32 v52, v2
	v_mov_b32_e32 v53, v2
	v_mov_b32_e32 v54, v2
	v_mov_b32_e32 v55, v2
	v_mov_b32_e32 v56, v2
	v_mov_b32_e32 v57, v2
	v_mov_b32_e32 v58, v2
	v_mov_b32_e32 v59, v2
	v_mov_b32_e32 v60, v2
	v_mov_b32_e32 v61, v2
	v_mov_b32_e32 v62, v2
	v_mov_b32_e32 v63, v2
	v_mov_b32_e32 v64, v2
	v_mov_b32_e32 v65, v2
	v_mov_b32_e32 v66, v2
	v_mov_b32_e32 v67, v2
	v_mov_b32_e32 v68, v2
	v_mov_b32_e32 v69, v2
	v_mov_b32_e32 v70, v2
	v_mov_b32_e32 v71, v2
	v_mov_b32_e32 v72, v2
	v_mov_b32_e32 v73, v2
	v_mov_b32_e32 v74, v2
	v_mov_b32_e32 v75, v2
	v_mov_b32_e32 v76, v2
	v_mov_b32_e32 v77, v2
	v_mov_b32_e32 v78, v2
	v_mov_b32_e32 v79, v2
	v_mov_b32_e32 v80, v2
	v_mov_b32_e32 v81, v2
	v_mov_b32_e32 v82, v2
	v_mov_b32_e32 v83, v2
	v_mov_b32_e32 v84, v2
	v_mov_b32_e32 v85, v2
	v_mov_b32_e32 v86, v2
	v_mov_b32_e32 v87, v2
	v_mov_b32_e32 v88, v2
	v_mov_b32_e32 v89, v2
	v_mov_b32_e32 v90, v2
	v_mov_b32_e32 v91, v2
	v_mov_b32_e32 v92, v2
	v_mov_b32_e32 v93, v2
	v_mov_b32_e32 v94, v2
	v_mov_b32_e32 v95, v2
	v_mov_b32_e32 v96, v2
	v_mov_b32_e32 v97, v2
	v_mov_b32_e32 v98, v2
	v_mov_b32_e32 v99, v2
	v_mov_b32_e32 v100, v2
	v_mov_b32_e32 v101, v2
	v_mov_b32_e32 v102, v2
	v_mov_b32_e32 v103, v2
	v_mov_b32_e32 v104, v2
	v_mov_b32_e32 v105, v2
	v_mov_b32_e32 v106, v2
	v_mov_b32_e32 v107, v2
	v_mov_b32_e32 v108, v2
	v_mov_b32_e32 v109, v2
	v_mov_b32_e32 v110, v2
	v_mov_b32_e32 v111, v2
	v_mov_b32_e32 v112, v2
	v_mov_b32_e32 v113, v2
	v_mov_b32_e32 v114, v2
	v_mov_b32_e32 v115, v2
	v_mov_b32_e32 v116, v2
	v_mov_b32_e32 v117, v2
	v_mov_b32_e32 v118, v2
	v_mov_b32_e32 v119, v2
	v_mov_b32_e32 v120, v2
	v_mov_b32_e32 v121, v2
	v_mov_b32_e32 v122, v2
	v_mov_b32_e32 v123, v2
	v_mov_b32_e32 v124, v2
	v_mov_b32_e32 v125, v2
	v_mov_b32_e32 v126, v2
	v_mov_b32_e32 v127, v2
	v_mov_b32_e32 v128, v2
	v_mov_b32_e32 v129, v2
	s_mul_i32 s0, s40, 0x6000
	v_add_u32_e32 v213, s0, v187
	v_lshl_add_u64 v[214:215], v[184:185], 0, v[0:1]
	v_readfirstlane_b32 s0, v213
	v_lshl_add_u64 v[216:217], v[214:215], 0, s[24:25]
	s_mov_b32 m0, s0
	v_lshl_add_u64 v[214:215], v[214:215], 0, s[26:27]
	s_nop 0
	v_readfirstlane_b32 s100, v216
	v_readfirstlane_b32 s101, v217
	s_nop 1
	v_subrev_u32_e32 v230, s100, v216
	v_add_u32_e32 v216, 0x1000, v213
	v_add_u32_e32 v218, 0x2000, v213
	v_readfirstlane_b32 s0, v216
	s_mov_b32 m0, s0
	v_readfirstlane_b32 s0, v218
	v_subrev_u32_e32 v231, s100, v214
	v_lshl_add_u64 v[214:215], v[182:183], 0, v[0:1]
	v_add_u32_e32 v218, 0x3000, v213
	v_lshl_add_u64 v[216:217], v[214:215], 0, s[10:11]
	s_mov_b32 m0, s0
	v_readfirstlane_b32 s0, v218
	v_add_u32_e32 v218, 0x4000, v213
	s_nop 0
	v_readfirstlane_b32 vcc_lo, v216
	v_readfirstlane_b32 vcc_hi, v217
	s_nop 1
	v_subrev_u32_e32 v232, vcc_lo, v216
	v_lshl_add_u64 v[216:217], v[214:215], 0, s[14:15]
	s_mov_b32 m0, s0
	v_readfirstlane_b32 s0, v218
	v_add_u32_e32 v213, 0x5000, v213
	v_subrev_u32_e32 v233, vcc_lo, v216
	v_lshl_add_u64 v[216:217], v[214:215], 0, s[16:17]
	s_mov_b32 m0, s0
	v_readfirstlane_b32 s0, v213
	v_subrev_u32_e32 v234, vcc_lo, v216
	v_lshl_add_u64 v[214:215], v[214:215], 0, s[18:19]
	s_mov_b32 m0, s0
	s_nop 0
	v_subrev_u32_e32 v235, vcc_lo, v214
	v_mov_b32_e32 v184, v230
	v_mov_b32_e32 v185, v231
	v_mov_b32_e32 v182, v232
	v_mov_b32_e32 v183, v233
	v_mov_b32_e32 v253, v234
	v_mov_b32_e32 v254, v235
	v_readfirstlane_b32 s0, v187
	s_branch .LBB0_2744

; DEVI int otid() { int t = threadIdx.x; asm volatile("" : "+v"(t)); return t; }
; #define RAW_BARRIER() do { asm volatile("s_waitcnt lgkmcnt(0)" ::: "memory"); __builtin_amdgcn_s_barrier(); } while (0)
; template <int EPI, int NB>
; DEVI void gemm_tile(const GemmJob& J, int m0, int n0, unsigned char* smem) {
;     ...
;   const int tid = otid(), lane = tid & 63, wid = tid >> 6, wm = wid >> 1, wn = wid & 1;
;   const int l16 = lane & 15, g = lane >> 4;
;   f32x4 acc[4][NB];
; #pragma unroll
;   for (int i = 0; i < 4; ++i)
; #pragma unroll
;     for (int j = 0; j < NB; ++j) acc[i][j] = (f32x4){0.f, 0.f, 0.f, 0.f};
;   const int srow = tid >> 2, sch = tid & 3;
;   const int gch = sch ^ ((0 - (tid >> 4)) & 3);
;   const bf16_t* Ag = J.A + (size_t)(m0 + srow) * (J.ablk ? 32 : J.lda) + gch * 8;
;   const bf16_t* Bg = J.Bt + (size_t)(n0 + srow) * 32 + gch * 8;
;   const size_t Astep = (size_t)64 * (J.ablk ? 32 : J.lda), Ak = J.ablk ? (size_t)MROWS * 32 : (size_t)32, Bstep = (size_t)64 * 32, Bk = (size_t)J.NR * 32;
;   const int nk = J.K >> 5;
;   unsigned char* lds_t = smem + tid * 16;
;   const unsigned lbase = (unsigned)(uintptr_t)(__attribute__((address_space(3))) unsigned char*)smem;
;     ...
;   asm volatile("s_waitcnt vmcnt(0)" ::: "memory");
;   RAW_BARRIER();
; #pragma unroll
;   for (int st = 0; st < S - 1; ++st) GEMM_ISSUE(st, st);
; template <int EPI, int NB>
; DEVI void gemm_run(const GemmJob& J, unsigned char* smem, int rot) {
;     ...
;     for (int q0 = lb; q0 < ntot; q0 += nlb) {
;       const int q = J.rev ? ntot - 1 - q0 : q0;
;       int grp = q / gsz; const int qq = q - grp * gsz;
;       const int mg = min(8, mcnt - grp * 8);
;       const int nt = qq / mg, mi = qq - nt * mg;
;       gemm_tile<EPI, NB>(J, (mlo + grp * 8 + mi) * 128, (J.nt0 + nt) * BN, smem);
.LBB0_2819:
	s_not_b32 s0, s9
	s_add_i32 s0, s1, s0
	s_ashr_i32 s1, s0, 31
	s_lshr_b32 s1, s1, 27
	s_add_i32 s1, s0, s1
	s_ashr_i32 s41, s1, 5
	s_lshl_b32 s3, s41, 3
	v_readlane_b32 s2, v251, 48
	s_sub_i32 s2, s2, s3
	s_min_i32 s20, s2, 8
	s_abs_i32 s40, s20
	v_cvt_f32_u32_e32 v0, s40
	s_sub_i32 s43, 0, s40
	s_andn2_b32 s1, s1, 31
	s_sub_i32 s0, s0, s1
	v_rcp_iflag_f32_e32 v0, v0
	s_abs_i32 s1, s0
	s_xor_b32 s42, s0, s20
	s_ashr_i32 s42, s42, 31
	v_mul_f32_e32 v0, 0x4f7ffffe, v0
	v_cvt_u32_f32_e32 v0, v0
	v_mov_b32_e32 v186, v177
	s_nop 0
	v_readfirstlane_b32 s44, v0
	s_mul_i32 s43, s43, s44
	s_mul_hi_u32 s43, s44, s43
	s_add_i32 s44, s44, s43
	s_mul_hi_u32 s43, s1, s44
	s_mul_i32 s44, s43, s40
	s_sub_i32 s1, s1, s44
	s_add_i32 s45, s43, 1
	s_sub_i32 s44, s1, s40
	s_cmp_ge_u32 s1, s40
	s_cselect_b32 s43, s45, s43
	s_cselect_b32 s1, s44, s1
	s_add_i32 s44, s43, 1
	s_cmp_ge_u32 s1, s40
	s_cselect_b32 s1, s44, s43
	s_xor_b32 s1, s1, s42
	s_sub_i32 s1, s1, s42
	s_mul_i32 s42, s20, s1
	v_readlane_b32 s20, v250, 37
	s_add_i32 s3, s3, s20
	s_add_i32 s3, s3, s0
	s_sub_i32 s0, s3, s42
	s_lshl_b32 s20, s0, 7
	s_lshl_b32 s3, s1, 8
	v_ashrrev_i32_e32 v10, 2, v186
	v_lshrrev_b32_e32 v0, 4, v186
	v_sub_u32_e32 v11, 0, v0
	v_add_u32_e32 v2, s20, v10
	v_add_u32_e32 v4, s3, v10
	v_xor_b32_e32 v0, v186, v11
	v_ashrrev_i32_e32 v3, 31, v2
	v_ashrrev_i32_e32 v5, 31, v4
	v_lshlrev_b64 v[2:3], 6, v[2:3]
	v_lshlrev_b32_e32 v0, 4, v0
	v_lshlrev_b64 v[4:5], 6, v[4:5]
	v_lshl_add_u64 v[2:3], v[152:153], 0, v[2:3]
	v_and_b32_e32 v0, 48, v0
	v_lshl_add_u64 v[6:7], v[178:179], 0, v[4:5]
	v_lshlrev_b32_e32 v187, 4, v186
	v_lshl_add_u64 v[2:3], v[2:3], 0, v[0:1]
	v_lshl_add_u64 v[6:7], v[6:7], 0, v[0:1]
	v_readfirstlane_b32 s0, v187
	v_add_u32_e32 v0, 0x1000, v187
	s_mov_b32 m0, s0
	s_mov_b64 s[28:29], 0x1000
	v_readfirstlane_b32 s0, v0
	v_add_u32_e32 v0, 0x2000, v187
	s_waitcnt lgkmcnt(0)
	s_barrier
	global_load_lds_dwordx4 v[2:3], off
	v_lshl_add_u64 v[8:9], v[2:3], 0, s[28:29]
	s_mov_b32 m0, s0
	v_readfirstlane_b32 s0, v0
	v_add_u32_e32 v0, 0x3000, v187
	global_load_lds_dwordx4 v[8:9], off
	s_mov_b32 m0, s0
	v_readfirstlane_b32 s0, v0
	global_load_lds_dwordx4 v[6:7], off
	v_lshl_add_u64 v[8:9], v[6:7], 0, s[28:29]
	s_mov_b32 m0, s0
	s_mov_b64 s[0:1], 0x2000
	v_add_u32_e32 v0, 0x4000, v187
	global_load_lds_dwordx4 v[8:9], off
	v_lshl_add_u64 v[8:9], v[6:7], 0, s[0:1]
	v_readfirstlane_b32 s0, v0
	s_mov_b32 m0, s0
	s_mov_b64 s[0:1], 0x3000
	v_add_u32_e32 v0, 0x5000, v187
	global_load_lds_dwordx4 v[8:9], off
	v_lshl_add_u64 v[8:9], v[6:7], 0, s[0:1]
	v_readfirstlane_b32 s0, v0
	v_add_u32_e32 v0, 0x6000, v187
	s_mov_b32 m0, s0
	v_readfirstlane_b32 s0, v0
	global_load_lds_dwordx4 v[8:9], off
	s_mov_b32 m0, s0
	s_mov_b64 s[0:1], 0x30b000
	v_add_u32_e32 v0, 0x7000, v187
	v_lshl_add_u64 v[8:9], v[2:3], 0, s[94:95]
	v_lshl_add_u64 v[2:3], v[2:3], 0, s[0:1]
	v_readfirstlane_b32 s0, v0
	v_add_u32_e32 v0, 0x8000, v187
	global_load_lds_dwordx4 v[8:9], off
	s_mov_b32 m0, s0
	v_readfirstlane_b32 s0, v0
	global_load_lds_dwordx4 v[2:3], off
	v_lshl_add_u64 v[2:3], v[6:7], 0, s[22:23]
	s_mov_b32 m0, s0
	s_mov_b64 s[0:1], 0x11000
	v_add_u32_e32 v0, 0x9000, v187
	global_load_lds_dwordx4 v[2:3], off
	v_lshl_add_u64 v[2:3], v[6:7], 0, s[0:1]
	v_readfirstlane_b32 s0, v0
	s_mov_b32 m0, s0
	s_mov_b64 s[0:1], 0x12000
	v_add_u32_e32 v0, 0xa000, v187
	global_load_lds_dwordx4 v[2:3], off
	v_lshl_add_u64 v[2:3], v[6:7], 0, s[0:1]
	v_readfirstlane_b32 s0, v0
	s_mov_b32 m0, s0
	s_mov_b64 s[0:1], 0x13000
	v_add_u32_e32 v0, 0xb000, v187
	global_load_lds_dwordx4 v[2:3], off
	v_lshl_add_u64 v[2:3], v[6:7], 0, s[0:1]
	v_readfirstlane_b32 s0, v0
	s_mov_b32 m0, s0
	v_lshlrev_b32_e32 v0, 2, v186
	global_load_lds_dwordx4 v[2:3], off
	v_and_b32_e32 v0, 48, v0
	v_ashrrev_i32_e32 v2, 1, v186
	v_and_b32_e32 v208, 15, v186
	v_sub_u32_e32 v0, 0, v0
	v_and_b32_e32 v209, 0xffffffc0, v2
	v_bitop3_b32 v0, v186, 48, v0 bitop3:0x48
	v_or_b32_e32 v2, v209, v208
	v_lshl_or_b32 v211, v2, 6, v0
	v_lshlrev_b32_e32 v2, 1, v186
	v_and_b32_e32 v210, 0x80, v2
	s_sub_i32 s0, s8, s42
	s_mul_i32 s41, s41, 24
	v_or_b32_e32 v2, v210, v208
	s_sub_i32 s0, s0, s41
	v_lshl_or_b32 v0, v2, 6, v0
	v_lshl_add_u32 v2, s0, 7, v10
	v_ashrrev_i32_e32 v3, 31, v2
	v_lshlrev_b64 v[2:3], 6, v[2:3]
	v_add_u32_e32 v212, 0x2000, v0
	v_bitop3_b32 v0, v186, 3, v11 bitop3:0x48
	v_lshl_add_u64 v[184:185], v[130:131], 0, v[2:3]
	v_mov_b32_e32 v2, 0
	s_mov_b32 s2, 0
	s_mov_b32 s40, 2
	s_mov_b64 s[30:31], 0x1000
	v_lshlrev_b32_e32 v0, 4, v0
; #define RAW_BARRIER() do { asm volatile("s_waitcnt lgkmcnt(0)" ::: "memory"); __builtin_amdgcn_s_barrier(); } while (0)
; template <int EPI, int NB>
; DEVI void gemm_tile(const GemmJob& J, int m0, int n0, unsigned char* smem) {
;     ...
;   f32x4 acc[4][NB];
; #pragma unroll
;   for (int i = 0; i < 4; ++i)
; #pragma unroll
;     for (int j = 0; j < NB; ++j) acc[i][j] = (f32x4){0.f, 0.f, 0.f, 0.f};
;   const int srow = tid >> 2, sch = tid & 3;
;   const int gch = sch ^ ((0 - (tid >> 4)) & 3);
;   const bf16_t* Ag = J.A + (size_t)(m0 + srow) * (J.ablk ? 32 : J.lda) + gch * 8;
;   const bf16_t* Bg = J.Bt + (size_t)(n0 + srow) * 32 + gch * 8;
;   const size_t Astep = (size_t)64 * (J.ablk ? 32 : J.lda), Ak = J.ablk ? (size_t)MROWS * 32 : (size_t)32, Bstep = (size_t)64 * 32, Bk = (size_t)J.NR * 32;
;   const int nk = J.K >> 5;
;   unsigned char* lds_t = smem + tid * 16;
;   const unsigned lbase = (unsigned)(uintptr_t)(__attribute__((address_space(3))) unsigned char*)smem;
;     ...
;   asm volatile("s_waitcnt vmcnt(0)" ::: "memory");
;   RAW_BARRIER();
; #pragma unroll
;   for (int st = 0; st < S - 1; ++st) GEMM_ISSUE(st, st);
;   const int fsl = (g ^ ((0 - (l16 >> 2)) & 3)) << 4;
;   const int aofs = (wm * 64 + l16) * 64 + fsl;
;   const int bofs = A_BYTES + (wn * NB * 16 + l16) * 64 + fsl;
;   int cs = 0, is = S - 1;
; #pragma clang loop unroll(disable)
;   for (int kt = 0; kt < nk; ++kt) {
;     if (nk - 1 - kt >= S - 2) {
;       if constexpr (NB == 8) asm volatile("s_waitcnt vmcnt(6)" ::: "memory");
;       else                   asm volatile("s_waitcnt vmcnt(8)" ::: "memory");
;     } else {
;       asm volatile("s_waitcnt vmcnt(0)" ::: "memory");
;     }
;     RAW_BARRIER();
;     if (kt + S - 1 < nk) GEMM_ISSUE(kt + S - 1, is);
;     is = (is + 1 == S) ? 0 : is + 1;
	v_lshl_add_u64 v[182:183], v[180:181], 0, v[4:5]
	s_mov_b32 s41, 0
	v_mov_b32_e32 v3, v2
	v_mov_b32_e32 v4, v2
	v_mov_b32_e32 v5, v2
	v_mov_b32_e32 v6, v2
	v_mov_b32_e32 v7, v2
	v_mov_b32_e32 v8, v2
	v_mov_b32_e32 v9, v2
	v_mov_b32_e32 v10, v2
	v_mov_b32_e32 v11, v2
	v_mov_b32_e32 v12, v2
	v_mov_b32_e32 v13, v2
	v_mov_b32_e32 v14, v2
	v_mov_b32_e32 v15, v2
	v_mov_b32_e32 v16, v2
	v_mov_b32_e32 v17, v2
	v_mov_b32_e32 v18, v2
	v_mov_b32_e32 v19, v2
	v_mov_b32_e32 v20, v2
	v_mov_b32_e32 v21, v2
	v_mov_b32_e32 v22, v2
	v_mov_b32_e32 v23, v2
	v_mov_b32_e32 v24, v2
	v_mov_b32_e32 v25, v2
	v_mov_b32_e32 v26, v2
	v_mov_b32_e32 v27, v2
	v_mov_b32_e32 v28, v2
	v_mov_b32_e32 v29, v2
	v_mov_b32_e32 v30, v2
	v_mov_b32_e32 v31, v2
	v_mov_b32_e32 v32, v2
	v_mov_b32_e32 v33, v2
	v_mov_b32_e32 v34, v2
	v_mov_b32_e32 v35, v2
	v_mov_b32_e32 v36, v2
	v_mov_b32_e32 v37, v2
	v_mov_b32_e32 v38, v2
	v_mov_b32_e32 v39, v2
	v_mov_b32_e32 v40, v2
	v_mov_b32_e32 v41, v2
	v_mov_b32_e32 v42, v2
	v_mov_b32_e32 v43, v2
	v_mov_b32_e32 v44, v2
	v_mov_b32_e32 v45, v2
	v_mov_b32_e32 v46, v2
	v_mov_b32_e32 v47, v2
	v_mov_b32_e32 v48, v2
	v_mov_b32_e32 v49, v2
	v_mov_b32_e32 v50, v2
	v_mov_b32_e32 v51, v2
	v_mov_b32_e32 v52, v2
	v_mov_b32_e32 v53, v2
	v_mov_b32_e32 v54, v2
	v_mov_b32_e32 v55, v2
	v_mov_b32_e32 v56, v2
	v_mov_b32_e32 v57, v2
	v_mov_b32_e32 v58, v2
	v_mov_b32_e32 v59, v2
	v_mov_b32_e32 v60, v2
	v_mov_b32_e32 v61, v2
	v_mov_b32_e32 v62, v2
	v_mov_b32_e32 v63, v2
	v_mov_b32_e32 v64, v2
	v_mov_b32_e32 v65, v2
	v_mov_b32_e32 v66, v2
	v_mov_b32_e32 v67, v2
	v_mov_b32_e32 v68, v2
	v_mov_b32_e32 v69, v2
	v_mov_b32_e32 v70, v2
	v_mov_b32_e32 v71, v2
	v_mov_b32_e32 v72, v2
	v_mov_b32_e32 v73, v2
	v_mov_b32_e32 v74, v2
	v_mov_b32_e32 v75, v2
	v_mov_b32_e32 v76, v2
	v_mov_b32_e32 v77, v2
	v_mov_b32_e32 v78, v2
	v_mov_b32_e32 v79, v2
	v_mov_b32_e32 v80, v2
	v_mov_b32_e32 v81, v2
	v_mov_b32_e32 v82, v2
	v_mov_b32_e32 v83, v2
	v_mov_b32_e32 v84, v2
	v_mov_b32_e32 v85, v2
	v_mov_b32_e32 v86, v2
	v_mov_b32_e32 v87, v2
	v_mov_b32_e32 v88, v2
	v_mov_b32_e32 v89, v2
	v_mov_b32_e32 v90, v2
	v_mov_b32_e32 v91, v2
	v_mov_b32_e32 v92, v2
	v_mov_b32_e32 v93, v2
	v_mov_b32_e32 v94, v2
	v_mov_b32_e32 v95, v2
	v_mov_b32_e32 v96, v2
	v_mov_b32_e32 v97, v2
	v_mov_b32_e32 v98, v2
	v_mov_b32_e32 v99, v2
	v_mov_b32_e32 v100, v2
	v_mov_b32_e32 v101, v2
	v_mov_b32_e32 v102, v2
	v_mov_b32_e32 v103, v2
	v_mov_b32_e32 v104, v2
	v_mov_b32_e32 v105, v2
	v_mov_b32_e32 v106, v2
	v_mov_b32_e32 v107, v2
	v_mov_b32_e32 v108, v2
	v_mov_b32_e32 v109, v2
	v_mov_b32_e32 v110, v2
	v_mov_b32_e32 v111, v2
	v_mov_b32_e32 v112, v2
	v_mov_b32_e32 v113, v2
	v_mov_b32_e32 v114, v2
	v_mov_b32_e32 v115, v2
	v_mov_b32_e32 v116, v2
	v_mov_b32_e32 v117, v2
	v_mov_b32_e32 v118, v2
	v_mov_b32_e32 v119, v2
	v_mov_b32_e32 v120, v2
	v_mov_b32_e32 v121, v2
	v_mov_b32_e32 v122, v2
	v_mov_b32_e32 v123, v2
	v_mov_b32_e32 v124, v2
	v_mov_b32_e32 v125, v2
	v_mov_b32_e32 v126, v2
	v_mov_b32_e32 v127, v2
	v_mov_b32_e32 v128, v2
	v_mov_b32_e32 v129, v2
	s_mul_i32 s0, s40, 0x6000
	v_add_u32_e32 v213, s0, v187
	v_lshl_add_u64 v[214:215], v[184:185], 0, v[0:1]
	v_readfirstlane_b32 s0, v213
	v_lshl_add_u64 v[216:217], v[214:215], 0, s[24:25]
	s_mov_b32 m0, s0
	v_lshl_add_u64 v[214:215], v[214:215], 0, s[26:27]
	s_nop 0
	v_readfirstlane_b32 s100, v216
	v_readfirstlane_b32 s101, v217
	s_nop 1
	v_subrev_u32_e32 v230, s100, v216
	v_add_u32_e32 v216, 0x1000, v213
	v_add_u32_e32 v218, 0x2000, v213
	v_readfirstlane_b32 s0, v216
	s_mov_b32 m0, s0
	v_readfirstlane_b32 s0, v218
	v_subrev_u32_e32 v231, s100, v214
	v_lshl_add_u64 v[214:215], v[182:183], 0, v[0:1]
	v_add_u32_e32 v218, 0x3000, v213
	v_lshl_add_u64 v[216:217], v[214:215], 0, s[10:11]
	s_mov_b32 m0, s0
	v_readfirstlane_b32 s0, v218
	v_add_u32_e32 v218, 0x4000, v213
	s_nop 0
	v_readfirstlane_b32 vcc_lo, v216
	v_readfirstlane_b32 vcc_hi, v217
	s_nop 1
	v_subrev_u32_e32 v232, vcc_lo, v216
	v_lshl_add_u64 v[216:217], v[214:215], 0, s[14:15]
	s_mov_b32 m0, s0
	v_readfirstlane_b32 s0, v218
	v_add_u32_e32 v213, 0x5000, v213
	v_subrev_u32_e32 v233, vcc_lo, v216
	v_lshl_add_u64 v[216:217], v[214:215], 0, s[16:17]
	s_mov_b32 m0, s0
	v_readfirstlane_b32 s0, v213
	v_subrev_u32_e32 v234, vcc_lo, v216
	v_lshl_add_u64 v[214:215], v[214:215], 0, s[18:19]
	s_mov_b32 m0, s0
	s_nop 0
	v_subrev_u32_e32 v235, vcc_lo, v214
	v_mov_b32_e32 v184, v230
	v_mov_b32_e32 v185, v231
	v_mov_b32_e32 v182, v232
	v_mov_b32_e32 v183, v233
	v_mov_b32_e32 v253, v234
	v_mov_b32_e32 v254, v235
	v_readfirstlane_b32 s0, v187
	s_branch .LBB0_2821
